# per-MMA-block s_setprio 1/0 flips removed from all 8-phase GEMM loops (A/B amplified on w_up: -4 % of the phase); barrier v4
# speedup vs baseline: 1.0108x; 1.0108x over previous
.LBB0_81:
	ds_read_b128 v[146:149], v152
	ds_read_b128 v[154:157], v152 offset:1024
	ds_read_b128 v[158:161], v152 offset:2048
	ds_read_b128 v[162:165], v152 offset:3072
	s_add_i32 s78, s1, 2
	s_cmp_gt_u32 s1, 13
	s_cselect_b32 s62, s75, s2
	s_cselect_b32 s58, s74, s0
	s_mov_b32 m0, s65
	ds_read_b128 v[166:169], v153
	ds_read_b128 v[170:173], v153 offset:1024
	ds_read_b128 v[174:177], v153 offset:2048
	ds_read_b128 v[178:181], v153 offset:3072
	ds_read_b128 v[182:185], v153 offset:4096
	ds_read_b128 v[186:189], v153 offset:5120
	ds_read_b128 v[190:193], v153 offset:6144
	ds_read_b128 v[194:197], v153 offset:7168
	global_load_lds_dwordx4 v[142:143], off
	s_mov_b32 m0, s66
	s_nop 0
	global_load_lds_dwordx4 v[144:145], off
	s_waitcnt lgkmcnt(8)
	s_barrier
	s_waitcnt lgkmcnt(0)
	s_waitcnt lgkmcnt(0)
	v_mfma_f32_16x16x32_bf16 v[124:127], v[146:149], v[166:169], v[124:127]
	v_mfma_f32_16x16x32_bf16 v[120:123], v[158:161], v[166:169], v[120:123]
	v_mfma_f32_16x16x32_bf16 v[108:111], v[146:149], v[174:177], v[108:111]
	v_mfma_f32_16x16x32_bf16 v[104:107], v[158:161], v[174:177], v[104:107]
	v_mfma_f32_16x16x32_bf16 v[92:95], v[146:149], v[182:185], v[92:95]
	v_mfma_f32_16x16x32_bf16 v[88:91], v[158:161], v[182:185], v[88:91]
	v_mfma_f32_16x16x32_bf16 v[76:79], v[146:149], v[190:193], v[76:79]
	v_mfma_f32_16x16x32_bf16 v[72:75], v[158:161], v[190:193], v[72:75]
	v_mfma_f32_16x16x32_bf16 v[124:127], v[154:157], v[170:173], v[124:127]
	v_mfma_f32_16x16x32_bf16 v[120:123], v[162:165], v[170:173], v[120:123]
	v_mfma_f32_16x16x32_bf16 v[108:111], v[154:157], v[178:181], v[108:111]
	v_mfma_f32_16x16x32_bf16 v[104:107], v[162:165], v[178:181], v[104:107]
	v_mfma_f32_16x16x32_bf16 v[92:95], v[154:157], v[186:189], v[92:95]
	v_mfma_f32_16x16x32_bf16 v[88:91], v[162:165], v[186:189], v[88:91]
	v_mfma_f32_16x16x32_bf16 v[76:79], v[154:157], v[194:197], v[76:79]
	v_mfma_f32_16x16x32_bf16 v[72:75], v[162:165], v[194:197], v[72:75]
	s_barrier
	s_cselect_b32 s8, 0, s78
	s_ashr_i32 s63, s62, 31
	s_lshl_b64 s[60:61], s[62:63], 11
	s_add_u32 s1, s70, s60
	s_addc_u32 s79, s71, s61
	s_lshl_b64 s[60:61], s[8:9], 7
	s_add_u32 s80, s1, s60
	s_addc_u32 s81, s79, s61
	s_mov_b32 m0, s19
	v_lshl_add_u64 v[214:215], s[80:81], 0, v[132:133]
	ds_read_b128 v[198:201], v152 offset:16384
	ds_read_b128 v[202:205], v152 offset:17408
	ds_read_b128 v[206:209], v152 offset:18432
	ds_read_b128 v[210:213], v152 offset:19456
	global_load_lds_dwordx4 v[214:215], off
	v_lshl_add_u64 v[214:215], s[80:81], 0, v[128:129]
	s_mov_b32 m0, s20
	s_nop 0
	global_load_lds_dwordx4 v[214:215], off
	s_barrier
	s_waitcnt lgkmcnt(0)
	s_waitcnt lgkmcnt(0)
	v_mfma_f32_16x16x32_bf16 v[116:119], v[198:201], v[166:169], v[116:119]
	v_mfma_f32_16x16x32_bf16 v[112:115], v[206:209], v[166:169], v[112:115]
	v_mfma_f32_16x16x32_bf16 v[100:103], v[198:201], v[174:177], v[100:103]
	v_mfma_f32_16x16x32_bf16 v[96:99], v[206:209], v[174:177], v[96:99]
	v_mfma_f32_16x16x32_bf16 v[84:87], v[198:201], v[182:185], v[84:87]
	v_mfma_f32_16x16x32_bf16 v[80:83], v[206:209], v[182:185], v[80:83]
	v_mfma_f32_16x16x32_bf16 v[68:71], v[198:201], v[190:193], v[68:71]
	v_mfma_f32_16x16x32_bf16 v[64:67], v[206:209], v[190:193], v[64:67]
	v_mfma_f32_16x16x32_bf16 v[116:119], v[202:205], v[170:173], v[116:119]
	v_mfma_f32_16x16x32_bf16 v[112:115], v[210:213], v[170:173], v[112:115]
	v_mfma_f32_16x16x32_bf16 v[100:103], v[202:205], v[178:181], v[100:103]
	v_mfma_f32_16x16x32_bf16 v[96:99], v[210:213], v[178:181], v[96:99]
	v_mfma_f32_16x16x32_bf16 v[84:87], v[202:205], v[186:189], v[84:87]
	v_mfma_f32_16x16x32_bf16 v[80:83], v[210:213], v[186:189], v[80:83]
	v_mfma_f32_16x16x32_bf16 v[68:71], v[202:205], v[194:197], v[68:71]
	v_mfma_f32_16x16x32_bf16 v[64:67], v[210:213], v[194:197], v[64:67]
	s_ashr_i32 s59, s58, 31
	s_lshl_b64 s[80:81], s[58:59], 11
	s_add_u32 s82, s16, s80
	s_addc_u32 s83, s17, s81
	s_add_u32 s80, s82, s60
	s_addc_u32 s81, s83, s61
	s_mov_b32 m0, s18
	v_lshl_add_u64 v[214:215], s[80:81], 0, v[134:135]
	s_barrier
	ds_read_b128 v[166:169], v153 offset:16384
	ds_read_b128 v[170:173], v153 offset:17408
	ds_read_b128 v[174:177], v153 offset:18432
	ds_read_b128 v[178:181], v153 offset:19456
	ds_read_b128 v[182:185], v153 offset:20480
	ds_read_b128 v[186:189], v153 offset:21504
	ds_read_b128 v[190:193], v153 offset:22528
	ds_read_b128 v[194:197], v153 offset:23552
	global_load_lds_dwordx4 v[214:215], off
	v_lshl_add_u64 v[214:215], s[80:81], 0, v[130:131]
	s_mov_b32 m0, s21
	s_nop 0
	global_load_lds_dwordx4 v[214:215], off
	s_barrier
	s_waitcnt lgkmcnt(0)
	s_waitcnt lgkmcnt(0)
	v_mfma_f32_16x16x32_bf16 v[60:63], v[146:149], v[166:169], v[60:63]
	v_mfma_f32_16x16x32_bf16 v[56:59], v[158:161], v[166:169], v[56:59]
	v_mfma_f32_16x16x32_bf16 v[44:47], v[146:149], v[174:177], v[44:47]
	v_mfma_f32_16x16x32_bf16 v[40:43], v[158:161], v[174:177], v[40:43]
	v_mfma_f32_16x16x32_bf16 v[28:31], v[146:149], v[182:185], v[28:31]
	v_mfma_f32_16x16x32_bf16 v[24:27], v[158:161], v[182:185], v[24:27]
	v_mfma_f32_16x16x32_bf16 v[12:15], v[146:149], v[190:193], v[12:15]
	v_mfma_f32_16x16x32_bf16 v[8:11], v[158:161], v[190:193], v[8:11]
	v_mfma_f32_16x16x32_bf16 v[60:63], v[154:157], v[170:173], v[60:63]
	v_mfma_f32_16x16x32_bf16 v[56:59], v[162:165], v[170:173], v[56:59]
	v_mfma_f32_16x16x32_bf16 v[44:47], v[154:157], v[178:181], v[44:47]
	v_mfma_f32_16x16x32_bf16 v[40:43], v[162:165], v[178:181], v[40:43]
	v_mfma_f32_16x16x32_bf16 v[28:31], v[154:157], v[186:189], v[28:31]
	v_mfma_f32_16x16x32_bf16 v[24:27], v[162:165], v[186:189], v[24:27]
	v_mfma_f32_16x16x32_bf16 v[12:15], v[154:157], v[194:197], v[12:15]
	v_mfma_f32_16x16x32_bf16 v[8:11], v[162:165], v[194:197], v[8:11]
	s_barrier
	s_bitset1_b32 s62, 7
	s_ashr_i32 s63, s62, 31
	s_lshl_b64 s[62:63], s[62:63], 11
	s_add_u32 s80, s70, s62
	s_addc_u32 s81, s71, s63
	s_add_u32 s62, s80, s60
	s_addc_u32 s63, s81, s61
	s_mov_b32 m0, s22
	v_lshl_add_u64 v[146:147], s[62:63], 0, v[132:133]
	global_load_lds_dwordx4 v[146:147], off
	v_lshl_add_u64 v[146:147], s[62:63], 0, v[128:129]
	s_mov_b32 m0, s23
	s_nop 0
	global_load_lds_dwordx4 v[146:147], off
	s_waitcnt vmcnt(6)
	s_barrier
	v_mfma_f32_16x16x32_bf16 v[52:55], v[198:201], v[166:169], v[52:55]
	v_mfma_f32_16x16x32_bf16 v[48:51], v[206:209], v[166:169], v[48:51]
	v_mfma_f32_16x16x32_bf16 v[36:39], v[198:201], v[174:177], v[36:39]
	v_mfma_f32_16x16x32_bf16 v[32:35], v[206:209], v[174:177], v[32:35]
	v_mfma_f32_16x16x32_bf16 v[20:23], v[198:201], v[182:185], v[20:23]
	v_mfma_f32_16x16x32_bf16 v[16:19], v[206:209], v[182:185], v[16:19]
	v_mfma_f32_16x16x32_bf16 v[4:7], v[198:201], v[190:193], v[4:7]
	v_mfma_f32_16x16x32_bf16 v[0:3], v[206:209], v[190:193], v[0:3]
	v_mfma_f32_16x16x32_bf16 v[52:55], v[202:205], v[170:173], v[52:55]
	v_mfma_f32_16x16x32_bf16 v[48:51], v[210:213], v[170:173], v[48:51]
	v_mfma_f32_16x16x32_bf16 v[36:39], v[202:205], v[178:181], v[36:39]
	v_mfma_f32_16x16x32_bf16 v[32:35], v[210:213], v[178:181], v[32:35]
	v_mfma_f32_16x16x32_bf16 v[20:23], v[202:205], v[186:189], v[20:23]
	v_mfma_f32_16x16x32_bf16 v[16:19], v[210:213], v[186:189], v[16:19]
	v_mfma_f32_16x16x32_bf16 v[4:7], v[202:205], v[194:197], v[4:7]
	v_mfma_f32_16x16x32_bf16 v[0:3], v[210:213], v[194:197], v[0:3]
	s_barrier
	ds_read_b128 v[146:149], v152 offset:32768
	ds_read_b128 v[154:157], v152 offset:33792
	ds_read_b128 v[158:161], v152 offset:34816
	ds_read_b128 v[162:165], v152 offset:35840
	s_bitset1_b32 s58, 7
	s_ashr_i32 s59, s58, 31
	s_lshl_b64 s[58:59], s[58:59], 11
	s_add_u32 s58, s16, s58
	s_addc_u32 s59, s17, s59
	s_add_u32 s58, s58, s60
	s_addc_u32 s59, s59, s61
	s_mov_b32 m0, s24
	v_lshl_add_u64 v[198:199], s[58:59], 0, v[134:135]
	ds_read_b128 v[166:169], v153 offset:32768
	ds_read_b128 v[170:173], v153 offset:33792
	ds_read_b128 v[174:177], v153 offset:34816
	ds_read_b128 v[178:181], v153 offset:35840
	ds_read_b128 v[182:185], v153 offset:36864
	ds_read_b128 v[186:189], v153 offset:37888
	ds_read_b128 v[190:193], v153 offset:38912
	ds_read_b128 v[194:197], v153 offset:39936
	global_load_lds_dwordx4 v[198:199], off
	v_lshl_add_u64 v[198:199], s[58:59], 0, v[130:131]
	s_mov_b32 m0, s25
	s_nop 0
	global_load_lds_dwordx4 v[198:199], off
	s_waitcnt lgkmcnt(8)
	s_barrier
	s_waitcnt lgkmcnt(0)
	s_waitcnt lgkmcnt(0)
	v_mfma_f32_16x16x32_bf16 v[124:127], v[146:149], v[166:169], v[124:127]
	v_mfma_f32_16x16x32_bf16 v[120:123], v[158:161], v[166:169], v[120:123]
	v_mfma_f32_16x16x32_bf16 v[108:111], v[146:149], v[174:177], v[108:111]
	v_mfma_f32_16x16x32_bf16 v[104:107], v[158:161], v[174:177], v[104:107]
	v_mfma_f32_16x16x32_bf16 v[92:95], v[146:149], v[182:185], v[92:95]
	v_mfma_f32_16x16x32_bf16 v[88:91], v[158:161], v[182:185], v[88:91]
	v_mfma_f32_16x16x32_bf16 v[76:79], v[146:149], v[190:193], v[76:79]
	v_mfma_f32_16x16x32_bf16 v[72:75], v[158:161], v[190:193], v[72:75]
	v_mfma_f32_16x16x32_bf16 v[124:127], v[154:157], v[170:173], v[124:127]
	v_mfma_f32_16x16x32_bf16 v[120:123], v[162:165], v[170:173], v[120:123]
	v_mfma_f32_16x16x32_bf16 v[108:111], v[154:157], v[178:181], v[108:111]
	v_mfma_f32_16x16x32_bf16 v[104:107], v[162:165], v[178:181], v[104:107]
	v_mfma_f32_16x16x32_bf16 v[92:95], v[154:157], v[186:189], v[92:95]
	v_mfma_f32_16x16x32_bf16 v[88:91], v[162:165], v[186:189], v[88:91]
	v_mfma_f32_16x16x32_bf16 v[76:79], v[154:157], v[194:197], v[76:79]
	v_mfma_f32_16x16x32_bf16 v[72:75], v[162:165], v[194:197], v[72:75]
	s_barrier
	s_or_b32 s8, s8, 1
	s_lshl_b64 s[58:59], s[8:9], 7
	s_add_u32 s60, s1, s58
	s_addc_u32 s61, s79, s59
	s_mov_b32 m0, s26
	v_lshl_add_u64 v[214:215], s[60:61], 0, v[132:133]
	ds_read_b128 v[198:201], v152 offset:49152
	ds_read_b128 v[202:205], v152 offset:50176
	ds_read_b128 v[206:209], v152 offset:51200
	ds_read_b128 v[210:213], v152 offset:52224
	global_load_lds_dwordx4 v[214:215], off
	v_lshl_add_u64 v[214:215], s[60:61], 0, v[128:129]
	s_mov_b32 m0, s27
	s_nop 0
	global_load_lds_dwordx4 v[214:215], off
	s_barrier
	s_waitcnt lgkmcnt(0)
	s_waitcnt lgkmcnt(0)
	v_mfma_f32_16x16x32_bf16 v[116:119], v[198:201], v[166:169], v[116:119]
	v_mfma_f32_16x16x32_bf16 v[112:115], v[206:209], v[166:169], v[112:115]
	v_mfma_f32_16x16x32_bf16 v[100:103], v[198:201], v[174:177], v[100:103]
	v_mfma_f32_16x16x32_bf16 v[96:99], v[206:209], v[174:177], v[96:99]
	v_mfma_f32_16x16x32_bf16 v[84:87], v[198:201], v[182:185], v[84:87]
	v_mfma_f32_16x16x32_bf16 v[80:83], v[206:209], v[182:185], v[80:83]
	v_mfma_f32_16x16x32_bf16 v[68:71], v[198:201], v[190:193], v[68:71]
	v_mfma_f32_16x16x32_bf16 v[64:67], v[206:209], v[190:193], v[64:67]
	v_mfma_f32_16x16x32_bf16 v[116:119], v[202:205], v[170:173], v[116:119]
	v_mfma_f32_16x16x32_bf16 v[112:115], v[210:213], v[170:173], v[112:115]
	v_mfma_f32_16x16x32_bf16 v[100:103], v[202:205], v[178:181], v[100:103]
	v_mfma_f32_16x16x32_bf16 v[96:99], v[210:213], v[178:181], v[96:99]
	v_mfma_f32_16x16x32_bf16 v[84:87], v[202:205], v[186:189], v[84:87]
	v_mfma_f32_16x16x32_bf16 v[80:83], v[210:213], v[186:189], v[80:83]
	v_mfma_f32_16x16x32_bf16 v[68:71], v[202:205], v[194:197], v[68:71]
	v_mfma_f32_16x16x32_bf16 v[64:67], v[210:213], v[194:197], v[64:67]
	s_add_u32 s60, s82, s58
	s_addc_u32 s61, s83, s59
	s_mov_b32 m0, s28
	v_lshl_add_u64 v[214:215], s[60:61], 0, v[134:135]
	s_barrier
	ds_read_b128 v[166:169], v153 offset:49152
	ds_read_b128 v[170:173], v153 offset:50176
	ds_read_b128 v[174:177], v153 offset:51200
	ds_read_b128 v[178:181], v153 offset:52224
	ds_read_b128 v[182:185], v153 offset:53248
	ds_read_b128 v[186:189], v153 offset:54272
	ds_read_b128 v[190:193], v153 offset:55296
	ds_read_b128 v[194:197], v153 offset:56320
	global_load_lds_dwordx4 v[214:215], off
	v_lshl_add_u64 v[214:215], s[60:61], 0, v[130:131]
	s_mov_b32 m0, s29
	s_nop 0
	global_load_lds_dwordx4 v[214:215], off
	s_barrier
	s_waitcnt lgkmcnt(0)
	s_waitcnt lgkmcnt(0)
	v_mfma_f32_16x16x32_bf16 v[60:63], v[146:149], v[166:169], v[60:63]
	v_mfma_f32_16x16x32_bf16 v[56:59], v[158:161], v[166:169], v[56:59]
	v_mfma_f32_16x16x32_bf16 v[44:47], v[146:149], v[174:177], v[44:47]
	v_mfma_f32_16x16x32_bf16 v[40:43], v[158:161], v[174:177], v[40:43]
	v_mfma_f32_16x16x32_bf16 v[28:31], v[146:149], v[182:185], v[28:31]
	v_mfma_f32_16x16x32_bf16 v[24:27], v[158:161], v[182:185], v[24:27]
	v_mfma_f32_16x16x32_bf16 v[12:15], v[146:149], v[190:193], v[12:15]
	v_mfma_f32_16x16x32_bf16 v[8:11], v[158:161], v[190:193], v[8:11]
	v_mfma_f32_16x16x32_bf16 v[60:63], v[154:157], v[170:173], v[60:63]
	v_mfma_f32_16x16x32_bf16 v[56:59], v[162:165], v[170:173], v[56:59]
	v_mfma_f32_16x16x32_bf16 v[44:47], v[154:157], v[178:181], v[44:47]
	v_mfma_f32_16x16x32_bf16 v[40:43], v[162:165], v[178:181], v[40:43]
	v_mfma_f32_16x16x32_bf16 v[28:31], v[154:157], v[186:189], v[28:31]
	v_mfma_f32_16x16x32_bf16 v[24:27], v[162:165], v[186:189], v[24:27]
	v_mfma_f32_16x16x32_bf16 v[12:15], v[154:157], v[194:197], v[12:15]
	v_mfma_f32_16x16x32_bf16 v[8:11], v[162:165], v[194:197], v[8:11]
	s_barrier
	s_add_u32 s58, s80, s58
	s_addc_u32 s59, s81, s59
	s_mov_b32 m0, s30
	v_lshl_add_u64 v[146:147], s[58:59], 0, v[132:133]
	global_load_lds_dwordx4 v[146:147], off
	v_lshl_add_u64 v[146:147], s[58:59], 0, v[128:129]
	s_mov_b32 m0, s31
	s_nop 0
	global_load_lds_dwordx4 v[146:147], off
	s_waitcnt vmcnt(6)
	s_barrier
	v_mfma_f32_16x16x32_bf16 v[52:55], v[198:201], v[166:169], v[52:55]
	v_mfma_f32_16x16x32_bf16 v[48:51], v[206:209], v[166:169], v[48:51]
	v_mfma_f32_16x16x32_bf16 v[36:39], v[198:201], v[174:177], v[36:39]
	v_mfma_f32_16x16x32_bf16 v[32:35], v[206:209], v[174:177], v[32:35]
	v_mfma_f32_16x16x32_bf16 v[20:23], v[198:201], v[182:185], v[20:23]
	v_mfma_f32_16x16x32_bf16 v[16:19], v[206:209], v[182:185], v[16:19]
	v_mfma_f32_16x16x32_bf16 v[4:7], v[198:201], v[190:193], v[4:7]
	v_mfma_f32_16x16x32_bf16 v[0:3], v[206:209], v[190:193], v[0:3]
	v_mfma_f32_16x16x32_bf16 v[52:55], v[202:205], v[170:173], v[52:55]
	v_mfma_f32_16x16x32_bf16 v[48:51], v[210:213], v[170:173], v[48:51]
	v_mfma_f32_16x16x32_bf16 v[36:39], v[202:205], v[178:181], v[36:39]
	v_mfma_f32_16x16x32_bf16 v[32:35], v[210:213], v[178:181], v[32:35]
	v_mfma_f32_16x16x32_bf16 v[20:23], v[202:205], v[186:189], v[20:23]
	v_mfma_f32_16x16x32_bf16 v[16:19], v[210:213], v[186:189], v[16:19]
	v_mfma_f32_16x16x32_bf16 v[4:7], v[202:205], v[194:197], v[4:7]
	v_mfma_f32_16x16x32_bf16 v[0:3], v[210:213], v[194:197], v[0:3]
	v_lshl_add_u64 v[142:143], v[142:143], 0, s[10:11]
	v_lshl_add_u64 v[144:145], v[144:145], 0, s[10:11]
	s_cmp_ge_u32 s78, s3
	s_mov_b32 s1, s78
	s_barrier
	s_cbranch_scc0 .LBB0_81
	s_andn2_b64 vcc, exec, s[56:57]
	s_cbranch_vccnz .LBB0_84
	s_bitset1_b32 s0, 7
	s_ashr_i32 s1, s0, 31
	s_lshl_b64 s[0:1], s[0:1], 11
	s_add_u32 s0, s16, s0
	s_addc_u32 s1, s17, s1
	v_lshl_add_u64 v[194:195], s[0:1], 0, v[134:135]
	s_mov_b32 m0, s65
	v_lshl_add_u64 v[194:195], v[194:195], 0, s[52:53]
	ds_read_b128 v[142:145], v152
	ds_read_b128 v[146:149], v152 offset:1024
	ds_read_b128 v[154:157], v152 offset:2048
	ds_read_b128 v[158:161], v152 offset:3072
	ds_read_b128 v[162:165], v153
	ds_read_b128 v[166:169], v153 offset:1024
	ds_read_b128 v[170:173], v153 offset:2048
	ds_read_b128 v[174:177], v153 offset:3072
	ds_read_b128 v[178:181], v153 offset:4096
	ds_read_b128 v[182:185], v153 offset:5120
	ds_read_b128 v[186:189], v153 offset:6144
	ds_read_b128 v[190:193], v153 offset:7168
	global_load_lds_dwordx4 v[194:195], off
	v_lshl_add_u64 v[194:195], s[0:1], 0, v[130:131]
	v_lshl_add_u64 v[194:195], v[194:195], 0, s[52:53]
	s_mov_b32 m0, s66
	s_nop 0
	global_load_lds_dwordx4 v[194:195], off
	s_barrier
	s_waitcnt lgkmcnt(0)
	s_waitcnt lgkmcnt(0)
	v_mfma_f32_16x16x32_bf16 v[124:127], v[142:145], v[162:165], v[124:127]
	v_mfma_f32_16x16x32_bf16 v[120:123], v[154:157], v[162:165], v[120:123]
	v_mfma_f32_16x16x32_bf16 v[108:111], v[142:145], v[170:173], v[108:111]
	v_mfma_f32_16x16x32_bf16 v[104:107], v[154:157], v[170:173], v[104:107]
	v_mfma_f32_16x16x32_bf16 v[92:95], v[142:145], v[178:181], v[92:95]
	v_mfma_f32_16x16x32_bf16 v[88:91], v[154:157], v[178:181], v[88:91]
	v_mfma_f32_16x16x32_bf16 v[76:79], v[142:145], v[186:189], v[76:79]
	v_mfma_f32_16x16x32_bf16 v[72:75], v[154:157], v[186:189], v[72:75]
	v_mfma_f32_16x16x32_bf16 v[124:127], v[146:149], v[166:169], v[124:127]
	v_mfma_f32_16x16x32_bf16 v[120:123], v[158:161], v[166:169], v[120:123]
	v_mfma_f32_16x16x32_bf16 v[108:111], v[146:149], v[174:177], v[108:111]
	v_mfma_f32_16x16x32_bf16 v[104:107], v[158:161], v[174:177], v[104:107]
	v_mfma_f32_16x16x32_bf16 v[92:95], v[146:149], v[182:185], v[92:95]
	v_mfma_f32_16x16x32_bf16 v[88:91], v[158:161], v[182:185], v[88:91]
	v_mfma_f32_16x16x32_bf16 v[76:79], v[146:149], v[190:193], v[76:79]
	v_mfma_f32_16x16x32_bf16 v[72:75], v[158:161], v[190:193], v[72:75]
	s_barrier
	ds_read_b128 v[194:197], v152 offset:16384
	ds_read_b128 v[198:201], v152 offset:17408
	ds_read_b128 v[202:205], v152 offset:18432
	ds_read_b128 v[206:209], v152 offset:19456
	s_barrier
	s_waitcnt lgkmcnt(0)
	s_waitcnt lgkmcnt(0)
	v_mfma_f32_16x16x32_bf16 v[116:119], v[194:197], v[162:165], v[116:119]
	v_mfma_f32_16x16x32_bf16 v[112:115], v[202:205], v[162:165], v[112:115]
	v_mfma_f32_16x16x32_bf16 v[100:103], v[194:197], v[170:173], v[100:103]
	v_mfma_f32_16x16x32_bf16 v[96:99], v[202:205], v[170:173], v[96:99]
	v_mfma_f32_16x16x32_bf16 v[84:87], v[194:197], v[178:181], v[84:87]
	v_mfma_f32_16x16x32_bf16 v[80:83], v[202:205], v[178:181], v[80:83]
	v_mfma_f32_16x16x32_bf16 v[68:71], v[194:197], v[186:189], v[68:71]
	v_mfma_f32_16x16x32_bf16 v[64:67], v[202:205], v[186:189], v[64:67]
	v_mfma_f32_16x16x32_bf16 v[116:119], v[198:201], v[166:169], v[116:119]
	v_mfma_f32_16x16x32_bf16 v[112:115], v[206:209], v[166:169], v[112:115]
	v_mfma_f32_16x16x32_bf16 v[100:103], v[198:201], v[174:177], v[100:103]
	v_mfma_f32_16x16x32_bf16 v[96:99], v[206:209], v[174:177], v[96:99]
	v_mfma_f32_16x16x32_bf16 v[84:87], v[198:201], v[182:185], v[84:87]
	v_mfma_f32_16x16x32_bf16 v[80:83], v[206:209], v[182:185], v[80:83]
	v_mfma_f32_16x16x32_bf16 v[68:71], v[198:201], v[190:193], v[68:71]
	v_mfma_f32_16x16x32_bf16 v[64:67], v[206:209], v[190:193], v[64:67]
	s_barrier
	ds_read_b128 v[162:165], v153 offset:16384
	ds_read_b128 v[166:169], v153 offset:17408
	ds_read_b128 v[170:173], v153 offset:18432
	ds_read_b128 v[174:177], v153 offset:19456
	ds_read_b128 v[178:181], v153 offset:20480
	ds_read_b128 v[182:185], v153 offset:21504
	ds_read_b128 v[186:189], v153 offset:22528
	ds_read_b128 v[190:193], v153 offset:23552
	s_waitcnt vmcnt(4)
	s_barrier
	s_waitcnt lgkmcnt(0)
	s_waitcnt lgkmcnt(0)
	v_mfma_f32_16x16x32_bf16 v[60:63], v[142:145], v[162:165], v[60:63]
	v_mfma_f32_16x16x32_bf16 v[56:59], v[154:157], v[162:165], v[56:59]
	v_mfma_f32_16x16x32_bf16 v[44:47], v[142:145], v[170:173], v[44:47]
	v_mfma_f32_16x16x32_bf16 v[40:43], v[154:157], v[170:173], v[40:43]
	v_mfma_f32_16x16x32_bf16 v[28:31], v[142:145], v[178:181], v[28:31]
	v_mfma_f32_16x16x32_bf16 v[24:27], v[154:157], v[178:181], v[24:27]
	v_mfma_f32_16x16x32_bf16 v[12:15], v[142:145], v[186:189], v[12:15]
	v_mfma_f32_16x16x32_bf16 v[8:11], v[154:157], v[186:189], v[8:11]
	v_mfma_f32_16x16x32_bf16 v[60:63], v[146:149], v[166:169], v[60:63]
	v_mfma_f32_16x16x32_bf16 v[56:59], v[158:161], v[166:169], v[56:59]
	v_mfma_f32_16x16x32_bf16 v[44:47], v[146:149], v[174:177], v[44:47]
	v_mfma_f32_16x16x32_bf16 v[40:43], v[158:161], v[174:177], v[40:43]
	v_mfma_f32_16x16x32_bf16 v[28:31], v[146:149], v[182:185], v[28:31]
	v_mfma_f32_16x16x32_bf16 v[24:27], v[158:161], v[182:185], v[24:27]
	v_mfma_f32_16x16x32_bf16 v[12:15], v[146:149], v[190:193], v[12:15]
	v_mfma_f32_16x16x32_bf16 v[8:11], v[158:161], v[190:193], v[8:11]
	v_mfma_f32_16x16x32_bf16 v[52:55], v[194:197], v[162:165], v[52:55]
	v_mfma_f32_16x16x32_bf16 v[48:51], v[202:205], v[162:165], v[48:51]
	v_mfma_f32_16x16x32_bf16 v[36:39], v[194:197], v[170:173], v[36:39]
	v_mfma_f32_16x16x32_bf16 v[32:35], v[202:205], v[170:173], v[32:35]
	v_mfma_f32_16x16x32_bf16 v[20:23], v[194:197], v[178:181], v[20:23]
	v_mfma_f32_16x16x32_bf16 v[16:19], v[202:205], v[178:181], v[16:19]
	v_mfma_f32_16x16x32_bf16 v[4:7], v[194:197], v[186:189], v[4:7]
	v_mfma_f32_16x16x32_bf16 v[0:3], v[202:205], v[186:189], v[0:3]
	v_mfma_f32_16x16x32_bf16 v[52:55], v[198:201], v[166:169], v[52:55]
	v_mfma_f32_16x16x32_bf16 v[48:51], v[206:209], v[166:169], v[48:51]
	v_mfma_f32_16x16x32_bf16 v[36:39], v[198:201], v[174:177], v[36:39]
	v_mfma_f32_16x16x32_bf16 v[32:35], v[206:209], v[174:177], v[32:35]
	v_mfma_f32_16x16x32_bf16 v[20:23], v[198:201], v[182:185], v[20:23]
	v_mfma_f32_16x16x32_bf16 v[16:19], v[206:209], v[182:185], v[16:19]
	v_mfma_f32_16x16x32_bf16 v[4:7], v[198:201], v[190:193], v[4:7]
	v_mfma_f32_16x16x32_bf16 v[0:3], v[206:209], v[190:193], v[0:3]
	s_barrier
	ds_read_b128 v[142:145], v152 offset:32768
	ds_read_b128 v[146:149], v152 offset:33792
	ds_read_b128 v[154:157], v152 offset:34816
	ds_read_b128 v[158:161], v152 offset:35840
	ds_read_b128 v[162:165], v153 offset:32768
	ds_read_b128 v[166:169], v153 offset:33792
	ds_read_b128 v[170:173], v153 offset:34816
	ds_read_b128 v[174:177], v153 offset:35840
	ds_read_b128 v[178:181], v153 offset:36864
	ds_read_b128 v[182:185], v153 offset:37888
	ds_read_b128 v[186:189], v153 offset:38912
	ds_read_b128 v[190:193], v153 offset:39936
	s_waitcnt vmcnt(2)
	s_barrier
	s_waitcnt lgkmcnt(0)
	s_waitcnt lgkmcnt(0)
	v_mfma_f32_16x16x32_bf16 v[124:127], v[142:145], v[162:165], v[124:127]
	v_mfma_f32_16x16x32_bf16 v[120:123], v[154:157], v[162:165], v[120:123]
	v_mfma_f32_16x16x32_bf16 v[108:111], v[142:145], v[170:173], v[108:111]
	v_mfma_f32_16x16x32_bf16 v[104:107], v[154:157], v[170:173], v[104:107]
	v_mfma_f32_16x16x32_bf16 v[92:95], v[142:145], v[178:181], v[92:95]
	v_mfma_f32_16x16x32_bf16 v[88:91], v[154:157], v[178:181], v[88:91]
	v_mfma_f32_16x16x32_bf16 v[76:79], v[142:145], v[186:189], v[76:79]
	v_mfma_f32_16x16x32_bf16 v[72:75], v[154:157], v[186:189], v[72:75]
	v_mfma_f32_16x16x32_bf16 v[124:127], v[146:149], v[166:169], v[124:127]
	v_mfma_f32_16x16x32_bf16 v[120:123], v[158:161], v[166:169], v[120:123]
	v_mfma_f32_16x16x32_bf16 v[108:111], v[146:149], v[174:177], v[108:111]
	v_mfma_f32_16x16x32_bf16 v[104:107], v[158:161], v[174:177], v[104:107]
	v_mfma_f32_16x16x32_bf16 v[92:95], v[146:149], v[182:185], v[92:95]
	v_mfma_f32_16x16x32_bf16 v[88:91], v[158:161], v[182:185], v[88:91]
	v_mfma_f32_16x16x32_bf16 v[76:79], v[146:149], v[190:193], v[76:79]
	v_mfma_f32_16x16x32_bf16 v[72:75], v[158:161], v[190:193], v[72:75]
	s_barrier
	ds_read_b128 v[194:197], v152 offset:49152
	ds_read_b128 v[198:201], v152 offset:50176
	ds_read_b128 v[202:205], v152 offset:51200
	ds_read_b128 v[206:209], v152 offset:52224
	s_waitcnt vmcnt(0)
	s_barrier
	s_waitcnt lgkmcnt(0)
	s_waitcnt lgkmcnt(0)
	v_mfma_f32_16x16x32_bf16 v[116:119], v[194:197], v[162:165], v[116:119]
	v_mfma_f32_16x16x32_bf16 v[112:115], v[202:205], v[162:165], v[112:115]
	v_mfma_f32_16x16x32_bf16 v[100:103], v[194:197], v[170:173], v[100:103]
	v_mfma_f32_16x16x32_bf16 v[96:99], v[202:205], v[170:173], v[96:99]
	v_mfma_f32_16x16x32_bf16 v[84:87], v[194:197], v[178:181], v[84:87]
	v_mfma_f32_16x16x32_bf16 v[80:83], v[202:205], v[178:181], v[80:83]
	v_mfma_f32_16x16x32_bf16 v[68:71], v[194:197], v[186:189], v[68:71]
	v_mfma_f32_16x16x32_bf16 v[64:67], v[202:205], v[186:189], v[64:67]
	v_mfma_f32_16x16x32_bf16 v[116:119], v[198:201], v[166:169], v[116:119]
	v_mfma_f32_16x16x32_bf16 v[112:115], v[206:209], v[166:169], v[112:115]
	v_mfma_f32_16x16x32_bf16 v[100:103], v[198:201], v[174:177], v[100:103]
	v_mfma_f32_16x16x32_bf16 v[96:99], v[206:209], v[174:177], v[96:99]
	v_mfma_f32_16x16x32_bf16 v[84:87], v[198:201], v[182:185], v[84:87]
	v_mfma_f32_16x16x32_bf16 v[80:83], v[206:209], v[182:185], v[80:83]
	v_mfma_f32_16x16x32_bf16 v[68:71], v[198:201], v[190:193], v[68:71]
	v_mfma_f32_16x16x32_bf16 v[64:67], v[206:209], v[190:193], v[64:67]
	s_barrier
	ds_read_b128 v[162:165], v153 offset:49152
	ds_read_b128 v[166:169], v153 offset:50176
	ds_read_b128 v[170:173], v153 offset:51200
	ds_read_b128 v[174:177], v153 offset:52224
	ds_read_b128 v[178:181], v153 offset:53248
	ds_read_b128 v[182:185], v153 offset:54272
	ds_read_b128 v[186:189], v153 offset:55296
	ds_read_b128 v[190:193], v153 offset:56320
	s_barrier
	s_waitcnt lgkmcnt(0)
	s_waitcnt lgkmcnt(0)
	v_mfma_f32_16x16x32_bf16 v[60:63], v[142:145], v[162:165], v[60:63]
	v_mfma_f32_16x16x32_bf16 v[56:59], v[154:157], v[162:165], v[56:59]
	v_mfma_f32_16x16x32_bf16 v[44:47], v[142:145], v[170:173], v[44:47]
	v_mfma_f32_16x16x32_bf16 v[40:43], v[154:157], v[170:173], v[40:43]
	v_mfma_f32_16x16x32_bf16 v[28:31], v[142:145], v[178:181], v[28:31]
	v_mfma_f32_16x16x32_bf16 v[24:27], v[154:157], v[178:181], v[24:27]
	v_mfma_f32_16x16x32_bf16 v[12:15], v[142:145], v[186:189], v[12:15]
	v_mfma_f32_16x16x32_bf16 v[8:11], v[154:157], v[186:189], v[8:11]
	v_mfma_f32_16x16x32_bf16 v[60:63], v[146:149], v[166:169], v[60:63]
	v_mfma_f32_16x16x32_bf16 v[56:59], v[158:161], v[166:169], v[56:59]
	v_mfma_f32_16x16x32_bf16 v[44:47], v[146:149], v[174:177], v[44:47]
	v_mfma_f32_16x16x32_bf16 v[40:43], v[158:161], v[174:177], v[40:43]
	v_mfma_f32_16x16x32_bf16 v[28:31], v[146:149], v[182:185], v[28:31]
	v_mfma_f32_16x16x32_bf16 v[24:27], v[158:161], v[182:185], v[24:27]
	v_mfma_f32_16x16x32_bf16 v[12:15], v[146:149], v[190:193], v[12:15]
	v_mfma_f32_16x16x32_bf16 v[8:11], v[158:161], v[190:193], v[8:11]
	v_mfma_f32_16x16x32_bf16 v[52:55], v[194:197], v[162:165], v[52:55]
	v_mfma_f32_16x16x32_bf16 v[48:51], v[202:205], v[162:165], v[48:51]
	v_mfma_f32_16x16x32_bf16 v[36:39], v[194:197], v[170:173], v[36:39]
	v_mfma_f32_16x16x32_bf16 v[32:35], v[202:205], v[170:173], v[32:35]
	v_mfma_f32_16x16x32_bf16 v[20:23], v[194:197], v[178:181], v[20:23]
	v_mfma_f32_16x16x32_bf16 v[16:19], v[202:205], v[178:181], v[16:19]
	v_mfma_f32_16x16x32_bf16 v[4:7], v[194:197], v[186:189], v[4:7]
	v_mfma_f32_16x16x32_bf16 v[0:3], v[202:205], v[186:189], v[0:3]
	v_mfma_f32_16x16x32_bf16 v[52:55], v[198:201], v[166:169], v[52:55]
	v_mfma_f32_16x16x32_bf16 v[48:51], v[206:209], v[166:169], v[48:51]
	v_mfma_f32_16x16x32_bf16 v[36:39], v[198:201], v[174:177], v[36:39]
	v_mfma_f32_16x16x32_bf16 v[32:35], v[206:209], v[174:177], v[32:35]
	v_mfma_f32_16x16x32_bf16 v[20:23], v[198:201], v[182:185], v[20:23]
	v_mfma_f32_16x16x32_bf16 v[16:19], v[206:209], v[182:185], v[16:19]
	v_mfma_f32_16x16x32_bf16 v[4:7], v[198:201], v[190:193], v[4:7]
	v_mfma_f32_16x16x32_bf16 v[0:3], v[206:209], v[190:193], v[0:3]
	s_barrier

.LBB0_230:
	ds_read_b128 v[148:151], v146
	ds_read_b128 v[152:155], v146 offset:1024
	ds_read_b128 v[156:159], v146 offset:2048
	ds_read_b128 v[160:163], v146 offset:3072
	s_add_i32 s76, s53, 2
	s_cmp_eq_u32 s53, 0
	s_cselect_b32 s58, s54, s72
	s_cselect_b32 s56, s52, s67
	s_mov_b32 m0, s62
	ds_read_b128 v[164:167], v147
	ds_read_b128 v[168:171], v147 offset:1024
	ds_read_b128 v[172:175], v147 offset:2048
	ds_read_b128 v[176:179], v147 offset:3072
	ds_read_b128 v[180:183], v147 offset:4096
	ds_read_b128 v[184:187], v147 offset:5120
	ds_read_b128 v[188:191], v147 offset:6144
	ds_read_b128 v[192:195], v147 offset:7168
	global_load_lds_dwordx4 v[140:141], off
	s_mov_b32 m0, s63
	s_nop 0
	global_load_lds_dwordx4 v[142:143], off
	s_waitcnt lgkmcnt(8)
	s_barrier
	s_waitcnt lgkmcnt(0)
	s_waitcnt lgkmcnt(0)
	v_mfma_f32_16x16x32_bf16 v[124:127], v[148:151], v[164:167], v[124:127]
	v_mfma_f32_16x16x32_bf16 v[120:123], v[156:159], v[164:167], v[120:123]
	v_mfma_f32_16x16x32_bf16 v[116:119], v[148:151], v[172:175], v[116:119]
	v_mfma_f32_16x16x32_bf16 v[108:111], v[156:159], v[172:175], v[108:111]
	v_mfma_f32_16x16x32_bf16 v[100:103], v[148:151], v[180:183], v[100:103]
	v_mfma_f32_16x16x32_bf16 v[92:95], v[156:159], v[180:183], v[92:95]
	v_mfma_f32_16x16x32_bf16 v[84:87], v[148:151], v[188:191], v[84:87]
	v_mfma_f32_16x16x32_bf16 v[76:79], v[156:159], v[188:191], v[76:79]
	v_mfma_f32_16x16x32_bf16 v[124:127], v[152:155], v[168:171], v[124:127]
	v_mfma_f32_16x16x32_bf16 v[120:123], v[160:163], v[168:171], v[120:123]
	v_mfma_f32_16x16x32_bf16 v[116:119], v[152:155], v[176:179], v[116:119]
	v_mfma_f32_16x16x32_bf16 v[108:111], v[160:163], v[176:179], v[108:111]
	v_mfma_f32_16x16x32_bf16 v[100:103], v[152:155], v[184:187], v[100:103]
	v_mfma_f32_16x16x32_bf16 v[92:95], v[160:163], v[184:187], v[92:95]
	v_mfma_f32_16x16x32_bf16 v[84:87], v[152:155], v[192:195], v[84:87]
	v_mfma_f32_16x16x32_bf16 v[76:79], v[160:163], v[192:195], v[76:79]
	s_barrier
	s_cselect_b32 s53, 0x100, 0
	s_ashr_i32 s59, s58, 31
	s_lshl_b64 s[78:79], s[58:59], 9
	s_add_u32 s57, s17, s78
	s_addc_u32 s59, s18, s79
	s_add_u32 s78, s57, s53
	s_addc_u32 s79, s59, 0
	s_mov_b32 m0, s20
	v_lshl_add_u64 v[212:213], s[78:79], 0, v[132:133]
	ds_read_b128 v[196:199], v146 offset:16384
	ds_read_b128 v[200:203], v146 offset:17408
	ds_read_b128 v[204:207], v146 offset:18432
	ds_read_b128 v[208:211], v146 offset:19456
	global_load_lds_dwordx4 v[212:213], off
	v_lshl_add_u64 v[214:215], s[78:79], 0, v[128:129]
	s_mov_b32 m0, s21
	s_nop 0
	global_load_lds_dwordx4 v[214:215], off
	s_barrier
	s_waitcnt lgkmcnt(0)
	s_waitcnt lgkmcnt(0)
	v_mfma_f32_16x16x32_bf16 v[112:115], v[196:199], v[164:167], v[112:115]
	v_mfma_f32_16x16x32_bf16 v[104:107], v[204:207], v[164:167], v[104:107]
	v_mfma_f32_16x16x32_bf16 v[96:99], v[196:199], v[172:175], v[96:99]
	v_mfma_f32_16x16x32_bf16 v[88:91], v[204:207], v[172:175], v[88:91]
	v_mfma_f32_16x16x32_bf16 v[80:83], v[196:199], v[180:183], v[80:83]
	v_mfma_f32_16x16x32_bf16 v[72:75], v[204:207], v[180:183], v[72:75]
	v_mfma_f32_16x16x32_bf16 v[68:71], v[196:199], v[188:191], v[68:71]
	v_mfma_f32_16x16x32_bf16 v[64:67], v[204:207], v[188:191], v[64:67]
	v_mfma_f32_16x16x32_bf16 v[112:115], v[200:203], v[168:171], v[112:115]
	v_mfma_f32_16x16x32_bf16 v[104:107], v[208:211], v[168:171], v[104:107]
	v_mfma_f32_16x16x32_bf16 v[96:99], v[200:203], v[176:179], v[96:99]
	v_mfma_f32_16x16x32_bf16 v[88:91], v[208:211], v[176:179], v[88:91]
	v_mfma_f32_16x16x32_bf16 v[80:83], v[200:203], v[184:187], v[80:83]
	v_mfma_f32_16x16x32_bf16 v[72:75], v[208:211], v[184:187], v[72:75]
	v_mfma_f32_16x16x32_bf16 v[68:71], v[200:203], v[192:195], v[68:71]
	v_mfma_f32_16x16x32_bf16 v[64:67], v[208:211], v[192:195], v[64:67]
	s_ashr_i32 s57, s56, 31
	s_lshl_b64 s[78:79], s[56:57], 9
	s_add_u32 s57, s9, s78
	s_addc_u32 s59, s16, s79
	s_add_u32 s78, s57, s53
	s_addc_u32 s79, s59, 0
	s_mov_b32 m0, s19
	v_lshl_add_u64 v[216:217], s[78:79], 0, v[134:135]
	s_barrier
	ds_read_b128 v[164:167], v147 offset:16384
	ds_read_b128 v[168:171], v147 offset:17408
	ds_read_b128 v[172:175], v147 offset:18432
	ds_read_b128 v[176:179], v147 offset:19456
	ds_read_b128 v[180:183], v147 offset:20480
	ds_read_b128 v[184:187], v147 offset:21504
	ds_read_b128 v[188:191], v147 offset:22528
	ds_read_b128 v[192:195], v147 offset:23552
	global_load_lds_dwordx4 v[216:217], off
	v_lshl_add_u64 v[218:219], s[78:79], 0, v[130:131]
	s_mov_b32 m0, s22
	s_nop 0
	global_load_lds_dwordx4 v[218:219], off
	s_barrier
	s_waitcnt lgkmcnt(0)
	s_waitcnt lgkmcnt(0)
	v_mfma_f32_16x16x32_bf16 v[60:63], v[148:151], v[164:167], v[60:63]
	v_mfma_f32_16x16x32_bf16 v[56:59], v[156:159], v[164:167], v[56:59]
	v_mfma_f32_16x16x32_bf16 v[52:55], v[148:151], v[172:175], v[52:55]
	v_mfma_f32_16x16x32_bf16 v[44:47], v[156:159], v[172:175], v[44:47]
	v_mfma_f32_16x16x32_bf16 v[36:39], v[148:151], v[180:183], v[36:39]
	v_mfma_f32_16x16x32_bf16 v[28:31], v[156:159], v[180:183], v[28:31]
	v_mfma_f32_16x16x32_bf16 v[20:23], v[148:151], v[188:191], v[20:23]
	v_mfma_f32_16x16x32_bf16 v[12:15], v[156:159], v[188:191], v[12:15]
	v_mfma_f32_16x16x32_bf16 v[60:63], v[152:155], v[168:171], v[60:63]
	v_mfma_f32_16x16x32_bf16 v[56:59], v[160:163], v[168:171], v[56:59]
	v_mfma_f32_16x16x32_bf16 v[52:55], v[152:155], v[176:179], v[52:55]
	v_mfma_f32_16x16x32_bf16 v[44:47], v[160:163], v[176:179], v[44:47]
	v_mfma_f32_16x16x32_bf16 v[36:39], v[152:155], v[184:187], v[36:39]
	v_mfma_f32_16x16x32_bf16 v[28:31], v[160:163], v[184:187], v[28:31]
	v_mfma_f32_16x16x32_bf16 v[20:23], v[152:155], v[192:195], v[20:23]
	v_mfma_f32_16x16x32_bf16 v[12:15], v[160:163], v[192:195], v[12:15]
	s_barrier
	s_bitset1_b32 s58, 7
	s_ashr_i32 s59, s58, 31
	s_lshl_b64 s[58:59], s[58:59], 9
	s_add_u32 s57, s17, s58
	s_addc_u32 s59, s18, s59
	s_add_u32 s58, s57, s53
	s_addc_u32 s59, s59, 0
	s_mov_b32 m0, s23
	v_lshl_add_u64 v[220:221], s[58:59], 0, v[132:133]
	global_load_lds_dwordx4 v[220:221], off
	v_lshl_add_u64 v[222:223], s[58:59], 0, v[128:129]
	s_mov_b32 m0, s24
	s_nop 0
	global_load_lds_dwordx4 v[222:223], off
	s_waitcnt vmcnt(6)
	s_barrier
	v_mfma_f32_16x16x32_bf16 v[48:51], v[196:199], v[164:167], v[48:51]
	v_mfma_f32_16x16x32_bf16 v[40:43], v[204:207], v[164:167], v[40:43]
	v_mfma_f32_16x16x32_bf16 v[32:35], v[196:199], v[172:175], v[32:35]
	v_mfma_f32_16x16x32_bf16 v[24:27], v[204:207], v[172:175], v[24:27]
	v_mfma_f32_16x16x32_bf16 v[16:19], v[196:199], v[180:183], v[16:19]
	v_mfma_f32_16x16x32_bf16 v[8:11], v[204:207], v[180:183], v[8:11]
	v_mfma_f32_16x16x32_bf16 v[4:7], v[196:199], v[188:191], v[4:7]
	v_mfma_f32_16x16x32_bf16 v[0:3], v[204:207], v[188:191], v[0:3]
	v_mfma_f32_16x16x32_bf16 v[48:51], v[200:203], v[168:171], v[48:51]
	v_mfma_f32_16x16x32_bf16 v[40:43], v[208:211], v[168:171], v[40:43]
	v_mfma_f32_16x16x32_bf16 v[32:35], v[200:203], v[176:179], v[32:35]
	v_mfma_f32_16x16x32_bf16 v[24:27], v[208:211], v[176:179], v[24:27]
	v_mfma_f32_16x16x32_bf16 v[16:19], v[200:203], v[184:187], v[16:19]
	v_mfma_f32_16x16x32_bf16 v[8:11], v[208:211], v[184:187], v[8:11]
	v_mfma_f32_16x16x32_bf16 v[4:7], v[200:203], v[192:195], v[4:7]
	v_mfma_f32_16x16x32_bf16 v[0:3], v[208:211], v[192:195], v[0:3]
	s_barrier
	ds_read_b128 v[148:151], v146 offset:32768
	ds_read_b128 v[152:155], v146 offset:33792
	ds_read_b128 v[156:159], v146 offset:34816
	ds_read_b128 v[160:163], v146 offset:35840
	s_bitset1_b32 s56, 7
	s_ashr_i32 s57, s56, 31
	s_lshl_b64 s[56:57], s[56:57], 9
	s_add_u32 s56, s9, s56
	s_addc_u32 s57, s16, s57
	s_add_u32 s56, s56, s53
	s_addc_u32 s57, s57, 0
	s_mov_b32 m0, s25
	v_lshl_add_u64 v[196:197], s[56:57], 0, v[134:135]
	ds_read_b128 v[164:167], v147 offset:32768
	ds_read_b128 v[168:171], v147 offset:33792
	ds_read_b128 v[172:175], v147 offset:34816
	ds_read_b128 v[176:179], v147 offset:35840
	ds_read_b128 v[180:183], v147 offset:36864
	ds_read_b128 v[184:187], v147 offset:37888
	ds_read_b128 v[188:191], v147 offset:38912
	ds_read_b128 v[192:195], v147 offset:39936
	global_load_lds_dwordx4 v[196:197], off
	v_lshl_add_u64 v[196:197], s[56:57], 0, v[130:131]
	s_mov_b32 m0, s26
	s_nop 0
	global_load_lds_dwordx4 v[196:197], off
	s_waitcnt lgkmcnt(8)
	s_barrier
	s_waitcnt lgkmcnt(0)
	s_waitcnt lgkmcnt(0)
	v_mfma_f32_16x16x32_bf16 v[124:127], v[148:151], v[164:167], v[124:127]
	v_mfma_f32_16x16x32_bf16 v[120:123], v[156:159], v[164:167], v[120:123]
	v_mfma_f32_16x16x32_bf16 v[116:119], v[148:151], v[172:175], v[116:119]
	v_mfma_f32_16x16x32_bf16 v[108:111], v[156:159], v[172:175], v[108:111]
	v_mfma_f32_16x16x32_bf16 v[100:103], v[148:151], v[180:183], v[100:103]
	v_mfma_f32_16x16x32_bf16 v[92:95], v[156:159], v[180:183], v[92:95]
	v_mfma_f32_16x16x32_bf16 v[84:87], v[148:151], v[188:191], v[84:87]
	v_mfma_f32_16x16x32_bf16 v[76:79], v[156:159], v[188:191], v[76:79]
	v_mfma_f32_16x16x32_bf16 v[124:127], v[152:155], v[168:171], v[124:127]
	v_mfma_f32_16x16x32_bf16 v[120:123], v[160:163], v[168:171], v[120:123]
	v_mfma_f32_16x16x32_bf16 v[116:119], v[152:155], v[176:179], v[116:119]
	v_mfma_f32_16x16x32_bf16 v[108:111], v[160:163], v[176:179], v[108:111]
	v_mfma_f32_16x16x32_bf16 v[100:103], v[152:155], v[184:187], v[100:103]
	v_mfma_f32_16x16x32_bf16 v[92:95], v[160:163], v[184:187], v[92:95]
	v_mfma_f32_16x16x32_bf16 v[84:87], v[152:155], v[192:195], v[84:87]
	v_mfma_f32_16x16x32_bf16 v[76:79], v[160:163], v[192:195], v[76:79]
	s_barrier
	s_mov_b32 m0, s27
	v_lshl_add_u64 v[212:213], v[212:213], 0, s[0:1]
	ds_read_b128 v[196:199], v146 offset:49152
	ds_read_b128 v[200:203], v146 offset:50176
	ds_read_b128 v[204:207], v146 offset:51200
	ds_read_b128 v[208:211], v146 offset:52224
	global_load_lds_dwordx4 v[212:213], off
	v_lshl_add_u64 v[212:213], v[214:215], 0, s[0:1]
	s_mov_b32 m0, s28
	s_nop 0
	global_load_lds_dwordx4 v[212:213], off
	s_barrier
	s_waitcnt lgkmcnt(0)
	s_waitcnt lgkmcnt(0)
	v_mfma_f32_16x16x32_bf16 v[112:115], v[196:199], v[164:167], v[112:115]
	v_mfma_f32_16x16x32_bf16 v[104:107], v[204:207], v[164:167], v[104:107]
	v_mfma_f32_16x16x32_bf16 v[96:99], v[196:199], v[172:175], v[96:99]
	v_mfma_f32_16x16x32_bf16 v[88:91], v[204:207], v[172:175], v[88:91]
	v_mfma_f32_16x16x32_bf16 v[80:83], v[196:199], v[180:183], v[80:83]
	v_mfma_f32_16x16x32_bf16 v[72:75], v[204:207], v[180:183], v[72:75]
	v_mfma_f32_16x16x32_bf16 v[68:71], v[196:199], v[188:191], v[68:71]
	v_mfma_f32_16x16x32_bf16 v[64:67], v[204:207], v[188:191], v[64:67]
	v_mfma_f32_16x16x32_bf16 v[112:115], v[200:203], v[168:171], v[112:115]
	v_mfma_f32_16x16x32_bf16 v[104:107], v[208:211], v[168:171], v[104:107]
	v_mfma_f32_16x16x32_bf16 v[96:99], v[200:203], v[176:179], v[96:99]
	v_mfma_f32_16x16x32_bf16 v[88:91], v[208:211], v[176:179], v[88:91]
	v_mfma_f32_16x16x32_bf16 v[80:83], v[200:203], v[184:187], v[80:83]
	v_mfma_f32_16x16x32_bf16 v[72:75], v[208:211], v[184:187], v[72:75]
	v_mfma_f32_16x16x32_bf16 v[68:71], v[200:203], v[192:195], v[68:71]
	v_mfma_f32_16x16x32_bf16 v[64:67], v[208:211], v[192:195], v[64:67]
	s_mov_b32 m0, s29
	v_lshl_add_u64 v[212:213], v[216:217], 0, s[0:1]
	s_barrier
	ds_read_b128 v[164:167], v147 offset:49152
	ds_read_b128 v[168:171], v147 offset:50176
	ds_read_b128 v[172:175], v147 offset:51200
	ds_read_b128 v[176:179], v147 offset:52224
	ds_read_b128 v[180:183], v147 offset:53248
	ds_read_b128 v[184:187], v147 offset:54272
	ds_read_b128 v[188:191], v147 offset:55296
	ds_read_b128 v[192:195], v147 offset:56320
	global_load_lds_dwordx4 v[212:213], off
	v_lshl_add_u64 v[212:213], v[218:219], 0, s[0:1]
	s_mov_b32 m0, s30
	s_nop 0
	global_load_lds_dwordx4 v[212:213], off
	s_barrier
	s_waitcnt lgkmcnt(0)
	s_waitcnt lgkmcnt(0)
	v_mfma_f32_16x16x32_bf16 v[60:63], v[148:151], v[164:167], v[60:63]
	v_mfma_f32_16x16x32_bf16 v[56:59], v[156:159], v[164:167], v[56:59]
	v_mfma_f32_16x16x32_bf16 v[52:55], v[148:151], v[172:175], v[52:55]
	v_mfma_f32_16x16x32_bf16 v[44:47], v[156:159], v[172:175], v[44:47]
	v_mfma_f32_16x16x32_bf16 v[36:39], v[148:151], v[180:183], v[36:39]
	v_mfma_f32_16x16x32_bf16 v[28:31], v[156:159], v[180:183], v[28:31]
	v_mfma_f32_16x16x32_bf16 v[20:23], v[148:151], v[188:191], v[20:23]
	v_mfma_f32_16x16x32_bf16 v[12:15], v[156:159], v[188:191], v[12:15]
	v_mfma_f32_16x16x32_bf16 v[60:63], v[152:155], v[168:171], v[60:63]
	v_mfma_f32_16x16x32_bf16 v[56:59], v[160:163], v[168:171], v[56:59]
	v_mfma_f32_16x16x32_bf16 v[52:55], v[152:155], v[176:179], v[52:55]
	v_mfma_f32_16x16x32_bf16 v[44:47], v[160:163], v[176:179], v[44:47]
	v_mfma_f32_16x16x32_bf16 v[36:39], v[152:155], v[184:187], v[36:39]
	v_mfma_f32_16x16x32_bf16 v[28:31], v[160:163], v[184:187], v[28:31]
	v_mfma_f32_16x16x32_bf16 v[20:23], v[152:155], v[192:195], v[20:23]
	v_mfma_f32_16x16x32_bf16 v[12:15], v[160:163], v[192:195], v[12:15]
	s_barrier
	s_mov_b32 m0, s31
	v_lshl_add_u64 v[148:149], v[220:221], 0, s[0:1]
	global_load_lds_dwordx4 v[148:149], off
	v_lshl_add_u64 v[148:149], v[222:223], 0, s[0:1]
	s_mov_b32 m0, s33
	s_nop 0
	global_load_lds_dwordx4 v[148:149], off
	s_waitcnt vmcnt(6)
	s_barrier
	v_mfma_f32_16x16x32_bf16 v[48:51], v[196:199], v[164:167], v[48:51]
	v_mfma_f32_16x16x32_bf16 v[40:43], v[204:207], v[164:167], v[40:43]
	v_mfma_f32_16x16x32_bf16 v[32:35], v[196:199], v[172:175], v[32:35]
	v_mfma_f32_16x16x32_bf16 v[24:27], v[204:207], v[172:175], v[24:27]
	v_mfma_f32_16x16x32_bf16 v[16:19], v[196:199], v[180:183], v[16:19]
	v_mfma_f32_16x16x32_bf16 v[8:11], v[204:207], v[180:183], v[8:11]
	v_mfma_f32_16x16x32_bf16 v[4:7], v[196:199], v[188:191], v[4:7]
	v_mfma_f32_16x16x32_bf16 v[0:3], v[204:207], v[188:191], v[0:3]
	v_mfma_f32_16x16x32_bf16 v[48:51], v[200:203], v[168:171], v[48:51]
	v_mfma_f32_16x16x32_bf16 v[40:43], v[208:211], v[168:171], v[40:43]
	v_mfma_f32_16x16x32_bf16 v[32:35], v[200:203], v[176:179], v[32:35]
	v_mfma_f32_16x16x32_bf16 v[24:27], v[208:211], v[176:179], v[24:27]
	v_mfma_f32_16x16x32_bf16 v[16:19], v[200:203], v[184:187], v[16:19]
	v_mfma_f32_16x16x32_bf16 v[8:11], v[208:211], v[184:187], v[8:11]
	v_mfma_f32_16x16x32_bf16 v[4:7], v[200:203], v[192:195], v[4:7]
	v_mfma_f32_16x16x32_bf16 v[0:3], v[208:211], v[192:195], v[0:3]
	v_lshl_add_u64 v[140:141], v[140:141], 0, s[4:5]
	v_lshl_add_u64 v[142:143], v[142:143], 0, s[4:5]
	s_cmp_ge_u32 s76, s75
	s_mov_b32 s53, s76
	s_barrier
	s_cbranch_scc0 .LBB0_230
	s_andn2_b64 vcc, exec, s[10:11]
	s_cbranch_vccnz .LBB0_226
	s_bitset1_b32 s52, 7
	s_ashr_i32 s53, s52, 31
	s_lshl_b64 s[52:53], s[52:53], 9
	s_add_u32 s52, s9, s52
	s_addc_u32 s53, s16, s53
	v_lshl_add_u64 v[192:193], s[52:53], 0, v[134:135]
	s_mov_b32 m0, s62
	v_lshl_add_u64 v[192:193], v[192:193], 0, s[6:7]
	ds_read_b128 v[140:143], v146
	ds_read_b128 v[148:151], v146 offset:1024
	ds_read_b128 v[152:155], v146 offset:2048
	ds_read_b128 v[156:159], v146 offset:3072
	ds_read_b128 v[160:163], v147
	ds_read_b128 v[164:167], v147 offset:1024
	ds_read_b128 v[168:171], v147 offset:2048
	ds_read_b128 v[172:175], v147 offset:3072
	ds_read_b128 v[176:179], v147 offset:4096
	ds_read_b128 v[180:183], v147 offset:5120
	ds_read_b128 v[184:187], v147 offset:6144
	ds_read_b128 v[188:191], v147 offset:7168
	global_load_lds_dwordx4 v[192:193], off
	v_lshl_add_u64 v[192:193], s[52:53], 0, v[130:131]
	v_lshl_add_u64 v[192:193], v[192:193], 0, s[6:7]
	s_mov_b32 m0, s63
	s_nop 0
	global_load_lds_dwordx4 v[192:193], off
	s_barrier
	s_waitcnt lgkmcnt(0)
	s_waitcnt lgkmcnt(0)
	v_mfma_f32_16x16x32_bf16 v[124:127], v[140:143], v[160:163], v[124:127]
	v_mfma_f32_16x16x32_bf16 v[120:123], v[152:155], v[160:163], v[120:123]
	v_mfma_f32_16x16x32_bf16 v[116:119], v[140:143], v[168:171], v[116:119]
	v_mfma_f32_16x16x32_bf16 v[108:111], v[152:155], v[168:171], v[108:111]
	v_mfma_f32_16x16x32_bf16 v[100:103], v[140:143], v[176:179], v[100:103]
	v_mfma_f32_16x16x32_bf16 v[92:95], v[152:155], v[176:179], v[92:95]
	v_mfma_f32_16x16x32_bf16 v[84:87], v[140:143], v[184:187], v[84:87]
	v_mfma_f32_16x16x32_bf16 v[76:79], v[152:155], v[184:187], v[76:79]
	v_mfma_f32_16x16x32_bf16 v[124:127], v[148:151], v[164:167], v[124:127]
	v_mfma_f32_16x16x32_bf16 v[120:123], v[156:159], v[164:167], v[120:123]
	v_mfma_f32_16x16x32_bf16 v[116:119], v[148:151], v[172:175], v[116:119]
	v_mfma_f32_16x16x32_bf16 v[108:111], v[156:159], v[172:175], v[108:111]
	v_mfma_f32_16x16x32_bf16 v[100:103], v[148:151], v[180:183], v[100:103]
	v_mfma_f32_16x16x32_bf16 v[92:95], v[156:159], v[180:183], v[92:95]
	v_mfma_f32_16x16x32_bf16 v[84:87], v[148:151], v[188:191], v[84:87]
	v_mfma_f32_16x16x32_bf16 v[76:79], v[156:159], v[188:191], v[76:79]
	s_barrier
	ds_read_b128 v[192:195], v146 offset:16384
	ds_read_b128 v[196:199], v146 offset:17408
	ds_read_b128 v[200:203], v146 offset:18432
	ds_read_b128 v[204:207], v146 offset:19456
	s_barrier
	s_waitcnt lgkmcnt(0)
	s_waitcnt lgkmcnt(0)
	v_mfma_f32_16x16x32_bf16 v[112:115], v[192:195], v[160:163], v[112:115]
	v_mfma_f32_16x16x32_bf16 v[104:107], v[200:203], v[160:163], v[104:107]
	v_mfma_f32_16x16x32_bf16 v[96:99], v[192:195], v[168:171], v[96:99]
	v_mfma_f32_16x16x32_bf16 v[88:91], v[200:203], v[168:171], v[88:91]
	v_mfma_f32_16x16x32_bf16 v[80:83], v[192:195], v[176:179], v[80:83]
	v_mfma_f32_16x16x32_bf16 v[72:75], v[200:203], v[176:179], v[72:75]
	v_mfma_f32_16x16x32_bf16 v[68:71], v[192:195], v[184:187], v[68:71]
	v_mfma_f32_16x16x32_bf16 v[64:67], v[200:203], v[184:187], v[64:67]
	v_mfma_f32_16x16x32_bf16 v[112:115], v[196:199], v[164:167], v[112:115]
	v_mfma_f32_16x16x32_bf16 v[104:107], v[204:207], v[164:167], v[104:107]
	v_mfma_f32_16x16x32_bf16 v[96:99], v[196:199], v[172:175], v[96:99]
	v_mfma_f32_16x16x32_bf16 v[88:91], v[204:207], v[172:175], v[88:91]
	v_mfma_f32_16x16x32_bf16 v[80:83], v[196:199], v[180:183], v[80:83]
	v_mfma_f32_16x16x32_bf16 v[72:75], v[204:207], v[180:183], v[72:75]
	v_mfma_f32_16x16x32_bf16 v[68:71], v[196:199], v[188:191], v[68:71]
	v_mfma_f32_16x16x32_bf16 v[64:67], v[204:207], v[188:191], v[64:67]
	s_barrier
	ds_read_b128 v[160:163], v147 offset:16384
	ds_read_b128 v[164:167], v147 offset:17408
	ds_read_b128 v[168:171], v147 offset:18432
	ds_read_b128 v[172:175], v147 offset:19456
	ds_read_b128 v[176:179], v147 offset:20480
	ds_read_b128 v[180:183], v147 offset:21504
	ds_read_b128 v[184:187], v147 offset:22528
	ds_read_b128 v[188:191], v147 offset:23552
	s_waitcnt vmcnt(4)
	s_barrier
	s_waitcnt lgkmcnt(0)
	s_waitcnt lgkmcnt(0)
	v_mfma_f32_16x16x32_bf16 v[60:63], v[140:143], v[160:163], v[60:63]
	v_mfma_f32_16x16x32_bf16 v[56:59], v[152:155], v[160:163], v[56:59]
	v_mfma_f32_16x16x32_bf16 v[52:55], v[140:143], v[168:171], v[52:55]
	v_mfma_f32_16x16x32_bf16 v[44:47], v[152:155], v[168:171], v[44:47]
	v_mfma_f32_16x16x32_bf16 v[36:39], v[140:143], v[176:179], v[36:39]
	v_mfma_f32_16x16x32_bf16 v[28:31], v[152:155], v[176:179], v[28:31]
	v_mfma_f32_16x16x32_bf16 v[20:23], v[140:143], v[184:187], v[20:23]
	v_mfma_f32_16x16x32_bf16 v[12:15], v[152:155], v[184:187], v[12:15]
	v_mfma_f32_16x16x32_bf16 v[60:63], v[148:151], v[164:167], v[60:63]
	v_mfma_f32_16x16x32_bf16 v[56:59], v[156:159], v[164:167], v[56:59]
	v_mfma_f32_16x16x32_bf16 v[52:55], v[148:151], v[172:175], v[52:55]
	v_mfma_f32_16x16x32_bf16 v[44:47], v[156:159], v[172:175], v[44:47]
	v_mfma_f32_16x16x32_bf16 v[36:39], v[148:151], v[180:183], v[36:39]
	v_mfma_f32_16x16x32_bf16 v[28:31], v[156:159], v[180:183], v[28:31]
	v_mfma_f32_16x16x32_bf16 v[20:23], v[148:151], v[188:191], v[20:23]
	v_mfma_f32_16x16x32_bf16 v[12:15], v[156:159], v[188:191], v[12:15]
	v_mfma_f32_16x16x32_bf16 v[48:51], v[192:195], v[160:163], v[48:51]
	v_mfma_f32_16x16x32_bf16 v[40:43], v[200:203], v[160:163], v[40:43]
	v_mfma_f32_16x16x32_bf16 v[32:35], v[192:195], v[168:171], v[32:35]
	v_mfma_f32_16x16x32_bf16 v[24:27], v[200:203], v[168:171], v[24:27]
	v_mfma_f32_16x16x32_bf16 v[16:19], v[192:195], v[176:179], v[16:19]
	v_mfma_f32_16x16x32_bf16 v[8:11], v[200:203], v[176:179], v[8:11]
	v_mfma_f32_16x16x32_bf16 v[4:7], v[192:195], v[184:187], v[4:7]
	v_mfma_f32_16x16x32_bf16 v[0:3], v[200:203], v[184:187], v[0:3]
	v_mfma_f32_16x16x32_bf16 v[48:51], v[196:199], v[164:167], v[48:51]
	v_mfma_f32_16x16x32_bf16 v[40:43], v[204:207], v[164:167], v[40:43]
	v_mfma_f32_16x16x32_bf16 v[32:35], v[196:199], v[172:175], v[32:35]
	v_mfma_f32_16x16x32_bf16 v[24:27], v[204:207], v[172:175], v[24:27]
	v_mfma_f32_16x16x32_bf16 v[16:19], v[196:199], v[180:183], v[16:19]
	v_mfma_f32_16x16x32_bf16 v[8:11], v[204:207], v[180:183], v[8:11]
	v_mfma_f32_16x16x32_bf16 v[4:7], v[196:199], v[188:191], v[4:7]
	v_mfma_f32_16x16x32_bf16 v[0:3], v[204:207], v[188:191], v[0:3]
	s_barrier
	ds_read_b128 v[140:143], v146 offset:32768
	ds_read_b128 v[148:151], v146 offset:33792
	ds_read_b128 v[152:155], v146 offset:34816
	ds_read_b128 v[156:159], v146 offset:35840
	ds_read_b128 v[160:163], v147 offset:32768
	ds_read_b128 v[164:167], v147 offset:33792
	ds_read_b128 v[168:171], v147 offset:34816
	ds_read_b128 v[172:175], v147 offset:35840
	ds_read_b128 v[176:179], v147 offset:36864
	ds_read_b128 v[180:183], v147 offset:37888
	ds_read_b128 v[184:187], v147 offset:38912
	ds_read_b128 v[188:191], v147 offset:39936
	s_waitcnt vmcnt(2)
	s_barrier
	s_waitcnt lgkmcnt(0)
	s_waitcnt lgkmcnt(0)
	v_mfma_f32_16x16x32_bf16 v[124:127], v[140:143], v[160:163], v[124:127]
	v_mfma_f32_16x16x32_bf16 v[120:123], v[152:155], v[160:163], v[120:123]
	v_mfma_f32_16x16x32_bf16 v[116:119], v[140:143], v[168:171], v[116:119]
	v_mfma_f32_16x16x32_bf16 v[108:111], v[152:155], v[168:171], v[108:111]
	v_mfma_f32_16x16x32_bf16 v[100:103], v[140:143], v[176:179], v[100:103]
	v_mfma_f32_16x16x32_bf16 v[92:95], v[152:155], v[176:179], v[92:95]
	v_mfma_f32_16x16x32_bf16 v[84:87], v[140:143], v[184:187], v[84:87]
	v_mfma_f32_16x16x32_bf16 v[76:79], v[152:155], v[184:187], v[76:79]
	v_mfma_f32_16x16x32_bf16 v[124:127], v[148:151], v[164:167], v[124:127]
	v_mfma_f32_16x16x32_bf16 v[120:123], v[156:159], v[164:167], v[120:123]
	v_mfma_f32_16x16x32_bf16 v[116:119], v[148:151], v[172:175], v[116:119]
	v_mfma_f32_16x16x32_bf16 v[108:111], v[156:159], v[172:175], v[108:111]
	v_mfma_f32_16x16x32_bf16 v[100:103], v[148:151], v[180:183], v[100:103]
	v_mfma_f32_16x16x32_bf16 v[92:95], v[156:159], v[180:183], v[92:95]
	v_mfma_f32_16x16x32_bf16 v[84:87], v[148:151], v[188:191], v[84:87]
	v_mfma_f32_16x16x32_bf16 v[76:79], v[156:159], v[188:191], v[76:79]
	s_barrier
	ds_read_b128 v[192:195], v146 offset:49152
	ds_read_b128 v[196:199], v146 offset:50176
	ds_read_b128 v[200:203], v146 offset:51200
	ds_read_b128 v[204:207], v146 offset:52224
	s_waitcnt vmcnt(0)
	s_barrier
	s_waitcnt lgkmcnt(0)
	s_waitcnt lgkmcnt(0)
	v_mfma_f32_16x16x32_bf16 v[112:115], v[192:195], v[160:163], v[112:115]
	v_mfma_f32_16x16x32_bf16 v[104:107], v[200:203], v[160:163], v[104:107]
	v_mfma_f32_16x16x32_bf16 v[96:99], v[192:195], v[168:171], v[96:99]
	v_mfma_f32_16x16x32_bf16 v[88:91], v[200:203], v[168:171], v[88:91]
	v_mfma_f32_16x16x32_bf16 v[80:83], v[192:195], v[176:179], v[80:83]
	v_mfma_f32_16x16x32_bf16 v[72:75], v[200:203], v[176:179], v[72:75]
	v_mfma_f32_16x16x32_bf16 v[68:71], v[192:195], v[184:187], v[68:71]
	v_mfma_f32_16x16x32_bf16 v[64:67], v[200:203], v[184:187], v[64:67]
	v_mfma_f32_16x16x32_bf16 v[112:115], v[196:199], v[164:167], v[112:115]
	v_mfma_f32_16x16x32_bf16 v[104:107], v[204:207], v[164:167], v[104:107]
	v_mfma_f32_16x16x32_bf16 v[96:99], v[196:199], v[172:175], v[96:99]
	v_mfma_f32_16x16x32_bf16 v[88:91], v[204:207], v[172:175], v[88:91]
	v_mfma_f32_16x16x32_bf16 v[80:83], v[196:199], v[180:183], v[80:83]
	v_mfma_f32_16x16x32_bf16 v[72:75], v[204:207], v[180:183], v[72:75]
	v_mfma_f32_16x16x32_bf16 v[68:71], v[196:199], v[188:191], v[68:71]
	v_mfma_f32_16x16x32_bf16 v[64:67], v[204:207], v[188:191], v[64:67]
	s_barrier
	ds_read_b128 v[160:163], v147 offset:49152
	ds_read_b128 v[164:167], v147 offset:50176
	ds_read_b128 v[168:171], v147 offset:51200
	ds_read_b128 v[172:175], v147 offset:52224
	ds_read_b128 v[176:179], v147 offset:53248
	ds_read_b128 v[180:183], v147 offset:54272
	ds_read_b128 v[184:187], v147 offset:55296
	ds_read_b128 v[188:191], v147 offset:56320
	s_barrier
	s_waitcnt lgkmcnt(0)
	s_waitcnt lgkmcnt(0)
	v_mfma_f32_16x16x32_bf16 v[60:63], v[140:143], v[160:163], v[60:63]
	v_mfma_f32_16x16x32_bf16 v[56:59], v[152:155], v[160:163], v[56:59]
	v_mfma_f32_16x16x32_bf16 v[52:55], v[140:143], v[168:171], v[52:55]
	v_mfma_f32_16x16x32_bf16 v[44:47], v[152:155], v[168:171], v[44:47]
	v_mfma_f32_16x16x32_bf16 v[36:39], v[140:143], v[176:179], v[36:39]
	v_mfma_f32_16x16x32_bf16 v[28:31], v[152:155], v[176:179], v[28:31]
	v_mfma_f32_16x16x32_bf16 v[20:23], v[140:143], v[184:187], v[20:23]
	v_mfma_f32_16x16x32_bf16 v[12:15], v[152:155], v[184:187], v[12:15]
	v_mfma_f32_16x16x32_bf16 v[60:63], v[148:151], v[164:167], v[60:63]
	v_mfma_f32_16x16x32_bf16 v[56:59], v[156:159], v[164:167], v[56:59]
	v_mfma_f32_16x16x32_bf16 v[52:55], v[148:151], v[172:175], v[52:55]
	v_mfma_f32_16x16x32_bf16 v[44:47], v[156:159], v[172:175], v[44:47]
	v_mfma_f32_16x16x32_bf16 v[36:39], v[148:151], v[180:183], v[36:39]
	v_mfma_f32_16x16x32_bf16 v[28:31], v[156:159], v[180:183], v[28:31]
	v_mfma_f32_16x16x32_bf16 v[20:23], v[148:151], v[188:191], v[20:23]
	v_mfma_f32_16x16x32_bf16 v[12:15], v[156:159], v[188:191], v[12:15]
	v_mfma_f32_16x16x32_bf16 v[48:51], v[192:195], v[160:163], v[48:51]
	v_mfma_f32_16x16x32_bf16 v[40:43], v[200:203], v[160:163], v[40:43]
	v_mfma_f32_16x16x32_bf16 v[32:35], v[192:195], v[168:171], v[32:35]
	v_mfma_f32_16x16x32_bf16 v[24:27], v[200:203], v[168:171], v[24:27]
	v_mfma_f32_16x16x32_bf16 v[16:19], v[192:195], v[176:179], v[16:19]
	v_mfma_f32_16x16x32_bf16 v[8:11], v[200:203], v[176:179], v[8:11]
	v_mfma_f32_16x16x32_bf16 v[4:7], v[192:195], v[184:187], v[4:7]
	v_mfma_f32_16x16x32_bf16 v[0:3], v[200:203], v[184:187], v[0:3]
	v_mfma_f32_16x16x32_bf16 v[48:51], v[196:199], v[164:167], v[48:51]
	v_mfma_f32_16x16x32_bf16 v[40:43], v[204:207], v[164:167], v[40:43]
	v_mfma_f32_16x16x32_bf16 v[32:35], v[196:199], v[172:175], v[32:35]
	v_mfma_f32_16x16x32_bf16 v[24:27], v[204:207], v[172:175], v[24:27]
	v_mfma_f32_16x16x32_bf16 v[16:19], v[196:199], v[180:183], v[16:19]
	v_mfma_f32_16x16x32_bf16 v[8:11], v[204:207], v[180:183], v[8:11]
	v_mfma_f32_16x16x32_bf16 v[4:7], v[196:199], v[188:191], v[4:7]
	v_mfma_f32_16x16x32_bf16 v[0:3], v[204:207], v[188:191], v[0:3]
	s_barrier
	s_branch .LBB0_226

.LBB0_241:
	s_or_b64 exec, exec, s[8:9]
	s_ashr_i32 s8, s58, 31
	s_lshr_b32 s8, s8, 29
	s_add_i32 s8, s58, s8
	s_ashr_i32 s9, s8, 3
	s_and_b32 s8, s8, -8
	s_sub_i32 s8, s58, s8
	s_cmp_lt_i32 s8, 0
	s_cselect_b32 s10, s21, 0x60
	s_mul_i32 s8, s10, s8
	s_add_i32 s8, s8, s9
	s_ashr_i32 s9, s8, 31
	s_lshr_b32 s9, s9, 27
	s_add_i32 s9, s8, s9
	s_and_b32 s10, s9, 0xffe0
	s_sub_i32 s8, s8, s10
	s_bfe_i32 s10, s8, 0x80000
	s_bfe_u32 s10, s10, 0x3000c
	s_add_i32 s10, s8, s10
	s_bfe_i32 s11, s10, 0x80000
	s_and_b32 s10, s10, 0xf8
	s_sub_i32 s8, s8, s10
	s_sext_i32_i8 s8, s8
	s_lshl_b32 s9, s9, 6
	s_sext_i32_i16 s11, s11
	s_and_b32 s9, s9, 0xfffff800
	s_lshl_b32 s8, s8, 8
	s_add_i32 s52, s8, s9
	s_lshl_b32 s8, s11, 5
	s_and_b32 s10, s8, 0xffffff00
	s_ashr_i32 s11, s10, 31
	s_lshl_b64 s[8:9], s[10:11], 8
	s_add_u32 s8, s18, s8
	s_addc_u32 s9, s19, s9
	v_lshl_add_u64 v[0:1], s[8:9], 0, v[132:133]
	s_mov_b32 m0, s29
	v_lshl_add_u64 v[0:1], v[0:1], 0, s[6:7]
	s_ashr_i32 s53, s52, 31
	s_waitcnt vmcnt(4)
	s_barrier
	global_load_lds_dwordx4 v[0:1], off
	v_lshl_add_u64 v[0:1], s[8:9], 0, v[128:129]
	s_lshl_b64 s[8:9], s[52:53], 8
	s_add_u32 s8, s16, s8
	v_lshl_add_u64 v[0:1], v[0:1], 0, s[6:7]
	s_mov_b32 m0, s30
	s_addc_u32 s9, s17, s9
	global_load_lds_dwordx4 v[0:1], off
	v_lshl_add_u64 v[0:1], s[8:9], 0, v[134:135]
	v_lshl_add_u64 v[0:1], v[0:1], 0, s[6:7]
	s_mov_b32 m0, s54
	s_nop 0
	global_load_lds_dwordx4 v[0:1], off
	v_lshl_add_u64 v[0:1], s[8:9], 0, v[130:131]
	s_or_b32 s8, s10, 0x80
	s_ashr_i32 s9, s8, 31
	s_lshl_b64 s[8:9], s[8:9], 8
	s_add_u32 s8, s18, s8
	v_lshl_add_u64 v[0:1], v[0:1], 0, s[6:7]
	s_mov_b32 m0, s55
	s_addc_u32 s9, s19, s9
	global_load_lds_dwordx4 v[0:1], off
	v_lshl_add_u64 v[0:1], s[8:9], 0, v[132:133]
	v_lshl_add_u64 v[0:1], v[0:1], 0, s[6:7]
	s_mov_b32 m0, s31
	s_nop 0
	global_load_lds_dwordx4 v[0:1], off
	v_lshl_add_u64 v[0:1], s[8:9], 0, v[128:129]
	s_or_b32 s8, s52, 0x80
	s_ashr_i32 s9, s8, 31
	s_lshl_b64 s[8:9], s[8:9], 8
	s_add_u32 s8, s16, s8
	s_addc_u32 s9, s17, s9
	v_lshl_add_u64 v[0:1], v[0:1], 0, s[6:7]
	s_mov_b32 m0, s33
	v_lshl_add_u64 v[48:49], s[8:9], 0, v[134:135]
	global_load_lds_dwordx4 v[0:1], off
	v_lshl_add_u64 v[48:49], v[48:49], 0, s[6:7]
	s_mov_b32 m0, s56
	s_waitcnt vmcnt(6)
	s_barrier
	ds_read_b128 v[0:3], v141
	ds_read_b128 v[4:7], v141 offset:1024
	ds_read_b128 v[8:11], v141 offset:2048
	ds_read_b128 v[12:15], v141 offset:3072
	ds_read_b128 v[16:19], v142
	ds_read_b128 v[20:23], v142 offset:1024
	ds_read_b128 v[24:27], v142 offset:2048
	ds_read_b128 v[28:31], v142 offset:3072
	ds_read_b128 v[32:35], v142 offset:4096
	ds_read_b128 v[36:39], v142 offset:5120
	ds_read_b128 v[40:43], v142 offset:6144
	ds_read_b128 v[44:47], v142 offset:7168
	global_load_lds_dwordx4 v[48:49], off
	v_lshl_add_u64 v[48:49], s[8:9], 0, v[130:131]
	v_lshl_add_u64 v[48:49], v[48:49], 0, s[6:7]
	s_mov_b32 m0, s57
	s_nop 0
	global_load_lds_dwordx4 v[48:49], off
	s_barrier
	s_waitcnt lgkmcnt(0)
	s_waitcnt lgkmcnt(0)
	v_mfma_f32_16x16x32_bf16 v[48:51], v[0:3], v[16:19], 0
	v_mfma_f32_16x16x32_bf16 v[52:55], v[8:11], v[16:19], 0
	v_mfma_f32_16x16x32_bf16 v[56:59], v[0:3], v[24:27], 0
	v_mfma_f32_16x16x32_bf16 v[60:63], v[8:11], v[24:27], 0
	v_mfma_f32_16x16x32_bf16 v[64:67], v[0:3], v[32:35], 0
	v_mfma_f32_16x16x32_bf16 v[68:71], v[8:11], v[32:35], 0
	v_mfma_f32_16x16x32_bf16 v[72:75], v[0:3], v[40:43], 0
	v_mfma_f32_16x16x32_bf16 v[76:79], v[8:11], v[40:43], 0
	v_mfma_f32_16x16x32_bf16 v[48:51], v[4:7], v[20:23], v[48:51]
	v_mfma_f32_16x16x32_bf16 v[52:55], v[12:15], v[20:23], v[52:55]
	v_mfma_f32_16x16x32_bf16 v[56:59], v[4:7], v[28:31], v[56:59]
	v_mfma_f32_16x16x32_bf16 v[60:63], v[12:15], v[28:31], v[60:63]
	v_mfma_f32_16x16x32_bf16 v[64:67], v[4:7], v[36:39], v[64:67]
	v_mfma_f32_16x16x32_bf16 v[68:71], v[12:15], v[36:39], v[68:71]
	v_mfma_f32_16x16x32_bf16 v[72:75], v[4:7], v[44:47], v[72:75]
	v_mfma_f32_16x16x32_bf16 v[76:79], v[12:15], v[44:47], v[76:79]
	s_barrier
	ds_read_b128 v[80:83], v141 offset:16384
	ds_read_b128 v[84:87], v141 offset:17408
	ds_read_b128 v[88:91], v141 offset:18432
	ds_read_b128 v[92:95], v141 offset:19456
	s_barrier
	s_waitcnt lgkmcnt(0)
	s_waitcnt lgkmcnt(0)
	v_mfma_f32_16x16x32_bf16 v[96:99], v[80:83], v[16:19], 0
	v_mfma_f32_16x16x32_bf16 v[16:19], v[88:91], v[16:19], 0
	v_mfma_f32_16x16x32_bf16 v[104:107], v[84:87], v[20:23], v[96:99]
	v_mfma_f32_16x16x32_bf16 v[16:19], v[92:95], v[20:23], v[16:19]
	v_mfma_f32_16x16x32_bf16 v[20:23], v[80:83], v[24:27], 0
	v_mfma_f32_16x16x32_bf16 v[24:27], v[88:91], v[24:27], 0
	v_mfma_f32_16x16x32_bf16 v[20:23], v[84:87], v[28:31], v[20:23]
	v_mfma_f32_16x16x32_bf16 v[24:27], v[92:95], v[28:31], v[24:27]
	v_mfma_f32_16x16x32_bf16 v[28:31], v[80:83], v[32:35], 0
	v_mfma_f32_16x16x32_bf16 v[32:35], v[88:91], v[32:35], 0
	v_mfma_f32_16x16x32_bf16 v[28:31], v[84:87], v[36:39], v[28:31]
	v_mfma_f32_16x16x32_bf16 v[32:35], v[92:95], v[36:39], v[32:35]
	v_mfma_f32_16x16x32_bf16 v[36:39], v[80:83], v[40:43], 0
	v_mfma_f32_16x16x32_bf16 v[40:43], v[88:91], v[40:43], 0
	v_mfma_f32_16x16x32_bf16 v[36:39], v[84:87], v[44:47], v[36:39]
	v_mfma_f32_16x16x32_bf16 v[40:43], v[92:95], v[44:47], v[40:43]
	s_barrier
	ds_read_b128 v[44:47], v142 offset:16384
	ds_read_b128 v[96:99], v142 offset:17408
	ds_read_b128 v[100:103], v142 offset:18432
	ds_read_b128 v[108:111], v142 offset:19456
	ds_read_b128 v[112:115], v142 offset:20480
	ds_read_b128 v[116:119], v142 offset:21504
	ds_read_b128 v[120:123], v142 offset:22528
	ds_read_b128 v[124:127], v142 offset:23552
	s_waitcnt vmcnt(4)
	s_barrier
	s_waitcnt lgkmcnt(0)
	s_waitcnt lgkmcnt(0)
	v_mfma_f32_16x16x32_bf16 v[136:139], v[0:3], v[44:47], 0
	v_mfma_f32_16x16x32_bf16 v[148:151], v[0:3], v[100:103], 0
	v_mfma_f32_16x16x32_bf16 v[156:159], v[0:3], v[112:115], 0
	v_mfma_f32_16x16x32_bf16 v[0:3], v[0:3], v[120:123], 0
	v_mfma_f32_16x16x32_bf16 v[136:139], v[4:7], v[96:99], v[136:139]
	v_mfma_f32_16x16x32_bf16 v[148:151], v[4:7], v[108:111], v[148:151]
	v_mfma_f32_16x16x32_bf16 v[156:159], v[4:7], v[116:119], v[156:159]
	v_mfma_f32_16x16x32_bf16 v[0:3], v[4:7], v[124:127], v[0:3]
	v_mfma_f32_16x16x32_bf16 v[4:7], v[8:11], v[120:123], 0
	v_mfma_f32_16x16x32_bf16 v[144:147], v[8:11], v[44:47], 0
	v_mfma_f32_16x16x32_bf16 v[152:155], v[8:11], v[100:103], 0
	v_mfma_f32_16x16x32_bf16 v[160:163], v[8:11], v[112:115], 0
	v_mfma_f32_16x16x32_bf16 v[4:7], v[12:15], v[124:127], v[4:7]
	v_mfma_f32_16x16x32_bf16 v[144:147], v[12:15], v[96:99], v[144:147]
	v_mfma_f32_16x16x32_bf16 v[152:155], v[12:15], v[108:111], v[152:155]
	v_mfma_f32_16x16x32_bf16 v[160:163], v[12:15], v[116:119], v[160:163]
	v_mfma_f32_16x16x32_bf16 v[8:11], v[80:83], v[44:47], 0
	v_mfma_f32_16x16x32_bf16 v[12:15], v[84:87], v[96:99], v[8:11]
	v_mfma_f32_16x16x32_bf16 v[8:11], v[88:91], v[44:47], 0
	v_mfma_f32_16x16x32_bf16 v[44:47], v[92:95], v[96:99], v[8:11]
	v_mfma_f32_16x16x32_bf16 v[8:11], v[80:83], v[100:103], 0
	v_mfma_f32_16x16x32_bf16 v[164:167], v[84:87], v[108:111], v[8:11]
	v_mfma_f32_16x16x32_bf16 v[8:11], v[88:91], v[100:103], 0
	v_mfma_f32_16x16x32_bf16 v[168:171], v[92:95], v[108:111], v[8:11]
	v_mfma_f32_16x16x32_bf16 v[8:11], v[80:83], v[112:115], 0
	v_mfma_f32_16x16x32_bf16 v[172:175], v[84:87], v[116:119], v[8:11]
	v_mfma_f32_16x16x32_bf16 v[8:11], v[88:91], v[112:115], 0
	v_mfma_f32_16x16x32_bf16 v[176:179], v[92:95], v[116:119], v[8:11]
	v_mfma_f32_16x16x32_bf16 v[8:11], v[80:83], v[120:123], 0
	v_mfma_f32_16x16x32_bf16 v[180:183], v[84:87], v[124:127], v[8:11]
	v_mfma_f32_16x16x32_bf16 v[8:11], v[88:91], v[120:123], 0
	v_mfma_f32_16x16x32_bf16 v[184:187], v[92:95], v[124:127], v[8:11]
	s_barrier
	s_nop 4
	ds_read_b128 v[8:11], v141 offset:32768
	ds_read_b128 v[188:191], v141 offset:33792
	ds_read_b128 v[192:195], v141 offset:34816
	ds_read_b128 v[196:199], v141 offset:35840
	ds_read_b128 v[88:91], v142 offset:32768
	ds_read_b128 v[92:95], v142 offset:33792
	ds_read_b128 v[200:203], v142 offset:34816
	ds_read_b128 v[204:207], v142 offset:35840
	ds_read_b128 v[208:211], v142 offset:36864
	ds_read_b128 v[212:215], v142 offset:37888
	ds_read_b128 v[216:219], v142 offset:38912
	ds_read_b128 v[220:223], v142 offset:39936
	s_waitcnt vmcnt(2)
	s_barrier
	s_waitcnt lgkmcnt(0)
	s_waitcnt lgkmcnt(0)
	v_mfma_f32_16x16x32_bf16 v[48:51], v[8:11], v[88:91], v[48:51]
	v_mfma_f32_16x16x32_bf16 v[116:119], v[188:191], v[92:95], v[48:51]
	v_mfma_f32_16x16x32_bf16 v[48:51], v[192:195], v[88:91], v[52:55]
	v_mfma_f32_16x16x32_bf16 v[112:115], v[196:199], v[92:95], v[48:51]
	v_mfma_f32_16x16x32_bf16 v[48:51], v[8:11], v[200:203], v[56:59]
	v_mfma_f32_16x16x32_bf16 v[100:103], v[188:191], v[204:207], v[48:51]
	v_mfma_f32_16x16x32_bf16 v[48:51], v[192:195], v[200:203], v[60:63]
	v_mfma_f32_16x16x32_bf16 v[96:99], v[196:199], v[204:207], v[48:51]
	v_mfma_f32_16x16x32_bf16 v[48:51], v[8:11], v[208:211], v[64:67]
	v_mfma_f32_16x16x32_bf16 v[84:87], v[188:191], v[212:215], v[48:51]
	v_mfma_f32_16x16x32_bf16 v[48:51], v[192:195], v[208:211], v[68:71]
	v_mfma_f32_16x16x32_bf16 v[80:83], v[196:199], v[212:215], v[48:51]
	v_mfma_f32_16x16x32_bf16 v[48:51], v[8:11], v[216:219], v[72:75]
	v_mfma_f32_16x16x32_bf16 v[60:63], v[188:191], v[220:223], v[48:51]
	v_mfma_f32_16x16x32_bf16 v[48:51], v[192:195], v[216:219], v[76:79]
	v_mfma_f32_16x16x32_bf16 v[48:51], v[196:199], v[220:223], v[48:51]
	s_barrier
	ds_read_b128 v[224:227], v141 offset:49152
	ds_read_b128 v[228:231], v141 offset:50176
	ds_read_b128 v[232:235], v141 offset:51200
	ds_read_b128 v[236:239], v141 offset:52224
	s_waitcnt vmcnt(0)
	s_barrier
	s_waitcnt lgkmcnt(0)
	s_waitcnt lgkmcnt(0)
	v_mfma_f32_16x16x32_bf16 v[16:19], v[232:235], v[88:91], v[16:19]
	v_mfma_f32_16x16x32_bf16 v[120:123], v[236:239], v[92:95], v[16:19]
	v_mfma_f32_16x16x32_bf16 v[16:19], v[224:227], v[200:203], v[20:23]
	v_mfma_f32_16x16x32_bf16 v[108:111], v[228:231], v[204:207], v[16:19]
	v_mfma_f32_16x16x32_bf16 v[16:19], v[232:235], v[200:203], v[24:27]
	v_mfma_f32_16x16x32_bf16 v[52:55], v[224:227], v[88:91], v[104:107]
	v_mfma_f32_16x16x32_bf16 v[104:107], v[236:239], v[204:207], v[16:19]
	v_mfma_f32_16x16x32_bf16 v[16:19], v[224:227], v[208:211], v[28:31]
	v_mfma_f32_16x16x32_bf16 v[124:127], v[228:231], v[92:95], v[52:55]
	v_mfma_f32_16x16x32_bf16 v[92:95], v[228:231], v[212:215], v[16:19]
	v_mfma_f32_16x16x32_bf16 v[16:19], v[232:235], v[208:211], v[32:35]
	v_mfma_f32_16x16x32_bf16 v[88:91], v[236:239], v[212:215], v[16:19]
	v_mfma_f32_16x16x32_bf16 v[16:19], v[224:227], v[216:219], v[36:39]
	v_mfma_f32_16x16x32_bf16 v[76:79], v[228:231], v[220:223], v[16:19]
	v_mfma_f32_16x16x32_bf16 v[16:19], v[232:235], v[216:219], v[40:43]
	v_mfma_f32_16x16x32_bf16 v[72:75], v[236:239], v[220:223], v[16:19]
	s_barrier
	ds_read_b128 v[20:23], v142 offset:49152
	ds_read_b128 v[28:31], v142 offset:50176
	ds_read_b128 v[36:39], v142 offset:51200
	ds_read_b128 v[200:203], v142 offset:52224
	ds_read_b128 v[204:207], v142 offset:53248
	ds_read_b128 v[208:211], v142 offset:54272
	ds_read_b128 v[212:215], v142 offset:55296
	ds_read_b128 v[216:219], v142 offset:56320
	s_barrier
	s_waitcnt lgkmcnt(0)
	s_waitcnt lgkmcnt(0)
	v_mfma_f32_16x16x32_bf16 v[16:19], v[8:11], v[20:23], v[136:139]
	v_mfma_f32_16x16x32_bf16 v[64:67], v[188:191], v[28:31], v[16:19]
	v_mfma_f32_16x16x32_bf16 v[16:19], v[192:195], v[20:23], v[144:147]
	v_mfma_f32_16x16x32_bf16 v[52:55], v[196:199], v[28:31], v[16:19]
	v_mfma_f32_16x16x32_bf16 v[16:19], v[8:11], v[36:39], v[148:151]
	v_mfma_f32_16x16x32_bf16 v[40:43], v[188:191], v[200:203], v[16:19]
	v_mfma_f32_16x16x32_bf16 v[16:19], v[192:195], v[36:39], v[152:155]
	v_mfma_f32_16x16x32_bf16 v[32:35], v[196:199], v[200:203], v[16:19]
	v_mfma_f32_16x16x32_bf16 v[16:19], v[8:11], v[204:207], v[156:159]
	v_mfma_f32_16x16x32_bf16 v[0:3], v[8:11], v[212:215], v[0:3]
	v_mfma_f32_16x16x32_bf16 v[24:27], v[188:191], v[208:211], v[16:19]
	v_mfma_f32_16x16x32_bf16 v[16:19], v[192:195], v[204:207], v[160:163]
	v_mfma_f32_16x16x32_bf16 v[8:11], v[188:191], v[216:219], v[0:3]
	v_mfma_f32_16x16x32_bf16 v[0:3], v[192:195], v[212:215], v[4:7]
	v_mfma_f32_16x16x32_bf16 v[16:19], v[196:199], v[208:211], v[16:19]
	v_mfma_f32_16x16x32_bf16 v[0:3], v[196:199], v[216:219], v[0:3]
	v_mfma_f32_16x16x32_bf16 v[4:7], v[224:227], v[20:23], v[12:15]
	v_mfma_f32_16x16x32_bf16 v[68:71], v[228:231], v[28:31], v[4:7]
	v_mfma_f32_16x16x32_bf16 v[4:7], v[232:235], v[20:23], v[44:47]
	v_mfma_f32_16x16x32_bf16 v[56:59], v[236:239], v[28:31], v[4:7]
	v_mfma_f32_16x16x32_bf16 v[4:7], v[224:227], v[36:39], v[164:167]
	v_mfma_f32_16x16x32_bf16 v[44:47], v[228:231], v[200:203], v[4:7]
	v_mfma_f32_16x16x32_bf16 v[4:7], v[232:235], v[36:39], v[168:171]
	v_mfma_f32_16x16x32_bf16 v[36:39], v[236:239], v[200:203], v[4:7]
	v_mfma_f32_16x16x32_bf16 v[4:7], v[224:227], v[204:207], v[172:175]
	v_mfma_f32_16x16x32_bf16 v[28:31], v[228:231], v[208:211], v[4:7]
	v_mfma_f32_16x16x32_bf16 v[4:7], v[232:235], v[204:207], v[176:179]
	v_mfma_f32_16x16x32_bf16 v[20:23], v[236:239], v[208:211], v[4:7]
	v_mfma_f32_16x16x32_bf16 v[4:7], v[224:227], v[212:215], v[180:183]
	v_mfma_f32_16x16x32_bf16 v[12:15], v[228:231], v[216:219], v[4:7]
	v_mfma_f32_16x16x32_bf16 v[4:7], v[232:235], v[212:215], v[184:187]
	v_mfma_f32_16x16x32_bf16 v[4:7], v[236:239], v[216:219], v[4:7]
	s_barrier
	s_and_saveexec_b64 s[8:9], s[2:3]
	s_cbranch_execz .LBB0_243
	s_barrier

.LBB0_321:
	ds_read_b128 v[148:151], v146
	ds_read_b128 v[152:155], v146 offset:1024
	ds_read_b128 v[156:159], v146 offset:2048
	ds_read_b128 v[160:163], v146 offset:3072
	s_add_i32 s11, s2, 2
	s_cmp_gt_u32 s2, 13
	s_cselect_b32 s58, s74, s52
	s_cselect_b32 s54, s73, s10
	s_mov_b32 m0, s62
	ds_read_b128 v[164:167], v147
	ds_read_b128 v[168:171], v147 offset:1024
	ds_read_b128 v[172:175], v147 offset:2048
	ds_read_b128 v[176:179], v147 offset:3072
	ds_read_b128 v[180:183], v147 offset:4096
	ds_read_b128 v[184:187], v147 offset:5120
	ds_read_b128 v[188:191], v147 offset:6144
	ds_read_b128 v[192:195], v147 offset:7168
	global_load_lds_dwordx4 v[140:141], off
	s_mov_b32 m0, s63
	s_nop 0
	global_load_lds_dwordx4 v[142:143], off
	s_waitcnt lgkmcnt(8)
	s_barrier
	s_waitcnt lgkmcnt(0)
	s_waitcnt lgkmcnt(0)
	v_mfma_f32_16x16x32_bf16 v[124:127], v[148:151], v[164:167], v[124:127]
	v_mfma_f32_16x16x32_bf16 v[120:123], v[156:159], v[164:167], v[120:123]
	v_mfma_f32_16x16x32_bf16 v[116:119], v[148:151], v[172:175], v[116:119]
	v_mfma_f32_16x16x32_bf16 v[112:115], v[156:159], v[172:175], v[112:115]
	v_mfma_f32_16x16x32_bf16 v[100:103], v[148:151], v[180:183], v[100:103]
	v_mfma_f32_16x16x32_bf16 v[96:99], v[156:159], v[180:183], v[96:99]
	v_mfma_f32_16x16x32_bf16 v[84:87], v[148:151], v[188:191], v[84:87]
	v_mfma_f32_16x16x32_bf16 v[80:83], v[156:159], v[188:191], v[80:83]
	v_mfma_f32_16x16x32_bf16 v[124:127], v[152:155], v[168:171], v[124:127]
	v_mfma_f32_16x16x32_bf16 v[120:123], v[160:163], v[168:171], v[120:123]
	v_mfma_f32_16x16x32_bf16 v[116:119], v[152:155], v[176:179], v[116:119]
	v_mfma_f32_16x16x32_bf16 v[112:115], v[160:163], v[176:179], v[112:115]
	v_mfma_f32_16x16x32_bf16 v[100:103], v[152:155], v[184:187], v[100:103]
	v_mfma_f32_16x16x32_bf16 v[96:99], v[160:163], v[184:187], v[96:99]
	v_mfma_f32_16x16x32_bf16 v[84:87], v[152:155], v[192:195], v[84:87]
	v_mfma_f32_16x16x32_bf16 v[80:83], v[160:163], v[192:195], v[80:83]
	s_barrier
	s_cselect_b32 s2, 0, s11
	s_ashr_i32 s59, s58, 31
	s_lshl_b64 s[56:57], s[58:59], 11
	s_add_u32 s78, s18, s56
	s_addc_u32 s79, s19, s57
	s_lshl_b64 s[56:57], s[2:3], 7
	s_add_u32 s76, s78, s56
	s_addc_u32 s77, s79, s57
	s_mov_b32 m0, s21
	v_lshl_add_u64 v[212:213], s[76:77], 0, v[132:133]
	ds_read_b128 v[196:199], v146 offset:16384
	ds_read_b128 v[200:203], v146 offset:17408
	ds_read_b128 v[204:207], v146 offset:18432
	ds_read_b128 v[208:211], v146 offset:19456
	global_load_lds_dwordx4 v[212:213], off
	v_lshl_add_u64 v[212:213], s[76:77], 0, v[128:129]
	s_mov_b32 m0, s22
	s_nop 0
	global_load_lds_dwordx4 v[212:213], off
	s_barrier
	s_waitcnt lgkmcnt(0)
	s_waitcnt lgkmcnt(0)
	v_mfma_f32_16x16x32_bf16 v[108:111], v[196:199], v[164:167], v[108:111]
	v_mfma_f32_16x16x32_bf16 v[104:107], v[204:207], v[164:167], v[104:107]
	v_mfma_f32_16x16x32_bf16 v[92:95], v[196:199], v[172:175], v[92:95]
	v_mfma_f32_16x16x32_bf16 v[88:91], v[204:207], v[172:175], v[88:91]
	v_mfma_f32_16x16x32_bf16 v[76:79], v[196:199], v[180:183], v[76:79]
	v_mfma_f32_16x16x32_bf16 v[72:75], v[204:207], v[180:183], v[72:75]
	v_mfma_f32_16x16x32_bf16 v[68:71], v[196:199], v[188:191], v[68:71]
	v_mfma_f32_16x16x32_bf16 v[64:67], v[204:207], v[188:191], v[64:67]
	v_mfma_f32_16x16x32_bf16 v[108:111], v[200:203], v[168:171], v[108:111]
	v_mfma_f32_16x16x32_bf16 v[104:107], v[208:211], v[168:171], v[104:107]
	v_mfma_f32_16x16x32_bf16 v[92:95], v[200:203], v[176:179], v[92:95]
	v_mfma_f32_16x16x32_bf16 v[88:91], v[208:211], v[176:179], v[88:91]
	v_mfma_f32_16x16x32_bf16 v[76:79], v[200:203], v[184:187], v[76:79]
	v_mfma_f32_16x16x32_bf16 v[72:75], v[208:211], v[184:187], v[72:75]
	v_mfma_f32_16x16x32_bf16 v[68:71], v[200:203], v[192:195], v[68:71]
	v_mfma_f32_16x16x32_bf16 v[64:67], v[208:211], v[192:195], v[64:67]
	s_ashr_i32 s55, s54, 31
	s_lshl_b64 s[76:77], s[54:55], 11
	s_add_u32 s80, s16, s76
	s_addc_u32 s81, s17, s77
	s_add_u32 s76, s80, s56
	s_addc_u32 s77, s81, s57
	s_mov_b32 m0, s20
	v_lshl_add_u64 v[212:213], s[76:77], 0, v[134:135]
	s_barrier
	ds_read_b128 v[164:167], v147 offset:16384
	ds_read_b128 v[168:171], v147 offset:17408
	ds_read_b128 v[172:175], v147 offset:18432
	ds_read_b128 v[176:179], v147 offset:19456
	ds_read_b128 v[180:183], v147 offset:20480
	ds_read_b128 v[184:187], v147 offset:21504
	ds_read_b128 v[188:191], v147 offset:22528
	ds_read_b128 v[192:195], v147 offset:23552
	global_load_lds_dwordx4 v[212:213], off
	v_lshl_add_u64 v[212:213], s[76:77], 0, v[130:131]
	s_mov_b32 m0, s23
	s_nop 0
	global_load_lds_dwordx4 v[212:213], off
	s_barrier
	s_waitcnt lgkmcnt(0)
	s_waitcnt lgkmcnt(0)
	v_mfma_f32_16x16x32_bf16 v[60:63], v[148:151], v[164:167], v[60:63]
	v_mfma_f32_16x16x32_bf16 v[56:59], v[156:159], v[164:167], v[56:59]
	v_mfma_f32_16x16x32_bf16 v[52:55], v[148:151], v[172:175], v[52:55]
	v_mfma_f32_16x16x32_bf16 v[48:51], v[156:159], v[172:175], v[48:51]
	v_mfma_f32_16x16x32_bf16 v[36:39], v[148:151], v[180:183], v[36:39]
	v_mfma_f32_16x16x32_bf16 v[32:35], v[156:159], v[180:183], v[32:35]
	v_mfma_f32_16x16x32_bf16 v[20:23], v[148:151], v[188:191], v[20:23]
	v_mfma_f32_16x16x32_bf16 v[16:19], v[156:159], v[188:191], v[16:19]
	v_mfma_f32_16x16x32_bf16 v[60:63], v[152:155], v[168:171], v[60:63]
	v_mfma_f32_16x16x32_bf16 v[56:59], v[160:163], v[168:171], v[56:59]
	v_mfma_f32_16x16x32_bf16 v[52:55], v[152:155], v[176:179], v[52:55]
	v_mfma_f32_16x16x32_bf16 v[48:51], v[160:163], v[176:179], v[48:51]
	v_mfma_f32_16x16x32_bf16 v[36:39], v[152:155], v[184:187], v[36:39]
	v_mfma_f32_16x16x32_bf16 v[32:35], v[160:163], v[184:187], v[32:35]
	v_mfma_f32_16x16x32_bf16 v[20:23], v[152:155], v[192:195], v[20:23]
	v_mfma_f32_16x16x32_bf16 v[16:19], v[160:163], v[192:195], v[16:19]
	s_barrier
	s_bitset1_b32 s58, 7
	s_ashr_i32 s59, s58, 31
	s_lshl_b64 s[58:59], s[58:59], 11
	s_add_u32 s76, s18, s58
	s_addc_u32 s77, s19, s59
	s_add_u32 s58, s76, s56
	s_addc_u32 s59, s77, s57
	s_mov_b32 m0, s24
	v_lshl_add_u64 v[148:149], s[58:59], 0, v[132:133]
	global_load_lds_dwordx4 v[148:149], off
	v_lshl_add_u64 v[148:149], s[58:59], 0, v[128:129]
	s_mov_b32 m0, s25
	s_nop 0
	global_load_lds_dwordx4 v[148:149], off
	s_waitcnt vmcnt(6)
	s_barrier
	v_mfma_f32_16x16x32_bf16 v[44:47], v[196:199], v[164:167], v[44:47]
	v_mfma_f32_16x16x32_bf16 v[40:43], v[204:207], v[164:167], v[40:43]
	v_mfma_f32_16x16x32_bf16 v[28:31], v[196:199], v[172:175], v[28:31]
	v_mfma_f32_16x16x32_bf16 v[24:27], v[204:207], v[172:175], v[24:27]
	v_mfma_f32_16x16x32_bf16 v[12:15], v[196:199], v[180:183], v[12:15]
	v_mfma_f32_16x16x32_bf16 v[8:11], v[204:207], v[180:183], v[8:11]
	v_mfma_f32_16x16x32_bf16 v[4:7], v[196:199], v[188:191], v[4:7]
	v_mfma_f32_16x16x32_bf16 v[0:3], v[204:207], v[188:191], v[0:3]
	v_mfma_f32_16x16x32_bf16 v[44:47], v[200:203], v[168:171], v[44:47]
	v_mfma_f32_16x16x32_bf16 v[40:43], v[208:211], v[168:171], v[40:43]
	v_mfma_f32_16x16x32_bf16 v[28:31], v[200:203], v[176:179], v[28:31]
	v_mfma_f32_16x16x32_bf16 v[24:27], v[208:211], v[176:179], v[24:27]
	v_mfma_f32_16x16x32_bf16 v[12:15], v[200:203], v[184:187], v[12:15]
	v_mfma_f32_16x16x32_bf16 v[8:11], v[208:211], v[184:187], v[8:11]
	v_mfma_f32_16x16x32_bf16 v[4:7], v[200:203], v[192:195], v[4:7]
	v_mfma_f32_16x16x32_bf16 v[0:3], v[208:211], v[192:195], v[0:3]
	s_barrier
	ds_read_b128 v[148:151], v146 offset:32768
	ds_read_b128 v[152:155], v146 offset:33792
	ds_read_b128 v[156:159], v146 offset:34816
	ds_read_b128 v[160:163], v146 offset:35840
	s_bitset1_b32 s54, 7
	s_ashr_i32 s55, s54, 31
	s_lshl_b64 s[54:55], s[54:55], 11
	s_add_u32 s54, s16, s54
	s_addc_u32 s55, s17, s55
	s_add_u32 s54, s54, s56
	s_addc_u32 s55, s55, s57
	s_mov_b32 m0, s26
	v_lshl_add_u64 v[196:197], s[54:55], 0, v[134:135]
	ds_read_b128 v[164:167], v147 offset:32768
	ds_read_b128 v[168:171], v147 offset:33792
	ds_read_b128 v[172:175], v147 offset:34816
	ds_read_b128 v[176:179], v147 offset:35840
	ds_read_b128 v[180:183], v147 offset:36864
	ds_read_b128 v[184:187], v147 offset:37888
	ds_read_b128 v[188:191], v147 offset:38912
	ds_read_b128 v[192:195], v147 offset:39936
	global_load_lds_dwordx4 v[196:197], off
	v_lshl_add_u64 v[196:197], s[54:55], 0, v[130:131]
	s_mov_b32 m0, s27
	s_nop 0
	global_load_lds_dwordx4 v[196:197], off
	s_waitcnt lgkmcnt(8)
	s_barrier
	s_waitcnt lgkmcnt(0)
	s_waitcnt lgkmcnt(0)
	v_mfma_f32_16x16x32_bf16 v[124:127], v[148:151], v[164:167], v[124:127]
	v_mfma_f32_16x16x32_bf16 v[120:123], v[156:159], v[164:167], v[120:123]
	v_mfma_f32_16x16x32_bf16 v[116:119], v[148:151], v[172:175], v[116:119]
	v_mfma_f32_16x16x32_bf16 v[112:115], v[156:159], v[172:175], v[112:115]
	v_mfma_f32_16x16x32_bf16 v[100:103], v[148:151], v[180:183], v[100:103]
	v_mfma_f32_16x16x32_bf16 v[96:99], v[156:159], v[180:183], v[96:99]
	v_mfma_f32_16x16x32_bf16 v[84:87], v[148:151], v[188:191], v[84:87]
	v_mfma_f32_16x16x32_bf16 v[80:83], v[156:159], v[188:191], v[80:83]
	v_mfma_f32_16x16x32_bf16 v[124:127], v[152:155], v[168:171], v[124:127]
	v_mfma_f32_16x16x32_bf16 v[120:123], v[160:163], v[168:171], v[120:123]
	v_mfma_f32_16x16x32_bf16 v[116:119], v[152:155], v[176:179], v[116:119]
	v_mfma_f32_16x16x32_bf16 v[112:115], v[160:163], v[176:179], v[112:115]
	v_mfma_f32_16x16x32_bf16 v[100:103], v[152:155], v[184:187], v[100:103]
	v_mfma_f32_16x16x32_bf16 v[96:99], v[160:163], v[184:187], v[96:99]
	v_mfma_f32_16x16x32_bf16 v[84:87], v[152:155], v[192:195], v[84:87]
	v_mfma_f32_16x16x32_bf16 v[80:83], v[160:163], v[192:195], v[80:83]
	s_barrier
	s_or_b32 s2, s2, 1
	s_lshl_b64 s[54:55], s[2:3], 7
	s_add_u32 s56, s78, s54
	s_addc_u32 s57, s79, s55
	s_mov_b32 m0, s28
	v_lshl_add_u64 v[212:213], s[56:57], 0, v[132:133]
	ds_read_b128 v[196:199], v146 offset:49152
	ds_read_b128 v[200:203], v146 offset:50176
	ds_read_b128 v[204:207], v146 offset:51200
	ds_read_b128 v[208:211], v146 offset:52224
	global_load_lds_dwordx4 v[212:213], off
	v_lshl_add_u64 v[212:213], s[56:57], 0, v[128:129]
	s_mov_b32 m0, s29
	s_nop 0
	global_load_lds_dwordx4 v[212:213], off
	s_barrier
	s_waitcnt lgkmcnt(0)
	s_waitcnt lgkmcnt(0)
	v_mfma_f32_16x16x32_bf16 v[108:111], v[196:199], v[164:167], v[108:111]
	v_mfma_f32_16x16x32_bf16 v[104:107], v[204:207], v[164:167], v[104:107]
	v_mfma_f32_16x16x32_bf16 v[92:95], v[196:199], v[172:175], v[92:95]
	v_mfma_f32_16x16x32_bf16 v[88:91], v[204:207], v[172:175], v[88:91]
	v_mfma_f32_16x16x32_bf16 v[76:79], v[196:199], v[180:183], v[76:79]
	v_mfma_f32_16x16x32_bf16 v[72:75], v[204:207], v[180:183], v[72:75]
	v_mfma_f32_16x16x32_bf16 v[68:71], v[196:199], v[188:191], v[68:71]
	v_mfma_f32_16x16x32_bf16 v[64:67], v[204:207], v[188:191], v[64:67]
	v_mfma_f32_16x16x32_bf16 v[108:111], v[200:203], v[168:171], v[108:111]
	v_mfma_f32_16x16x32_bf16 v[104:107], v[208:211], v[168:171], v[104:107]
	v_mfma_f32_16x16x32_bf16 v[92:95], v[200:203], v[176:179], v[92:95]
	v_mfma_f32_16x16x32_bf16 v[88:91], v[208:211], v[176:179], v[88:91]
	v_mfma_f32_16x16x32_bf16 v[76:79], v[200:203], v[184:187], v[76:79]
	v_mfma_f32_16x16x32_bf16 v[72:75], v[208:211], v[184:187], v[72:75]
	v_mfma_f32_16x16x32_bf16 v[68:71], v[200:203], v[192:195], v[68:71]
	v_mfma_f32_16x16x32_bf16 v[64:67], v[208:211], v[192:195], v[64:67]
	s_add_u32 s56, s80, s54
	s_addc_u32 s57, s81, s55
	s_mov_b32 m0, s30
	v_lshl_add_u64 v[212:213], s[56:57], 0, v[134:135]
	s_barrier
	ds_read_b128 v[164:167], v147 offset:49152
	ds_read_b128 v[168:171], v147 offset:50176
	ds_read_b128 v[172:175], v147 offset:51200
	ds_read_b128 v[176:179], v147 offset:52224
	ds_read_b128 v[180:183], v147 offset:53248
	ds_read_b128 v[184:187], v147 offset:54272
	ds_read_b128 v[188:191], v147 offset:55296
	ds_read_b128 v[192:195], v147 offset:56320
	global_load_lds_dwordx4 v[212:213], off
	v_lshl_add_u64 v[212:213], s[56:57], 0, v[130:131]
	s_mov_b32 m0, s31
	s_nop 0
	global_load_lds_dwordx4 v[212:213], off
	s_barrier
	s_waitcnt lgkmcnt(0)
	s_waitcnt lgkmcnt(0)
	v_mfma_f32_16x16x32_bf16 v[60:63], v[148:151], v[164:167], v[60:63]
	v_mfma_f32_16x16x32_bf16 v[56:59], v[156:159], v[164:167], v[56:59]
	v_mfma_f32_16x16x32_bf16 v[52:55], v[148:151], v[172:175], v[52:55]
	v_mfma_f32_16x16x32_bf16 v[48:51], v[156:159], v[172:175], v[48:51]
	v_mfma_f32_16x16x32_bf16 v[36:39], v[148:151], v[180:183], v[36:39]
	v_mfma_f32_16x16x32_bf16 v[32:35], v[156:159], v[180:183], v[32:35]
	v_mfma_f32_16x16x32_bf16 v[20:23], v[148:151], v[188:191], v[20:23]
	v_mfma_f32_16x16x32_bf16 v[16:19], v[156:159], v[188:191], v[16:19]
	v_mfma_f32_16x16x32_bf16 v[60:63], v[152:155], v[168:171], v[60:63]
	v_mfma_f32_16x16x32_bf16 v[56:59], v[160:163], v[168:171], v[56:59]
	v_mfma_f32_16x16x32_bf16 v[52:55], v[152:155], v[176:179], v[52:55]
	v_mfma_f32_16x16x32_bf16 v[48:51], v[160:163], v[176:179], v[48:51]
	v_mfma_f32_16x16x32_bf16 v[36:39], v[152:155], v[184:187], v[36:39]
	v_mfma_f32_16x16x32_bf16 v[32:35], v[160:163], v[184:187], v[32:35]
	v_mfma_f32_16x16x32_bf16 v[20:23], v[152:155], v[192:195], v[20:23]
	v_mfma_f32_16x16x32_bf16 v[16:19], v[160:163], v[192:195], v[16:19]
	s_barrier
	s_add_u32 s54, s76, s54
	s_addc_u32 s55, s77, s55
	s_mov_b32 m0, s33
	v_lshl_add_u64 v[148:149], s[54:55], 0, v[132:133]
	global_load_lds_dwordx4 v[148:149], off
	v_lshl_add_u64 v[148:149], s[54:55], 0, v[128:129]
	s_mov_b32 m0, s53
	s_nop 0
	global_load_lds_dwordx4 v[148:149], off
	s_waitcnt vmcnt(6)
	s_barrier
	v_mfma_f32_16x16x32_bf16 v[44:47], v[196:199], v[164:167], v[44:47]
	v_mfma_f32_16x16x32_bf16 v[40:43], v[204:207], v[164:167], v[40:43]
	v_mfma_f32_16x16x32_bf16 v[28:31], v[196:199], v[172:175], v[28:31]
	v_mfma_f32_16x16x32_bf16 v[24:27], v[204:207], v[172:175], v[24:27]
	v_mfma_f32_16x16x32_bf16 v[12:15], v[196:199], v[180:183], v[12:15]
	v_mfma_f32_16x16x32_bf16 v[8:11], v[204:207], v[180:183], v[8:11]
	v_mfma_f32_16x16x32_bf16 v[4:7], v[196:199], v[188:191], v[4:7]
	v_mfma_f32_16x16x32_bf16 v[0:3], v[204:207], v[188:191], v[0:3]
	v_mfma_f32_16x16x32_bf16 v[44:47], v[200:203], v[168:171], v[44:47]
	v_mfma_f32_16x16x32_bf16 v[40:43], v[208:211], v[168:171], v[40:43]
	v_mfma_f32_16x16x32_bf16 v[28:31], v[200:203], v[176:179], v[28:31]
	v_mfma_f32_16x16x32_bf16 v[24:27], v[208:211], v[176:179], v[24:27]
	v_mfma_f32_16x16x32_bf16 v[12:15], v[200:203], v[184:187], v[12:15]
	v_mfma_f32_16x16x32_bf16 v[8:11], v[208:211], v[184:187], v[8:11]
	v_mfma_f32_16x16x32_bf16 v[4:7], v[200:203], v[192:195], v[4:7]
	v_mfma_f32_16x16x32_bf16 v[0:3], v[208:211], v[192:195], v[0:3]
	v_lshl_add_u64 v[140:141], v[140:141], 0, s[4:5]
	v_lshl_add_u64 v[142:143], v[142:143], 0, s[4:5]
	s_cmp_ge_u32 s11, s75
	s_mov_b32 s2, s11
	s_barrier
	s_cbranch_scc0 .LBB0_321
	s_andn2_b64 vcc, exec, s[8:9]
	s_cbranch_vccnz .LBB0_317
	s_bitset1_b32 s10, 7
	s_ashr_i32 s11, s10, 31
	s_lshl_b64 s[10:11], s[10:11], 11
	s_add_u32 s10, s16, s10
	s_addc_u32 s11, s17, s11
	v_lshl_add_u64 v[192:193], s[10:11], 0, v[134:135]
	s_mov_b32 m0, s62
	v_lshl_add_u64 v[192:193], v[192:193], 0, s[6:7]
	ds_read_b128 v[140:143], v146
	ds_read_b128 v[148:151], v146 offset:1024
	ds_read_b128 v[152:155], v146 offset:2048
	ds_read_b128 v[156:159], v146 offset:3072
	ds_read_b128 v[160:163], v147
	ds_read_b128 v[164:167], v147 offset:1024
	ds_read_b128 v[168:171], v147 offset:2048
	ds_read_b128 v[172:175], v147 offset:3072
	ds_read_b128 v[176:179], v147 offset:4096
	ds_read_b128 v[180:183], v147 offset:5120
	ds_read_b128 v[184:187], v147 offset:6144
	ds_read_b128 v[188:191], v147 offset:7168
	global_load_lds_dwordx4 v[192:193], off
	v_lshl_add_u64 v[192:193], s[10:11], 0, v[130:131]
	v_lshl_add_u64 v[192:193], v[192:193], 0, s[6:7]
	s_mov_b32 m0, s63
	s_nop 0
	global_load_lds_dwordx4 v[192:193], off
	s_barrier
	s_waitcnt lgkmcnt(0)
	s_waitcnt lgkmcnt(0)
	v_mfma_f32_16x16x32_bf16 v[124:127], v[140:143], v[160:163], v[124:127]
	v_mfma_f32_16x16x32_bf16 v[120:123], v[152:155], v[160:163], v[120:123]
	v_mfma_f32_16x16x32_bf16 v[116:119], v[140:143], v[168:171], v[116:119]
	v_mfma_f32_16x16x32_bf16 v[112:115], v[152:155], v[168:171], v[112:115]
	v_mfma_f32_16x16x32_bf16 v[100:103], v[140:143], v[176:179], v[100:103]
	v_mfma_f32_16x16x32_bf16 v[96:99], v[152:155], v[176:179], v[96:99]
	v_mfma_f32_16x16x32_bf16 v[84:87], v[140:143], v[184:187], v[84:87]
	v_mfma_f32_16x16x32_bf16 v[80:83], v[152:155], v[184:187], v[80:83]
	v_mfma_f32_16x16x32_bf16 v[124:127], v[148:151], v[164:167], v[124:127]
	v_mfma_f32_16x16x32_bf16 v[120:123], v[156:159], v[164:167], v[120:123]
	v_mfma_f32_16x16x32_bf16 v[116:119], v[148:151], v[172:175], v[116:119]
	v_mfma_f32_16x16x32_bf16 v[112:115], v[156:159], v[172:175], v[112:115]
	v_mfma_f32_16x16x32_bf16 v[100:103], v[148:151], v[180:183], v[100:103]
	v_mfma_f32_16x16x32_bf16 v[96:99], v[156:159], v[180:183], v[96:99]
	v_mfma_f32_16x16x32_bf16 v[84:87], v[148:151], v[188:191], v[84:87]
	v_mfma_f32_16x16x32_bf16 v[80:83], v[156:159], v[188:191], v[80:83]
	s_barrier
	ds_read_b128 v[192:195], v146 offset:16384
	ds_read_b128 v[196:199], v146 offset:17408
	ds_read_b128 v[200:203], v146 offset:18432
	ds_read_b128 v[204:207], v146 offset:19456
	s_barrier
	s_waitcnt lgkmcnt(0)
	s_waitcnt lgkmcnt(0)
	v_mfma_f32_16x16x32_bf16 v[108:111], v[192:195], v[160:163], v[108:111]
	v_mfma_f32_16x16x32_bf16 v[104:107], v[200:203], v[160:163], v[104:107]
	v_mfma_f32_16x16x32_bf16 v[92:95], v[192:195], v[168:171], v[92:95]
	v_mfma_f32_16x16x32_bf16 v[88:91], v[200:203], v[168:171], v[88:91]
	v_mfma_f32_16x16x32_bf16 v[76:79], v[192:195], v[176:179], v[76:79]
	v_mfma_f32_16x16x32_bf16 v[72:75], v[200:203], v[176:179], v[72:75]
	v_mfma_f32_16x16x32_bf16 v[68:71], v[192:195], v[184:187], v[68:71]
	v_mfma_f32_16x16x32_bf16 v[64:67], v[200:203], v[184:187], v[64:67]
	v_mfma_f32_16x16x32_bf16 v[108:111], v[196:199], v[164:167], v[108:111]
	v_mfma_f32_16x16x32_bf16 v[104:107], v[204:207], v[164:167], v[104:107]
	v_mfma_f32_16x16x32_bf16 v[92:95], v[196:199], v[172:175], v[92:95]
	v_mfma_f32_16x16x32_bf16 v[88:91], v[204:207], v[172:175], v[88:91]
	v_mfma_f32_16x16x32_bf16 v[76:79], v[196:199], v[180:183], v[76:79]
	v_mfma_f32_16x16x32_bf16 v[72:75], v[204:207], v[180:183], v[72:75]
	v_mfma_f32_16x16x32_bf16 v[68:71], v[196:199], v[188:191], v[68:71]
	v_mfma_f32_16x16x32_bf16 v[64:67], v[204:207], v[188:191], v[64:67]
	s_barrier
	ds_read_b128 v[160:163], v147 offset:16384
	ds_read_b128 v[164:167], v147 offset:17408
	ds_read_b128 v[168:171], v147 offset:18432
	ds_read_b128 v[172:175], v147 offset:19456
	ds_read_b128 v[176:179], v147 offset:20480
	ds_read_b128 v[180:183], v147 offset:21504
	ds_read_b128 v[184:187], v147 offset:22528
	ds_read_b128 v[188:191], v147 offset:23552
	s_waitcnt vmcnt(4)
	s_barrier
	s_waitcnt lgkmcnt(0)
	s_waitcnt lgkmcnt(0)
	v_mfma_f32_16x16x32_bf16 v[60:63], v[140:143], v[160:163], v[60:63]
	v_mfma_f32_16x16x32_bf16 v[56:59], v[152:155], v[160:163], v[56:59]
	v_mfma_f32_16x16x32_bf16 v[52:55], v[140:143], v[168:171], v[52:55]
	v_mfma_f32_16x16x32_bf16 v[48:51], v[152:155], v[168:171], v[48:51]
	v_mfma_f32_16x16x32_bf16 v[36:39], v[140:143], v[176:179], v[36:39]
	v_mfma_f32_16x16x32_bf16 v[32:35], v[152:155], v[176:179], v[32:35]
	v_mfma_f32_16x16x32_bf16 v[20:23], v[140:143], v[184:187], v[20:23]
	v_mfma_f32_16x16x32_bf16 v[16:19], v[152:155], v[184:187], v[16:19]
	v_mfma_f32_16x16x32_bf16 v[60:63], v[148:151], v[164:167], v[60:63]
	v_mfma_f32_16x16x32_bf16 v[56:59], v[156:159], v[164:167], v[56:59]
	v_mfma_f32_16x16x32_bf16 v[52:55], v[148:151], v[172:175], v[52:55]
	v_mfma_f32_16x16x32_bf16 v[48:51], v[156:159], v[172:175], v[48:51]
	v_mfma_f32_16x16x32_bf16 v[36:39], v[148:151], v[180:183], v[36:39]
	v_mfma_f32_16x16x32_bf16 v[32:35], v[156:159], v[180:183], v[32:35]
	v_mfma_f32_16x16x32_bf16 v[20:23], v[148:151], v[188:191], v[20:23]
	v_mfma_f32_16x16x32_bf16 v[16:19], v[156:159], v[188:191], v[16:19]
	v_mfma_f32_16x16x32_bf16 v[44:47], v[192:195], v[160:163], v[44:47]
	v_mfma_f32_16x16x32_bf16 v[40:43], v[200:203], v[160:163], v[40:43]
	v_mfma_f32_16x16x32_bf16 v[28:31], v[192:195], v[168:171], v[28:31]
	v_mfma_f32_16x16x32_bf16 v[24:27], v[200:203], v[168:171], v[24:27]
	v_mfma_f32_16x16x32_bf16 v[12:15], v[192:195], v[176:179], v[12:15]
	v_mfma_f32_16x16x32_bf16 v[8:11], v[200:203], v[176:179], v[8:11]
	v_mfma_f32_16x16x32_bf16 v[4:7], v[192:195], v[184:187], v[4:7]
	v_mfma_f32_16x16x32_bf16 v[0:3], v[200:203], v[184:187], v[0:3]
	v_mfma_f32_16x16x32_bf16 v[44:47], v[196:199], v[164:167], v[44:47]
	v_mfma_f32_16x16x32_bf16 v[40:43], v[204:207], v[164:167], v[40:43]
	v_mfma_f32_16x16x32_bf16 v[28:31], v[196:199], v[172:175], v[28:31]
	v_mfma_f32_16x16x32_bf16 v[24:27], v[204:207], v[172:175], v[24:27]
	v_mfma_f32_16x16x32_bf16 v[12:15], v[196:199], v[180:183], v[12:15]
	v_mfma_f32_16x16x32_bf16 v[8:11], v[204:207], v[180:183], v[8:11]
	v_mfma_f32_16x16x32_bf16 v[4:7], v[196:199], v[188:191], v[4:7]
	v_mfma_f32_16x16x32_bf16 v[0:3], v[204:207], v[188:191], v[0:3]
	s_barrier
	ds_read_b128 v[140:143], v146 offset:32768
	ds_read_b128 v[148:151], v146 offset:33792
	ds_read_b128 v[152:155], v146 offset:34816
	ds_read_b128 v[156:159], v146 offset:35840
	ds_read_b128 v[160:163], v147 offset:32768
	ds_read_b128 v[164:167], v147 offset:33792
	ds_read_b128 v[168:171], v147 offset:34816
	ds_read_b128 v[172:175], v147 offset:35840
	ds_read_b128 v[176:179], v147 offset:36864
	ds_read_b128 v[180:183], v147 offset:37888
	ds_read_b128 v[184:187], v147 offset:38912
	ds_read_b128 v[188:191], v147 offset:39936
	s_waitcnt vmcnt(2)
	s_barrier
	s_waitcnt lgkmcnt(0)
	s_waitcnt lgkmcnt(0)
	v_mfma_f32_16x16x32_bf16 v[124:127], v[140:143], v[160:163], v[124:127]
	v_mfma_f32_16x16x32_bf16 v[120:123], v[152:155], v[160:163], v[120:123]
	v_mfma_f32_16x16x32_bf16 v[116:119], v[140:143], v[168:171], v[116:119]
	v_mfma_f32_16x16x32_bf16 v[112:115], v[152:155], v[168:171], v[112:115]
	v_mfma_f32_16x16x32_bf16 v[100:103], v[140:143], v[176:179], v[100:103]
	v_mfma_f32_16x16x32_bf16 v[96:99], v[152:155], v[176:179], v[96:99]
	v_mfma_f32_16x16x32_bf16 v[84:87], v[140:143], v[184:187], v[84:87]
	v_mfma_f32_16x16x32_bf16 v[80:83], v[152:155], v[184:187], v[80:83]
	v_mfma_f32_16x16x32_bf16 v[124:127], v[148:151], v[164:167], v[124:127]
	v_mfma_f32_16x16x32_bf16 v[120:123], v[156:159], v[164:167], v[120:123]
	v_mfma_f32_16x16x32_bf16 v[116:119], v[148:151], v[172:175], v[116:119]
	v_mfma_f32_16x16x32_bf16 v[112:115], v[156:159], v[172:175], v[112:115]
	v_mfma_f32_16x16x32_bf16 v[100:103], v[148:151], v[180:183], v[100:103]
	v_mfma_f32_16x16x32_bf16 v[96:99], v[156:159], v[180:183], v[96:99]
	v_mfma_f32_16x16x32_bf16 v[84:87], v[148:151], v[188:191], v[84:87]
	v_mfma_f32_16x16x32_bf16 v[80:83], v[156:159], v[188:191], v[80:83]
	s_barrier
	ds_read_b128 v[192:195], v146 offset:49152
	ds_read_b128 v[196:199], v146 offset:50176
	ds_read_b128 v[200:203], v146 offset:51200
	ds_read_b128 v[204:207], v146 offset:52224
	s_waitcnt vmcnt(0)
	s_barrier
	s_waitcnt lgkmcnt(0)
	s_waitcnt lgkmcnt(0)
	v_mfma_f32_16x16x32_bf16 v[108:111], v[192:195], v[160:163], v[108:111]
	v_mfma_f32_16x16x32_bf16 v[104:107], v[200:203], v[160:163], v[104:107]
	v_mfma_f32_16x16x32_bf16 v[92:95], v[192:195], v[168:171], v[92:95]
	v_mfma_f32_16x16x32_bf16 v[88:91], v[200:203], v[168:171], v[88:91]
	v_mfma_f32_16x16x32_bf16 v[76:79], v[192:195], v[176:179], v[76:79]
	v_mfma_f32_16x16x32_bf16 v[72:75], v[200:203], v[176:179], v[72:75]
	v_mfma_f32_16x16x32_bf16 v[68:71], v[192:195], v[184:187], v[68:71]
	v_mfma_f32_16x16x32_bf16 v[64:67], v[200:203], v[184:187], v[64:67]
	v_mfma_f32_16x16x32_bf16 v[108:111], v[196:199], v[164:167], v[108:111]
	v_mfma_f32_16x16x32_bf16 v[104:107], v[204:207], v[164:167], v[104:107]
	v_mfma_f32_16x16x32_bf16 v[92:95], v[196:199], v[172:175], v[92:95]
	v_mfma_f32_16x16x32_bf16 v[88:91], v[204:207], v[172:175], v[88:91]
	v_mfma_f32_16x16x32_bf16 v[76:79], v[196:199], v[180:183], v[76:79]
	v_mfma_f32_16x16x32_bf16 v[72:75], v[204:207], v[180:183], v[72:75]
	v_mfma_f32_16x16x32_bf16 v[68:71], v[196:199], v[188:191], v[68:71]
	v_mfma_f32_16x16x32_bf16 v[64:67], v[204:207], v[188:191], v[64:67]
	s_barrier
	ds_read_b128 v[160:163], v147 offset:49152
	ds_read_b128 v[164:167], v147 offset:50176
	ds_read_b128 v[168:171], v147 offset:51200
	ds_read_b128 v[172:175], v147 offset:52224
	ds_read_b128 v[176:179], v147 offset:53248
	ds_read_b128 v[180:183], v147 offset:54272
	ds_read_b128 v[184:187], v147 offset:55296
	ds_read_b128 v[188:191], v147 offset:56320
	s_barrier
	s_waitcnt lgkmcnt(0)
	s_waitcnt lgkmcnt(0)
	v_mfma_f32_16x16x32_bf16 v[60:63], v[140:143], v[160:163], v[60:63]
	v_mfma_f32_16x16x32_bf16 v[56:59], v[152:155], v[160:163], v[56:59]
	v_mfma_f32_16x16x32_bf16 v[52:55], v[140:143], v[168:171], v[52:55]
	v_mfma_f32_16x16x32_bf16 v[48:51], v[152:155], v[168:171], v[48:51]
	v_mfma_f32_16x16x32_bf16 v[36:39], v[140:143], v[176:179], v[36:39]
	v_mfma_f32_16x16x32_bf16 v[32:35], v[152:155], v[176:179], v[32:35]
	v_mfma_f32_16x16x32_bf16 v[20:23], v[140:143], v[184:187], v[20:23]
	v_mfma_f32_16x16x32_bf16 v[16:19], v[152:155], v[184:187], v[16:19]
	v_mfma_f32_16x16x32_bf16 v[60:63], v[148:151], v[164:167], v[60:63]
	v_mfma_f32_16x16x32_bf16 v[56:59], v[156:159], v[164:167], v[56:59]
	v_mfma_f32_16x16x32_bf16 v[52:55], v[148:151], v[172:175], v[52:55]
	v_mfma_f32_16x16x32_bf16 v[48:51], v[156:159], v[172:175], v[48:51]
	v_mfma_f32_16x16x32_bf16 v[36:39], v[148:151], v[180:183], v[36:39]
	v_mfma_f32_16x16x32_bf16 v[32:35], v[156:159], v[180:183], v[32:35]
	v_mfma_f32_16x16x32_bf16 v[20:23], v[148:151], v[188:191], v[20:23]
	v_mfma_f32_16x16x32_bf16 v[16:19], v[156:159], v[188:191], v[16:19]
	v_mfma_f32_16x16x32_bf16 v[44:47], v[192:195], v[160:163], v[44:47]
	v_mfma_f32_16x16x32_bf16 v[40:43], v[200:203], v[160:163], v[40:43]
	v_mfma_f32_16x16x32_bf16 v[28:31], v[192:195], v[168:171], v[28:31]
	v_mfma_f32_16x16x32_bf16 v[24:27], v[200:203], v[168:171], v[24:27]
	v_mfma_f32_16x16x32_bf16 v[12:15], v[192:195], v[176:179], v[12:15]
	v_mfma_f32_16x16x32_bf16 v[8:11], v[200:203], v[176:179], v[8:11]
	v_mfma_f32_16x16x32_bf16 v[4:7], v[192:195], v[184:187], v[4:7]
	v_mfma_f32_16x16x32_bf16 v[0:3], v[200:203], v[184:187], v[0:3]
	v_mfma_f32_16x16x32_bf16 v[44:47], v[196:199], v[164:167], v[44:47]
	v_mfma_f32_16x16x32_bf16 v[40:43], v[204:207], v[164:167], v[40:43]
	v_mfma_f32_16x16x32_bf16 v[28:31], v[196:199], v[172:175], v[28:31]
	v_mfma_f32_16x16x32_bf16 v[24:27], v[204:207], v[172:175], v[24:27]
	v_mfma_f32_16x16x32_bf16 v[12:15], v[196:199], v[180:183], v[12:15]
	v_mfma_f32_16x16x32_bf16 v[8:11], v[204:207], v[180:183], v[8:11]
	v_mfma_f32_16x16x32_bf16 v[4:7], v[196:199], v[188:191], v[4:7]
	v_mfma_f32_16x16x32_bf16 v[0:3], v[204:207], v[188:191], v[0:3]
	s_barrier
	s_branch .LBB0_317

.LBB0_367:
	ds_read_b128 v[148:151], v146
	ds_read_b128 v[152:155], v146 offset:1024
	ds_read_b128 v[156:159], v146 offset:2048
	ds_read_b128 v[160:163], v146 offset:3072
	s_add_i32 s11, s2, 2
	s_cmp_gt_u32 s2, 13
	s_cselect_b32 s54, s64, s36
	s_cselect_b32 s38, s63, s10
	s_mov_b32 m0, s58
	ds_read_b128 v[164:167], v147
	ds_read_b128 v[168:171], v147 offset:1024
	ds_read_b128 v[172:175], v147 offset:2048
	ds_read_b128 v[176:179], v147 offset:3072
	ds_read_b128 v[180:183], v147 offset:4096
	ds_read_b128 v[184:187], v147 offset:5120
	ds_read_b128 v[188:191], v147 offset:6144
	ds_read_b128 v[192:195], v147 offset:7168
	global_load_lds_dwordx4 v[140:141], off
	s_mov_b32 m0, s59
	s_nop 0
	global_load_lds_dwordx4 v[142:143], off
	s_waitcnt lgkmcnt(8)
	s_barrier
	s_waitcnt lgkmcnt(0)
	s_waitcnt lgkmcnt(0)
	v_mfma_f32_16x16x32_bf16 v[124:127], v[148:151], v[164:167], v[124:127]
	v_mfma_f32_16x16x32_bf16 v[120:123], v[156:159], v[164:167], v[120:123]
	v_mfma_f32_16x16x32_bf16 v[108:111], v[148:151], v[172:175], v[108:111]
	v_mfma_f32_16x16x32_bf16 v[104:107], v[156:159], v[172:175], v[104:107]
	v_mfma_f32_16x16x32_bf16 v[92:95], v[148:151], v[180:183], v[92:95]
	v_mfma_f32_16x16x32_bf16 v[88:91], v[156:159], v[180:183], v[88:91]
	v_mfma_f32_16x16x32_bf16 v[76:79], v[148:151], v[188:191], v[76:79]
	v_mfma_f32_16x16x32_bf16 v[72:75], v[156:159], v[188:191], v[72:75]
	v_mfma_f32_16x16x32_bf16 v[124:127], v[152:155], v[168:171], v[124:127]
	v_mfma_f32_16x16x32_bf16 v[120:123], v[160:163], v[168:171], v[120:123]
	v_mfma_f32_16x16x32_bf16 v[108:111], v[152:155], v[176:179], v[108:111]
	v_mfma_f32_16x16x32_bf16 v[104:107], v[160:163], v[176:179], v[104:107]
	v_mfma_f32_16x16x32_bf16 v[92:95], v[152:155], v[184:187], v[92:95]
	v_mfma_f32_16x16x32_bf16 v[88:91], v[160:163], v[184:187], v[88:91]
	v_mfma_f32_16x16x32_bf16 v[76:79], v[152:155], v[192:195], v[76:79]
	v_mfma_f32_16x16x32_bf16 v[72:75], v[160:163], v[192:195], v[72:75]
	s_barrier
	s_cselect_b32 s2, 0, s11
	s_ashr_i32 s55, s54, 31
	s_lshl_b64 s[52:53], s[54:55], 11
	s_add_u32 s74, s18, s52
	s_addc_u32 s75, s19, s53
	s_lshl_b64 s[52:53], s[2:3], 7
	s_add_u32 s72, s74, s52
	s_addc_u32 s73, s75, s53
	s_mov_b32 m0, s21
	v_lshl_add_u64 v[212:213], s[72:73], 0, v[132:133]
	ds_read_b128 v[196:199], v146 offset:16384
	ds_read_b128 v[200:203], v146 offset:17408
	ds_read_b128 v[204:207], v146 offset:18432
	ds_read_b128 v[208:211], v146 offset:19456
	global_load_lds_dwordx4 v[212:213], off
	v_lshl_add_u64 v[212:213], s[72:73], 0, v[128:129]
	s_mov_b32 m0, s22
	s_nop 0
	global_load_lds_dwordx4 v[212:213], off
	s_barrier
	s_waitcnt lgkmcnt(0)
	s_waitcnt lgkmcnt(0)
	v_mfma_f32_16x16x32_bf16 v[116:119], v[196:199], v[164:167], v[116:119]
	v_mfma_f32_16x16x32_bf16 v[112:115], v[204:207], v[164:167], v[112:115]
	v_mfma_f32_16x16x32_bf16 v[100:103], v[196:199], v[172:175], v[100:103]
	v_mfma_f32_16x16x32_bf16 v[96:99], v[204:207], v[172:175], v[96:99]
	v_mfma_f32_16x16x32_bf16 v[84:87], v[196:199], v[180:183], v[84:87]
	v_mfma_f32_16x16x32_bf16 v[80:83], v[204:207], v[180:183], v[80:83]
	v_mfma_f32_16x16x32_bf16 v[68:71], v[196:199], v[188:191], v[68:71]
	v_mfma_f32_16x16x32_bf16 v[64:67], v[204:207], v[188:191], v[64:67]
	v_mfma_f32_16x16x32_bf16 v[116:119], v[200:203], v[168:171], v[116:119]
	v_mfma_f32_16x16x32_bf16 v[112:115], v[208:211], v[168:171], v[112:115]
	v_mfma_f32_16x16x32_bf16 v[100:103], v[200:203], v[176:179], v[100:103]
	v_mfma_f32_16x16x32_bf16 v[96:99], v[208:211], v[176:179], v[96:99]
	v_mfma_f32_16x16x32_bf16 v[84:87], v[200:203], v[184:187], v[84:87]
	v_mfma_f32_16x16x32_bf16 v[80:83], v[208:211], v[184:187], v[80:83]
	v_mfma_f32_16x16x32_bf16 v[68:71], v[200:203], v[192:195], v[68:71]
	v_mfma_f32_16x16x32_bf16 v[64:67], v[208:211], v[192:195], v[64:67]
	s_ashr_i32 s39, s38, 31
	s_lshl_b64 s[72:73], s[38:39], 11
	s_add_u32 s76, s16, s72
	s_addc_u32 s77, s17, s73
	s_add_u32 s72, s76, s52
	s_addc_u32 s73, s77, s53
	s_mov_b32 m0, s20
	v_lshl_add_u64 v[212:213], s[72:73], 0, v[134:135]
	s_barrier
	ds_read_b128 v[164:167], v147 offset:16384
	ds_read_b128 v[168:171], v147 offset:17408
	ds_read_b128 v[172:175], v147 offset:18432
	ds_read_b128 v[176:179], v147 offset:19456
	ds_read_b128 v[180:183], v147 offset:20480
	ds_read_b128 v[184:187], v147 offset:21504
	ds_read_b128 v[188:191], v147 offset:22528
	ds_read_b128 v[192:195], v147 offset:23552
	global_load_lds_dwordx4 v[212:213], off
	v_lshl_add_u64 v[212:213], s[72:73], 0, v[130:131]
	s_mov_b32 m0, s23
	s_nop 0
	global_load_lds_dwordx4 v[212:213], off
	s_barrier
	s_waitcnt lgkmcnt(0)
	s_waitcnt lgkmcnt(0)
	v_mfma_f32_16x16x32_bf16 v[60:63], v[148:151], v[164:167], v[60:63]
	v_mfma_f32_16x16x32_bf16 v[56:59], v[156:159], v[164:167], v[56:59]
	v_mfma_f32_16x16x32_bf16 v[44:47], v[148:151], v[172:175], v[44:47]
	v_mfma_f32_16x16x32_bf16 v[40:43], v[156:159], v[172:175], v[40:43]
	v_mfma_f32_16x16x32_bf16 v[28:31], v[148:151], v[180:183], v[28:31]
	v_mfma_f32_16x16x32_bf16 v[24:27], v[156:159], v[180:183], v[24:27]
	v_mfma_f32_16x16x32_bf16 v[12:15], v[148:151], v[188:191], v[12:15]
	v_mfma_f32_16x16x32_bf16 v[8:11], v[156:159], v[188:191], v[8:11]
	v_mfma_f32_16x16x32_bf16 v[60:63], v[152:155], v[168:171], v[60:63]
	v_mfma_f32_16x16x32_bf16 v[56:59], v[160:163], v[168:171], v[56:59]
	v_mfma_f32_16x16x32_bf16 v[44:47], v[152:155], v[176:179], v[44:47]
	v_mfma_f32_16x16x32_bf16 v[40:43], v[160:163], v[176:179], v[40:43]
	v_mfma_f32_16x16x32_bf16 v[28:31], v[152:155], v[184:187], v[28:31]
	v_mfma_f32_16x16x32_bf16 v[24:27], v[160:163], v[184:187], v[24:27]
	v_mfma_f32_16x16x32_bf16 v[12:15], v[152:155], v[192:195], v[12:15]
	v_mfma_f32_16x16x32_bf16 v[8:11], v[160:163], v[192:195], v[8:11]
	s_barrier
	s_bitset1_b32 s54, 7
	s_ashr_i32 s55, s54, 31
	s_lshl_b64 s[54:55], s[54:55], 11
	s_add_u32 s72, s18, s54
	s_addc_u32 s73, s19, s55
	s_add_u32 s54, s72, s52
	s_addc_u32 s55, s73, s53
	s_mov_b32 m0, s24
	v_lshl_add_u64 v[148:149], s[54:55], 0, v[132:133]
	global_load_lds_dwordx4 v[148:149], off
	v_lshl_add_u64 v[148:149], s[54:55], 0, v[128:129]
	s_mov_b32 m0, s25
	s_nop 0
	global_load_lds_dwordx4 v[148:149], off
	s_waitcnt vmcnt(6)
	s_barrier
	v_mfma_f32_16x16x32_bf16 v[52:55], v[196:199], v[164:167], v[52:55]
	v_mfma_f32_16x16x32_bf16 v[48:51], v[204:207], v[164:167], v[48:51]
	v_mfma_f32_16x16x32_bf16 v[36:39], v[196:199], v[172:175], v[36:39]
	v_mfma_f32_16x16x32_bf16 v[32:35], v[204:207], v[172:175], v[32:35]
	v_mfma_f32_16x16x32_bf16 v[20:23], v[196:199], v[180:183], v[20:23]
	v_mfma_f32_16x16x32_bf16 v[16:19], v[204:207], v[180:183], v[16:19]
	v_mfma_f32_16x16x32_bf16 v[4:7], v[196:199], v[188:191], v[4:7]
	v_mfma_f32_16x16x32_bf16 v[0:3], v[204:207], v[188:191], v[0:3]
	v_mfma_f32_16x16x32_bf16 v[52:55], v[200:203], v[168:171], v[52:55]
	v_mfma_f32_16x16x32_bf16 v[48:51], v[208:211], v[168:171], v[48:51]
	v_mfma_f32_16x16x32_bf16 v[36:39], v[200:203], v[176:179], v[36:39]
	v_mfma_f32_16x16x32_bf16 v[32:35], v[208:211], v[176:179], v[32:35]
	v_mfma_f32_16x16x32_bf16 v[20:23], v[200:203], v[184:187], v[20:23]
	v_mfma_f32_16x16x32_bf16 v[16:19], v[208:211], v[184:187], v[16:19]
	v_mfma_f32_16x16x32_bf16 v[4:7], v[200:203], v[192:195], v[4:7]
	v_mfma_f32_16x16x32_bf16 v[0:3], v[208:211], v[192:195], v[0:3]
	s_barrier
	ds_read_b128 v[148:151], v146 offset:32768
	ds_read_b128 v[152:155], v146 offset:33792
	ds_read_b128 v[156:159], v146 offset:34816
	ds_read_b128 v[160:163], v146 offset:35840
	s_bitset1_b32 s38, 7
	s_ashr_i32 s39, s38, 31
	s_lshl_b64 s[38:39], s[38:39], 11
	s_add_u32 s38, s16, s38
	s_addc_u32 s39, s17, s39
	s_add_u32 s38, s38, s52
	s_addc_u32 s39, s39, s53
	s_mov_b32 m0, s26
	v_lshl_add_u64 v[196:197], s[38:39], 0, v[134:135]
	ds_read_b128 v[164:167], v147 offset:32768
	ds_read_b128 v[168:171], v147 offset:33792
	ds_read_b128 v[172:175], v147 offset:34816
	ds_read_b128 v[176:179], v147 offset:35840
	ds_read_b128 v[180:183], v147 offset:36864
	ds_read_b128 v[184:187], v147 offset:37888
	ds_read_b128 v[188:191], v147 offset:38912
	ds_read_b128 v[192:195], v147 offset:39936
	global_load_lds_dwordx4 v[196:197], off
	v_lshl_add_u64 v[196:197], s[38:39], 0, v[130:131]
	s_mov_b32 m0, s27
	s_nop 0
	global_load_lds_dwordx4 v[196:197], off
	s_waitcnt lgkmcnt(8)
	s_barrier
	s_waitcnt lgkmcnt(0)
	s_waitcnt lgkmcnt(0)
	v_mfma_f32_16x16x32_bf16 v[124:127], v[148:151], v[164:167], v[124:127]
	v_mfma_f32_16x16x32_bf16 v[120:123], v[156:159], v[164:167], v[120:123]
	v_mfma_f32_16x16x32_bf16 v[108:111], v[148:151], v[172:175], v[108:111]
	v_mfma_f32_16x16x32_bf16 v[104:107], v[156:159], v[172:175], v[104:107]
	v_mfma_f32_16x16x32_bf16 v[92:95], v[148:151], v[180:183], v[92:95]
	v_mfma_f32_16x16x32_bf16 v[88:91], v[156:159], v[180:183], v[88:91]
	v_mfma_f32_16x16x32_bf16 v[76:79], v[148:151], v[188:191], v[76:79]
	v_mfma_f32_16x16x32_bf16 v[72:75], v[156:159], v[188:191], v[72:75]
	v_mfma_f32_16x16x32_bf16 v[124:127], v[152:155], v[168:171], v[124:127]
	v_mfma_f32_16x16x32_bf16 v[120:123], v[160:163], v[168:171], v[120:123]
	v_mfma_f32_16x16x32_bf16 v[108:111], v[152:155], v[176:179], v[108:111]
	v_mfma_f32_16x16x32_bf16 v[104:107], v[160:163], v[176:179], v[104:107]
	v_mfma_f32_16x16x32_bf16 v[92:95], v[152:155], v[184:187], v[92:95]
	v_mfma_f32_16x16x32_bf16 v[88:91], v[160:163], v[184:187], v[88:91]
	v_mfma_f32_16x16x32_bf16 v[76:79], v[152:155], v[192:195], v[76:79]
	v_mfma_f32_16x16x32_bf16 v[72:75], v[160:163], v[192:195], v[72:75]
	s_barrier
	s_or_b32 s2, s2, 1
	s_lshl_b64 s[38:39], s[2:3], 7
	s_add_u32 s52, s74, s38
	s_addc_u32 s53, s75, s39
	s_mov_b32 m0, s28
	v_lshl_add_u64 v[212:213], s[52:53], 0, v[132:133]
	ds_read_b128 v[196:199], v146 offset:49152
	ds_read_b128 v[200:203], v146 offset:50176
	ds_read_b128 v[204:207], v146 offset:51200
	ds_read_b128 v[208:211], v146 offset:52224
	global_load_lds_dwordx4 v[212:213], off
	v_lshl_add_u64 v[212:213], s[52:53], 0, v[128:129]
	s_mov_b32 m0, s29
	s_nop 0
	global_load_lds_dwordx4 v[212:213], off
	s_barrier
	s_waitcnt lgkmcnt(0)
	s_waitcnt lgkmcnt(0)
	v_mfma_f32_16x16x32_bf16 v[116:119], v[196:199], v[164:167], v[116:119]
	v_mfma_f32_16x16x32_bf16 v[112:115], v[204:207], v[164:167], v[112:115]
	v_mfma_f32_16x16x32_bf16 v[100:103], v[196:199], v[172:175], v[100:103]
	v_mfma_f32_16x16x32_bf16 v[96:99], v[204:207], v[172:175], v[96:99]
	v_mfma_f32_16x16x32_bf16 v[84:87], v[196:199], v[180:183], v[84:87]
	v_mfma_f32_16x16x32_bf16 v[80:83], v[204:207], v[180:183], v[80:83]
	v_mfma_f32_16x16x32_bf16 v[68:71], v[196:199], v[188:191], v[68:71]
	v_mfma_f32_16x16x32_bf16 v[64:67], v[204:207], v[188:191], v[64:67]
	v_mfma_f32_16x16x32_bf16 v[116:119], v[200:203], v[168:171], v[116:119]
	v_mfma_f32_16x16x32_bf16 v[112:115], v[208:211], v[168:171], v[112:115]
	v_mfma_f32_16x16x32_bf16 v[100:103], v[200:203], v[176:179], v[100:103]
	v_mfma_f32_16x16x32_bf16 v[96:99], v[208:211], v[176:179], v[96:99]
	v_mfma_f32_16x16x32_bf16 v[84:87], v[200:203], v[184:187], v[84:87]
	v_mfma_f32_16x16x32_bf16 v[80:83], v[208:211], v[184:187], v[80:83]
	v_mfma_f32_16x16x32_bf16 v[68:71], v[200:203], v[192:195], v[68:71]
	v_mfma_f32_16x16x32_bf16 v[64:67], v[208:211], v[192:195], v[64:67]
	s_add_u32 s52, s76, s38
	s_addc_u32 s53, s77, s39
	s_mov_b32 m0, s30
	v_lshl_add_u64 v[212:213], s[52:53], 0, v[134:135]
	s_barrier
	ds_read_b128 v[164:167], v147 offset:49152
	ds_read_b128 v[168:171], v147 offset:50176
	ds_read_b128 v[172:175], v147 offset:51200
	ds_read_b128 v[176:179], v147 offset:52224
	ds_read_b128 v[180:183], v147 offset:53248
	ds_read_b128 v[184:187], v147 offset:54272
	ds_read_b128 v[188:191], v147 offset:55296
	ds_read_b128 v[192:195], v147 offset:56320
	global_load_lds_dwordx4 v[212:213], off
	v_lshl_add_u64 v[212:213], s[52:53], 0, v[130:131]
	s_mov_b32 m0, s31
	s_nop 0
	global_load_lds_dwordx4 v[212:213], off
	s_barrier
	s_waitcnt lgkmcnt(0)
	s_waitcnt lgkmcnt(0)
	v_mfma_f32_16x16x32_bf16 v[60:63], v[148:151], v[164:167], v[60:63]
	v_mfma_f32_16x16x32_bf16 v[56:59], v[156:159], v[164:167], v[56:59]
	v_mfma_f32_16x16x32_bf16 v[44:47], v[148:151], v[172:175], v[44:47]
	v_mfma_f32_16x16x32_bf16 v[40:43], v[156:159], v[172:175], v[40:43]
	v_mfma_f32_16x16x32_bf16 v[28:31], v[148:151], v[180:183], v[28:31]
	v_mfma_f32_16x16x32_bf16 v[24:27], v[156:159], v[180:183], v[24:27]
	v_mfma_f32_16x16x32_bf16 v[12:15], v[148:151], v[188:191], v[12:15]
	v_mfma_f32_16x16x32_bf16 v[8:11], v[156:159], v[188:191], v[8:11]
	v_mfma_f32_16x16x32_bf16 v[60:63], v[152:155], v[168:171], v[60:63]
	v_mfma_f32_16x16x32_bf16 v[56:59], v[160:163], v[168:171], v[56:59]
	v_mfma_f32_16x16x32_bf16 v[44:47], v[152:155], v[176:179], v[44:47]
	v_mfma_f32_16x16x32_bf16 v[40:43], v[160:163], v[176:179], v[40:43]
	v_mfma_f32_16x16x32_bf16 v[28:31], v[152:155], v[184:187], v[28:31]
	v_mfma_f32_16x16x32_bf16 v[24:27], v[160:163], v[184:187], v[24:27]
	v_mfma_f32_16x16x32_bf16 v[12:15], v[152:155], v[192:195], v[12:15]
	v_mfma_f32_16x16x32_bf16 v[8:11], v[160:163], v[192:195], v[8:11]
	s_barrier
	s_add_u32 s38, s72, s38
	s_addc_u32 s39, s73, s39
	s_mov_b32 m0, s33
	v_lshl_add_u64 v[148:149], s[38:39], 0, v[132:133]
	global_load_lds_dwordx4 v[148:149], off
	v_lshl_add_u64 v[148:149], s[38:39], 0, v[128:129]
	s_mov_b32 m0, s37
	s_nop 0
	global_load_lds_dwordx4 v[148:149], off
	s_waitcnt vmcnt(6)
	s_barrier
	v_mfma_f32_16x16x32_bf16 v[52:55], v[196:199], v[164:167], v[52:55]
	v_mfma_f32_16x16x32_bf16 v[48:51], v[204:207], v[164:167], v[48:51]
	v_mfma_f32_16x16x32_bf16 v[36:39], v[196:199], v[172:175], v[36:39]
	v_mfma_f32_16x16x32_bf16 v[32:35], v[204:207], v[172:175], v[32:35]
	v_mfma_f32_16x16x32_bf16 v[20:23], v[196:199], v[180:183], v[20:23]
	v_mfma_f32_16x16x32_bf16 v[16:19], v[204:207], v[180:183], v[16:19]
	v_mfma_f32_16x16x32_bf16 v[4:7], v[196:199], v[188:191], v[4:7]
	v_mfma_f32_16x16x32_bf16 v[0:3], v[204:207], v[188:191], v[0:3]
	v_mfma_f32_16x16x32_bf16 v[52:55], v[200:203], v[168:171], v[52:55]
	v_mfma_f32_16x16x32_bf16 v[48:51], v[208:211], v[168:171], v[48:51]
	v_mfma_f32_16x16x32_bf16 v[36:39], v[200:203], v[176:179], v[36:39]
	v_mfma_f32_16x16x32_bf16 v[32:35], v[208:211], v[176:179], v[32:35]
	v_mfma_f32_16x16x32_bf16 v[20:23], v[200:203], v[184:187], v[20:23]
	v_mfma_f32_16x16x32_bf16 v[16:19], v[208:211], v[184:187], v[16:19]
	v_mfma_f32_16x16x32_bf16 v[4:7], v[200:203], v[192:195], v[4:7]
	v_mfma_f32_16x16x32_bf16 v[0:3], v[208:211], v[192:195], v[0:3]
	v_lshl_add_u64 v[140:141], v[140:141], 0, s[4:5]
	v_lshl_add_u64 v[142:143], v[142:143], 0, s[4:5]
	s_cmp_ge_u32 s11, s67
	s_mov_b32 s2, s11
	s_barrier
	s_cbranch_scc0 .LBB0_367
	s_andn2_b64 vcc, exec, s[8:9]
	s_cbranch_vccnz .LBB0_363
	s_bitset1_b32 s10, 7
	s_ashr_i32 s11, s10, 31
	s_lshl_b64 s[10:11], s[10:11], 11
	s_add_u32 s10, s16, s10
	s_addc_u32 s11, s17, s11
	v_lshl_add_u64 v[192:193], s[10:11], 0, v[134:135]
	s_mov_b32 m0, s58
	v_lshl_add_u64 v[192:193], v[192:193], 0, s[6:7]
	ds_read_b128 v[140:143], v146
	ds_read_b128 v[148:151], v146 offset:1024
	ds_read_b128 v[152:155], v146 offset:2048
	ds_read_b128 v[156:159], v146 offset:3072
	ds_read_b128 v[160:163], v147
	ds_read_b128 v[164:167], v147 offset:1024
	ds_read_b128 v[168:171], v147 offset:2048
	ds_read_b128 v[172:175], v147 offset:3072
	ds_read_b128 v[176:179], v147 offset:4096
	ds_read_b128 v[180:183], v147 offset:5120
	ds_read_b128 v[184:187], v147 offset:6144
	ds_read_b128 v[188:191], v147 offset:7168
	global_load_lds_dwordx4 v[192:193], off
	v_lshl_add_u64 v[192:193], s[10:11], 0, v[130:131]
	v_lshl_add_u64 v[192:193], v[192:193], 0, s[6:7]
	s_mov_b32 m0, s59
	s_nop 0
	global_load_lds_dwordx4 v[192:193], off
	s_barrier
	s_waitcnt lgkmcnt(0)
	s_waitcnt lgkmcnt(0)
	v_mfma_f32_16x16x32_bf16 v[124:127], v[140:143], v[160:163], v[124:127]
	v_mfma_f32_16x16x32_bf16 v[120:123], v[152:155], v[160:163], v[120:123]
	v_mfma_f32_16x16x32_bf16 v[108:111], v[140:143], v[168:171], v[108:111]
	v_mfma_f32_16x16x32_bf16 v[104:107], v[152:155], v[168:171], v[104:107]
	v_mfma_f32_16x16x32_bf16 v[92:95], v[140:143], v[176:179], v[92:95]
	v_mfma_f32_16x16x32_bf16 v[88:91], v[152:155], v[176:179], v[88:91]
	v_mfma_f32_16x16x32_bf16 v[76:79], v[140:143], v[184:187], v[76:79]
	v_mfma_f32_16x16x32_bf16 v[72:75], v[152:155], v[184:187], v[72:75]
	v_mfma_f32_16x16x32_bf16 v[124:127], v[148:151], v[164:167], v[124:127]
	v_mfma_f32_16x16x32_bf16 v[120:123], v[156:159], v[164:167], v[120:123]
	v_mfma_f32_16x16x32_bf16 v[108:111], v[148:151], v[172:175], v[108:111]
	v_mfma_f32_16x16x32_bf16 v[104:107], v[156:159], v[172:175], v[104:107]
	v_mfma_f32_16x16x32_bf16 v[92:95], v[148:151], v[180:183], v[92:95]
	v_mfma_f32_16x16x32_bf16 v[88:91], v[156:159], v[180:183], v[88:91]
	v_mfma_f32_16x16x32_bf16 v[76:79], v[148:151], v[188:191], v[76:79]
	v_mfma_f32_16x16x32_bf16 v[72:75], v[156:159], v[188:191], v[72:75]
	s_barrier
	ds_read_b128 v[192:195], v146 offset:16384
	ds_read_b128 v[196:199], v146 offset:17408
	ds_read_b128 v[200:203], v146 offset:18432
	ds_read_b128 v[204:207], v146 offset:19456
	s_barrier
	s_waitcnt lgkmcnt(0)
	s_waitcnt lgkmcnt(0)
	v_mfma_f32_16x16x32_bf16 v[116:119], v[192:195], v[160:163], v[116:119]
	v_mfma_f32_16x16x32_bf16 v[112:115], v[200:203], v[160:163], v[112:115]
	v_mfma_f32_16x16x32_bf16 v[100:103], v[192:195], v[168:171], v[100:103]
	v_mfma_f32_16x16x32_bf16 v[96:99], v[200:203], v[168:171], v[96:99]
	v_mfma_f32_16x16x32_bf16 v[84:87], v[192:195], v[176:179], v[84:87]
	v_mfma_f32_16x16x32_bf16 v[80:83], v[200:203], v[176:179], v[80:83]
	v_mfma_f32_16x16x32_bf16 v[68:71], v[192:195], v[184:187], v[68:71]
	v_mfma_f32_16x16x32_bf16 v[64:67], v[200:203], v[184:187], v[64:67]
	v_mfma_f32_16x16x32_bf16 v[116:119], v[196:199], v[164:167], v[116:119]
	v_mfma_f32_16x16x32_bf16 v[112:115], v[204:207], v[164:167], v[112:115]
	v_mfma_f32_16x16x32_bf16 v[100:103], v[196:199], v[172:175], v[100:103]
	v_mfma_f32_16x16x32_bf16 v[96:99], v[204:207], v[172:175], v[96:99]
	v_mfma_f32_16x16x32_bf16 v[84:87], v[196:199], v[180:183], v[84:87]
	v_mfma_f32_16x16x32_bf16 v[80:83], v[204:207], v[180:183], v[80:83]
	v_mfma_f32_16x16x32_bf16 v[68:71], v[196:199], v[188:191], v[68:71]
	v_mfma_f32_16x16x32_bf16 v[64:67], v[204:207], v[188:191], v[64:67]
	s_barrier
	ds_read_b128 v[160:163], v147 offset:16384
	ds_read_b128 v[164:167], v147 offset:17408
	ds_read_b128 v[168:171], v147 offset:18432
	ds_read_b128 v[172:175], v147 offset:19456
	ds_read_b128 v[176:179], v147 offset:20480
	ds_read_b128 v[180:183], v147 offset:21504
	ds_read_b128 v[184:187], v147 offset:22528
	ds_read_b128 v[188:191], v147 offset:23552
	s_waitcnt vmcnt(4)
	s_barrier
	s_waitcnt lgkmcnt(0)
	s_waitcnt lgkmcnt(0)
	v_mfma_f32_16x16x32_bf16 v[60:63], v[140:143], v[160:163], v[60:63]
	v_mfma_f32_16x16x32_bf16 v[56:59], v[152:155], v[160:163], v[56:59]
	v_mfma_f32_16x16x32_bf16 v[44:47], v[140:143], v[168:171], v[44:47]
	v_mfma_f32_16x16x32_bf16 v[40:43], v[152:155], v[168:171], v[40:43]
	v_mfma_f32_16x16x32_bf16 v[28:31], v[140:143], v[176:179], v[28:31]
	v_mfma_f32_16x16x32_bf16 v[24:27], v[152:155], v[176:179], v[24:27]
	v_mfma_f32_16x16x32_bf16 v[12:15], v[140:143], v[184:187], v[12:15]
	v_mfma_f32_16x16x32_bf16 v[8:11], v[152:155], v[184:187], v[8:11]
	v_mfma_f32_16x16x32_bf16 v[60:63], v[148:151], v[164:167], v[60:63]
	v_mfma_f32_16x16x32_bf16 v[56:59], v[156:159], v[164:167], v[56:59]
	v_mfma_f32_16x16x32_bf16 v[44:47], v[148:151], v[172:175], v[44:47]
	v_mfma_f32_16x16x32_bf16 v[40:43], v[156:159], v[172:175], v[40:43]
	v_mfma_f32_16x16x32_bf16 v[28:31], v[148:151], v[180:183], v[28:31]
	v_mfma_f32_16x16x32_bf16 v[24:27], v[156:159], v[180:183], v[24:27]
	v_mfma_f32_16x16x32_bf16 v[12:15], v[148:151], v[188:191], v[12:15]
	v_mfma_f32_16x16x32_bf16 v[8:11], v[156:159], v[188:191], v[8:11]
	v_mfma_f32_16x16x32_bf16 v[52:55], v[192:195], v[160:163], v[52:55]
	v_mfma_f32_16x16x32_bf16 v[48:51], v[200:203], v[160:163], v[48:51]
	v_mfma_f32_16x16x32_bf16 v[36:39], v[192:195], v[168:171], v[36:39]
	v_mfma_f32_16x16x32_bf16 v[32:35], v[200:203], v[168:171], v[32:35]
	v_mfma_f32_16x16x32_bf16 v[20:23], v[192:195], v[176:179], v[20:23]
	v_mfma_f32_16x16x32_bf16 v[16:19], v[200:203], v[176:179], v[16:19]
	v_mfma_f32_16x16x32_bf16 v[4:7], v[192:195], v[184:187], v[4:7]
	v_mfma_f32_16x16x32_bf16 v[0:3], v[200:203], v[184:187], v[0:3]
	v_mfma_f32_16x16x32_bf16 v[52:55], v[196:199], v[164:167], v[52:55]
	v_mfma_f32_16x16x32_bf16 v[48:51], v[204:207], v[164:167], v[48:51]
	v_mfma_f32_16x16x32_bf16 v[36:39], v[196:199], v[172:175], v[36:39]
	v_mfma_f32_16x16x32_bf16 v[32:35], v[204:207], v[172:175], v[32:35]
	v_mfma_f32_16x16x32_bf16 v[20:23], v[196:199], v[180:183], v[20:23]
	v_mfma_f32_16x16x32_bf16 v[16:19], v[204:207], v[180:183], v[16:19]
	v_mfma_f32_16x16x32_bf16 v[4:7], v[196:199], v[188:191], v[4:7]
	v_mfma_f32_16x16x32_bf16 v[0:3], v[204:207], v[188:191], v[0:3]
	s_barrier
	ds_read_b128 v[140:143], v146 offset:32768
	ds_read_b128 v[148:151], v146 offset:33792
	ds_read_b128 v[152:155], v146 offset:34816
	ds_read_b128 v[156:159], v146 offset:35840
	ds_read_b128 v[160:163], v147 offset:32768
	ds_read_b128 v[164:167], v147 offset:33792
	ds_read_b128 v[168:171], v147 offset:34816
	ds_read_b128 v[172:175], v147 offset:35840
	ds_read_b128 v[176:179], v147 offset:36864
	ds_read_b128 v[180:183], v147 offset:37888
	ds_read_b128 v[184:187], v147 offset:38912
	ds_read_b128 v[188:191], v147 offset:39936
	s_waitcnt vmcnt(2)
	s_barrier
	s_waitcnt lgkmcnt(0)
	s_waitcnt lgkmcnt(0)
	v_mfma_f32_16x16x32_bf16 v[124:127], v[140:143], v[160:163], v[124:127]
	v_mfma_f32_16x16x32_bf16 v[120:123], v[152:155], v[160:163], v[120:123]
	v_mfma_f32_16x16x32_bf16 v[108:111], v[140:143], v[168:171], v[108:111]
	v_mfma_f32_16x16x32_bf16 v[104:107], v[152:155], v[168:171], v[104:107]
	v_mfma_f32_16x16x32_bf16 v[92:95], v[140:143], v[176:179], v[92:95]
	v_mfma_f32_16x16x32_bf16 v[88:91], v[152:155], v[176:179], v[88:91]
	v_mfma_f32_16x16x32_bf16 v[76:79], v[140:143], v[184:187], v[76:79]
	v_mfma_f32_16x16x32_bf16 v[72:75], v[152:155], v[184:187], v[72:75]
	v_mfma_f32_16x16x32_bf16 v[124:127], v[148:151], v[164:167], v[124:127]
	v_mfma_f32_16x16x32_bf16 v[120:123], v[156:159], v[164:167], v[120:123]
	v_mfma_f32_16x16x32_bf16 v[108:111], v[148:151], v[172:175], v[108:111]
	v_mfma_f32_16x16x32_bf16 v[104:107], v[156:159], v[172:175], v[104:107]
	v_mfma_f32_16x16x32_bf16 v[92:95], v[148:151], v[180:183], v[92:95]
	v_mfma_f32_16x16x32_bf16 v[88:91], v[156:159], v[180:183], v[88:91]
	v_mfma_f32_16x16x32_bf16 v[76:79], v[148:151], v[188:191], v[76:79]
	v_mfma_f32_16x16x32_bf16 v[72:75], v[156:159], v[188:191], v[72:75]
	s_barrier
	ds_read_b128 v[192:195], v146 offset:49152
	ds_read_b128 v[196:199], v146 offset:50176
	ds_read_b128 v[200:203], v146 offset:51200
	ds_read_b128 v[204:207], v146 offset:52224
	s_waitcnt vmcnt(0)
	s_barrier
	s_waitcnt lgkmcnt(0)
	s_waitcnt lgkmcnt(0)
	v_mfma_f32_16x16x32_bf16 v[116:119], v[192:195], v[160:163], v[116:119]
	v_mfma_f32_16x16x32_bf16 v[112:115], v[200:203], v[160:163], v[112:115]
	v_mfma_f32_16x16x32_bf16 v[100:103], v[192:195], v[168:171], v[100:103]
	v_mfma_f32_16x16x32_bf16 v[96:99], v[200:203], v[168:171], v[96:99]
	v_mfma_f32_16x16x32_bf16 v[84:87], v[192:195], v[176:179], v[84:87]
	v_mfma_f32_16x16x32_bf16 v[80:83], v[200:203], v[176:179], v[80:83]
	v_mfma_f32_16x16x32_bf16 v[68:71], v[192:195], v[184:187], v[68:71]
	v_mfma_f32_16x16x32_bf16 v[64:67], v[200:203], v[184:187], v[64:67]
	v_mfma_f32_16x16x32_bf16 v[116:119], v[196:199], v[164:167], v[116:119]
	v_mfma_f32_16x16x32_bf16 v[112:115], v[204:207], v[164:167], v[112:115]
	v_mfma_f32_16x16x32_bf16 v[100:103], v[196:199], v[172:175], v[100:103]
	v_mfma_f32_16x16x32_bf16 v[96:99], v[204:207], v[172:175], v[96:99]
	v_mfma_f32_16x16x32_bf16 v[84:87], v[196:199], v[180:183], v[84:87]
	v_mfma_f32_16x16x32_bf16 v[80:83], v[204:207], v[180:183], v[80:83]
	v_mfma_f32_16x16x32_bf16 v[68:71], v[196:199], v[188:191], v[68:71]
	v_mfma_f32_16x16x32_bf16 v[64:67], v[204:207], v[188:191], v[64:67]
	s_barrier
	ds_read_b128 v[160:163], v147 offset:49152
	ds_read_b128 v[164:167], v147 offset:50176
	ds_read_b128 v[168:171], v147 offset:51200
	ds_read_b128 v[172:175], v147 offset:52224
	ds_read_b128 v[176:179], v147 offset:53248
	ds_read_b128 v[180:183], v147 offset:54272
	ds_read_b128 v[184:187], v147 offset:55296
	ds_read_b128 v[188:191], v147 offset:56320
	s_barrier
	s_waitcnt lgkmcnt(0)
	s_waitcnt lgkmcnt(0)
	v_mfma_f32_16x16x32_bf16 v[60:63], v[140:143], v[160:163], v[60:63]
	v_mfma_f32_16x16x32_bf16 v[56:59], v[152:155], v[160:163], v[56:59]
	v_mfma_f32_16x16x32_bf16 v[44:47], v[140:143], v[168:171], v[44:47]
	v_mfma_f32_16x16x32_bf16 v[40:43], v[152:155], v[168:171], v[40:43]
	v_mfma_f32_16x16x32_bf16 v[28:31], v[140:143], v[176:179], v[28:31]
	v_mfma_f32_16x16x32_bf16 v[24:27], v[152:155], v[176:179], v[24:27]
	v_mfma_f32_16x16x32_bf16 v[12:15], v[140:143], v[184:187], v[12:15]
	v_mfma_f32_16x16x32_bf16 v[8:11], v[152:155], v[184:187], v[8:11]
	v_mfma_f32_16x16x32_bf16 v[60:63], v[148:151], v[164:167], v[60:63]
	v_mfma_f32_16x16x32_bf16 v[56:59], v[156:159], v[164:167], v[56:59]
	v_mfma_f32_16x16x32_bf16 v[44:47], v[148:151], v[172:175], v[44:47]
	v_mfma_f32_16x16x32_bf16 v[40:43], v[156:159], v[172:175], v[40:43]
	v_mfma_f32_16x16x32_bf16 v[28:31], v[148:151], v[180:183], v[28:31]
	v_mfma_f32_16x16x32_bf16 v[24:27], v[156:159], v[180:183], v[24:27]
	v_mfma_f32_16x16x32_bf16 v[12:15], v[148:151], v[188:191], v[12:15]
	v_mfma_f32_16x16x32_bf16 v[8:11], v[156:159], v[188:191], v[8:11]
	v_mfma_f32_16x16x32_bf16 v[52:55], v[192:195], v[160:163], v[52:55]
	v_mfma_f32_16x16x32_bf16 v[48:51], v[200:203], v[160:163], v[48:51]
	v_mfma_f32_16x16x32_bf16 v[36:39], v[192:195], v[168:171], v[36:39]
	v_mfma_f32_16x16x32_bf16 v[32:35], v[200:203], v[168:171], v[32:35]
	v_mfma_f32_16x16x32_bf16 v[20:23], v[192:195], v[176:179], v[20:23]
	v_mfma_f32_16x16x32_bf16 v[16:19], v[200:203], v[176:179], v[16:19]
	v_mfma_f32_16x16x32_bf16 v[4:7], v[192:195], v[184:187], v[4:7]
	v_mfma_f32_16x16x32_bf16 v[0:3], v[200:203], v[184:187], v[0:3]
	v_mfma_f32_16x16x32_bf16 v[52:55], v[196:199], v[164:167], v[52:55]
	v_mfma_f32_16x16x32_bf16 v[48:51], v[204:207], v[164:167], v[48:51]
	v_mfma_f32_16x16x32_bf16 v[36:39], v[196:199], v[172:175], v[36:39]
	v_mfma_f32_16x16x32_bf16 v[32:35], v[204:207], v[172:175], v[32:35]
	v_mfma_f32_16x16x32_bf16 v[20:23], v[196:199], v[180:183], v[20:23]
	v_mfma_f32_16x16x32_bf16 v[16:19], v[204:207], v[180:183], v[16:19]
	v_mfma_f32_16x16x32_bf16 v[4:7], v[196:199], v[188:191], v[4:7]
	v_mfma_f32_16x16x32_bf16 v[0:3], v[204:207], v[188:191], v[0:3]
	s_barrier
	s_branch .LBB0_363

.LBB0_392:
	ds_read_b128 v[148:151], v146
	ds_read_b128 v[152:155], v146 offset:1024
	ds_read_b128 v[156:159], v146 offset:2048
	ds_read_b128 v[160:163], v146 offset:3072
	s_add_i32 s9, s2, 2
	s_cmp_gt_u32 s2, 61
	s_cselect_b32 s52, s64, s10
	s_cselect_b32 s36, s63, s8
	s_mov_b32 m0, s56
	ds_read_b128 v[164:167], v147
	ds_read_b128 v[168:171], v147 offset:1024
	ds_read_b128 v[172:175], v147 offset:2048
	ds_read_b128 v[176:179], v147 offset:3072
	ds_read_b128 v[180:183], v147 offset:4096
	ds_read_b128 v[184:187], v147 offset:5120
	ds_read_b128 v[188:191], v147 offset:6144
	ds_read_b128 v[192:195], v147 offset:7168
	global_load_lds_dwordx4 v[140:141], off
	s_mov_b32 m0, s57
	s_nop 0
	global_load_lds_dwordx4 v[142:143], off
	s_waitcnt lgkmcnt(8)
	s_barrier
	s_waitcnt lgkmcnt(0)
	s_waitcnt lgkmcnt(0)
	v_mfma_f32_16x16x32_bf16 v[124:127], v[148:151], v[164:167], v[124:127]
	v_mfma_f32_16x16x32_bf16 v[120:123], v[156:159], v[164:167], v[120:123]
	v_mfma_f32_16x16x32_bf16 v[116:119], v[148:151], v[172:175], v[116:119]
	v_mfma_f32_16x16x32_bf16 v[112:115], v[156:159], v[172:175], v[112:115]
	v_mfma_f32_16x16x32_bf16 v[100:103], v[148:151], v[180:183], v[100:103]
	v_mfma_f32_16x16x32_bf16 v[96:99], v[156:159], v[180:183], v[96:99]
	v_mfma_f32_16x16x32_bf16 v[84:87], v[148:151], v[188:191], v[84:87]
	v_mfma_f32_16x16x32_bf16 v[80:83], v[156:159], v[188:191], v[80:83]
	v_mfma_f32_16x16x32_bf16 v[124:127], v[152:155], v[168:171], v[124:127]
	v_mfma_f32_16x16x32_bf16 v[120:123], v[160:163], v[168:171], v[120:123]
	v_mfma_f32_16x16x32_bf16 v[116:119], v[152:155], v[176:179], v[116:119]
	v_mfma_f32_16x16x32_bf16 v[112:115], v[160:163], v[176:179], v[112:115]
	v_mfma_f32_16x16x32_bf16 v[100:103], v[152:155], v[184:187], v[100:103]
	v_mfma_f32_16x16x32_bf16 v[96:99], v[160:163], v[184:187], v[96:99]
	v_mfma_f32_16x16x32_bf16 v[84:87], v[152:155], v[192:195], v[84:87]
	v_mfma_f32_16x16x32_bf16 v[80:83], v[160:163], v[192:195], v[80:83]
	s_barrier
	s_cselect_b32 s2, 0, s9
	s_ashr_i32 s53, s52, 31
	s_lshl_b64 s[38:39], s[52:53], 13
	s_add_u32 s72, s18, s38
	s_addc_u32 s73, s19, s39
	s_lshl_b64 s[38:39], s[2:3], 7
	s_add_u32 s66, s72, s38
	s_addc_u32 s67, s73, s39
	s_mov_b32 m0, s11
	v_lshl_add_u64 v[212:213], s[66:67], 0, v[132:133]
	ds_read_b128 v[196:199], v146 offset:16384
	ds_read_b128 v[200:203], v146 offset:17408
	ds_read_b128 v[204:207], v146 offset:18432
	ds_read_b128 v[208:211], v146 offset:19456
	global_load_lds_dwordx4 v[212:213], off
	v_lshl_add_u64 v[212:213], s[66:67], 0, v[128:129]
	s_mov_b32 m0, s21
	s_nop 0
	global_load_lds_dwordx4 v[212:213], off
	s_barrier
	s_waitcnt lgkmcnt(0)
	s_waitcnt lgkmcnt(0)
	v_mfma_f32_16x16x32_bf16 v[108:111], v[196:199], v[164:167], v[108:111]
	v_mfma_f32_16x16x32_bf16 v[104:107], v[204:207], v[164:167], v[104:107]
	v_mfma_f32_16x16x32_bf16 v[92:95], v[196:199], v[172:175], v[92:95]
	v_mfma_f32_16x16x32_bf16 v[88:91], v[204:207], v[172:175], v[88:91]
	v_mfma_f32_16x16x32_bf16 v[76:79], v[196:199], v[180:183], v[76:79]
	v_mfma_f32_16x16x32_bf16 v[72:75], v[204:207], v[180:183], v[72:75]
	v_mfma_f32_16x16x32_bf16 v[68:71], v[196:199], v[188:191], v[68:71]
	v_mfma_f32_16x16x32_bf16 v[64:67], v[204:207], v[188:191], v[64:67]
	v_mfma_f32_16x16x32_bf16 v[108:111], v[200:203], v[168:171], v[108:111]
	v_mfma_f32_16x16x32_bf16 v[104:107], v[208:211], v[168:171], v[104:107]
	v_mfma_f32_16x16x32_bf16 v[92:95], v[200:203], v[176:179], v[92:95]
	v_mfma_f32_16x16x32_bf16 v[88:91], v[208:211], v[176:179], v[88:91]
	v_mfma_f32_16x16x32_bf16 v[76:79], v[200:203], v[184:187], v[76:79]
	v_mfma_f32_16x16x32_bf16 v[72:75], v[208:211], v[184:187], v[72:75]
	v_mfma_f32_16x16x32_bf16 v[68:71], v[200:203], v[192:195], v[68:71]
	v_mfma_f32_16x16x32_bf16 v[64:67], v[208:211], v[192:195], v[64:67]
	s_ashr_i32 s37, s36, 31
	s_lshl_b64 s[66:67], s[36:37], 13
	s_add_u32 s74, s16, s66
	s_addc_u32 s75, s17, s67
	s_add_u32 s66, s74, s38
	s_addc_u32 s67, s75, s39
	s_mov_b32 m0, s20
	v_lshl_add_u64 v[212:213], s[66:67], 0, v[134:135]
	s_barrier
	ds_read_b128 v[164:167], v147 offset:16384
	ds_read_b128 v[168:171], v147 offset:17408
	ds_read_b128 v[172:175], v147 offset:18432
	ds_read_b128 v[176:179], v147 offset:19456
	ds_read_b128 v[180:183], v147 offset:20480
	ds_read_b128 v[184:187], v147 offset:21504
	ds_read_b128 v[188:191], v147 offset:22528
	ds_read_b128 v[192:195], v147 offset:23552
	global_load_lds_dwordx4 v[212:213], off
	v_lshl_add_u64 v[212:213], s[66:67], 0, v[130:131]
	s_mov_b32 m0, s22
	s_nop 0
	global_load_lds_dwordx4 v[212:213], off
	s_barrier
	s_waitcnt lgkmcnt(0)
	s_waitcnt lgkmcnt(0)
	v_mfma_f32_16x16x32_bf16 v[60:63], v[148:151], v[164:167], v[60:63]
	v_mfma_f32_16x16x32_bf16 v[56:59], v[156:159], v[164:167], v[56:59]
	v_mfma_f32_16x16x32_bf16 v[52:55], v[148:151], v[172:175], v[52:55]
	v_mfma_f32_16x16x32_bf16 v[48:51], v[156:159], v[172:175], v[48:51]
	v_mfma_f32_16x16x32_bf16 v[36:39], v[148:151], v[180:183], v[36:39]
	v_mfma_f32_16x16x32_bf16 v[32:35], v[156:159], v[180:183], v[32:35]
	v_mfma_f32_16x16x32_bf16 v[20:23], v[148:151], v[188:191], v[20:23]
	v_mfma_f32_16x16x32_bf16 v[16:19], v[156:159], v[188:191], v[16:19]
	v_mfma_f32_16x16x32_bf16 v[60:63], v[152:155], v[168:171], v[60:63]
	v_mfma_f32_16x16x32_bf16 v[56:59], v[160:163], v[168:171], v[56:59]
	v_mfma_f32_16x16x32_bf16 v[52:55], v[152:155], v[176:179], v[52:55]
	v_mfma_f32_16x16x32_bf16 v[48:51], v[160:163], v[176:179], v[48:51]
	v_mfma_f32_16x16x32_bf16 v[36:39], v[152:155], v[184:187], v[36:39]
	v_mfma_f32_16x16x32_bf16 v[32:35], v[160:163], v[184:187], v[32:35]
	v_mfma_f32_16x16x32_bf16 v[20:23], v[152:155], v[192:195], v[20:23]
	v_mfma_f32_16x16x32_bf16 v[16:19], v[160:163], v[192:195], v[16:19]
	s_barrier
	s_bitset1_b32 s52, 7
	s_ashr_i32 s53, s52, 31
	s_lshl_b64 s[52:53], s[52:53], 13
	s_add_u32 s66, s18, s52
	s_addc_u32 s67, s19, s53
	s_add_u32 s52, s66, s38
	s_addc_u32 s53, s67, s39
	s_mov_b32 m0, s23
	v_lshl_add_u64 v[148:149], s[52:53], 0, v[132:133]
	global_load_lds_dwordx4 v[148:149], off
	v_lshl_add_u64 v[148:149], s[52:53], 0, v[128:129]
	s_mov_b32 m0, s24
	s_nop 0
	global_load_lds_dwordx4 v[148:149], off
	s_waitcnt vmcnt(6)
	s_barrier
	v_mfma_f32_16x16x32_bf16 v[44:47], v[196:199], v[164:167], v[44:47]
	v_mfma_f32_16x16x32_bf16 v[40:43], v[204:207], v[164:167], v[40:43]
	v_mfma_f32_16x16x32_bf16 v[28:31], v[196:199], v[172:175], v[28:31]
	v_mfma_f32_16x16x32_bf16 v[24:27], v[204:207], v[172:175], v[24:27]
	v_mfma_f32_16x16x32_bf16 v[12:15], v[196:199], v[180:183], v[12:15]
	v_mfma_f32_16x16x32_bf16 v[8:11], v[204:207], v[180:183], v[8:11]
	v_mfma_f32_16x16x32_bf16 v[4:7], v[196:199], v[188:191], v[4:7]
	v_mfma_f32_16x16x32_bf16 v[0:3], v[204:207], v[188:191], v[0:3]
	v_mfma_f32_16x16x32_bf16 v[44:47], v[200:203], v[168:171], v[44:47]
	v_mfma_f32_16x16x32_bf16 v[40:43], v[208:211], v[168:171], v[40:43]
	v_mfma_f32_16x16x32_bf16 v[28:31], v[200:203], v[176:179], v[28:31]
	v_mfma_f32_16x16x32_bf16 v[24:27], v[208:211], v[176:179], v[24:27]
	v_mfma_f32_16x16x32_bf16 v[12:15], v[200:203], v[184:187], v[12:15]
	v_mfma_f32_16x16x32_bf16 v[8:11], v[208:211], v[184:187], v[8:11]
	v_mfma_f32_16x16x32_bf16 v[4:7], v[200:203], v[192:195], v[4:7]
	v_mfma_f32_16x16x32_bf16 v[0:3], v[208:211], v[192:195], v[0:3]
	s_barrier
	ds_read_b128 v[148:151], v146 offset:32768
	ds_read_b128 v[152:155], v146 offset:33792
	ds_read_b128 v[156:159], v146 offset:34816
	ds_read_b128 v[160:163], v146 offset:35840
	s_bitset1_b32 s36, 7
	s_ashr_i32 s37, s36, 31
	s_lshl_b64 s[36:37], s[36:37], 13
	s_add_u32 s36, s16, s36
	s_addc_u32 s37, s17, s37
	s_add_u32 s36, s36, s38
	s_addc_u32 s37, s37, s39
	s_mov_b32 m0, s25
	v_lshl_add_u64 v[196:197], s[36:37], 0, v[134:135]
	ds_read_b128 v[164:167], v147 offset:32768
	ds_read_b128 v[168:171], v147 offset:33792
	ds_read_b128 v[172:175], v147 offset:34816
	ds_read_b128 v[176:179], v147 offset:35840
	ds_read_b128 v[180:183], v147 offset:36864
	ds_read_b128 v[184:187], v147 offset:37888
	ds_read_b128 v[188:191], v147 offset:38912
	ds_read_b128 v[192:195], v147 offset:39936
	global_load_lds_dwordx4 v[196:197], off
	v_lshl_add_u64 v[196:197], s[36:37], 0, v[130:131]
	s_mov_b32 m0, s26
	s_nop 0
	global_load_lds_dwordx4 v[196:197], off
	s_waitcnt lgkmcnt(8)
	s_barrier
	s_waitcnt lgkmcnt(0)
	s_waitcnt lgkmcnt(0)
	v_mfma_f32_16x16x32_bf16 v[124:127], v[148:151], v[164:167], v[124:127]
	v_mfma_f32_16x16x32_bf16 v[120:123], v[156:159], v[164:167], v[120:123]
	v_mfma_f32_16x16x32_bf16 v[116:119], v[148:151], v[172:175], v[116:119]
	v_mfma_f32_16x16x32_bf16 v[112:115], v[156:159], v[172:175], v[112:115]
	v_mfma_f32_16x16x32_bf16 v[100:103], v[148:151], v[180:183], v[100:103]
	v_mfma_f32_16x16x32_bf16 v[96:99], v[156:159], v[180:183], v[96:99]
	v_mfma_f32_16x16x32_bf16 v[84:87], v[148:151], v[188:191], v[84:87]
	v_mfma_f32_16x16x32_bf16 v[80:83], v[156:159], v[188:191], v[80:83]
	v_mfma_f32_16x16x32_bf16 v[124:127], v[152:155], v[168:171], v[124:127]
	v_mfma_f32_16x16x32_bf16 v[120:123], v[160:163], v[168:171], v[120:123]
	v_mfma_f32_16x16x32_bf16 v[116:119], v[152:155], v[176:179], v[116:119]
	v_mfma_f32_16x16x32_bf16 v[112:115], v[160:163], v[176:179], v[112:115]
	v_mfma_f32_16x16x32_bf16 v[100:103], v[152:155], v[184:187], v[100:103]
	v_mfma_f32_16x16x32_bf16 v[96:99], v[160:163], v[184:187], v[96:99]
	v_mfma_f32_16x16x32_bf16 v[84:87], v[152:155], v[192:195], v[84:87]
	v_mfma_f32_16x16x32_bf16 v[80:83], v[160:163], v[192:195], v[80:83]
	s_barrier
	s_or_b32 s2, s2, 1
	s_lshl_b64 s[36:37], s[2:3], 7
	s_add_u32 s38, s72, s36
	s_addc_u32 s39, s73, s37
	s_mov_b32 m0, s27
	v_lshl_add_u64 v[212:213], s[38:39], 0, v[132:133]
	ds_read_b128 v[196:199], v146 offset:49152
	ds_read_b128 v[200:203], v146 offset:50176
	ds_read_b128 v[204:207], v146 offset:51200
	ds_read_b128 v[208:211], v146 offset:52224
	global_load_lds_dwordx4 v[212:213], off
	v_lshl_add_u64 v[212:213], s[38:39], 0, v[128:129]
	s_mov_b32 m0, s28
	s_nop 0
	global_load_lds_dwordx4 v[212:213], off
	s_barrier
	s_waitcnt lgkmcnt(0)
	s_waitcnt lgkmcnt(0)
	v_mfma_f32_16x16x32_bf16 v[108:111], v[196:199], v[164:167], v[108:111]
	v_mfma_f32_16x16x32_bf16 v[104:107], v[204:207], v[164:167], v[104:107]
	v_mfma_f32_16x16x32_bf16 v[92:95], v[196:199], v[172:175], v[92:95]
	v_mfma_f32_16x16x32_bf16 v[88:91], v[204:207], v[172:175], v[88:91]
	v_mfma_f32_16x16x32_bf16 v[76:79], v[196:199], v[180:183], v[76:79]
	v_mfma_f32_16x16x32_bf16 v[72:75], v[204:207], v[180:183], v[72:75]
	v_mfma_f32_16x16x32_bf16 v[68:71], v[196:199], v[188:191], v[68:71]
	v_mfma_f32_16x16x32_bf16 v[64:67], v[204:207], v[188:191], v[64:67]
	v_mfma_f32_16x16x32_bf16 v[108:111], v[200:203], v[168:171], v[108:111]
	v_mfma_f32_16x16x32_bf16 v[104:107], v[208:211], v[168:171], v[104:107]
	v_mfma_f32_16x16x32_bf16 v[92:95], v[200:203], v[176:179], v[92:95]
	v_mfma_f32_16x16x32_bf16 v[88:91], v[208:211], v[176:179], v[88:91]
	v_mfma_f32_16x16x32_bf16 v[76:79], v[200:203], v[184:187], v[76:79]
	v_mfma_f32_16x16x32_bf16 v[72:75], v[208:211], v[184:187], v[72:75]
	v_mfma_f32_16x16x32_bf16 v[68:71], v[200:203], v[192:195], v[68:71]
	v_mfma_f32_16x16x32_bf16 v[64:67], v[208:211], v[192:195], v[64:67]
	s_add_u32 s38, s74, s36
	s_addc_u32 s39, s75, s37
	s_mov_b32 m0, s29
	v_lshl_add_u64 v[212:213], s[38:39], 0, v[134:135]
	s_barrier
	ds_read_b128 v[164:167], v147 offset:49152
	ds_read_b128 v[168:171], v147 offset:50176
	ds_read_b128 v[172:175], v147 offset:51200
	ds_read_b128 v[176:179], v147 offset:52224
	ds_read_b128 v[180:183], v147 offset:53248
	ds_read_b128 v[184:187], v147 offset:54272
	ds_read_b128 v[188:191], v147 offset:55296
	ds_read_b128 v[192:195], v147 offset:56320
	global_load_lds_dwordx4 v[212:213], off
	v_lshl_add_u64 v[212:213], s[38:39], 0, v[130:131]
	s_mov_b32 m0, s30
	s_nop 0
	global_load_lds_dwordx4 v[212:213], off
	s_barrier
	s_waitcnt lgkmcnt(0)
	s_waitcnt lgkmcnt(0)
	v_mfma_f32_16x16x32_bf16 v[60:63], v[148:151], v[164:167], v[60:63]
	v_mfma_f32_16x16x32_bf16 v[56:59], v[156:159], v[164:167], v[56:59]
	v_mfma_f32_16x16x32_bf16 v[52:55], v[148:151], v[172:175], v[52:55]
	v_mfma_f32_16x16x32_bf16 v[48:51], v[156:159], v[172:175], v[48:51]
	v_mfma_f32_16x16x32_bf16 v[36:39], v[148:151], v[180:183], v[36:39]
	v_mfma_f32_16x16x32_bf16 v[32:35], v[156:159], v[180:183], v[32:35]
	v_mfma_f32_16x16x32_bf16 v[20:23], v[148:151], v[188:191], v[20:23]
	v_mfma_f32_16x16x32_bf16 v[16:19], v[156:159], v[188:191], v[16:19]
	v_mfma_f32_16x16x32_bf16 v[60:63], v[152:155], v[168:171], v[60:63]
	v_mfma_f32_16x16x32_bf16 v[56:59], v[160:163], v[168:171], v[56:59]
	v_mfma_f32_16x16x32_bf16 v[52:55], v[152:155], v[176:179], v[52:55]
	v_mfma_f32_16x16x32_bf16 v[48:51], v[160:163], v[176:179], v[48:51]
	v_mfma_f32_16x16x32_bf16 v[36:39], v[152:155], v[184:187], v[36:39]
	v_mfma_f32_16x16x32_bf16 v[32:35], v[160:163], v[184:187], v[32:35]
	v_mfma_f32_16x16x32_bf16 v[20:23], v[152:155], v[192:195], v[20:23]
	v_mfma_f32_16x16x32_bf16 v[16:19], v[160:163], v[192:195], v[16:19]
	s_barrier
	s_add_u32 s36, s66, s36
	s_addc_u32 s37, s67, s37
	s_mov_b32 m0, s31
	v_lshl_add_u64 v[148:149], s[36:37], 0, v[132:133]
	global_load_lds_dwordx4 v[148:149], off
	v_lshl_add_u64 v[148:149], s[36:37], 0, v[128:129]
	s_mov_b32 m0, s33
	s_nop 0
	global_load_lds_dwordx4 v[148:149], off
	s_waitcnt vmcnt(6)
	s_barrier
	v_mfma_f32_16x16x32_bf16 v[44:47], v[196:199], v[164:167], v[44:47]
	v_mfma_f32_16x16x32_bf16 v[40:43], v[204:207], v[164:167], v[40:43]
	v_mfma_f32_16x16x32_bf16 v[28:31], v[196:199], v[172:175], v[28:31]
	v_mfma_f32_16x16x32_bf16 v[24:27], v[204:207], v[172:175], v[24:27]
	v_mfma_f32_16x16x32_bf16 v[12:15], v[196:199], v[180:183], v[12:15]
	v_mfma_f32_16x16x32_bf16 v[8:11], v[204:207], v[180:183], v[8:11]
	v_mfma_f32_16x16x32_bf16 v[4:7], v[196:199], v[188:191], v[4:7]
	v_mfma_f32_16x16x32_bf16 v[0:3], v[204:207], v[188:191], v[0:3]
	v_mfma_f32_16x16x32_bf16 v[44:47], v[200:203], v[168:171], v[44:47]
	v_mfma_f32_16x16x32_bf16 v[40:43], v[208:211], v[168:171], v[40:43]
	v_mfma_f32_16x16x32_bf16 v[28:31], v[200:203], v[176:179], v[28:31]
	v_mfma_f32_16x16x32_bf16 v[24:27], v[208:211], v[176:179], v[24:27]
	v_mfma_f32_16x16x32_bf16 v[12:15], v[200:203], v[184:187], v[12:15]
	v_mfma_f32_16x16x32_bf16 v[8:11], v[208:211], v[184:187], v[8:11]
	v_mfma_f32_16x16x32_bf16 v[4:7], v[200:203], v[192:195], v[4:7]
	v_mfma_f32_16x16x32_bf16 v[0:3], v[208:211], v[192:195], v[0:3]
	v_lshl_add_u64 v[140:141], v[140:141], 0, s[4:5]
	v_lshl_add_u64 v[142:143], v[142:143], 0, s[4:5]
	s_cmp_ge_u32 s9, s65
	s_mov_b32 s2, s9
	s_barrier
	s_cbranch_scc0 .LBB0_392
	s_andn2_b64 vcc, exec, s[6:7]
	s_cbranch_vccnz .LBB0_388
	s_bitset1_b32 s8, 7
	s_ashr_i32 s9, s8, 31
	s_lshl_b64 s[8:9], s[8:9], 13
	s_add_u32 s2, s16, s8
	s_addc_u32 s9, s17, s9
	s_add_u32 s8, s2, 0x1f80
	s_addc_u32 s9, s9, 0
	s_mov_b32 m0, s56
	v_lshl_add_u64 v[192:193], s[8:9], 0, v[134:135]
	ds_read_b128 v[140:143], v146
	ds_read_b128 v[148:151], v146 offset:1024
	ds_read_b128 v[152:155], v146 offset:2048
	ds_read_b128 v[156:159], v146 offset:3072
	ds_read_b128 v[160:163], v147
	ds_read_b128 v[164:167], v147 offset:1024
	ds_read_b128 v[168:171], v147 offset:2048
	ds_read_b128 v[172:175], v147 offset:3072
	ds_read_b128 v[176:179], v147 offset:4096
	ds_read_b128 v[180:183], v147 offset:5120
	ds_read_b128 v[184:187], v147 offset:6144
	ds_read_b128 v[188:191], v147 offset:7168
	global_load_lds_dwordx4 v[192:193], off
	v_lshl_add_u64 v[192:193], s[8:9], 0, v[130:131]
	s_mov_b32 m0, s57
	s_nop 0
	global_load_lds_dwordx4 v[192:193], off
	s_barrier
	s_waitcnt lgkmcnt(0)
	s_waitcnt lgkmcnt(0)
	v_mfma_f32_16x16x32_bf16 v[124:127], v[140:143], v[160:163], v[124:127]
	v_mfma_f32_16x16x32_bf16 v[120:123], v[152:155], v[160:163], v[120:123]
	v_mfma_f32_16x16x32_bf16 v[116:119], v[140:143], v[168:171], v[116:119]
	v_mfma_f32_16x16x32_bf16 v[112:115], v[152:155], v[168:171], v[112:115]
	v_mfma_f32_16x16x32_bf16 v[100:103], v[140:143], v[176:179], v[100:103]
	v_mfma_f32_16x16x32_bf16 v[96:99], v[152:155], v[176:179], v[96:99]
	v_mfma_f32_16x16x32_bf16 v[84:87], v[140:143], v[184:187], v[84:87]
	v_mfma_f32_16x16x32_bf16 v[80:83], v[152:155], v[184:187], v[80:83]
	v_mfma_f32_16x16x32_bf16 v[124:127], v[148:151], v[164:167], v[124:127]
	v_mfma_f32_16x16x32_bf16 v[120:123], v[156:159], v[164:167], v[120:123]
	v_mfma_f32_16x16x32_bf16 v[116:119], v[148:151], v[172:175], v[116:119]
	v_mfma_f32_16x16x32_bf16 v[112:115], v[156:159], v[172:175], v[112:115]
	v_mfma_f32_16x16x32_bf16 v[100:103], v[148:151], v[180:183], v[100:103]
	v_mfma_f32_16x16x32_bf16 v[96:99], v[156:159], v[180:183], v[96:99]
	v_mfma_f32_16x16x32_bf16 v[84:87], v[148:151], v[188:191], v[84:87]
	v_mfma_f32_16x16x32_bf16 v[80:83], v[156:159], v[188:191], v[80:83]
	s_barrier
	ds_read_b128 v[192:195], v146 offset:16384
	ds_read_b128 v[196:199], v146 offset:17408
	ds_read_b128 v[200:203], v146 offset:18432
	ds_read_b128 v[204:207], v146 offset:19456
	s_barrier
	s_waitcnt lgkmcnt(0)
	s_waitcnt lgkmcnt(0)
	v_mfma_f32_16x16x32_bf16 v[108:111], v[192:195], v[160:163], v[108:111]
	v_mfma_f32_16x16x32_bf16 v[104:107], v[200:203], v[160:163], v[104:107]
	v_mfma_f32_16x16x32_bf16 v[92:95], v[192:195], v[168:171], v[92:95]
	v_mfma_f32_16x16x32_bf16 v[88:91], v[200:203], v[168:171], v[88:91]
	v_mfma_f32_16x16x32_bf16 v[76:79], v[192:195], v[176:179], v[76:79]
	v_mfma_f32_16x16x32_bf16 v[72:75], v[200:203], v[176:179], v[72:75]
	v_mfma_f32_16x16x32_bf16 v[68:71], v[192:195], v[184:187], v[68:71]
	v_mfma_f32_16x16x32_bf16 v[64:67], v[200:203], v[184:187], v[64:67]
	v_mfma_f32_16x16x32_bf16 v[108:111], v[196:199], v[164:167], v[108:111]
	v_mfma_f32_16x16x32_bf16 v[104:107], v[204:207], v[164:167], v[104:107]
	v_mfma_f32_16x16x32_bf16 v[92:95], v[196:199], v[172:175], v[92:95]
	v_mfma_f32_16x16x32_bf16 v[88:91], v[204:207], v[172:175], v[88:91]
	v_mfma_f32_16x16x32_bf16 v[76:79], v[196:199], v[180:183], v[76:79]
	v_mfma_f32_16x16x32_bf16 v[72:75], v[204:207], v[180:183], v[72:75]
	v_mfma_f32_16x16x32_bf16 v[68:71], v[196:199], v[188:191], v[68:71]
	v_mfma_f32_16x16x32_bf16 v[64:67], v[204:207], v[188:191], v[64:67]
	s_barrier
	ds_read_b128 v[160:163], v147 offset:16384
	ds_read_b128 v[164:167], v147 offset:17408
	ds_read_b128 v[168:171], v147 offset:18432
	ds_read_b128 v[172:175], v147 offset:19456
	ds_read_b128 v[176:179], v147 offset:20480
	ds_read_b128 v[180:183], v147 offset:21504
	ds_read_b128 v[184:187], v147 offset:22528
	ds_read_b128 v[188:191], v147 offset:23552
	s_waitcnt vmcnt(4)
	s_barrier
	s_waitcnt lgkmcnt(0)
	s_waitcnt lgkmcnt(0)
	v_mfma_f32_16x16x32_bf16 v[60:63], v[140:143], v[160:163], v[60:63]
	v_mfma_f32_16x16x32_bf16 v[56:59], v[152:155], v[160:163], v[56:59]
	v_mfma_f32_16x16x32_bf16 v[52:55], v[140:143], v[168:171], v[52:55]
	v_mfma_f32_16x16x32_bf16 v[48:51], v[152:155], v[168:171], v[48:51]
	v_mfma_f32_16x16x32_bf16 v[36:39], v[140:143], v[176:179], v[36:39]
	v_mfma_f32_16x16x32_bf16 v[32:35], v[152:155], v[176:179], v[32:35]
	v_mfma_f32_16x16x32_bf16 v[20:23], v[140:143], v[184:187], v[20:23]
	v_mfma_f32_16x16x32_bf16 v[16:19], v[152:155], v[184:187], v[16:19]
	v_mfma_f32_16x16x32_bf16 v[60:63], v[148:151], v[164:167], v[60:63]
	v_mfma_f32_16x16x32_bf16 v[56:59], v[156:159], v[164:167], v[56:59]
	v_mfma_f32_16x16x32_bf16 v[52:55], v[148:151], v[172:175], v[52:55]
	v_mfma_f32_16x16x32_bf16 v[48:51], v[156:159], v[172:175], v[48:51]
	v_mfma_f32_16x16x32_bf16 v[36:39], v[148:151], v[180:183], v[36:39]
	v_mfma_f32_16x16x32_bf16 v[32:35], v[156:159], v[180:183], v[32:35]
	v_mfma_f32_16x16x32_bf16 v[20:23], v[148:151], v[188:191], v[20:23]
	v_mfma_f32_16x16x32_bf16 v[16:19], v[156:159], v[188:191], v[16:19]
	v_mfma_f32_16x16x32_bf16 v[44:47], v[192:195], v[160:163], v[44:47]
	v_mfma_f32_16x16x32_bf16 v[40:43], v[200:203], v[160:163], v[40:43]
	v_mfma_f32_16x16x32_bf16 v[28:31], v[192:195], v[168:171], v[28:31]
	v_mfma_f32_16x16x32_bf16 v[24:27], v[200:203], v[168:171], v[24:27]
	v_mfma_f32_16x16x32_bf16 v[12:15], v[192:195], v[176:179], v[12:15]
	v_mfma_f32_16x16x32_bf16 v[8:11], v[200:203], v[176:179], v[8:11]
	v_mfma_f32_16x16x32_bf16 v[4:7], v[192:195], v[184:187], v[4:7]
	v_mfma_f32_16x16x32_bf16 v[0:3], v[200:203], v[184:187], v[0:3]
	v_mfma_f32_16x16x32_bf16 v[44:47], v[196:199], v[164:167], v[44:47]
	v_mfma_f32_16x16x32_bf16 v[40:43], v[204:207], v[164:167], v[40:43]
	v_mfma_f32_16x16x32_bf16 v[28:31], v[196:199], v[172:175], v[28:31]
	v_mfma_f32_16x16x32_bf16 v[24:27], v[204:207], v[172:175], v[24:27]
	v_mfma_f32_16x16x32_bf16 v[12:15], v[196:199], v[180:183], v[12:15]
	v_mfma_f32_16x16x32_bf16 v[8:11], v[204:207], v[180:183], v[8:11]
	v_mfma_f32_16x16x32_bf16 v[4:7], v[196:199], v[188:191], v[4:7]
	v_mfma_f32_16x16x32_bf16 v[0:3], v[204:207], v[188:191], v[0:3]
	s_barrier
	ds_read_b128 v[140:143], v146 offset:32768
	ds_read_b128 v[148:151], v146 offset:33792
	ds_read_b128 v[152:155], v146 offset:34816
	ds_read_b128 v[156:159], v146 offset:35840
	ds_read_b128 v[160:163], v147 offset:32768
	ds_read_b128 v[164:167], v147 offset:33792
	ds_read_b128 v[168:171], v147 offset:34816
	ds_read_b128 v[172:175], v147 offset:35840
	ds_read_b128 v[176:179], v147 offset:36864
	ds_read_b128 v[180:183], v147 offset:37888
	ds_read_b128 v[184:187], v147 offset:38912
	ds_read_b128 v[188:191], v147 offset:39936
	s_waitcnt vmcnt(2)
	s_barrier
	s_waitcnt lgkmcnt(0)
	s_waitcnt lgkmcnt(0)
	v_mfma_f32_16x16x32_bf16 v[124:127], v[140:143], v[160:163], v[124:127]
	v_mfma_f32_16x16x32_bf16 v[120:123], v[152:155], v[160:163], v[120:123]
	v_mfma_f32_16x16x32_bf16 v[116:119], v[140:143], v[168:171], v[116:119]
	v_mfma_f32_16x16x32_bf16 v[112:115], v[152:155], v[168:171], v[112:115]
	v_mfma_f32_16x16x32_bf16 v[100:103], v[140:143], v[176:179], v[100:103]
	v_mfma_f32_16x16x32_bf16 v[96:99], v[152:155], v[176:179], v[96:99]
	v_mfma_f32_16x16x32_bf16 v[84:87], v[140:143], v[184:187], v[84:87]
	v_mfma_f32_16x16x32_bf16 v[80:83], v[152:155], v[184:187], v[80:83]
	v_mfma_f32_16x16x32_bf16 v[124:127], v[148:151], v[164:167], v[124:127]
	v_mfma_f32_16x16x32_bf16 v[120:123], v[156:159], v[164:167], v[120:123]
	v_mfma_f32_16x16x32_bf16 v[116:119], v[148:151], v[172:175], v[116:119]
	v_mfma_f32_16x16x32_bf16 v[112:115], v[156:159], v[172:175], v[112:115]
	v_mfma_f32_16x16x32_bf16 v[100:103], v[148:151], v[180:183], v[100:103]
	v_mfma_f32_16x16x32_bf16 v[96:99], v[156:159], v[180:183], v[96:99]
	v_mfma_f32_16x16x32_bf16 v[84:87], v[148:151], v[188:191], v[84:87]
	v_mfma_f32_16x16x32_bf16 v[80:83], v[156:159], v[188:191], v[80:83]
	s_barrier
	ds_read_b128 v[192:195], v146 offset:49152
	ds_read_b128 v[196:199], v146 offset:50176
	ds_read_b128 v[200:203], v146 offset:51200
	ds_read_b128 v[204:207], v146 offset:52224
	s_waitcnt vmcnt(0)
	s_barrier
	s_waitcnt lgkmcnt(0)
	s_waitcnt lgkmcnt(0)
	v_mfma_f32_16x16x32_bf16 v[108:111], v[192:195], v[160:163], v[108:111]
	v_mfma_f32_16x16x32_bf16 v[104:107], v[200:203], v[160:163], v[104:107]
	v_mfma_f32_16x16x32_bf16 v[92:95], v[192:195], v[168:171], v[92:95]
	v_mfma_f32_16x16x32_bf16 v[88:91], v[200:203], v[168:171], v[88:91]
	v_mfma_f32_16x16x32_bf16 v[76:79], v[192:195], v[176:179], v[76:79]
	v_mfma_f32_16x16x32_bf16 v[72:75], v[200:203], v[176:179], v[72:75]
	v_mfma_f32_16x16x32_bf16 v[68:71], v[192:195], v[184:187], v[68:71]
	v_mfma_f32_16x16x32_bf16 v[64:67], v[200:203], v[184:187], v[64:67]
	v_mfma_f32_16x16x32_bf16 v[108:111], v[196:199], v[164:167], v[108:111]
	v_mfma_f32_16x16x32_bf16 v[104:107], v[204:207], v[164:167], v[104:107]
	v_mfma_f32_16x16x32_bf16 v[92:95], v[196:199], v[172:175], v[92:95]
	v_mfma_f32_16x16x32_bf16 v[88:91], v[204:207], v[172:175], v[88:91]
	v_mfma_f32_16x16x32_bf16 v[76:79], v[196:199], v[180:183], v[76:79]
	v_mfma_f32_16x16x32_bf16 v[72:75], v[204:207], v[180:183], v[72:75]
	v_mfma_f32_16x16x32_bf16 v[68:71], v[196:199], v[188:191], v[68:71]
	v_mfma_f32_16x16x32_bf16 v[64:67], v[204:207], v[188:191], v[64:67]
	s_barrier
	ds_read_b128 v[160:163], v147 offset:49152
	ds_read_b128 v[164:167], v147 offset:50176
	ds_read_b128 v[168:171], v147 offset:51200
	ds_read_b128 v[172:175], v147 offset:52224
	ds_read_b128 v[176:179], v147 offset:53248
	ds_read_b128 v[180:183], v147 offset:54272
	ds_read_b128 v[184:187], v147 offset:55296
	ds_read_b128 v[188:191], v147 offset:56320
	s_barrier
	s_waitcnt lgkmcnt(0)
	s_waitcnt lgkmcnt(0)
	v_mfma_f32_16x16x32_bf16 v[60:63], v[140:143], v[160:163], v[60:63]
	v_mfma_f32_16x16x32_bf16 v[56:59], v[152:155], v[160:163], v[56:59]
	v_mfma_f32_16x16x32_bf16 v[52:55], v[140:143], v[168:171], v[52:55]
	v_mfma_f32_16x16x32_bf16 v[48:51], v[152:155], v[168:171], v[48:51]
	v_mfma_f32_16x16x32_bf16 v[36:39], v[140:143], v[176:179], v[36:39]
	v_mfma_f32_16x16x32_bf16 v[32:35], v[152:155], v[176:179], v[32:35]
	v_mfma_f32_16x16x32_bf16 v[20:23], v[140:143], v[184:187], v[20:23]
	v_mfma_f32_16x16x32_bf16 v[16:19], v[152:155], v[184:187], v[16:19]
	v_mfma_f32_16x16x32_bf16 v[60:63], v[148:151], v[164:167], v[60:63]
	v_mfma_f32_16x16x32_bf16 v[56:59], v[156:159], v[164:167], v[56:59]
	v_mfma_f32_16x16x32_bf16 v[52:55], v[148:151], v[172:175], v[52:55]
	v_mfma_f32_16x16x32_bf16 v[48:51], v[156:159], v[172:175], v[48:51]
	v_mfma_f32_16x16x32_bf16 v[36:39], v[148:151], v[180:183], v[36:39]
	v_mfma_f32_16x16x32_bf16 v[32:35], v[156:159], v[180:183], v[32:35]
	v_mfma_f32_16x16x32_bf16 v[20:23], v[148:151], v[188:191], v[20:23]
	v_mfma_f32_16x16x32_bf16 v[16:19], v[156:159], v[188:191], v[16:19]
	v_mfma_f32_16x16x32_bf16 v[44:47], v[192:195], v[160:163], v[44:47]
	v_mfma_f32_16x16x32_bf16 v[40:43], v[200:203], v[160:163], v[40:43]
	v_mfma_f32_16x16x32_bf16 v[28:31], v[192:195], v[168:171], v[28:31]
	v_mfma_f32_16x16x32_bf16 v[24:27], v[200:203], v[168:171], v[24:27]
	v_mfma_f32_16x16x32_bf16 v[12:15], v[192:195], v[176:179], v[12:15]
	v_mfma_f32_16x16x32_bf16 v[8:11], v[200:203], v[176:179], v[8:11]
	v_mfma_f32_16x16x32_bf16 v[4:7], v[192:195], v[184:187], v[4:7]
	v_mfma_f32_16x16x32_bf16 v[0:3], v[200:203], v[184:187], v[0:3]
	v_mfma_f32_16x16x32_bf16 v[44:47], v[196:199], v[164:167], v[44:47]
	v_mfma_f32_16x16x32_bf16 v[40:43], v[204:207], v[164:167], v[40:43]
	v_mfma_f32_16x16x32_bf16 v[28:31], v[196:199], v[172:175], v[28:31]
	v_mfma_f32_16x16x32_bf16 v[24:27], v[204:207], v[172:175], v[24:27]
	v_mfma_f32_16x16x32_bf16 v[12:15], v[196:199], v[180:183], v[12:15]
	v_mfma_f32_16x16x32_bf16 v[8:11], v[204:207], v[180:183], v[8:11]
	v_mfma_f32_16x16x32_bf16 v[4:7], v[196:199], v[188:191], v[4:7]
	v_mfma_f32_16x16x32_bf16 v[0:3], v[204:207], v[188:191], v[0:3]
	s_barrier
	s_branch .LBB0_388

.LBB0_461:
	ds_read_b128 v[146:149], v152
	ds_read_b128 v[154:157], v152 offset:1024
	ds_read_b128 v[158:161], v152 offset:2048
	ds_read_b128 v[162:165], v152 offset:3072
	s_add_i32 s62, s1, 2
	s_cmp_gt_u32 s1, 13
	s_cselect_b32 s40, s59, s2
	s_cselect_b32 s36, s58, s0
	s_mov_b32 m0, s53
	ds_read_b128 v[166:169], v153
	ds_read_b128 v[170:173], v153 offset:1024
	ds_read_b128 v[174:177], v153 offset:2048
	ds_read_b128 v[178:181], v153 offset:3072
	ds_read_b128 v[182:185], v153 offset:4096
	ds_read_b128 v[186:189], v153 offset:5120
	ds_read_b128 v[190:193], v153 offset:6144
	ds_read_b128 v[194:197], v153 offset:7168
	global_load_lds_dwordx4 v[142:143], off
	s_mov_b32 m0, s54
	s_nop 0
	global_load_lds_dwordx4 v[144:145], off
	s_waitcnt lgkmcnt(8)
	s_barrier
	s_waitcnt lgkmcnt(0)
	s_waitcnt lgkmcnt(0)
	v_mfma_f32_16x16x32_bf16 v[124:127], v[146:149], v[166:169], v[124:127]
	v_mfma_f32_16x16x32_bf16 v[120:123], v[158:161], v[166:169], v[120:123]
	v_mfma_f32_16x16x32_bf16 v[108:111], v[146:149], v[174:177], v[108:111]
	v_mfma_f32_16x16x32_bf16 v[104:107], v[158:161], v[174:177], v[104:107]
	v_mfma_f32_16x16x32_bf16 v[92:95], v[146:149], v[182:185], v[92:95]
	v_mfma_f32_16x16x32_bf16 v[88:91], v[158:161], v[182:185], v[88:91]
	v_mfma_f32_16x16x32_bf16 v[76:79], v[146:149], v[190:193], v[76:79]
	v_mfma_f32_16x16x32_bf16 v[72:75], v[158:161], v[190:193], v[72:75]
	v_mfma_f32_16x16x32_bf16 v[124:127], v[154:157], v[170:173], v[124:127]
	v_mfma_f32_16x16x32_bf16 v[120:123], v[162:165], v[170:173], v[120:123]
	v_mfma_f32_16x16x32_bf16 v[108:111], v[154:157], v[178:181], v[108:111]
	v_mfma_f32_16x16x32_bf16 v[104:107], v[162:165], v[178:181], v[104:107]
	v_mfma_f32_16x16x32_bf16 v[92:95], v[154:157], v[186:189], v[92:95]
	v_mfma_f32_16x16x32_bf16 v[88:91], v[162:165], v[186:189], v[88:91]
	v_mfma_f32_16x16x32_bf16 v[76:79], v[154:157], v[194:197], v[76:79]
	v_mfma_f32_16x16x32_bf16 v[72:75], v[162:165], v[194:197], v[72:75]
	s_barrier
	s_cselect_b32 s8, 0, s62
	s_ashr_i32 s41, s40, 31
	s_lshl_b64 s[38:39], s[40:41], 11
	s_add_u32 s1, s70, s38
	s_addc_u32 s63, s71, s39
	s_lshl_b64 s[38:39], s[8:9], 7
	s_add_u32 s64, s1, s38
	s_addc_u32 s65, s63, s39
	s_mov_b32 m0, s19
	v_lshl_add_u64 v[214:215], s[64:65], 0, v[132:133]
	ds_read_b128 v[198:201], v152 offset:16384
	ds_read_b128 v[202:205], v152 offset:17408
	ds_read_b128 v[206:209], v152 offset:18432
	ds_read_b128 v[210:213], v152 offset:19456
	global_load_lds_dwordx4 v[214:215], off
	v_lshl_add_u64 v[214:215], s[64:65], 0, v[128:129]
	s_mov_b32 m0, s22
	s_nop 0
	global_load_lds_dwordx4 v[214:215], off
	s_barrier
	s_waitcnt lgkmcnt(0)
	s_waitcnt lgkmcnt(0)
	v_mfma_f32_16x16x32_bf16 v[116:119], v[198:201], v[166:169], v[116:119]
	v_mfma_f32_16x16x32_bf16 v[112:115], v[206:209], v[166:169], v[112:115]
	v_mfma_f32_16x16x32_bf16 v[100:103], v[198:201], v[174:177], v[100:103]
	v_mfma_f32_16x16x32_bf16 v[96:99], v[206:209], v[174:177], v[96:99]
	v_mfma_f32_16x16x32_bf16 v[84:87], v[198:201], v[182:185], v[84:87]
	v_mfma_f32_16x16x32_bf16 v[80:83], v[206:209], v[182:185], v[80:83]
	v_mfma_f32_16x16x32_bf16 v[68:71], v[198:201], v[190:193], v[68:71]
	v_mfma_f32_16x16x32_bf16 v[64:67], v[206:209], v[190:193], v[64:67]
	v_mfma_f32_16x16x32_bf16 v[116:119], v[202:205], v[170:173], v[116:119]
	v_mfma_f32_16x16x32_bf16 v[112:115], v[210:213], v[170:173], v[112:115]
	v_mfma_f32_16x16x32_bf16 v[100:103], v[202:205], v[178:181], v[100:103]
	v_mfma_f32_16x16x32_bf16 v[96:99], v[210:213], v[178:181], v[96:99]
	v_mfma_f32_16x16x32_bf16 v[84:87], v[202:205], v[186:189], v[84:87]
	v_mfma_f32_16x16x32_bf16 v[80:83], v[210:213], v[186:189], v[80:83]
	v_mfma_f32_16x16x32_bf16 v[68:71], v[202:205], v[194:197], v[68:71]
	v_mfma_f32_16x16x32_bf16 v[64:67], v[210:213], v[194:197], v[64:67]
	s_ashr_i32 s37, s36, 31
	s_lshl_b64 s[64:65], s[36:37], 11
	s_add_u32 s66, s16, s64
	s_addc_u32 s67, s17, s65
	s_add_u32 s64, s66, s38
	s_addc_u32 s65, s67, s39
	s_mov_b32 m0, s18
	v_lshl_add_u64 v[214:215], s[64:65], 0, v[134:135]
	s_barrier
	ds_read_b128 v[166:169], v153 offset:16384
	ds_read_b128 v[170:173], v153 offset:17408
	ds_read_b128 v[174:177], v153 offset:18432
	ds_read_b128 v[178:181], v153 offset:19456
	ds_read_b128 v[182:185], v153 offset:20480
	ds_read_b128 v[186:189], v153 offset:21504
	ds_read_b128 v[190:193], v153 offset:22528
	ds_read_b128 v[194:197], v153 offset:23552
	global_load_lds_dwordx4 v[214:215], off
	v_lshl_add_u64 v[214:215], s[64:65], 0, v[130:131]
	s_mov_b32 m0, s23
	s_nop 0
	global_load_lds_dwordx4 v[214:215], off
	s_barrier
	s_waitcnt lgkmcnt(0)
	s_waitcnt lgkmcnt(0)
	v_mfma_f32_16x16x32_bf16 v[60:63], v[146:149], v[166:169], v[60:63]
	v_mfma_f32_16x16x32_bf16 v[56:59], v[158:161], v[166:169], v[56:59]
	v_mfma_f32_16x16x32_bf16 v[44:47], v[146:149], v[174:177], v[44:47]
	v_mfma_f32_16x16x32_bf16 v[40:43], v[158:161], v[174:177], v[40:43]
	v_mfma_f32_16x16x32_bf16 v[28:31], v[146:149], v[182:185], v[28:31]
	v_mfma_f32_16x16x32_bf16 v[24:27], v[158:161], v[182:185], v[24:27]
	v_mfma_f32_16x16x32_bf16 v[12:15], v[146:149], v[190:193], v[12:15]
	v_mfma_f32_16x16x32_bf16 v[8:11], v[158:161], v[190:193], v[8:11]
	v_mfma_f32_16x16x32_bf16 v[60:63], v[154:157], v[170:173], v[60:63]
	v_mfma_f32_16x16x32_bf16 v[56:59], v[162:165], v[170:173], v[56:59]
	v_mfma_f32_16x16x32_bf16 v[44:47], v[154:157], v[178:181], v[44:47]
	v_mfma_f32_16x16x32_bf16 v[40:43], v[162:165], v[178:181], v[40:43]
	v_mfma_f32_16x16x32_bf16 v[28:31], v[154:157], v[186:189], v[28:31]
	v_mfma_f32_16x16x32_bf16 v[24:27], v[162:165], v[186:189], v[24:27]
	v_mfma_f32_16x16x32_bf16 v[12:15], v[154:157], v[194:197], v[12:15]
	v_mfma_f32_16x16x32_bf16 v[8:11], v[162:165], v[194:197], v[8:11]
	s_barrier
	s_bitset1_b32 s40, 7
	s_ashr_i32 s41, s40, 31
	s_lshl_b64 s[40:41], s[40:41], 11
	s_add_u32 s64, s70, s40
	s_addc_u32 s65, s71, s41
	s_add_u32 s40, s64, s38
	s_addc_u32 s41, s65, s39
	s_mov_b32 m0, s24
	v_lshl_add_u64 v[146:147], s[40:41], 0, v[132:133]
	global_load_lds_dwordx4 v[146:147], off
	v_lshl_add_u64 v[146:147], s[40:41], 0, v[128:129]
	s_mov_b32 m0, s25
	s_nop 0
	global_load_lds_dwordx4 v[146:147], off
	s_waitcnt vmcnt(6)
	s_barrier
	v_mfma_f32_16x16x32_bf16 v[52:55], v[198:201], v[166:169], v[52:55]
	v_mfma_f32_16x16x32_bf16 v[48:51], v[206:209], v[166:169], v[48:51]
	v_mfma_f32_16x16x32_bf16 v[36:39], v[198:201], v[174:177], v[36:39]
	v_mfma_f32_16x16x32_bf16 v[32:35], v[206:209], v[174:177], v[32:35]
	v_mfma_f32_16x16x32_bf16 v[20:23], v[198:201], v[182:185], v[20:23]
	v_mfma_f32_16x16x32_bf16 v[16:19], v[206:209], v[182:185], v[16:19]
	v_mfma_f32_16x16x32_bf16 v[4:7], v[198:201], v[190:193], v[4:7]
	v_mfma_f32_16x16x32_bf16 v[0:3], v[206:209], v[190:193], v[0:3]
	v_mfma_f32_16x16x32_bf16 v[52:55], v[202:205], v[170:173], v[52:55]
	v_mfma_f32_16x16x32_bf16 v[48:51], v[210:213], v[170:173], v[48:51]
	v_mfma_f32_16x16x32_bf16 v[36:39], v[202:205], v[178:181], v[36:39]
	v_mfma_f32_16x16x32_bf16 v[32:35], v[210:213], v[178:181], v[32:35]
	v_mfma_f32_16x16x32_bf16 v[20:23], v[202:205], v[186:189], v[20:23]
	v_mfma_f32_16x16x32_bf16 v[16:19], v[210:213], v[186:189], v[16:19]
	v_mfma_f32_16x16x32_bf16 v[4:7], v[202:205], v[194:197], v[4:7]
	v_mfma_f32_16x16x32_bf16 v[0:3], v[210:213], v[194:197], v[0:3]
	s_barrier
	ds_read_b128 v[146:149], v152 offset:32768
	ds_read_b128 v[154:157], v152 offset:33792
	ds_read_b128 v[158:161], v152 offset:34816
	ds_read_b128 v[162:165], v152 offset:35840
	s_bitset1_b32 s36, 7
	s_ashr_i32 s37, s36, 31
	s_lshl_b64 s[36:37], s[36:37], 11
	s_add_u32 s36, s16, s36
	s_addc_u32 s37, s17, s37
	s_add_u32 s36, s36, s38
	s_addc_u32 s37, s37, s39
	s_mov_b32 m0, s27
	v_lshl_add_u64 v[198:199], s[36:37], 0, v[134:135]
	ds_read_b128 v[166:169], v153 offset:32768
	ds_read_b128 v[170:173], v153 offset:33792
	ds_read_b128 v[174:177], v153 offset:34816
	ds_read_b128 v[178:181], v153 offset:35840
	ds_read_b128 v[182:185], v153 offset:36864
	ds_read_b128 v[186:189], v153 offset:37888
	ds_read_b128 v[190:193], v153 offset:38912
	ds_read_b128 v[194:197], v153 offset:39936
	global_load_lds_dwordx4 v[198:199], off
	v_lshl_add_u64 v[198:199], s[36:37], 0, v[130:131]
	s_mov_b32 m0, s30
	s_nop 0
	global_load_lds_dwordx4 v[198:199], off
	s_waitcnt lgkmcnt(8)
	s_barrier
	s_waitcnt lgkmcnt(0)
	s_waitcnt lgkmcnt(0)
	v_mfma_f32_16x16x32_bf16 v[124:127], v[146:149], v[166:169], v[124:127]
	v_mfma_f32_16x16x32_bf16 v[120:123], v[158:161], v[166:169], v[120:123]
	v_mfma_f32_16x16x32_bf16 v[108:111], v[146:149], v[174:177], v[108:111]
	v_mfma_f32_16x16x32_bf16 v[104:107], v[158:161], v[174:177], v[104:107]
	v_mfma_f32_16x16x32_bf16 v[92:95], v[146:149], v[182:185], v[92:95]
	v_mfma_f32_16x16x32_bf16 v[88:91], v[158:161], v[182:185], v[88:91]
	v_mfma_f32_16x16x32_bf16 v[76:79], v[146:149], v[190:193], v[76:79]
	v_mfma_f32_16x16x32_bf16 v[72:75], v[158:161], v[190:193], v[72:75]
	v_mfma_f32_16x16x32_bf16 v[124:127], v[154:157], v[170:173], v[124:127]
	v_mfma_f32_16x16x32_bf16 v[120:123], v[162:165], v[170:173], v[120:123]
	v_mfma_f32_16x16x32_bf16 v[108:111], v[154:157], v[178:181], v[108:111]
	v_mfma_f32_16x16x32_bf16 v[104:107], v[162:165], v[178:181], v[104:107]
	v_mfma_f32_16x16x32_bf16 v[92:95], v[154:157], v[186:189], v[92:95]
	v_mfma_f32_16x16x32_bf16 v[88:91], v[162:165], v[186:189], v[88:91]
	v_mfma_f32_16x16x32_bf16 v[76:79], v[154:157], v[194:197], v[76:79]
	v_mfma_f32_16x16x32_bf16 v[72:75], v[162:165], v[194:197], v[72:75]
	s_barrier
	s_or_b32 s8, s8, 1
	s_lshl_b64 s[36:37], s[8:9], 7
	s_add_u32 s38, s1, s36
	s_addc_u32 s39, s63, s37
	s_mov_b32 m0, s31
	v_lshl_add_u64 v[214:215], s[38:39], 0, v[132:133]
	ds_read_b128 v[198:201], v152 offset:49152
	ds_read_b128 v[202:205], v152 offset:50176
	ds_read_b128 v[206:209], v152 offset:51200
	ds_read_b128 v[210:213], v152 offset:52224
	global_load_lds_dwordx4 v[214:215], off
	v_lshl_add_u64 v[214:215], s[38:39], 0, v[128:129]
	s_mov_b32 m0, s33
	s_nop 0
	global_load_lds_dwordx4 v[214:215], off
	s_barrier
	s_waitcnt lgkmcnt(0)
	s_waitcnt lgkmcnt(0)
	v_mfma_f32_16x16x32_bf16 v[116:119], v[198:201], v[166:169], v[116:119]
	v_mfma_f32_16x16x32_bf16 v[112:115], v[206:209], v[166:169], v[112:115]
	v_mfma_f32_16x16x32_bf16 v[100:103], v[198:201], v[174:177], v[100:103]
	v_mfma_f32_16x16x32_bf16 v[96:99], v[206:209], v[174:177], v[96:99]
	v_mfma_f32_16x16x32_bf16 v[84:87], v[198:201], v[182:185], v[84:87]
	v_mfma_f32_16x16x32_bf16 v[80:83], v[206:209], v[182:185], v[80:83]
	v_mfma_f32_16x16x32_bf16 v[68:71], v[198:201], v[190:193], v[68:71]
	v_mfma_f32_16x16x32_bf16 v[64:67], v[206:209], v[190:193], v[64:67]
	v_mfma_f32_16x16x32_bf16 v[116:119], v[202:205], v[170:173], v[116:119]
	v_mfma_f32_16x16x32_bf16 v[112:115], v[210:213], v[170:173], v[112:115]
	v_mfma_f32_16x16x32_bf16 v[100:103], v[202:205], v[178:181], v[100:103]
	v_mfma_f32_16x16x32_bf16 v[96:99], v[210:213], v[178:181], v[96:99]
	v_mfma_f32_16x16x32_bf16 v[84:87], v[202:205], v[186:189], v[84:87]
	v_mfma_f32_16x16x32_bf16 v[80:83], v[210:213], v[186:189], v[80:83]
	v_mfma_f32_16x16x32_bf16 v[68:71], v[202:205], v[194:197], v[68:71]
	v_mfma_f32_16x16x32_bf16 v[64:67], v[210:213], v[194:197], v[64:67]
	s_add_u32 s38, s66, s36
	s_addc_u32 s39, s67, s37
	s_mov_b32 m0, s42
	v_lshl_add_u64 v[214:215], s[38:39], 0, v[134:135]
	s_barrier
	ds_read_b128 v[166:169], v153 offset:49152
	ds_read_b128 v[170:173], v153 offset:50176
	ds_read_b128 v[174:177], v153 offset:51200
	ds_read_b128 v[178:181], v153 offset:52224
	ds_read_b128 v[182:185], v153 offset:53248
	ds_read_b128 v[186:189], v153 offset:54272
	ds_read_b128 v[190:193], v153 offset:55296
	ds_read_b128 v[194:197], v153 offset:56320
	global_load_lds_dwordx4 v[214:215], off
	v_lshl_add_u64 v[214:215], s[38:39], 0, v[130:131]
	s_mov_b32 m0, s43
	s_nop 0
	global_load_lds_dwordx4 v[214:215], off
	s_barrier
	s_waitcnt lgkmcnt(0)
	s_waitcnt lgkmcnt(0)
	v_mfma_f32_16x16x32_bf16 v[60:63], v[146:149], v[166:169], v[60:63]
	v_mfma_f32_16x16x32_bf16 v[56:59], v[158:161], v[166:169], v[56:59]
	v_mfma_f32_16x16x32_bf16 v[44:47], v[146:149], v[174:177], v[44:47]
	v_mfma_f32_16x16x32_bf16 v[40:43], v[158:161], v[174:177], v[40:43]
	v_mfma_f32_16x16x32_bf16 v[28:31], v[146:149], v[182:185], v[28:31]
	v_mfma_f32_16x16x32_bf16 v[24:27], v[158:161], v[182:185], v[24:27]
	v_mfma_f32_16x16x32_bf16 v[12:15], v[146:149], v[190:193], v[12:15]
	v_mfma_f32_16x16x32_bf16 v[8:11], v[158:161], v[190:193], v[8:11]
	v_mfma_f32_16x16x32_bf16 v[60:63], v[154:157], v[170:173], v[60:63]
	v_mfma_f32_16x16x32_bf16 v[56:59], v[162:165], v[170:173], v[56:59]
	v_mfma_f32_16x16x32_bf16 v[44:47], v[154:157], v[178:181], v[44:47]
	v_mfma_f32_16x16x32_bf16 v[40:43], v[162:165], v[178:181], v[40:43]
	v_mfma_f32_16x16x32_bf16 v[28:31], v[154:157], v[186:189], v[28:31]
	v_mfma_f32_16x16x32_bf16 v[24:27], v[162:165], v[186:189], v[24:27]
	v_mfma_f32_16x16x32_bf16 v[12:15], v[154:157], v[194:197], v[12:15]
	v_mfma_f32_16x16x32_bf16 v[8:11], v[162:165], v[194:197], v[8:11]
	s_barrier
	s_add_u32 s36, s64, s36
	s_addc_u32 s37, s65, s37
	s_mov_b32 m0, s46
	v_lshl_add_u64 v[146:147], s[36:37], 0, v[132:133]
	global_load_lds_dwordx4 v[146:147], off
	v_lshl_add_u64 v[146:147], s[36:37], 0, v[128:129]
	s_mov_b32 m0, s47
	s_nop 0
	global_load_lds_dwordx4 v[146:147], off
	s_waitcnt vmcnt(6)
	s_barrier
	v_mfma_f32_16x16x32_bf16 v[52:55], v[198:201], v[166:169], v[52:55]
	v_mfma_f32_16x16x32_bf16 v[48:51], v[206:209], v[166:169], v[48:51]
	v_mfma_f32_16x16x32_bf16 v[36:39], v[198:201], v[174:177], v[36:39]
	v_mfma_f32_16x16x32_bf16 v[32:35], v[206:209], v[174:177], v[32:35]
	v_mfma_f32_16x16x32_bf16 v[20:23], v[198:201], v[182:185], v[20:23]
	v_mfma_f32_16x16x32_bf16 v[16:19], v[206:209], v[182:185], v[16:19]
	v_mfma_f32_16x16x32_bf16 v[4:7], v[198:201], v[190:193], v[4:7]
	v_mfma_f32_16x16x32_bf16 v[0:3], v[206:209], v[190:193], v[0:3]
	v_mfma_f32_16x16x32_bf16 v[52:55], v[202:205], v[170:173], v[52:55]
	v_mfma_f32_16x16x32_bf16 v[48:51], v[210:213], v[170:173], v[48:51]
	v_mfma_f32_16x16x32_bf16 v[36:39], v[202:205], v[178:181], v[36:39]
	v_mfma_f32_16x16x32_bf16 v[32:35], v[210:213], v[178:181], v[32:35]
	v_mfma_f32_16x16x32_bf16 v[20:23], v[202:205], v[186:189], v[20:23]
	v_mfma_f32_16x16x32_bf16 v[16:19], v[210:213], v[186:189], v[16:19]
	v_mfma_f32_16x16x32_bf16 v[4:7], v[202:205], v[194:197], v[4:7]
	v_mfma_f32_16x16x32_bf16 v[0:3], v[210:213], v[194:197], v[0:3]
	v_lshl_add_u64 v[142:143], v[142:143], 0, s[10:11]
	v_lshl_add_u64 v[144:145], v[144:145], 0, s[10:11]
	s_cmp_ge_u32 s62, s3
	s_mov_b32 s1, s62
	s_barrier
	s_cbranch_scc0 .LBB0_461
	s_andn2_b64 vcc, exec, s[28:29]
	s_cbranch_vccnz .LBB0_464
	s_bitset1_b32 s0, 7
	s_ashr_i32 s1, s0, 31
	s_lshl_b64 s[0:1], s[0:1], 11
	s_add_u32 s0, s16, s0
	s_addc_u32 s1, s17, s1
	v_lshl_add_u64 v[194:195], s[0:1], 0, v[134:135]
	s_mov_b32 m0, s53
	v_lshl_add_u64 v[194:195], v[194:195], 0, s[20:21]
	ds_read_b128 v[142:145], v152
	ds_read_b128 v[146:149], v152 offset:1024
	ds_read_b128 v[154:157], v152 offset:2048
	ds_read_b128 v[158:161], v152 offset:3072
	ds_read_b128 v[162:165], v153
	ds_read_b128 v[166:169], v153 offset:1024
	ds_read_b128 v[170:173], v153 offset:2048
	ds_read_b128 v[174:177], v153 offset:3072
	ds_read_b128 v[178:181], v153 offset:4096
	ds_read_b128 v[182:185], v153 offset:5120
	ds_read_b128 v[186:189], v153 offset:6144
	ds_read_b128 v[190:193], v153 offset:7168
	global_load_lds_dwordx4 v[194:195], off
	v_lshl_add_u64 v[194:195], s[0:1], 0, v[130:131]
	v_lshl_add_u64 v[194:195], v[194:195], 0, s[20:21]
	s_mov_b32 m0, s54
	s_nop 0
	global_load_lds_dwordx4 v[194:195], off
	s_barrier
	s_waitcnt lgkmcnt(0)
	s_waitcnt lgkmcnt(0)
	v_mfma_f32_16x16x32_bf16 v[124:127], v[142:145], v[162:165], v[124:127]
	v_mfma_f32_16x16x32_bf16 v[120:123], v[154:157], v[162:165], v[120:123]
	v_mfma_f32_16x16x32_bf16 v[108:111], v[142:145], v[170:173], v[108:111]
	v_mfma_f32_16x16x32_bf16 v[104:107], v[154:157], v[170:173], v[104:107]
	v_mfma_f32_16x16x32_bf16 v[92:95], v[142:145], v[178:181], v[92:95]
	v_mfma_f32_16x16x32_bf16 v[88:91], v[154:157], v[178:181], v[88:91]
	v_mfma_f32_16x16x32_bf16 v[76:79], v[142:145], v[186:189], v[76:79]
	v_mfma_f32_16x16x32_bf16 v[72:75], v[154:157], v[186:189], v[72:75]
	v_mfma_f32_16x16x32_bf16 v[124:127], v[146:149], v[166:169], v[124:127]
	v_mfma_f32_16x16x32_bf16 v[120:123], v[158:161], v[166:169], v[120:123]
	v_mfma_f32_16x16x32_bf16 v[108:111], v[146:149], v[174:177], v[108:111]
	v_mfma_f32_16x16x32_bf16 v[104:107], v[158:161], v[174:177], v[104:107]
	v_mfma_f32_16x16x32_bf16 v[92:95], v[146:149], v[182:185], v[92:95]
	v_mfma_f32_16x16x32_bf16 v[88:91], v[158:161], v[182:185], v[88:91]
	v_mfma_f32_16x16x32_bf16 v[76:79], v[146:149], v[190:193], v[76:79]
	v_mfma_f32_16x16x32_bf16 v[72:75], v[158:161], v[190:193], v[72:75]
	s_barrier
	ds_read_b128 v[194:197], v152 offset:16384
	ds_read_b128 v[198:201], v152 offset:17408
	ds_read_b128 v[202:205], v152 offset:18432
	ds_read_b128 v[206:209], v152 offset:19456
	s_barrier
	s_waitcnt lgkmcnt(0)
	s_waitcnt lgkmcnt(0)
	v_mfma_f32_16x16x32_bf16 v[116:119], v[194:197], v[162:165], v[116:119]
	v_mfma_f32_16x16x32_bf16 v[112:115], v[202:205], v[162:165], v[112:115]
	v_mfma_f32_16x16x32_bf16 v[100:103], v[194:197], v[170:173], v[100:103]
	v_mfma_f32_16x16x32_bf16 v[96:99], v[202:205], v[170:173], v[96:99]
	v_mfma_f32_16x16x32_bf16 v[84:87], v[194:197], v[178:181], v[84:87]
	v_mfma_f32_16x16x32_bf16 v[80:83], v[202:205], v[178:181], v[80:83]
	v_mfma_f32_16x16x32_bf16 v[68:71], v[194:197], v[186:189], v[68:71]
	v_mfma_f32_16x16x32_bf16 v[64:67], v[202:205], v[186:189], v[64:67]
	v_mfma_f32_16x16x32_bf16 v[116:119], v[198:201], v[166:169], v[116:119]
	v_mfma_f32_16x16x32_bf16 v[112:115], v[206:209], v[166:169], v[112:115]
	v_mfma_f32_16x16x32_bf16 v[100:103], v[198:201], v[174:177], v[100:103]
	v_mfma_f32_16x16x32_bf16 v[96:99], v[206:209], v[174:177], v[96:99]
	v_mfma_f32_16x16x32_bf16 v[84:87], v[198:201], v[182:185], v[84:87]
	v_mfma_f32_16x16x32_bf16 v[80:83], v[206:209], v[182:185], v[80:83]
	v_mfma_f32_16x16x32_bf16 v[68:71], v[198:201], v[190:193], v[68:71]
	v_mfma_f32_16x16x32_bf16 v[64:67], v[206:209], v[190:193], v[64:67]
	s_barrier
	ds_read_b128 v[162:165], v153 offset:16384
	ds_read_b128 v[166:169], v153 offset:17408
	ds_read_b128 v[170:173], v153 offset:18432
	ds_read_b128 v[174:177], v153 offset:19456
	ds_read_b128 v[178:181], v153 offset:20480
	ds_read_b128 v[182:185], v153 offset:21504
	ds_read_b128 v[186:189], v153 offset:22528
	ds_read_b128 v[190:193], v153 offset:23552
	s_waitcnt vmcnt(4)
	s_barrier
	s_waitcnt lgkmcnt(0)
	s_waitcnt lgkmcnt(0)
	v_mfma_f32_16x16x32_bf16 v[60:63], v[142:145], v[162:165], v[60:63]
	v_mfma_f32_16x16x32_bf16 v[56:59], v[154:157], v[162:165], v[56:59]
	v_mfma_f32_16x16x32_bf16 v[44:47], v[142:145], v[170:173], v[44:47]
	v_mfma_f32_16x16x32_bf16 v[40:43], v[154:157], v[170:173], v[40:43]
	v_mfma_f32_16x16x32_bf16 v[28:31], v[142:145], v[178:181], v[28:31]
	v_mfma_f32_16x16x32_bf16 v[24:27], v[154:157], v[178:181], v[24:27]
	v_mfma_f32_16x16x32_bf16 v[12:15], v[142:145], v[186:189], v[12:15]
	v_mfma_f32_16x16x32_bf16 v[8:11], v[154:157], v[186:189], v[8:11]
	v_mfma_f32_16x16x32_bf16 v[60:63], v[146:149], v[166:169], v[60:63]
	v_mfma_f32_16x16x32_bf16 v[56:59], v[158:161], v[166:169], v[56:59]
	v_mfma_f32_16x16x32_bf16 v[44:47], v[146:149], v[174:177], v[44:47]
	v_mfma_f32_16x16x32_bf16 v[40:43], v[158:161], v[174:177], v[40:43]
	v_mfma_f32_16x16x32_bf16 v[28:31], v[146:149], v[182:185], v[28:31]
	v_mfma_f32_16x16x32_bf16 v[24:27], v[158:161], v[182:185], v[24:27]
	v_mfma_f32_16x16x32_bf16 v[12:15], v[146:149], v[190:193], v[12:15]
	v_mfma_f32_16x16x32_bf16 v[8:11], v[158:161], v[190:193], v[8:11]
	v_mfma_f32_16x16x32_bf16 v[52:55], v[194:197], v[162:165], v[52:55]
	v_mfma_f32_16x16x32_bf16 v[48:51], v[202:205], v[162:165], v[48:51]
	v_mfma_f32_16x16x32_bf16 v[36:39], v[194:197], v[170:173], v[36:39]
	v_mfma_f32_16x16x32_bf16 v[32:35], v[202:205], v[170:173], v[32:35]
	v_mfma_f32_16x16x32_bf16 v[20:23], v[194:197], v[178:181], v[20:23]
	v_mfma_f32_16x16x32_bf16 v[16:19], v[202:205], v[178:181], v[16:19]
	v_mfma_f32_16x16x32_bf16 v[4:7], v[194:197], v[186:189], v[4:7]
	v_mfma_f32_16x16x32_bf16 v[0:3], v[202:205], v[186:189], v[0:3]
	v_mfma_f32_16x16x32_bf16 v[52:55], v[198:201], v[166:169], v[52:55]
	v_mfma_f32_16x16x32_bf16 v[48:51], v[206:209], v[166:169], v[48:51]
	v_mfma_f32_16x16x32_bf16 v[36:39], v[198:201], v[174:177], v[36:39]
	v_mfma_f32_16x16x32_bf16 v[32:35], v[206:209], v[174:177], v[32:35]
	v_mfma_f32_16x16x32_bf16 v[20:23], v[198:201], v[182:185], v[20:23]
	v_mfma_f32_16x16x32_bf16 v[16:19], v[206:209], v[182:185], v[16:19]
	v_mfma_f32_16x16x32_bf16 v[4:7], v[198:201], v[190:193], v[4:7]
	v_mfma_f32_16x16x32_bf16 v[0:3], v[206:209], v[190:193], v[0:3]
	s_barrier
	ds_read_b128 v[142:145], v152 offset:32768
	ds_read_b128 v[146:149], v152 offset:33792
	ds_read_b128 v[154:157], v152 offset:34816
	ds_read_b128 v[158:161], v152 offset:35840
	ds_read_b128 v[162:165], v153 offset:32768
	ds_read_b128 v[166:169], v153 offset:33792
	ds_read_b128 v[170:173], v153 offset:34816
	ds_read_b128 v[174:177], v153 offset:35840
	ds_read_b128 v[178:181], v153 offset:36864
	ds_read_b128 v[182:185], v153 offset:37888
	ds_read_b128 v[186:189], v153 offset:38912
	ds_read_b128 v[190:193], v153 offset:39936
	s_waitcnt vmcnt(2)
	s_barrier
	s_waitcnt lgkmcnt(0)
	s_waitcnt lgkmcnt(0)
	v_mfma_f32_16x16x32_bf16 v[124:127], v[142:145], v[162:165], v[124:127]
	v_mfma_f32_16x16x32_bf16 v[120:123], v[154:157], v[162:165], v[120:123]
	v_mfma_f32_16x16x32_bf16 v[108:111], v[142:145], v[170:173], v[108:111]
	v_mfma_f32_16x16x32_bf16 v[104:107], v[154:157], v[170:173], v[104:107]
	v_mfma_f32_16x16x32_bf16 v[92:95], v[142:145], v[178:181], v[92:95]
	v_mfma_f32_16x16x32_bf16 v[88:91], v[154:157], v[178:181], v[88:91]
	v_mfma_f32_16x16x32_bf16 v[76:79], v[142:145], v[186:189], v[76:79]
	v_mfma_f32_16x16x32_bf16 v[72:75], v[154:157], v[186:189], v[72:75]
	v_mfma_f32_16x16x32_bf16 v[124:127], v[146:149], v[166:169], v[124:127]
	v_mfma_f32_16x16x32_bf16 v[120:123], v[158:161], v[166:169], v[120:123]
	v_mfma_f32_16x16x32_bf16 v[108:111], v[146:149], v[174:177], v[108:111]
	v_mfma_f32_16x16x32_bf16 v[104:107], v[158:161], v[174:177], v[104:107]
	v_mfma_f32_16x16x32_bf16 v[92:95], v[146:149], v[182:185], v[92:95]
	v_mfma_f32_16x16x32_bf16 v[88:91], v[158:161], v[182:185], v[88:91]
	v_mfma_f32_16x16x32_bf16 v[76:79], v[146:149], v[190:193], v[76:79]
	v_mfma_f32_16x16x32_bf16 v[72:75], v[158:161], v[190:193], v[72:75]
	s_barrier
	ds_read_b128 v[194:197], v152 offset:49152
	ds_read_b128 v[198:201], v152 offset:50176
	ds_read_b128 v[202:205], v152 offset:51200
	ds_read_b128 v[206:209], v152 offset:52224
	s_waitcnt vmcnt(0)
	s_barrier
	s_waitcnt lgkmcnt(0)
	s_waitcnt lgkmcnt(0)
	v_mfma_f32_16x16x32_bf16 v[116:119], v[194:197], v[162:165], v[116:119]
	v_mfma_f32_16x16x32_bf16 v[112:115], v[202:205], v[162:165], v[112:115]
	v_mfma_f32_16x16x32_bf16 v[100:103], v[194:197], v[170:173], v[100:103]
	v_mfma_f32_16x16x32_bf16 v[96:99], v[202:205], v[170:173], v[96:99]
	v_mfma_f32_16x16x32_bf16 v[84:87], v[194:197], v[178:181], v[84:87]
	v_mfma_f32_16x16x32_bf16 v[80:83], v[202:205], v[178:181], v[80:83]
	v_mfma_f32_16x16x32_bf16 v[68:71], v[194:197], v[186:189], v[68:71]
	v_mfma_f32_16x16x32_bf16 v[64:67], v[202:205], v[186:189], v[64:67]
	v_mfma_f32_16x16x32_bf16 v[116:119], v[198:201], v[166:169], v[116:119]
	v_mfma_f32_16x16x32_bf16 v[112:115], v[206:209], v[166:169], v[112:115]
	v_mfma_f32_16x16x32_bf16 v[100:103], v[198:201], v[174:177], v[100:103]
	v_mfma_f32_16x16x32_bf16 v[96:99], v[206:209], v[174:177], v[96:99]
	v_mfma_f32_16x16x32_bf16 v[84:87], v[198:201], v[182:185], v[84:87]
	v_mfma_f32_16x16x32_bf16 v[80:83], v[206:209], v[182:185], v[80:83]
	v_mfma_f32_16x16x32_bf16 v[68:71], v[198:201], v[190:193], v[68:71]
	v_mfma_f32_16x16x32_bf16 v[64:67], v[206:209], v[190:193], v[64:67]
	s_barrier
	ds_read_b128 v[162:165], v153 offset:49152
	ds_read_b128 v[166:169], v153 offset:50176
	ds_read_b128 v[170:173], v153 offset:51200
	ds_read_b128 v[174:177], v153 offset:52224
	ds_read_b128 v[178:181], v153 offset:53248
	ds_read_b128 v[182:185], v153 offset:54272
	ds_read_b128 v[186:189], v153 offset:55296
	ds_read_b128 v[190:193], v153 offset:56320
	s_barrier
	s_waitcnt lgkmcnt(0)
	s_waitcnt lgkmcnt(0)
	v_mfma_f32_16x16x32_bf16 v[60:63], v[142:145], v[162:165], v[60:63]
	v_mfma_f32_16x16x32_bf16 v[56:59], v[154:157], v[162:165], v[56:59]
	v_mfma_f32_16x16x32_bf16 v[44:47], v[142:145], v[170:173], v[44:47]
	v_mfma_f32_16x16x32_bf16 v[40:43], v[154:157], v[170:173], v[40:43]
	v_mfma_f32_16x16x32_bf16 v[28:31], v[142:145], v[178:181], v[28:31]
	v_mfma_f32_16x16x32_bf16 v[24:27], v[154:157], v[178:181], v[24:27]
	v_mfma_f32_16x16x32_bf16 v[12:15], v[142:145], v[186:189], v[12:15]
	v_mfma_f32_16x16x32_bf16 v[8:11], v[154:157], v[186:189], v[8:11]
	v_mfma_f32_16x16x32_bf16 v[60:63], v[146:149], v[166:169], v[60:63]
	v_mfma_f32_16x16x32_bf16 v[56:59], v[158:161], v[166:169], v[56:59]
	v_mfma_f32_16x16x32_bf16 v[44:47], v[146:149], v[174:177], v[44:47]
	v_mfma_f32_16x16x32_bf16 v[40:43], v[158:161], v[174:177], v[40:43]
	v_mfma_f32_16x16x32_bf16 v[28:31], v[146:149], v[182:185], v[28:31]
	v_mfma_f32_16x16x32_bf16 v[24:27], v[158:161], v[182:185], v[24:27]
	v_mfma_f32_16x16x32_bf16 v[12:15], v[146:149], v[190:193], v[12:15]
	v_mfma_f32_16x16x32_bf16 v[8:11], v[158:161], v[190:193], v[8:11]
	v_mfma_f32_16x16x32_bf16 v[52:55], v[194:197], v[162:165], v[52:55]
	v_mfma_f32_16x16x32_bf16 v[48:51], v[202:205], v[162:165], v[48:51]
	v_mfma_f32_16x16x32_bf16 v[36:39], v[194:197], v[170:173], v[36:39]
	v_mfma_f32_16x16x32_bf16 v[32:35], v[202:205], v[170:173], v[32:35]
	v_mfma_f32_16x16x32_bf16 v[20:23], v[194:197], v[178:181], v[20:23]
	v_mfma_f32_16x16x32_bf16 v[16:19], v[202:205], v[178:181], v[16:19]
	v_mfma_f32_16x16x32_bf16 v[4:7], v[194:197], v[186:189], v[4:7]
	v_mfma_f32_16x16x32_bf16 v[0:3], v[202:205], v[186:189], v[0:3]
	v_mfma_f32_16x16x32_bf16 v[52:55], v[198:201], v[166:169], v[52:55]
	v_mfma_f32_16x16x32_bf16 v[48:51], v[206:209], v[166:169], v[48:51]
	v_mfma_f32_16x16x32_bf16 v[36:39], v[198:201], v[174:177], v[36:39]
	v_mfma_f32_16x16x32_bf16 v[32:35], v[206:209], v[174:177], v[32:35]
	v_mfma_f32_16x16x32_bf16 v[20:23], v[198:201], v[182:185], v[20:23]
	v_mfma_f32_16x16x32_bf16 v[16:19], v[206:209], v[182:185], v[16:19]
	v_mfma_f32_16x16x32_bf16 v[4:7], v[198:201], v[190:193], v[4:7]
	v_mfma_f32_16x16x32_bf16 v[0:3], v[206:209], v[190:193], v[0:3]
	s_barrier

.LBB0_609:
	ds_read_b128 v[148:151], v146
	ds_read_b128 v[152:155], v146 offset:1024
	ds_read_b128 v[156:159], v146 offset:2048
	ds_read_b128 v[160:163], v146 offset:3072
	s_add_i32 s56, s21, 2
	s_cmp_eq_u32 s21, 0
	s_cselect_b32 s36, s26, s52
	s_cselect_b32 s28, s20, s51
	s_mov_b32 m0, s46
	ds_read_b128 v[164:167], v147
	ds_read_b128 v[168:171], v147 offset:1024
	ds_read_b128 v[172:175], v147 offset:2048
	ds_read_b128 v[176:179], v147 offset:3072
	ds_read_b128 v[180:183], v147 offset:4096
	ds_read_b128 v[184:187], v147 offset:5120
	ds_read_b128 v[188:191], v147 offset:6144
	ds_read_b128 v[192:195], v147 offset:7168
	global_load_lds_dwordx4 v[140:141], off
	s_mov_b32 m0, s47
	s_nop 0
	global_load_lds_dwordx4 v[142:143], off
	s_waitcnt lgkmcnt(8)
	s_barrier
	s_waitcnt lgkmcnt(0)
	s_waitcnt lgkmcnt(0)
	v_mfma_f32_16x16x32_bf16 v[124:127], v[148:151], v[164:167], v[124:127]
	v_mfma_f32_16x16x32_bf16 v[120:123], v[156:159], v[164:167], v[120:123]
	v_mfma_f32_16x16x32_bf16 v[116:119], v[148:151], v[172:175], v[116:119]
	v_mfma_f32_16x16x32_bf16 v[108:111], v[156:159], v[172:175], v[108:111]
	v_mfma_f32_16x16x32_bf16 v[100:103], v[148:151], v[180:183], v[100:103]
	v_mfma_f32_16x16x32_bf16 v[92:95], v[156:159], v[180:183], v[92:95]
	v_mfma_f32_16x16x32_bf16 v[84:87], v[148:151], v[188:191], v[84:87]
	v_mfma_f32_16x16x32_bf16 v[76:79], v[156:159], v[188:191], v[76:79]
	v_mfma_f32_16x16x32_bf16 v[124:127], v[152:155], v[168:171], v[124:127]
	v_mfma_f32_16x16x32_bf16 v[120:123], v[160:163], v[168:171], v[120:123]
	v_mfma_f32_16x16x32_bf16 v[116:119], v[152:155], v[176:179], v[116:119]
	v_mfma_f32_16x16x32_bf16 v[108:111], v[160:163], v[176:179], v[108:111]
	v_mfma_f32_16x16x32_bf16 v[100:103], v[152:155], v[184:187], v[100:103]
	v_mfma_f32_16x16x32_bf16 v[92:95], v[160:163], v[184:187], v[92:95]
	v_mfma_f32_16x16x32_bf16 v[84:87], v[152:155], v[192:195], v[84:87]
	v_mfma_f32_16x16x32_bf16 v[76:79], v[160:163], v[192:195], v[76:79]
	s_barrier
	s_cselect_b32 s21, 0x100, 0
	s_ashr_i32 s37, s36, 31
	s_lshl_b64 s[58:59], s[36:37], 9
	s_add_u32 s29, s17, s58
	s_addc_u32 s37, s18, s59
	s_add_u32 s58, s29, s21
	s_addc_u32 s59, s37, 0
	s_mov_b32 m0, s22
	v_lshl_add_u64 v[212:213], s[58:59], 0, v[132:133]
	ds_read_b128 v[196:199], v146 offset:16384
	ds_read_b128 v[200:203], v146 offset:17408
	ds_read_b128 v[204:207], v146 offset:18432
	ds_read_b128 v[208:211], v146 offset:19456
	global_load_lds_dwordx4 v[212:213], off
	v_lshl_add_u64 v[214:215], s[58:59], 0, v[128:129]
	s_mov_b32 m0, s23
	s_nop 0
	global_load_lds_dwordx4 v[214:215], off
	s_barrier
	s_waitcnt lgkmcnt(0)
	s_waitcnt lgkmcnt(0)
	v_mfma_f32_16x16x32_bf16 v[112:115], v[196:199], v[164:167], v[112:115]
	v_mfma_f32_16x16x32_bf16 v[104:107], v[204:207], v[164:167], v[104:107]
	v_mfma_f32_16x16x32_bf16 v[96:99], v[196:199], v[172:175], v[96:99]
	v_mfma_f32_16x16x32_bf16 v[88:91], v[204:207], v[172:175], v[88:91]
	v_mfma_f32_16x16x32_bf16 v[80:83], v[196:199], v[180:183], v[80:83]
	v_mfma_f32_16x16x32_bf16 v[72:75], v[204:207], v[180:183], v[72:75]
	v_mfma_f32_16x16x32_bf16 v[68:71], v[196:199], v[188:191], v[68:71]
	v_mfma_f32_16x16x32_bf16 v[64:67], v[204:207], v[188:191], v[64:67]
	v_mfma_f32_16x16x32_bf16 v[112:115], v[200:203], v[168:171], v[112:115]
	v_mfma_f32_16x16x32_bf16 v[104:107], v[208:211], v[168:171], v[104:107]
	v_mfma_f32_16x16x32_bf16 v[96:99], v[200:203], v[176:179], v[96:99]
	v_mfma_f32_16x16x32_bf16 v[88:91], v[208:211], v[176:179], v[88:91]
	v_mfma_f32_16x16x32_bf16 v[80:83], v[200:203], v[184:187], v[80:83]
	v_mfma_f32_16x16x32_bf16 v[72:75], v[208:211], v[184:187], v[72:75]
	v_mfma_f32_16x16x32_bf16 v[68:71], v[200:203], v[192:195], v[68:71]
	v_mfma_f32_16x16x32_bf16 v[64:67], v[208:211], v[192:195], v[64:67]
	s_ashr_i32 s29, s28, 31
	s_lshl_b64 s[58:59], s[28:29], 9
	s_add_u32 s29, s9, s58
	s_addc_u32 s37, s16, s59
	s_add_u32 s58, s29, s21
	s_addc_u32 s59, s37, 0
	s_mov_b32 m0, s19
	v_lshl_add_u64 v[216:217], s[58:59], 0, v[134:135]
	s_barrier
	ds_read_b128 v[164:167], v147 offset:16384
	ds_read_b128 v[168:171], v147 offset:17408
	ds_read_b128 v[172:175], v147 offset:18432
	ds_read_b128 v[176:179], v147 offset:19456
	ds_read_b128 v[180:183], v147 offset:20480
	ds_read_b128 v[184:187], v147 offset:21504
	ds_read_b128 v[188:191], v147 offset:22528
	ds_read_b128 v[192:195], v147 offset:23552
	global_load_lds_dwordx4 v[216:217], off
	v_lshl_add_u64 v[218:219], s[58:59], 0, v[130:131]
	s_mov_b32 m0, s24
	s_nop 0
	global_load_lds_dwordx4 v[218:219], off
	s_barrier
	s_waitcnt lgkmcnt(0)
	s_waitcnt lgkmcnt(0)
	v_mfma_f32_16x16x32_bf16 v[60:63], v[148:151], v[164:167], v[60:63]
	v_mfma_f32_16x16x32_bf16 v[56:59], v[156:159], v[164:167], v[56:59]
	v_mfma_f32_16x16x32_bf16 v[52:55], v[148:151], v[172:175], v[52:55]
	v_mfma_f32_16x16x32_bf16 v[44:47], v[156:159], v[172:175], v[44:47]
	v_mfma_f32_16x16x32_bf16 v[36:39], v[148:151], v[180:183], v[36:39]
	v_mfma_f32_16x16x32_bf16 v[28:31], v[156:159], v[180:183], v[28:31]
	v_mfma_f32_16x16x32_bf16 v[20:23], v[148:151], v[188:191], v[20:23]
	v_mfma_f32_16x16x32_bf16 v[12:15], v[156:159], v[188:191], v[12:15]
	v_mfma_f32_16x16x32_bf16 v[60:63], v[152:155], v[168:171], v[60:63]
	v_mfma_f32_16x16x32_bf16 v[56:59], v[160:163], v[168:171], v[56:59]
	v_mfma_f32_16x16x32_bf16 v[52:55], v[152:155], v[176:179], v[52:55]
	v_mfma_f32_16x16x32_bf16 v[44:47], v[160:163], v[176:179], v[44:47]
	v_mfma_f32_16x16x32_bf16 v[36:39], v[152:155], v[184:187], v[36:39]
	v_mfma_f32_16x16x32_bf16 v[28:31], v[160:163], v[184:187], v[28:31]
	v_mfma_f32_16x16x32_bf16 v[20:23], v[152:155], v[192:195], v[20:23]
	v_mfma_f32_16x16x32_bf16 v[12:15], v[160:163], v[192:195], v[12:15]
	s_barrier
	s_bitset1_b32 s36, 7
	s_ashr_i32 s37, s36, 31
	s_lshl_b64 s[36:37], s[36:37], 9
	s_add_u32 s29, s17, s36
	s_addc_u32 s37, s18, s37
	s_add_u32 s36, s29, s21
	s_addc_u32 s37, s37, 0
	s_mov_b32 m0, s25
	v_lshl_add_u64 v[220:221], s[36:37], 0, v[132:133]
	global_load_lds_dwordx4 v[220:221], off
	v_lshl_add_u64 v[222:223], s[36:37], 0, v[128:129]
	s_mov_b32 m0, s27
	s_nop 0
	global_load_lds_dwordx4 v[222:223], off
	s_waitcnt vmcnt(6)
	s_barrier
	v_mfma_f32_16x16x32_bf16 v[48:51], v[196:199], v[164:167], v[48:51]
	v_mfma_f32_16x16x32_bf16 v[40:43], v[204:207], v[164:167], v[40:43]
	v_mfma_f32_16x16x32_bf16 v[32:35], v[196:199], v[172:175], v[32:35]
	v_mfma_f32_16x16x32_bf16 v[24:27], v[204:207], v[172:175], v[24:27]
	v_mfma_f32_16x16x32_bf16 v[16:19], v[196:199], v[180:183], v[16:19]
	v_mfma_f32_16x16x32_bf16 v[8:11], v[204:207], v[180:183], v[8:11]
	v_mfma_f32_16x16x32_bf16 v[4:7], v[196:199], v[188:191], v[4:7]
	v_mfma_f32_16x16x32_bf16 v[0:3], v[204:207], v[188:191], v[0:3]
	v_mfma_f32_16x16x32_bf16 v[48:51], v[200:203], v[168:171], v[48:51]
	v_mfma_f32_16x16x32_bf16 v[40:43], v[208:211], v[168:171], v[40:43]
	v_mfma_f32_16x16x32_bf16 v[32:35], v[200:203], v[176:179], v[32:35]
	v_mfma_f32_16x16x32_bf16 v[24:27], v[208:211], v[176:179], v[24:27]
	v_mfma_f32_16x16x32_bf16 v[16:19], v[200:203], v[184:187], v[16:19]
	v_mfma_f32_16x16x32_bf16 v[8:11], v[208:211], v[184:187], v[8:11]
	v_mfma_f32_16x16x32_bf16 v[4:7], v[200:203], v[192:195], v[4:7]
	v_mfma_f32_16x16x32_bf16 v[0:3], v[208:211], v[192:195], v[0:3]
	s_barrier
	ds_read_b128 v[148:151], v146 offset:32768
	ds_read_b128 v[152:155], v146 offset:33792
	ds_read_b128 v[156:159], v146 offset:34816
	ds_read_b128 v[160:163], v146 offset:35840
	s_bitset1_b32 s28, 7
	s_ashr_i32 s29, s28, 31
	s_lshl_b64 s[28:29], s[28:29], 9
	s_add_u32 s28, s9, s28
	s_addc_u32 s29, s16, s29
	s_add_u32 s28, s28, s21
	s_addc_u32 s29, s29, 0
	s_mov_b32 m0, s30
	v_lshl_add_u64 v[196:197], s[28:29], 0, v[134:135]
	ds_read_b128 v[164:167], v147 offset:32768
	ds_read_b128 v[168:171], v147 offset:33792
	ds_read_b128 v[172:175], v147 offset:34816
	ds_read_b128 v[176:179], v147 offset:35840
	ds_read_b128 v[180:183], v147 offset:36864
	ds_read_b128 v[184:187], v147 offset:37888
	ds_read_b128 v[188:191], v147 offset:38912
	ds_read_b128 v[192:195], v147 offset:39936
	global_load_lds_dwordx4 v[196:197], off
	v_lshl_add_u64 v[196:197], s[28:29], 0, v[130:131]
	s_mov_b32 m0, s31
	s_nop 0
	global_load_lds_dwordx4 v[196:197], off
	s_waitcnt lgkmcnt(8)
	s_barrier
	s_waitcnt lgkmcnt(0)
	s_waitcnt lgkmcnt(0)
	v_mfma_f32_16x16x32_bf16 v[124:127], v[148:151], v[164:167], v[124:127]
	v_mfma_f32_16x16x32_bf16 v[120:123], v[156:159], v[164:167], v[120:123]
	v_mfma_f32_16x16x32_bf16 v[116:119], v[148:151], v[172:175], v[116:119]
	v_mfma_f32_16x16x32_bf16 v[108:111], v[156:159], v[172:175], v[108:111]
	v_mfma_f32_16x16x32_bf16 v[100:103], v[148:151], v[180:183], v[100:103]
	v_mfma_f32_16x16x32_bf16 v[92:95], v[156:159], v[180:183], v[92:95]
	v_mfma_f32_16x16x32_bf16 v[84:87], v[148:151], v[188:191], v[84:87]
	v_mfma_f32_16x16x32_bf16 v[76:79], v[156:159], v[188:191], v[76:79]
	v_mfma_f32_16x16x32_bf16 v[124:127], v[152:155], v[168:171], v[124:127]
	v_mfma_f32_16x16x32_bf16 v[120:123], v[160:163], v[168:171], v[120:123]
	v_mfma_f32_16x16x32_bf16 v[116:119], v[152:155], v[176:179], v[116:119]
	v_mfma_f32_16x16x32_bf16 v[108:111], v[160:163], v[176:179], v[108:111]
	v_mfma_f32_16x16x32_bf16 v[100:103], v[152:155], v[184:187], v[100:103]
	v_mfma_f32_16x16x32_bf16 v[92:95], v[160:163], v[184:187], v[92:95]
	v_mfma_f32_16x16x32_bf16 v[84:87], v[152:155], v[192:195], v[84:87]
	v_mfma_f32_16x16x32_bf16 v[76:79], v[160:163], v[192:195], v[76:79]
	s_barrier
	s_mov_b32 m0, s33
	v_lshl_add_u64 v[212:213], v[212:213], 0, s[0:1]
	ds_read_b128 v[196:199], v146 offset:49152
	ds_read_b128 v[200:203], v146 offset:50176
	ds_read_b128 v[204:207], v146 offset:51200
	ds_read_b128 v[208:211], v146 offset:52224
	global_load_lds_dwordx4 v[212:213], off
	v_lshl_add_u64 v[212:213], v[214:215], 0, s[0:1]
	s_mov_b32 m0, s38
	s_nop 0
	global_load_lds_dwordx4 v[212:213], off
	s_barrier
	s_waitcnt lgkmcnt(0)
	s_waitcnt lgkmcnt(0)
	v_mfma_f32_16x16x32_bf16 v[112:115], v[196:199], v[164:167], v[112:115]
	v_mfma_f32_16x16x32_bf16 v[104:107], v[204:207], v[164:167], v[104:107]
	v_mfma_f32_16x16x32_bf16 v[96:99], v[196:199], v[172:175], v[96:99]
	v_mfma_f32_16x16x32_bf16 v[88:91], v[204:207], v[172:175], v[88:91]
	v_mfma_f32_16x16x32_bf16 v[80:83], v[196:199], v[180:183], v[80:83]
	v_mfma_f32_16x16x32_bf16 v[72:75], v[204:207], v[180:183], v[72:75]
	v_mfma_f32_16x16x32_bf16 v[68:71], v[196:199], v[188:191], v[68:71]
	v_mfma_f32_16x16x32_bf16 v[64:67], v[204:207], v[188:191], v[64:67]
	v_mfma_f32_16x16x32_bf16 v[112:115], v[200:203], v[168:171], v[112:115]
	v_mfma_f32_16x16x32_bf16 v[104:107], v[208:211], v[168:171], v[104:107]
	v_mfma_f32_16x16x32_bf16 v[96:99], v[200:203], v[176:179], v[96:99]
	v_mfma_f32_16x16x32_bf16 v[88:91], v[208:211], v[176:179], v[88:91]
	v_mfma_f32_16x16x32_bf16 v[80:83], v[200:203], v[184:187], v[80:83]
	v_mfma_f32_16x16x32_bf16 v[72:75], v[208:211], v[184:187], v[72:75]
	v_mfma_f32_16x16x32_bf16 v[68:71], v[200:203], v[192:195], v[68:71]
	v_mfma_f32_16x16x32_bf16 v[64:67], v[208:211], v[192:195], v[64:67]
	s_mov_b32 m0, s39
	v_lshl_add_u64 v[212:213], v[216:217], 0, s[0:1]
	s_barrier
	ds_read_b128 v[164:167], v147 offset:49152
	ds_read_b128 v[168:171], v147 offset:50176
	ds_read_b128 v[172:175], v147 offset:51200
	ds_read_b128 v[176:179], v147 offset:52224
	ds_read_b128 v[180:183], v147 offset:53248
	ds_read_b128 v[184:187], v147 offset:54272
	ds_read_b128 v[188:191], v147 offset:55296
	ds_read_b128 v[192:195], v147 offset:56320
	global_load_lds_dwordx4 v[212:213], off
	v_lshl_add_u64 v[212:213], v[218:219], 0, s[0:1]
	s_mov_b32 m0, s40
	s_nop 0
	global_load_lds_dwordx4 v[212:213], off
	s_barrier
	s_waitcnt lgkmcnt(0)
	s_waitcnt lgkmcnt(0)
	v_mfma_f32_16x16x32_bf16 v[60:63], v[148:151], v[164:167], v[60:63]
	v_mfma_f32_16x16x32_bf16 v[56:59], v[156:159], v[164:167], v[56:59]
	v_mfma_f32_16x16x32_bf16 v[52:55], v[148:151], v[172:175], v[52:55]
	v_mfma_f32_16x16x32_bf16 v[44:47], v[156:159], v[172:175], v[44:47]
	v_mfma_f32_16x16x32_bf16 v[36:39], v[148:151], v[180:183], v[36:39]
	v_mfma_f32_16x16x32_bf16 v[28:31], v[156:159], v[180:183], v[28:31]
	v_mfma_f32_16x16x32_bf16 v[20:23], v[148:151], v[188:191], v[20:23]
	v_mfma_f32_16x16x32_bf16 v[12:15], v[156:159], v[188:191], v[12:15]
	v_mfma_f32_16x16x32_bf16 v[60:63], v[152:155], v[168:171], v[60:63]
	v_mfma_f32_16x16x32_bf16 v[56:59], v[160:163], v[168:171], v[56:59]
	v_mfma_f32_16x16x32_bf16 v[52:55], v[152:155], v[176:179], v[52:55]
	v_mfma_f32_16x16x32_bf16 v[44:47], v[160:163], v[176:179], v[44:47]
	v_mfma_f32_16x16x32_bf16 v[36:39], v[152:155], v[184:187], v[36:39]
	v_mfma_f32_16x16x32_bf16 v[28:31], v[160:163], v[184:187], v[28:31]
	v_mfma_f32_16x16x32_bf16 v[20:23], v[152:155], v[192:195], v[20:23]
	v_mfma_f32_16x16x32_bf16 v[12:15], v[160:163], v[192:195], v[12:15]
	s_barrier
	s_mov_b32 m0, s41
	v_lshl_add_u64 v[148:149], v[220:221], 0, s[0:1]
	global_load_lds_dwordx4 v[148:149], off
	v_lshl_add_u64 v[148:149], v[222:223], 0, s[0:1]
	s_mov_b32 m0, s42
	s_nop 0
	global_load_lds_dwordx4 v[148:149], off
	s_waitcnt vmcnt(6)
	s_barrier
	v_mfma_f32_16x16x32_bf16 v[48:51], v[196:199], v[164:167], v[48:51]
	v_mfma_f32_16x16x32_bf16 v[40:43], v[204:207], v[164:167], v[40:43]
	v_mfma_f32_16x16x32_bf16 v[32:35], v[196:199], v[172:175], v[32:35]
	v_mfma_f32_16x16x32_bf16 v[24:27], v[204:207], v[172:175], v[24:27]
	v_mfma_f32_16x16x32_bf16 v[16:19], v[196:199], v[180:183], v[16:19]
	v_mfma_f32_16x16x32_bf16 v[8:11], v[204:207], v[180:183], v[8:11]
	v_mfma_f32_16x16x32_bf16 v[4:7], v[196:199], v[188:191], v[4:7]
	v_mfma_f32_16x16x32_bf16 v[0:3], v[204:207], v[188:191], v[0:3]
	v_mfma_f32_16x16x32_bf16 v[48:51], v[200:203], v[168:171], v[48:51]
	v_mfma_f32_16x16x32_bf16 v[40:43], v[208:211], v[168:171], v[40:43]
	v_mfma_f32_16x16x32_bf16 v[32:35], v[200:203], v[176:179], v[32:35]
	v_mfma_f32_16x16x32_bf16 v[24:27], v[208:211], v[176:179], v[24:27]
	v_mfma_f32_16x16x32_bf16 v[16:19], v[200:203], v[184:187], v[16:19]
	v_mfma_f32_16x16x32_bf16 v[8:11], v[208:211], v[184:187], v[8:11]
	v_mfma_f32_16x16x32_bf16 v[4:7], v[200:203], v[192:195], v[4:7]
	v_mfma_f32_16x16x32_bf16 v[0:3], v[208:211], v[192:195], v[0:3]
	v_lshl_add_u64 v[140:141], v[140:141], 0, s[4:5]
	v_lshl_add_u64 v[142:143], v[142:143], 0, s[4:5]
	s_cmp_ge_u32 s56, s55
	s_mov_b32 s21, s56
	s_barrier
	s_cbranch_scc0 .LBB0_609
	s_andn2_b64 vcc, exec, s[10:11]
	s_cbranch_vccnz .LBB0_605
	s_bitset1_b32 s20, 7
	s_ashr_i32 s21, s20, 31
	s_lshl_b64 s[20:21], s[20:21], 9
	s_add_u32 s20, s9, s20
	s_addc_u32 s21, s16, s21
	v_lshl_add_u64 v[192:193], s[20:21], 0, v[134:135]
	s_mov_b32 m0, s46
	v_lshl_add_u64 v[192:193], v[192:193], 0, s[6:7]
	ds_read_b128 v[140:143], v146
	ds_read_b128 v[148:151], v146 offset:1024
	ds_read_b128 v[152:155], v146 offset:2048
	ds_read_b128 v[156:159], v146 offset:3072
	ds_read_b128 v[160:163], v147
	ds_read_b128 v[164:167], v147 offset:1024
	ds_read_b128 v[168:171], v147 offset:2048
	ds_read_b128 v[172:175], v147 offset:3072
	ds_read_b128 v[176:179], v147 offset:4096
	ds_read_b128 v[180:183], v147 offset:5120
	ds_read_b128 v[184:187], v147 offset:6144
	ds_read_b128 v[188:191], v147 offset:7168
	global_load_lds_dwordx4 v[192:193], off
	v_lshl_add_u64 v[192:193], s[20:21], 0, v[130:131]
	v_lshl_add_u64 v[192:193], v[192:193], 0, s[6:7]
	s_mov_b32 m0, s47
	s_nop 0
	global_load_lds_dwordx4 v[192:193], off
	s_barrier
	s_waitcnt lgkmcnt(0)
	s_waitcnt lgkmcnt(0)
	v_mfma_f32_16x16x32_bf16 v[124:127], v[140:143], v[160:163], v[124:127]
	v_mfma_f32_16x16x32_bf16 v[120:123], v[152:155], v[160:163], v[120:123]
	v_mfma_f32_16x16x32_bf16 v[116:119], v[140:143], v[168:171], v[116:119]
	v_mfma_f32_16x16x32_bf16 v[108:111], v[152:155], v[168:171], v[108:111]
	v_mfma_f32_16x16x32_bf16 v[100:103], v[140:143], v[176:179], v[100:103]
	v_mfma_f32_16x16x32_bf16 v[92:95], v[152:155], v[176:179], v[92:95]
	v_mfma_f32_16x16x32_bf16 v[84:87], v[140:143], v[184:187], v[84:87]
	v_mfma_f32_16x16x32_bf16 v[76:79], v[152:155], v[184:187], v[76:79]
	v_mfma_f32_16x16x32_bf16 v[124:127], v[148:151], v[164:167], v[124:127]
	v_mfma_f32_16x16x32_bf16 v[120:123], v[156:159], v[164:167], v[120:123]
	v_mfma_f32_16x16x32_bf16 v[116:119], v[148:151], v[172:175], v[116:119]
	v_mfma_f32_16x16x32_bf16 v[108:111], v[156:159], v[172:175], v[108:111]
	v_mfma_f32_16x16x32_bf16 v[100:103], v[148:151], v[180:183], v[100:103]
	v_mfma_f32_16x16x32_bf16 v[92:95], v[156:159], v[180:183], v[92:95]
	v_mfma_f32_16x16x32_bf16 v[84:87], v[148:151], v[188:191], v[84:87]
	v_mfma_f32_16x16x32_bf16 v[76:79], v[156:159], v[188:191], v[76:79]
	s_barrier
	ds_read_b128 v[192:195], v146 offset:16384
	ds_read_b128 v[196:199], v146 offset:17408
	ds_read_b128 v[200:203], v146 offset:18432
	ds_read_b128 v[204:207], v146 offset:19456
	s_barrier
	s_waitcnt lgkmcnt(0)
	s_waitcnt lgkmcnt(0)
	v_mfma_f32_16x16x32_bf16 v[112:115], v[192:195], v[160:163], v[112:115]
	v_mfma_f32_16x16x32_bf16 v[104:107], v[200:203], v[160:163], v[104:107]
	v_mfma_f32_16x16x32_bf16 v[96:99], v[192:195], v[168:171], v[96:99]
	v_mfma_f32_16x16x32_bf16 v[88:91], v[200:203], v[168:171], v[88:91]
	v_mfma_f32_16x16x32_bf16 v[80:83], v[192:195], v[176:179], v[80:83]
	v_mfma_f32_16x16x32_bf16 v[72:75], v[200:203], v[176:179], v[72:75]
	v_mfma_f32_16x16x32_bf16 v[68:71], v[192:195], v[184:187], v[68:71]
	v_mfma_f32_16x16x32_bf16 v[64:67], v[200:203], v[184:187], v[64:67]
	v_mfma_f32_16x16x32_bf16 v[112:115], v[196:199], v[164:167], v[112:115]
	v_mfma_f32_16x16x32_bf16 v[104:107], v[204:207], v[164:167], v[104:107]
	v_mfma_f32_16x16x32_bf16 v[96:99], v[196:199], v[172:175], v[96:99]
	v_mfma_f32_16x16x32_bf16 v[88:91], v[204:207], v[172:175], v[88:91]
	v_mfma_f32_16x16x32_bf16 v[80:83], v[196:199], v[180:183], v[80:83]
	v_mfma_f32_16x16x32_bf16 v[72:75], v[204:207], v[180:183], v[72:75]
	v_mfma_f32_16x16x32_bf16 v[68:71], v[196:199], v[188:191], v[68:71]
	v_mfma_f32_16x16x32_bf16 v[64:67], v[204:207], v[188:191], v[64:67]
	s_barrier
	ds_read_b128 v[160:163], v147 offset:16384
	ds_read_b128 v[164:167], v147 offset:17408
	ds_read_b128 v[168:171], v147 offset:18432
	ds_read_b128 v[172:175], v147 offset:19456
	ds_read_b128 v[176:179], v147 offset:20480
	ds_read_b128 v[180:183], v147 offset:21504
	ds_read_b128 v[184:187], v147 offset:22528
	ds_read_b128 v[188:191], v147 offset:23552
	s_waitcnt vmcnt(4)
	s_barrier
	s_waitcnt lgkmcnt(0)
	s_waitcnt lgkmcnt(0)
	v_mfma_f32_16x16x32_bf16 v[60:63], v[140:143], v[160:163], v[60:63]
	v_mfma_f32_16x16x32_bf16 v[56:59], v[152:155], v[160:163], v[56:59]
	v_mfma_f32_16x16x32_bf16 v[52:55], v[140:143], v[168:171], v[52:55]
	v_mfma_f32_16x16x32_bf16 v[44:47], v[152:155], v[168:171], v[44:47]
	v_mfma_f32_16x16x32_bf16 v[36:39], v[140:143], v[176:179], v[36:39]
	v_mfma_f32_16x16x32_bf16 v[28:31], v[152:155], v[176:179], v[28:31]
	v_mfma_f32_16x16x32_bf16 v[20:23], v[140:143], v[184:187], v[20:23]
	v_mfma_f32_16x16x32_bf16 v[12:15], v[152:155], v[184:187], v[12:15]
	v_mfma_f32_16x16x32_bf16 v[60:63], v[148:151], v[164:167], v[60:63]
	v_mfma_f32_16x16x32_bf16 v[56:59], v[156:159], v[164:167], v[56:59]
	v_mfma_f32_16x16x32_bf16 v[52:55], v[148:151], v[172:175], v[52:55]
	v_mfma_f32_16x16x32_bf16 v[44:47], v[156:159], v[172:175], v[44:47]
	v_mfma_f32_16x16x32_bf16 v[36:39], v[148:151], v[180:183], v[36:39]
	v_mfma_f32_16x16x32_bf16 v[28:31], v[156:159], v[180:183], v[28:31]
	v_mfma_f32_16x16x32_bf16 v[20:23], v[148:151], v[188:191], v[20:23]
	v_mfma_f32_16x16x32_bf16 v[12:15], v[156:159], v[188:191], v[12:15]
	v_mfma_f32_16x16x32_bf16 v[48:51], v[192:195], v[160:163], v[48:51]
	v_mfma_f32_16x16x32_bf16 v[40:43], v[200:203], v[160:163], v[40:43]
	v_mfma_f32_16x16x32_bf16 v[32:35], v[192:195], v[168:171], v[32:35]
	v_mfma_f32_16x16x32_bf16 v[24:27], v[200:203], v[168:171], v[24:27]
	v_mfma_f32_16x16x32_bf16 v[16:19], v[192:195], v[176:179], v[16:19]
	v_mfma_f32_16x16x32_bf16 v[8:11], v[200:203], v[176:179], v[8:11]
	v_mfma_f32_16x16x32_bf16 v[4:7], v[192:195], v[184:187], v[4:7]
	v_mfma_f32_16x16x32_bf16 v[0:3], v[200:203], v[184:187], v[0:3]
	v_mfma_f32_16x16x32_bf16 v[48:51], v[196:199], v[164:167], v[48:51]
	v_mfma_f32_16x16x32_bf16 v[40:43], v[204:207], v[164:167], v[40:43]
	v_mfma_f32_16x16x32_bf16 v[32:35], v[196:199], v[172:175], v[32:35]
	v_mfma_f32_16x16x32_bf16 v[24:27], v[204:207], v[172:175], v[24:27]
	v_mfma_f32_16x16x32_bf16 v[16:19], v[196:199], v[180:183], v[16:19]
	v_mfma_f32_16x16x32_bf16 v[8:11], v[204:207], v[180:183], v[8:11]
	v_mfma_f32_16x16x32_bf16 v[4:7], v[196:199], v[188:191], v[4:7]
	v_mfma_f32_16x16x32_bf16 v[0:3], v[204:207], v[188:191], v[0:3]
	s_barrier
	ds_read_b128 v[140:143], v146 offset:32768
	ds_read_b128 v[148:151], v146 offset:33792
	ds_read_b128 v[152:155], v146 offset:34816
	ds_read_b128 v[156:159], v146 offset:35840
	ds_read_b128 v[160:163], v147 offset:32768
	ds_read_b128 v[164:167], v147 offset:33792
	ds_read_b128 v[168:171], v147 offset:34816
	ds_read_b128 v[172:175], v147 offset:35840
	ds_read_b128 v[176:179], v147 offset:36864
	ds_read_b128 v[180:183], v147 offset:37888
	ds_read_b128 v[184:187], v147 offset:38912
	ds_read_b128 v[188:191], v147 offset:39936
	s_waitcnt vmcnt(2)
	s_barrier
	s_waitcnt lgkmcnt(0)
	s_waitcnt lgkmcnt(0)
	v_mfma_f32_16x16x32_bf16 v[124:127], v[140:143], v[160:163], v[124:127]
	v_mfma_f32_16x16x32_bf16 v[120:123], v[152:155], v[160:163], v[120:123]
	v_mfma_f32_16x16x32_bf16 v[116:119], v[140:143], v[168:171], v[116:119]
	v_mfma_f32_16x16x32_bf16 v[108:111], v[152:155], v[168:171], v[108:111]
	v_mfma_f32_16x16x32_bf16 v[100:103], v[140:143], v[176:179], v[100:103]
	v_mfma_f32_16x16x32_bf16 v[92:95], v[152:155], v[176:179], v[92:95]
	v_mfma_f32_16x16x32_bf16 v[84:87], v[140:143], v[184:187], v[84:87]
	v_mfma_f32_16x16x32_bf16 v[76:79], v[152:155], v[184:187], v[76:79]
	v_mfma_f32_16x16x32_bf16 v[124:127], v[148:151], v[164:167], v[124:127]
	v_mfma_f32_16x16x32_bf16 v[120:123], v[156:159], v[164:167], v[120:123]
	v_mfma_f32_16x16x32_bf16 v[116:119], v[148:151], v[172:175], v[116:119]
	v_mfma_f32_16x16x32_bf16 v[108:111], v[156:159], v[172:175], v[108:111]
	v_mfma_f32_16x16x32_bf16 v[100:103], v[148:151], v[180:183], v[100:103]
	v_mfma_f32_16x16x32_bf16 v[92:95], v[156:159], v[180:183], v[92:95]
	v_mfma_f32_16x16x32_bf16 v[84:87], v[148:151], v[188:191], v[84:87]
	v_mfma_f32_16x16x32_bf16 v[76:79], v[156:159], v[188:191], v[76:79]
	s_barrier
	ds_read_b128 v[192:195], v146 offset:49152
	ds_read_b128 v[196:199], v146 offset:50176
	ds_read_b128 v[200:203], v146 offset:51200
	ds_read_b128 v[204:207], v146 offset:52224
	s_waitcnt vmcnt(0)
	s_barrier
	s_waitcnt lgkmcnt(0)
	s_waitcnt lgkmcnt(0)
	v_mfma_f32_16x16x32_bf16 v[112:115], v[192:195], v[160:163], v[112:115]
	v_mfma_f32_16x16x32_bf16 v[104:107], v[200:203], v[160:163], v[104:107]
	v_mfma_f32_16x16x32_bf16 v[96:99], v[192:195], v[168:171], v[96:99]
	v_mfma_f32_16x16x32_bf16 v[88:91], v[200:203], v[168:171], v[88:91]
	v_mfma_f32_16x16x32_bf16 v[80:83], v[192:195], v[176:179], v[80:83]
	v_mfma_f32_16x16x32_bf16 v[72:75], v[200:203], v[176:179], v[72:75]
	v_mfma_f32_16x16x32_bf16 v[68:71], v[192:195], v[184:187], v[68:71]
	v_mfma_f32_16x16x32_bf16 v[64:67], v[200:203], v[184:187], v[64:67]
	v_mfma_f32_16x16x32_bf16 v[112:115], v[196:199], v[164:167], v[112:115]
	v_mfma_f32_16x16x32_bf16 v[104:107], v[204:207], v[164:167], v[104:107]
	v_mfma_f32_16x16x32_bf16 v[96:99], v[196:199], v[172:175], v[96:99]
	v_mfma_f32_16x16x32_bf16 v[88:91], v[204:207], v[172:175], v[88:91]
	v_mfma_f32_16x16x32_bf16 v[80:83], v[196:199], v[180:183], v[80:83]
	v_mfma_f32_16x16x32_bf16 v[72:75], v[204:207], v[180:183], v[72:75]
	v_mfma_f32_16x16x32_bf16 v[68:71], v[196:199], v[188:191], v[68:71]
	v_mfma_f32_16x16x32_bf16 v[64:67], v[204:207], v[188:191], v[64:67]
	s_barrier
	ds_read_b128 v[160:163], v147 offset:49152
	ds_read_b128 v[164:167], v147 offset:50176
	ds_read_b128 v[168:171], v147 offset:51200
	ds_read_b128 v[172:175], v147 offset:52224
	ds_read_b128 v[176:179], v147 offset:53248
	ds_read_b128 v[180:183], v147 offset:54272
	ds_read_b128 v[184:187], v147 offset:55296
	ds_read_b128 v[188:191], v147 offset:56320
	s_barrier
	s_waitcnt lgkmcnt(0)
	s_waitcnt lgkmcnt(0)
	v_mfma_f32_16x16x32_bf16 v[60:63], v[140:143], v[160:163], v[60:63]
	v_mfma_f32_16x16x32_bf16 v[56:59], v[152:155], v[160:163], v[56:59]
	v_mfma_f32_16x16x32_bf16 v[52:55], v[140:143], v[168:171], v[52:55]
	v_mfma_f32_16x16x32_bf16 v[44:47], v[152:155], v[168:171], v[44:47]
	v_mfma_f32_16x16x32_bf16 v[36:39], v[140:143], v[176:179], v[36:39]
	v_mfma_f32_16x16x32_bf16 v[28:31], v[152:155], v[176:179], v[28:31]
	v_mfma_f32_16x16x32_bf16 v[20:23], v[140:143], v[184:187], v[20:23]
	v_mfma_f32_16x16x32_bf16 v[12:15], v[152:155], v[184:187], v[12:15]
	v_mfma_f32_16x16x32_bf16 v[60:63], v[148:151], v[164:167], v[60:63]
	v_mfma_f32_16x16x32_bf16 v[56:59], v[156:159], v[164:167], v[56:59]
	v_mfma_f32_16x16x32_bf16 v[52:55], v[148:151], v[172:175], v[52:55]
	v_mfma_f32_16x16x32_bf16 v[44:47], v[156:159], v[172:175], v[44:47]
	v_mfma_f32_16x16x32_bf16 v[36:39], v[148:151], v[180:183], v[36:39]
	v_mfma_f32_16x16x32_bf16 v[28:31], v[156:159], v[180:183], v[28:31]
	v_mfma_f32_16x16x32_bf16 v[20:23], v[148:151], v[188:191], v[20:23]
	v_mfma_f32_16x16x32_bf16 v[12:15], v[156:159], v[188:191], v[12:15]
	v_mfma_f32_16x16x32_bf16 v[48:51], v[192:195], v[160:163], v[48:51]
	v_mfma_f32_16x16x32_bf16 v[40:43], v[200:203], v[160:163], v[40:43]
	v_mfma_f32_16x16x32_bf16 v[32:35], v[192:195], v[168:171], v[32:35]
	v_mfma_f32_16x16x32_bf16 v[24:27], v[200:203], v[168:171], v[24:27]
	v_mfma_f32_16x16x32_bf16 v[16:19], v[192:195], v[176:179], v[16:19]
	v_mfma_f32_16x16x32_bf16 v[8:11], v[200:203], v[176:179], v[8:11]
	v_mfma_f32_16x16x32_bf16 v[4:7], v[192:195], v[184:187], v[4:7]
	v_mfma_f32_16x16x32_bf16 v[0:3], v[200:203], v[184:187], v[0:3]
	v_mfma_f32_16x16x32_bf16 v[48:51], v[196:199], v[164:167], v[48:51]
	v_mfma_f32_16x16x32_bf16 v[40:43], v[204:207], v[164:167], v[40:43]
	v_mfma_f32_16x16x32_bf16 v[32:35], v[196:199], v[172:175], v[32:35]
	v_mfma_f32_16x16x32_bf16 v[24:27], v[204:207], v[172:175], v[24:27]
	v_mfma_f32_16x16x32_bf16 v[16:19], v[196:199], v[180:183], v[16:19]
	v_mfma_f32_16x16x32_bf16 v[8:11], v[204:207], v[180:183], v[8:11]
	v_mfma_f32_16x16x32_bf16 v[4:7], v[196:199], v[188:191], v[4:7]
	v_mfma_f32_16x16x32_bf16 v[0:3], v[204:207], v[188:191], v[0:3]
	s_barrier
	s_branch .LBB0_605

.LBB0_620:
	s_or_b64 exec, exec, s[8:9]
	s_ashr_i32 s8, s42, 31
	s_lshr_b32 s8, s8, 29
	s_add_i32 s8, s42, s8
	s_ashr_i32 s9, s8, 3
	s_and_b32 s8, s8, -8
	s_sub_i32 s8, s42, s8
	s_cmp_lt_i32 s8, 0
	s_cselect_b32 s10, s23, 0x60
	s_mul_i32 s8, s10, s8
	s_add_i32 s8, s8, s9
	s_ashr_i32 s9, s8, 31
	s_lshr_b32 s9, s9, 27
	s_add_i32 s9, s8, s9
	s_and_b32 s10, s9, 0xffe0
	s_sub_i32 s8, s8, s10
	s_bfe_i32 s10, s8, 0x80000
	s_bfe_u32 s10, s10, 0x3000c
	s_add_i32 s10, s8, s10
	s_bfe_i32 s11, s10, 0x80000
	s_and_b32 s10, s10, 0xf8
	s_sub_i32 s8, s8, s10
	s_sext_i32_i8 s8, s8
	s_lshl_b32 s9, s9, 6
	s_sext_i32_i16 s11, s11
	s_and_b32 s9, s9, 0xfffff800
	s_lshl_b32 s8, s8, 8
	s_add_i32 s20, s8, s9
	s_lshl_b32 s8, s11, 5
	s_and_b32 s10, s8, 0xffffff00
	s_ashr_i32 s11, s10, 31
	s_lshl_b64 s[8:9], s[10:11], 8
	s_add_u32 s8, s18, s8
	s_addc_u32 s9, s19, s9
	v_lshl_add_u64 v[0:1], s[8:9], 0, v[132:133]
	s_mov_b32 m0, s31
	v_lshl_add_u64 v[0:1], v[0:1], 0, s[6:7]
	s_ashr_i32 s21, s20, 31
	s_waitcnt vmcnt(4)
	s_barrier
	global_load_lds_dwordx4 v[0:1], off
	v_lshl_add_u64 v[0:1], s[8:9], 0, v[128:129]
	s_lshl_b64 s[8:9], s[20:21], 8
	s_add_u32 s8, s16, s8
	v_lshl_add_u64 v[0:1], v[0:1], 0, s[6:7]
	s_mov_b32 m0, s33
	s_addc_u32 s9, s17, s9
	global_load_lds_dwordx4 v[0:1], off
	v_lshl_add_u64 v[0:1], s[8:9], 0, v[134:135]
	v_lshl_add_u64 v[0:1], v[0:1], 0, s[6:7]
	s_mov_b32 m0, s38
	s_nop 0
	global_load_lds_dwordx4 v[0:1], off
	v_lshl_add_u64 v[0:1], s[8:9], 0, v[130:131]
	s_or_b32 s8, s10, 0x80
	s_ashr_i32 s9, s8, 31
	s_lshl_b64 s[8:9], s[8:9], 8
	s_add_u32 s8, s18, s8
	v_lshl_add_u64 v[0:1], v[0:1], 0, s[6:7]
	s_mov_b32 m0, s39
	s_addc_u32 s9, s19, s9
	global_load_lds_dwordx4 v[0:1], off
	v_lshl_add_u64 v[0:1], s[8:9], 0, v[132:133]
	v_lshl_add_u64 v[0:1], v[0:1], 0, s[6:7]
	s_mov_b32 m0, s36
	s_nop 0
	global_load_lds_dwordx4 v[0:1], off
	v_lshl_add_u64 v[0:1], s[8:9], 0, v[128:129]
	s_or_b32 s8, s20, 0x80
	s_ashr_i32 s9, s8, 31
	s_lshl_b64 s[8:9], s[8:9], 8
	s_add_u32 s8, s16, s8
	s_addc_u32 s9, s17, s9
	v_lshl_add_u64 v[0:1], v[0:1], 0, s[6:7]
	s_mov_b32 m0, s37
	v_lshl_add_u64 v[48:49], s[8:9], 0, v[134:135]
	global_load_lds_dwordx4 v[0:1], off
	v_lshl_add_u64 v[48:49], v[48:49], 0, s[6:7]
	s_mov_b32 m0, s40
	s_waitcnt vmcnt(6)
	s_barrier
	ds_read_b128 v[0:3], v141
	ds_read_b128 v[4:7], v141 offset:1024
	ds_read_b128 v[8:11], v141 offset:2048
	ds_read_b128 v[12:15], v141 offset:3072
	ds_read_b128 v[16:19], v142
	ds_read_b128 v[20:23], v142 offset:1024
	ds_read_b128 v[24:27], v142 offset:2048
	ds_read_b128 v[28:31], v142 offset:3072
	ds_read_b128 v[32:35], v142 offset:4096
	ds_read_b128 v[36:39], v142 offset:5120
	ds_read_b128 v[40:43], v142 offset:6144
	ds_read_b128 v[44:47], v142 offset:7168
	global_load_lds_dwordx4 v[48:49], off
	v_lshl_add_u64 v[48:49], s[8:9], 0, v[130:131]
	v_lshl_add_u64 v[48:49], v[48:49], 0, s[6:7]
	s_mov_b32 m0, s41
	s_nop 0
	global_load_lds_dwordx4 v[48:49], off
	s_barrier
	s_waitcnt lgkmcnt(0)
	s_waitcnt lgkmcnt(0)
	v_mfma_f32_16x16x32_bf16 v[48:51], v[0:3], v[16:19], 0
	v_mfma_f32_16x16x32_bf16 v[52:55], v[8:11], v[16:19], 0
	v_mfma_f32_16x16x32_bf16 v[56:59], v[0:3], v[24:27], 0
	v_mfma_f32_16x16x32_bf16 v[60:63], v[8:11], v[24:27], 0
	v_mfma_f32_16x16x32_bf16 v[64:67], v[0:3], v[32:35], 0
	v_mfma_f32_16x16x32_bf16 v[68:71], v[8:11], v[32:35], 0
	v_mfma_f32_16x16x32_bf16 v[72:75], v[0:3], v[40:43], 0
	v_mfma_f32_16x16x32_bf16 v[76:79], v[8:11], v[40:43], 0
	v_mfma_f32_16x16x32_bf16 v[48:51], v[4:7], v[20:23], v[48:51]
	v_mfma_f32_16x16x32_bf16 v[52:55], v[12:15], v[20:23], v[52:55]
	v_mfma_f32_16x16x32_bf16 v[56:59], v[4:7], v[28:31], v[56:59]
	v_mfma_f32_16x16x32_bf16 v[60:63], v[12:15], v[28:31], v[60:63]
	v_mfma_f32_16x16x32_bf16 v[64:67], v[4:7], v[36:39], v[64:67]
	v_mfma_f32_16x16x32_bf16 v[68:71], v[12:15], v[36:39], v[68:71]
	v_mfma_f32_16x16x32_bf16 v[72:75], v[4:7], v[44:47], v[72:75]
	v_mfma_f32_16x16x32_bf16 v[76:79], v[12:15], v[44:47], v[76:79]
	s_barrier
	ds_read_b128 v[80:83], v141 offset:16384
	ds_read_b128 v[84:87], v141 offset:17408
	ds_read_b128 v[88:91], v141 offset:18432
	ds_read_b128 v[92:95], v141 offset:19456
	s_barrier
	s_waitcnt lgkmcnt(0)
	s_waitcnt lgkmcnt(0)
	v_mfma_f32_16x16x32_bf16 v[96:99], v[80:83], v[16:19], 0
	v_mfma_f32_16x16x32_bf16 v[16:19], v[88:91], v[16:19], 0
	v_mfma_f32_16x16x32_bf16 v[104:107], v[84:87], v[20:23], v[96:99]
	v_mfma_f32_16x16x32_bf16 v[16:19], v[92:95], v[20:23], v[16:19]
	v_mfma_f32_16x16x32_bf16 v[20:23], v[80:83], v[24:27], 0
	v_mfma_f32_16x16x32_bf16 v[24:27], v[88:91], v[24:27], 0
	v_mfma_f32_16x16x32_bf16 v[20:23], v[84:87], v[28:31], v[20:23]
	v_mfma_f32_16x16x32_bf16 v[24:27], v[92:95], v[28:31], v[24:27]
	v_mfma_f32_16x16x32_bf16 v[28:31], v[80:83], v[32:35], 0
	v_mfma_f32_16x16x32_bf16 v[32:35], v[88:91], v[32:35], 0
	v_mfma_f32_16x16x32_bf16 v[28:31], v[84:87], v[36:39], v[28:31]
	v_mfma_f32_16x16x32_bf16 v[32:35], v[92:95], v[36:39], v[32:35]
	v_mfma_f32_16x16x32_bf16 v[36:39], v[80:83], v[40:43], 0
	v_mfma_f32_16x16x32_bf16 v[40:43], v[88:91], v[40:43], 0
	v_mfma_f32_16x16x32_bf16 v[36:39], v[84:87], v[44:47], v[36:39]
	v_mfma_f32_16x16x32_bf16 v[40:43], v[92:95], v[44:47], v[40:43]
	s_barrier
	ds_read_b128 v[44:47], v142 offset:16384
	ds_read_b128 v[96:99], v142 offset:17408
	ds_read_b128 v[100:103], v142 offset:18432
	ds_read_b128 v[108:111], v142 offset:19456
	ds_read_b128 v[112:115], v142 offset:20480
	ds_read_b128 v[116:119], v142 offset:21504
	ds_read_b128 v[120:123], v142 offset:22528
	ds_read_b128 v[124:127], v142 offset:23552
	s_waitcnt vmcnt(4)
	s_barrier
	s_waitcnt lgkmcnt(0)
	s_waitcnt lgkmcnt(0)
	v_mfma_f32_16x16x32_bf16 v[136:139], v[0:3], v[44:47], 0
	v_mfma_f32_16x16x32_bf16 v[148:151], v[0:3], v[100:103], 0
	v_mfma_f32_16x16x32_bf16 v[156:159], v[0:3], v[112:115], 0
	v_mfma_f32_16x16x32_bf16 v[0:3], v[0:3], v[120:123], 0
	v_mfma_f32_16x16x32_bf16 v[136:139], v[4:7], v[96:99], v[136:139]
	v_mfma_f32_16x16x32_bf16 v[148:151], v[4:7], v[108:111], v[148:151]
	v_mfma_f32_16x16x32_bf16 v[156:159], v[4:7], v[116:119], v[156:159]
	v_mfma_f32_16x16x32_bf16 v[0:3], v[4:7], v[124:127], v[0:3]
	v_mfma_f32_16x16x32_bf16 v[4:7], v[8:11], v[120:123], 0
	v_mfma_f32_16x16x32_bf16 v[144:147], v[8:11], v[44:47], 0
	v_mfma_f32_16x16x32_bf16 v[152:155], v[8:11], v[100:103], 0
	v_mfma_f32_16x16x32_bf16 v[160:163], v[8:11], v[112:115], 0
	v_mfma_f32_16x16x32_bf16 v[4:7], v[12:15], v[124:127], v[4:7]
	v_mfma_f32_16x16x32_bf16 v[144:147], v[12:15], v[96:99], v[144:147]
	v_mfma_f32_16x16x32_bf16 v[152:155], v[12:15], v[108:111], v[152:155]
	v_mfma_f32_16x16x32_bf16 v[160:163], v[12:15], v[116:119], v[160:163]
	v_mfma_f32_16x16x32_bf16 v[8:11], v[80:83], v[44:47], 0
	v_mfma_f32_16x16x32_bf16 v[12:15], v[84:87], v[96:99], v[8:11]
	v_mfma_f32_16x16x32_bf16 v[8:11], v[88:91], v[44:47], 0
	v_mfma_f32_16x16x32_bf16 v[44:47], v[92:95], v[96:99], v[8:11]
	v_mfma_f32_16x16x32_bf16 v[8:11], v[80:83], v[100:103], 0
	v_mfma_f32_16x16x32_bf16 v[164:167], v[84:87], v[108:111], v[8:11]
	v_mfma_f32_16x16x32_bf16 v[8:11], v[88:91], v[100:103], 0
	v_mfma_f32_16x16x32_bf16 v[168:171], v[92:95], v[108:111], v[8:11]
	v_mfma_f32_16x16x32_bf16 v[8:11], v[80:83], v[112:115], 0
	v_mfma_f32_16x16x32_bf16 v[172:175], v[84:87], v[116:119], v[8:11]
	v_mfma_f32_16x16x32_bf16 v[8:11], v[88:91], v[112:115], 0
	v_mfma_f32_16x16x32_bf16 v[176:179], v[92:95], v[116:119], v[8:11]
	v_mfma_f32_16x16x32_bf16 v[8:11], v[80:83], v[120:123], 0
	v_mfma_f32_16x16x32_bf16 v[180:183], v[84:87], v[124:127], v[8:11]
	v_mfma_f32_16x16x32_bf16 v[8:11], v[88:91], v[120:123], 0
	v_mfma_f32_16x16x32_bf16 v[184:187], v[92:95], v[124:127], v[8:11]
	s_barrier
	s_nop 4
	ds_read_b128 v[8:11], v141 offset:32768
	ds_read_b128 v[188:191], v141 offset:33792
	ds_read_b128 v[192:195], v141 offset:34816
	ds_read_b128 v[196:199], v141 offset:35840
	ds_read_b128 v[88:91], v142 offset:32768
	ds_read_b128 v[92:95], v142 offset:33792
	ds_read_b128 v[200:203], v142 offset:34816
	ds_read_b128 v[204:207], v142 offset:35840
	ds_read_b128 v[208:211], v142 offset:36864
	ds_read_b128 v[212:215], v142 offset:37888
	ds_read_b128 v[216:219], v142 offset:38912
	ds_read_b128 v[220:223], v142 offset:39936
	s_waitcnt vmcnt(2)
	s_barrier
	s_waitcnt lgkmcnt(0)
	s_waitcnt lgkmcnt(0)
	v_mfma_f32_16x16x32_bf16 v[48:51], v[8:11], v[88:91], v[48:51]
	v_mfma_f32_16x16x32_bf16 v[116:119], v[188:191], v[92:95], v[48:51]
	v_mfma_f32_16x16x32_bf16 v[48:51], v[192:195], v[88:91], v[52:55]
	v_mfma_f32_16x16x32_bf16 v[112:115], v[196:199], v[92:95], v[48:51]
	v_mfma_f32_16x16x32_bf16 v[48:51], v[8:11], v[200:203], v[56:59]
	v_mfma_f32_16x16x32_bf16 v[100:103], v[188:191], v[204:207], v[48:51]
	v_mfma_f32_16x16x32_bf16 v[48:51], v[192:195], v[200:203], v[60:63]
	v_mfma_f32_16x16x32_bf16 v[96:99], v[196:199], v[204:207], v[48:51]
	v_mfma_f32_16x16x32_bf16 v[48:51], v[8:11], v[208:211], v[64:67]
	v_mfma_f32_16x16x32_bf16 v[84:87], v[188:191], v[212:215], v[48:51]
	v_mfma_f32_16x16x32_bf16 v[48:51], v[192:195], v[208:211], v[68:71]
	v_mfma_f32_16x16x32_bf16 v[80:83], v[196:199], v[212:215], v[48:51]
	v_mfma_f32_16x16x32_bf16 v[48:51], v[8:11], v[216:219], v[72:75]
	v_mfma_f32_16x16x32_bf16 v[60:63], v[188:191], v[220:223], v[48:51]
	v_mfma_f32_16x16x32_bf16 v[48:51], v[192:195], v[216:219], v[76:79]
	v_mfma_f32_16x16x32_bf16 v[48:51], v[196:199], v[220:223], v[48:51]
	s_barrier
	ds_read_b128 v[224:227], v141 offset:49152
	ds_read_b128 v[228:231], v141 offset:50176
	ds_read_b128 v[232:235], v141 offset:51200
	ds_read_b128 v[236:239], v141 offset:52224
	s_waitcnt vmcnt(0)
	s_barrier
	s_waitcnt lgkmcnt(0)
	s_waitcnt lgkmcnt(0)
	v_mfma_f32_16x16x32_bf16 v[16:19], v[232:235], v[88:91], v[16:19]
	v_mfma_f32_16x16x32_bf16 v[120:123], v[236:239], v[92:95], v[16:19]
	v_mfma_f32_16x16x32_bf16 v[16:19], v[224:227], v[200:203], v[20:23]
	v_mfma_f32_16x16x32_bf16 v[108:111], v[228:231], v[204:207], v[16:19]
	v_mfma_f32_16x16x32_bf16 v[16:19], v[232:235], v[200:203], v[24:27]
	v_mfma_f32_16x16x32_bf16 v[52:55], v[224:227], v[88:91], v[104:107]
	v_mfma_f32_16x16x32_bf16 v[104:107], v[236:239], v[204:207], v[16:19]
	v_mfma_f32_16x16x32_bf16 v[16:19], v[224:227], v[208:211], v[28:31]
	v_mfma_f32_16x16x32_bf16 v[124:127], v[228:231], v[92:95], v[52:55]
	v_mfma_f32_16x16x32_bf16 v[92:95], v[228:231], v[212:215], v[16:19]
	v_mfma_f32_16x16x32_bf16 v[16:19], v[232:235], v[208:211], v[32:35]
	v_mfma_f32_16x16x32_bf16 v[88:91], v[236:239], v[212:215], v[16:19]
	v_mfma_f32_16x16x32_bf16 v[16:19], v[224:227], v[216:219], v[36:39]
	v_mfma_f32_16x16x32_bf16 v[76:79], v[228:231], v[220:223], v[16:19]
	v_mfma_f32_16x16x32_bf16 v[16:19], v[232:235], v[216:219], v[40:43]
	v_mfma_f32_16x16x32_bf16 v[72:75], v[236:239], v[220:223], v[16:19]
	s_barrier
	ds_read_b128 v[20:23], v142 offset:49152
	ds_read_b128 v[28:31], v142 offset:50176
	ds_read_b128 v[36:39], v142 offset:51200
	ds_read_b128 v[200:203], v142 offset:52224
	ds_read_b128 v[204:207], v142 offset:53248
	ds_read_b128 v[208:211], v142 offset:54272
	ds_read_b128 v[212:215], v142 offset:55296
	ds_read_b128 v[216:219], v142 offset:56320
	s_barrier
	s_waitcnt lgkmcnt(0)
	s_waitcnt lgkmcnt(0)
	v_mfma_f32_16x16x32_bf16 v[16:19], v[8:11], v[20:23], v[136:139]
	v_mfma_f32_16x16x32_bf16 v[64:67], v[188:191], v[28:31], v[16:19]
	v_mfma_f32_16x16x32_bf16 v[16:19], v[192:195], v[20:23], v[144:147]
	v_mfma_f32_16x16x32_bf16 v[52:55], v[196:199], v[28:31], v[16:19]
	v_mfma_f32_16x16x32_bf16 v[16:19], v[8:11], v[36:39], v[148:151]
	v_mfma_f32_16x16x32_bf16 v[40:43], v[188:191], v[200:203], v[16:19]
	v_mfma_f32_16x16x32_bf16 v[16:19], v[192:195], v[36:39], v[152:155]
	v_mfma_f32_16x16x32_bf16 v[32:35], v[196:199], v[200:203], v[16:19]
	v_mfma_f32_16x16x32_bf16 v[16:19], v[8:11], v[204:207], v[156:159]
	v_mfma_f32_16x16x32_bf16 v[0:3], v[8:11], v[212:215], v[0:3]
	v_mfma_f32_16x16x32_bf16 v[24:27], v[188:191], v[208:211], v[16:19]
	v_mfma_f32_16x16x32_bf16 v[16:19], v[192:195], v[204:207], v[160:163]
	v_mfma_f32_16x16x32_bf16 v[8:11], v[188:191], v[216:219], v[0:3]
	v_mfma_f32_16x16x32_bf16 v[0:3], v[192:195], v[212:215], v[4:7]
	v_mfma_f32_16x16x32_bf16 v[16:19], v[196:199], v[208:211], v[16:19]
	v_mfma_f32_16x16x32_bf16 v[0:3], v[196:199], v[216:219], v[0:3]
	v_mfma_f32_16x16x32_bf16 v[4:7], v[224:227], v[20:23], v[12:15]
	v_mfma_f32_16x16x32_bf16 v[68:71], v[228:231], v[28:31], v[4:7]
	v_mfma_f32_16x16x32_bf16 v[4:7], v[232:235], v[20:23], v[44:47]
	v_mfma_f32_16x16x32_bf16 v[56:59], v[236:239], v[28:31], v[4:7]
	v_mfma_f32_16x16x32_bf16 v[4:7], v[224:227], v[36:39], v[164:167]
	v_mfma_f32_16x16x32_bf16 v[44:47], v[228:231], v[200:203], v[4:7]
	v_mfma_f32_16x16x32_bf16 v[4:7], v[232:235], v[36:39], v[168:171]
	v_mfma_f32_16x16x32_bf16 v[36:39], v[236:239], v[200:203], v[4:7]
	v_mfma_f32_16x16x32_bf16 v[4:7], v[224:227], v[204:207], v[172:175]
	v_mfma_f32_16x16x32_bf16 v[28:31], v[228:231], v[208:211], v[4:7]
	v_mfma_f32_16x16x32_bf16 v[4:7], v[232:235], v[204:207], v[176:179]
	v_mfma_f32_16x16x32_bf16 v[20:23], v[236:239], v[208:211], v[4:7]
	v_mfma_f32_16x16x32_bf16 v[4:7], v[224:227], v[212:215], v[180:183]
	v_mfma_f32_16x16x32_bf16 v[12:15], v[228:231], v[216:219], v[4:7]
	v_mfma_f32_16x16x32_bf16 v[4:7], v[232:235], v[212:215], v[184:187]
	v_mfma_f32_16x16x32_bf16 v[4:7], v[236:239], v[216:219], v[4:7]
	s_barrier
	s_and_saveexec_b64 s[8:9], s[2:3]
	s_cbranch_execz .LBB0_622
	s_barrier

.LBB0_700:
	ds_read_b128 v[148:151], v146
	ds_read_b128 v[152:155], v146 offset:1024
	ds_read_b128 v[156:159], v146 offset:2048
	ds_read_b128 v[160:163], v146 offset:3072
	s_add_i32 s11, s2, 2
	s_cmp_gt_u32 s2, 13
	s_cselect_b32 s26, s54, s16
	s_cselect_b32 s18, s53, s10
	s_mov_b32 m0, s46
	ds_read_b128 v[164:167], v147
	ds_read_b128 v[168:171], v147 offset:1024
	ds_read_b128 v[172:175], v147 offset:2048
	ds_read_b128 v[176:179], v147 offset:3072
	ds_read_b128 v[180:183], v147 offset:4096
	ds_read_b128 v[184:187], v147 offset:5120
	ds_read_b128 v[188:191], v147 offset:6144
	ds_read_b128 v[192:195], v147 offset:7168
	global_load_lds_dwordx4 v[140:141], off
	s_mov_b32 m0, s47
	s_nop 0
	global_load_lds_dwordx4 v[142:143], off
	s_waitcnt lgkmcnt(8)
	s_barrier
	s_waitcnt lgkmcnt(0)
	s_waitcnt lgkmcnt(0)
	v_mfma_f32_16x16x32_bf16 v[124:127], v[148:151], v[164:167], v[124:127]
	v_mfma_f32_16x16x32_bf16 v[120:123], v[156:159], v[164:167], v[120:123]
	v_mfma_f32_16x16x32_bf16 v[116:119], v[148:151], v[172:175], v[116:119]
	v_mfma_f32_16x16x32_bf16 v[112:115], v[156:159], v[172:175], v[112:115]
	v_mfma_f32_16x16x32_bf16 v[100:103], v[148:151], v[180:183], v[100:103]
	v_mfma_f32_16x16x32_bf16 v[96:99], v[156:159], v[180:183], v[96:99]
	v_mfma_f32_16x16x32_bf16 v[84:87], v[148:151], v[188:191], v[84:87]
	v_mfma_f32_16x16x32_bf16 v[80:83], v[156:159], v[188:191], v[80:83]
	v_mfma_f32_16x16x32_bf16 v[124:127], v[152:155], v[168:171], v[124:127]
	v_mfma_f32_16x16x32_bf16 v[120:123], v[160:163], v[168:171], v[120:123]
	v_mfma_f32_16x16x32_bf16 v[116:119], v[152:155], v[176:179], v[116:119]
	v_mfma_f32_16x16x32_bf16 v[112:115], v[160:163], v[176:179], v[112:115]
	v_mfma_f32_16x16x32_bf16 v[100:103], v[152:155], v[184:187], v[100:103]
	v_mfma_f32_16x16x32_bf16 v[96:99], v[160:163], v[184:187], v[96:99]
	v_mfma_f32_16x16x32_bf16 v[84:87], v[152:155], v[192:195], v[84:87]
	v_mfma_f32_16x16x32_bf16 v[80:83], v[160:163], v[192:195], v[80:83]
	s_barrier
	s_cselect_b32 s2, 0, s11
	s_ashr_i32 s27, s26, 31
	s_lshl_b64 s[20:21], s[26:27], 11
	s_add_u32 s58, s24, s20
	s_addc_u32 s59, s25, s21
	s_lshl_b64 s[20:21], s[2:3], 7
	s_add_u32 s56, s58, s20
	s_addc_u32 s57, s59, s21
	s_mov_b32 m0, s17
	v_lshl_add_u64 v[212:213], s[56:57], 0, v[132:133]
	ds_read_b128 v[196:199], v146 offset:16384
	ds_read_b128 v[200:203], v146 offset:17408
	ds_read_b128 v[204:207], v146 offset:18432
	ds_read_b128 v[208:211], v146 offset:19456
	global_load_lds_dwordx4 v[212:213], off
	v_lshl_add_u64 v[212:213], s[56:57], 0, v[128:129]
	s_mov_b32 m0, s29
	s_nop 0
	global_load_lds_dwordx4 v[212:213], off
	s_barrier
	s_waitcnt lgkmcnt(0)
	s_waitcnt lgkmcnt(0)
	v_mfma_f32_16x16x32_bf16 v[108:111], v[196:199], v[164:167], v[108:111]
	v_mfma_f32_16x16x32_bf16 v[104:107], v[204:207], v[164:167], v[104:107]
	v_mfma_f32_16x16x32_bf16 v[92:95], v[196:199], v[172:175], v[92:95]
	v_mfma_f32_16x16x32_bf16 v[88:91], v[204:207], v[172:175], v[88:91]
	v_mfma_f32_16x16x32_bf16 v[76:79], v[196:199], v[180:183], v[76:79]
	v_mfma_f32_16x16x32_bf16 v[72:75], v[204:207], v[180:183], v[72:75]
	v_mfma_f32_16x16x32_bf16 v[68:71], v[196:199], v[188:191], v[68:71]
	v_mfma_f32_16x16x32_bf16 v[64:67], v[204:207], v[188:191], v[64:67]
	v_mfma_f32_16x16x32_bf16 v[108:111], v[200:203], v[168:171], v[108:111]
	v_mfma_f32_16x16x32_bf16 v[104:107], v[208:211], v[168:171], v[104:107]
	v_mfma_f32_16x16x32_bf16 v[92:95], v[200:203], v[176:179], v[92:95]
	v_mfma_f32_16x16x32_bf16 v[88:91], v[208:211], v[176:179], v[88:91]
	v_mfma_f32_16x16x32_bf16 v[76:79], v[200:203], v[184:187], v[76:79]
	v_mfma_f32_16x16x32_bf16 v[72:75], v[208:211], v[184:187], v[72:75]
	v_mfma_f32_16x16x32_bf16 v[68:71], v[200:203], v[192:195], v[68:71]
	v_mfma_f32_16x16x32_bf16 v[64:67], v[208:211], v[192:195], v[64:67]
	s_ashr_i32 s19, s18, 31
	s_lshl_b64 s[56:57], s[18:19], 11
	s_add_u32 s60, s22, s56
	s_addc_u32 s61, s23, s57
	s_add_u32 s56, s60, s20
	s_addc_u32 s57, s61, s21
	s_mov_b32 m0, s28
	v_lshl_add_u64 v[212:213], s[56:57], 0, v[134:135]
	s_barrier
	ds_read_b128 v[164:167], v147 offset:16384
	ds_read_b128 v[168:171], v147 offset:17408
	ds_read_b128 v[172:175], v147 offset:18432
	ds_read_b128 v[176:179], v147 offset:19456
	ds_read_b128 v[180:183], v147 offset:20480
	ds_read_b128 v[184:187], v147 offset:21504
	ds_read_b128 v[188:191], v147 offset:22528
	ds_read_b128 v[192:195], v147 offset:23552
	global_load_lds_dwordx4 v[212:213], off
	v_lshl_add_u64 v[212:213], s[56:57], 0, v[130:131]
	s_mov_b32 m0, s30
	s_nop 0
	global_load_lds_dwordx4 v[212:213], off
	s_barrier
	s_waitcnt lgkmcnt(0)
	s_waitcnt lgkmcnt(0)
	v_mfma_f32_16x16x32_bf16 v[60:63], v[148:151], v[164:167], v[60:63]
	v_mfma_f32_16x16x32_bf16 v[56:59], v[156:159], v[164:167], v[56:59]
	v_mfma_f32_16x16x32_bf16 v[52:55], v[148:151], v[172:175], v[52:55]
	v_mfma_f32_16x16x32_bf16 v[48:51], v[156:159], v[172:175], v[48:51]
	v_mfma_f32_16x16x32_bf16 v[36:39], v[148:151], v[180:183], v[36:39]
	v_mfma_f32_16x16x32_bf16 v[32:35], v[156:159], v[180:183], v[32:35]
	v_mfma_f32_16x16x32_bf16 v[20:23], v[148:151], v[188:191], v[20:23]
	v_mfma_f32_16x16x32_bf16 v[16:19], v[156:159], v[188:191], v[16:19]
	v_mfma_f32_16x16x32_bf16 v[60:63], v[152:155], v[168:171], v[60:63]
	v_mfma_f32_16x16x32_bf16 v[56:59], v[160:163], v[168:171], v[56:59]
	v_mfma_f32_16x16x32_bf16 v[52:55], v[152:155], v[176:179], v[52:55]
	v_mfma_f32_16x16x32_bf16 v[48:51], v[160:163], v[176:179], v[48:51]
	v_mfma_f32_16x16x32_bf16 v[36:39], v[152:155], v[184:187], v[36:39]
	v_mfma_f32_16x16x32_bf16 v[32:35], v[160:163], v[184:187], v[32:35]
	v_mfma_f32_16x16x32_bf16 v[20:23], v[152:155], v[192:195], v[20:23]
	v_mfma_f32_16x16x32_bf16 v[16:19], v[160:163], v[192:195], v[16:19]
	s_barrier
	s_bitset1_b32 s26, 7
	s_ashr_i32 s27, s26, 31
	s_lshl_b64 s[26:27], s[26:27], 11
	s_add_u32 s56, s24, s26
	s_addc_u32 s57, s25, s27
	s_add_u32 s26, s56, s20
	s_addc_u32 s27, s57, s21
	s_mov_b32 m0, s31
	v_lshl_add_u64 v[148:149], s[26:27], 0, v[132:133]
	global_load_lds_dwordx4 v[148:149], off
	v_lshl_add_u64 v[148:149], s[26:27], 0, v[128:129]
	s_mov_b32 m0, s33
	s_nop 0
	global_load_lds_dwordx4 v[148:149], off
	s_waitcnt vmcnt(6)
	s_barrier
	v_mfma_f32_16x16x32_bf16 v[44:47], v[196:199], v[164:167], v[44:47]
	v_mfma_f32_16x16x32_bf16 v[40:43], v[204:207], v[164:167], v[40:43]
	v_mfma_f32_16x16x32_bf16 v[28:31], v[196:199], v[172:175], v[28:31]
	v_mfma_f32_16x16x32_bf16 v[24:27], v[204:207], v[172:175], v[24:27]
	v_mfma_f32_16x16x32_bf16 v[12:15], v[196:199], v[180:183], v[12:15]
	v_mfma_f32_16x16x32_bf16 v[8:11], v[204:207], v[180:183], v[8:11]
	v_mfma_f32_16x16x32_bf16 v[4:7], v[196:199], v[188:191], v[4:7]
	v_mfma_f32_16x16x32_bf16 v[0:3], v[204:207], v[188:191], v[0:3]
	v_mfma_f32_16x16x32_bf16 v[44:47], v[200:203], v[168:171], v[44:47]
	v_mfma_f32_16x16x32_bf16 v[40:43], v[208:211], v[168:171], v[40:43]
	v_mfma_f32_16x16x32_bf16 v[28:31], v[200:203], v[176:179], v[28:31]
	v_mfma_f32_16x16x32_bf16 v[24:27], v[208:211], v[176:179], v[24:27]
	v_mfma_f32_16x16x32_bf16 v[12:15], v[200:203], v[184:187], v[12:15]
	v_mfma_f32_16x16x32_bf16 v[8:11], v[208:211], v[184:187], v[8:11]
	v_mfma_f32_16x16x32_bf16 v[4:7], v[200:203], v[192:195], v[4:7]
	v_mfma_f32_16x16x32_bf16 v[0:3], v[208:211], v[192:195], v[0:3]
	s_barrier
	ds_read_b128 v[148:151], v146 offset:32768
	ds_read_b128 v[152:155], v146 offset:33792
	ds_read_b128 v[156:159], v146 offset:34816
	ds_read_b128 v[160:163], v146 offset:35840
	s_bitset1_b32 s18, 7
	s_ashr_i32 s19, s18, 31
	s_lshl_b64 s[18:19], s[18:19], 11
	s_add_u32 s18, s22, s18
	s_addc_u32 s19, s23, s19
	s_add_u32 s18, s18, s20
	s_addc_u32 s19, s19, s21
	s_mov_b32 m0, s36
	v_lshl_add_u64 v[196:197], s[18:19], 0, v[134:135]
	ds_read_b128 v[164:167], v147 offset:32768
	ds_read_b128 v[168:171], v147 offset:33792
	ds_read_b128 v[172:175], v147 offset:34816
	ds_read_b128 v[176:179], v147 offset:35840
	ds_read_b128 v[180:183], v147 offset:36864
	ds_read_b128 v[184:187], v147 offset:37888
	ds_read_b128 v[188:191], v147 offset:38912
	ds_read_b128 v[192:195], v147 offset:39936
	global_load_lds_dwordx4 v[196:197], off
	v_lshl_add_u64 v[196:197], s[18:19], 0, v[130:131]
	s_mov_b32 m0, s37
	s_nop 0
	global_load_lds_dwordx4 v[196:197], off
	s_waitcnt lgkmcnt(8)
	s_barrier
	s_waitcnt lgkmcnt(0)
	s_waitcnt lgkmcnt(0)
	v_mfma_f32_16x16x32_bf16 v[124:127], v[148:151], v[164:167], v[124:127]
	v_mfma_f32_16x16x32_bf16 v[120:123], v[156:159], v[164:167], v[120:123]
	v_mfma_f32_16x16x32_bf16 v[116:119], v[148:151], v[172:175], v[116:119]
	v_mfma_f32_16x16x32_bf16 v[112:115], v[156:159], v[172:175], v[112:115]
	v_mfma_f32_16x16x32_bf16 v[100:103], v[148:151], v[180:183], v[100:103]
	v_mfma_f32_16x16x32_bf16 v[96:99], v[156:159], v[180:183], v[96:99]
	v_mfma_f32_16x16x32_bf16 v[84:87], v[148:151], v[188:191], v[84:87]
	v_mfma_f32_16x16x32_bf16 v[80:83], v[156:159], v[188:191], v[80:83]
	v_mfma_f32_16x16x32_bf16 v[124:127], v[152:155], v[168:171], v[124:127]
	v_mfma_f32_16x16x32_bf16 v[120:123], v[160:163], v[168:171], v[120:123]
	v_mfma_f32_16x16x32_bf16 v[116:119], v[152:155], v[176:179], v[116:119]
	v_mfma_f32_16x16x32_bf16 v[112:115], v[160:163], v[176:179], v[112:115]
	v_mfma_f32_16x16x32_bf16 v[100:103], v[152:155], v[184:187], v[100:103]
	v_mfma_f32_16x16x32_bf16 v[96:99], v[160:163], v[184:187], v[96:99]
	v_mfma_f32_16x16x32_bf16 v[84:87], v[152:155], v[192:195], v[84:87]
	v_mfma_f32_16x16x32_bf16 v[80:83], v[160:163], v[192:195], v[80:83]
	s_barrier
	s_or_b32 s2, s2, 1
	s_lshl_b64 s[18:19], s[2:3], 7
	s_add_u32 s20, s58, s18
	s_addc_u32 s21, s59, s19
	s_mov_b32 m0, s38
	v_lshl_add_u64 v[212:213], s[20:21], 0, v[132:133]
	ds_read_b128 v[196:199], v146 offset:49152
	ds_read_b128 v[200:203], v146 offset:50176
	ds_read_b128 v[204:207], v146 offset:51200
	ds_read_b128 v[208:211], v146 offset:52224
	global_load_lds_dwordx4 v[212:213], off
	v_lshl_add_u64 v[212:213], s[20:21], 0, v[128:129]
	s_mov_b32 m0, s39
	s_nop 0
	global_load_lds_dwordx4 v[212:213], off
	s_barrier
	s_waitcnt lgkmcnt(0)
	s_waitcnt lgkmcnt(0)
	v_mfma_f32_16x16x32_bf16 v[108:111], v[196:199], v[164:167], v[108:111]
	v_mfma_f32_16x16x32_bf16 v[104:107], v[204:207], v[164:167], v[104:107]
	v_mfma_f32_16x16x32_bf16 v[92:95], v[196:199], v[172:175], v[92:95]
	v_mfma_f32_16x16x32_bf16 v[88:91], v[204:207], v[172:175], v[88:91]
	v_mfma_f32_16x16x32_bf16 v[76:79], v[196:199], v[180:183], v[76:79]
	v_mfma_f32_16x16x32_bf16 v[72:75], v[204:207], v[180:183], v[72:75]
	v_mfma_f32_16x16x32_bf16 v[68:71], v[196:199], v[188:191], v[68:71]
	v_mfma_f32_16x16x32_bf16 v[64:67], v[204:207], v[188:191], v[64:67]
	v_mfma_f32_16x16x32_bf16 v[108:111], v[200:203], v[168:171], v[108:111]
	v_mfma_f32_16x16x32_bf16 v[104:107], v[208:211], v[168:171], v[104:107]
	v_mfma_f32_16x16x32_bf16 v[92:95], v[200:203], v[176:179], v[92:95]
	v_mfma_f32_16x16x32_bf16 v[88:91], v[208:211], v[176:179], v[88:91]
	v_mfma_f32_16x16x32_bf16 v[76:79], v[200:203], v[184:187], v[76:79]
	v_mfma_f32_16x16x32_bf16 v[72:75], v[208:211], v[184:187], v[72:75]
	v_mfma_f32_16x16x32_bf16 v[68:71], v[200:203], v[192:195], v[68:71]
	v_mfma_f32_16x16x32_bf16 v[64:67], v[208:211], v[192:195], v[64:67]
	s_add_u32 s20, s60, s18
	s_addc_u32 s21, s61, s19
	s_mov_b32 m0, s40
	v_lshl_add_u64 v[212:213], s[20:21], 0, v[134:135]
	s_barrier
	ds_read_b128 v[164:167], v147 offset:49152
	ds_read_b128 v[168:171], v147 offset:50176
	ds_read_b128 v[172:175], v147 offset:51200
	ds_read_b128 v[176:179], v147 offset:52224
	ds_read_b128 v[180:183], v147 offset:53248
	ds_read_b128 v[184:187], v147 offset:54272
	ds_read_b128 v[188:191], v147 offset:55296
	ds_read_b128 v[192:195], v147 offset:56320
	global_load_lds_dwordx4 v[212:213], off
	v_lshl_add_u64 v[212:213], s[20:21], 0, v[130:131]
	s_mov_b32 m0, s41
	s_nop 0
	global_load_lds_dwordx4 v[212:213], off
	s_barrier
	s_waitcnt lgkmcnt(0)
	s_waitcnt lgkmcnt(0)
	v_mfma_f32_16x16x32_bf16 v[60:63], v[148:151], v[164:167], v[60:63]
	v_mfma_f32_16x16x32_bf16 v[56:59], v[156:159], v[164:167], v[56:59]
	v_mfma_f32_16x16x32_bf16 v[52:55], v[148:151], v[172:175], v[52:55]
	v_mfma_f32_16x16x32_bf16 v[48:51], v[156:159], v[172:175], v[48:51]
	v_mfma_f32_16x16x32_bf16 v[36:39], v[148:151], v[180:183], v[36:39]
	v_mfma_f32_16x16x32_bf16 v[32:35], v[156:159], v[180:183], v[32:35]
	v_mfma_f32_16x16x32_bf16 v[20:23], v[148:151], v[188:191], v[20:23]
	v_mfma_f32_16x16x32_bf16 v[16:19], v[156:159], v[188:191], v[16:19]
	v_mfma_f32_16x16x32_bf16 v[60:63], v[152:155], v[168:171], v[60:63]
	v_mfma_f32_16x16x32_bf16 v[56:59], v[160:163], v[168:171], v[56:59]
	v_mfma_f32_16x16x32_bf16 v[52:55], v[152:155], v[176:179], v[52:55]
	v_mfma_f32_16x16x32_bf16 v[48:51], v[160:163], v[176:179], v[48:51]
	v_mfma_f32_16x16x32_bf16 v[36:39], v[152:155], v[184:187], v[36:39]
	v_mfma_f32_16x16x32_bf16 v[32:35], v[160:163], v[184:187], v[32:35]
	v_mfma_f32_16x16x32_bf16 v[20:23], v[152:155], v[192:195], v[20:23]
	v_mfma_f32_16x16x32_bf16 v[16:19], v[160:163], v[192:195], v[16:19]
	s_barrier
	s_add_u32 s18, s56, s18
	s_addc_u32 s19, s57, s19
	s_mov_b32 m0, s42
	v_lshl_add_u64 v[148:149], s[18:19], 0, v[132:133]
	global_load_lds_dwordx4 v[148:149], off
	v_lshl_add_u64 v[148:149], s[18:19], 0, v[128:129]
	s_mov_b32 m0, s43
	s_nop 0
	global_load_lds_dwordx4 v[148:149], off
	s_waitcnt vmcnt(6)
	s_barrier
	v_mfma_f32_16x16x32_bf16 v[44:47], v[196:199], v[164:167], v[44:47]
	v_mfma_f32_16x16x32_bf16 v[40:43], v[204:207], v[164:167], v[40:43]
	v_mfma_f32_16x16x32_bf16 v[28:31], v[196:199], v[172:175], v[28:31]
	v_mfma_f32_16x16x32_bf16 v[24:27], v[204:207], v[172:175], v[24:27]
	v_mfma_f32_16x16x32_bf16 v[12:15], v[196:199], v[180:183], v[12:15]
	v_mfma_f32_16x16x32_bf16 v[8:11], v[204:207], v[180:183], v[8:11]
	v_mfma_f32_16x16x32_bf16 v[4:7], v[196:199], v[188:191], v[4:7]
	v_mfma_f32_16x16x32_bf16 v[0:3], v[204:207], v[188:191], v[0:3]
	v_mfma_f32_16x16x32_bf16 v[44:47], v[200:203], v[168:171], v[44:47]
	v_mfma_f32_16x16x32_bf16 v[40:43], v[208:211], v[168:171], v[40:43]
	v_mfma_f32_16x16x32_bf16 v[28:31], v[200:203], v[176:179], v[28:31]
	v_mfma_f32_16x16x32_bf16 v[24:27], v[208:211], v[176:179], v[24:27]
	v_mfma_f32_16x16x32_bf16 v[12:15], v[200:203], v[184:187], v[12:15]
	v_mfma_f32_16x16x32_bf16 v[8:11], v[208:211], v[184:187], v[8:11]
	v_mfma_f32_16x16x32_bf16 v[4:7], v[200:203], v[192:195], v[4:7]
	v_mfma_f32_16x16x32_bf16 v[0:3], v[208:211], v[192:195], v[0:3]
	v_lshl_add_u64 v[140:141], v[140:141], 0, s[4:5]
	v_lshl_add_u64 v[142:143], v[142:143], 0, s[4:5]
	s_cmp_ge_u32 s11, s55
	s_mov_b32 s2, s11
	s_barrier
	s_cbranch_scc0 .LBB0_700
	s_andn2_b64 vcc, exec, s[8:9]
	s_cbranch_vccnz .LBB0_696
	s_bitset1_b32 s10, 7
	s_ashr_i32 s11, s10, 31
	s_lshl_b64 s[10:11], s[10:11], 11
	s_add_u32 s10, s22, s10
	s_addc_u32 s11, s23, s11
	v_lshl_add_u64 v[192:193], s[10:11], 0, v[134:135]
	s_mov_b32 m0, s46
	v_lshl_add_u64 v[192:193], v[192:193], 0, s[6:7]
	ds_read_b128 v[140:143], v146
	ds_read_b128 v[148:151], v146 offset:1024
	ds_read_b128 v[152:155], v146 offset:2048
	ds_read_b128 v[156:159], v146 offset:3072
	ds_read_b128 v[160:163], v147
	ds_read_b128 v[164:167], v147 offset:1024
	ds_read_b128 v[168:171], v147 offset:2048
	ds_read_b128 v[172:175], v147 offset:3072
	ds_read_b128 v[176:179], v147 offset:4096
	ds_read_b128 v[180:183], v147 offset:5120
	ds_read_b128 v[184:187], v147 offset:6144
	ds_read_b128 v[188:191], v147 offset:7168
	global_load_lds_dwordx4 v[192:193], off
	v_lshl_add_u64 v[192:193], s[10:11], 0, v[130:131]
	v_lshl_add_u64 v[192:193], v[192:193], 0, s[6:7]
	s_mov_b32 m0, s47
	s_nop 0
	global_load_lds_dwordx4 v[192:193], off
	s_barrier
	s_waitcnt lgkmcnt(0)
	s_waitcnt lgkmcnt(0)
	v_mfma_f32_16x16x32_bf16 v[124:127], v[140:143], v[160:163], v[124:127]
	v_mfma_f32_16x16x32_bf16 v[120:123], v[152:155], v[160:163], v[120:123]
	v_mfma_f32_16x16x32_bf16 v[116:119], v[140:143], v[168:171], v[116:119]
	v_mfma_f32_16x16x32_bf16 v[112:115], v[152:155], v[168:171], v[112:115]
	v_mfma_f32_16x16x32_bf16 v[100:103], v[140:143], v[176:179], v[100:103]
	v_mfma_f32_16x16x32_bf16 v[96:99], v[152:155], v[176:179], v[96:99]
	v_mfma_f32_16x16x32_bf16 v[84:87], v[140:143], v[184:187], v[84:87]
	v_mfma_f32_16x16x32_bf16 v[80:83], v[152:155], v[184:187], v[80:83]
	v_mfma_f32_16x16x32_bf16 v[124:127], v[148:151], v[164:167], v[124:127]
	v_mfma_f32_16x16x32_bf16 v[120:123], v[156:159], v[164:167], v[120:123]
	v_mfma_f32_16x16x32_bf16 v[116:119], v[148:151], v[172:175], v[116:119]
	v_mfma_f32_16x16x32_bf16 v[112:115], v[156:159], v[172:175], v[112:115]
	v_mfma_f32_16x16x32_bf16 v[100:103], v[148:151], v[180:183], v[100:103]
	v_mfma_f32_16x16x32_bf16 v[96:99], v[156:159], v[180:183], v[96:99]
	v_mfma_f32_16x16x32_bf16 v[84:87], v[148:151], v[188:191], v[84:87]
	v_mfma_f32_16x16x32_bf16 v[80:83], v[156:159], v[188:191], v[80:83]
	s_barrier
	ds_read_b128 v[192:195], v146 offset:16384
	ds_read_b128 v[196:199], v146 offset:17408
	ds_read_b128 v[200:203], v146 offset:18432
	ds_read_b128 v[204:207], v146 offset:19456
	s_barrier
	s_waitcnt lgkmcnt(0)
	s_waitcnt lgkmcnt(0)
	v_mfma_f32_16x16x32_bf16 v[108:111], v[192:195], v[160:163], v[108:111]
	v_mfma_f32_16x16x32_bf16 v[104:107], v[200:203], v[160:163], v[104:107]
	v_mfma_f32_16x16x32_bf16 v[92:95], v[192:195], v[168:171], v[92:95]
	v_mfma_f32_16x16x32_bf16 v[88:91], v[200:203], v[168:171], v[88:91]
	v_mfma_f32_16x16x32_bf16 v[76:79], v[192:195], v[176:179], v[76:79]
	v_mfma_f32_16x16x32_bf16 v[72:75], v[200:203], v[176:179], v[72:75]
	v_mfma_f32_16x16x32_bf16 v[68:71], v[192:195], v[184:187], v[68:71]
	v_mfma_f32_16x16x32_bf16 v[64:67], v[200:203], v[184:187], v[64:67]
	v_mfma_f32_16x16x32_bf16 v[108:111], v[196:199], v[164:167], v[108:111]
	v_mfma_f32_16x16x32_bf16 v[104:107], v[204:207], v[164:167], v[104:107]
	v_mfma_f32_16x16x32_bf16 v[92:95], v[196:199], v[172:175], v[92:95]
	v_mfma_f32_16x16x32_bf16 v[88:91], v[204:207], v[172:175], v[88:91]
	v_mfma_f32_16x16x32_bf16 v[76:79], v[196:199], v[180:183], v[76:79]
	v_mfma_f32_16x16x32_bf16 v[72:75], v[204:207], v[180:183], v[72:75]
	v_mfma_f32_16x16x32_bf16 v[68:71], v[196:199], v[188:191], v[68:71]
	v_mfma_f32_16x16x32_bf16 v[64:67], v[204:207], v[188:191], v[64:67]
	s_barrier
	ds_read_b128 v[160:163], v147 offset:16384
	ds_read_b128 v[164:167], v147 offset:17408
	ds_read_b128 v[168:171], v147 offset:18432
	ds_read_b128 v[172:175], v147 offset:19456
	ds_read_b128 v[176:179], v147 offset:20480
	ds_read_b128 v[180:183], v147 offset:21504
	ds_read_b128 v[184:187], v147 offset:22528
	ds_read_b128 v[188:191], v147 offset:23552
	s_waitcnt vmcnt(4)
	s_barrier
	s_waitcnt lgkmcnt(0)
	s_waitcnt lgkmcnt(0)
	v_mfma_f32_16x16x32_bf16 v[60:63], v[140:143], v[160:163], v[60:63]
	v_mfma_f32_16x16x32_bf16 v[56:59], v[152:155], v[160:163], v[56:59]
	v_mfma_f32_16x16x32_bf16 v[52:55], v[140:143], v[168:171], v[52:55]
	v_mfma_f32_16x16x32_bf16 v[48:51], v[152:155], v[168:171], v[48:51]
	v_mfma_f32_16x16x32_bf16 v[36:39], v[140:143], v[176:179], v[36:39]
	v_mfma_f32_16x16x32_bf16 v[32:35], v[152:155], v[176:179], v[32:35]
	v_mfma_f32_16x16x32_bf16 v[20:23], v[140:143], v[184:187], v[20:23]
	v_mfma_f32_16x16x32_bf16 v[16:19], v[152:155], v[184:187], v[16:19]
	v_mfma_f32_16x16x32_bf16 v[60:63], v[148:151], v[164:167], v[60:63]
	v_mfma_f32_16x16x32_bf16 v[56:59], v[156:159], v[164:167], v[56:59]
	v_mfma_f32_16x16x32_bf16 v[52:55], v[148:151], v[172:175], v[52:55]
	v_mfma_f32_16x16x32_bf16 v[48:51], v[156:159], v[172:175], v[48:51]
	v_mfma_f32_16x16x32_bf16 v[36:39], v[148:151], v[180:183], v[36:39]
	v_mfma_f32_16x16x32_bf16 v[32:35], v[156:159], v[180:183], v[32:35]
	v_mfma_f32_16x16x32_bf16 v[20:23], v[148:151], v[188:191], v[20:23]
	v_mfma_f32_16x16x32_bf16 v[16:19], v[156:159], v[188:191], v[16:19]
	v_mfma_f32_16x16x32_bf16 v[44:47], v[192:195], v[160:163], v[44:47]
	v_mfma_f32_16x16x32_bf16 v[40:43], v[200:203], v[160:163], v[40:43]
	v_mfma_f32_16x16x32_bf16 v[28:31], v[192:195], v[168:171], v[28:31]
	v_mfma_f32_16x16x32_bf16 v[24:27], v[200:203], v[168:171], v[24:27]
	v_mfma_f32_16x16x32_bf16 v[12:15], v[192:195], v[176:179], v[12:15]
	v_mfma_f32_16x16x32_bf16 v[8:11], v[200:203], v[176:179], v[8:11]
	v_mfma_f32_16x16x32_bf16 v[4:7], v[192:195], v[184:187], v[4:7]
	v_mfma_f32_16x16x32_bf16 v[0:3], v[200:203], v[184:187], v[0:3]
	v_mfma_f32_16x16x32_bf16 v[44:47], v[196:199], v[164:167], v[44:47]
	v_mfma_f32_16x16x32_bf16 v[40:43], v[204:207], v[164:167], v[40:43]
	v_mfma_f32_16x16x32_bf16 v[28:31], v[196:199], v[172:175], v[28:31]
	v_mfma_f32_16x16x32_bf16 v[24:27], v[204:207], v[172:175], v[24:27]
	v_mfma_f32_16x16x32_bf16 v[12:15], v[196:199], v[180:183], v[12:15]
	v_mfma_f32_16x16x32_bf16 v[8:11], v[204:207], v[180:183], v[8:11]
	v_mfma_f32_16x16x32_bf16 v[4:7], v[196:199], v[188:191], v[4:7]
	v_mfma_f32_16x16x32_bf16 v[0:3], v[204:207], v[188:191], v[0:3]
	s_barrier
	ds_read_b128 v[140:143], v146 offset:32768
	ds_read_b128 v[148:151], v146 offset:33792
	ds_read_b128 v[152:155], v146 offset:34816
	ds_read_b128 v[156:159], v146 offset:35840
	ds_read_b128 v[160:163], v147 offset:32768
	ds_read_b128 v[164:167], v147 offset:33792
	ds_read_b128 v[168:171], v147 offset:34816
	ds_read_b128 v[172:175], v147 offset:35840
	ds_read_b128 v[176:179], v147 offset:36864
	ds_read_b128 v[180:183], v147 offset:37888
	ds_read_b128 v[184:187], v147 offset:38912
	ds_read_b128 v[188:191], v147 offset:39936
	s_waitcnt vmcnt(2)
	s_barrier
	s_waitcnt lgkmcnt(0)
	s_waitcnt lgkmcnt(0)
	v_mfma_f32_16x16x32_bf16 v[124:127], v[140:143], v[160:163], v[124:127]
	v_mfma_f32_16x16x32_bf16 v[120:123], v[152:155], v[160:163], v[120:123]
	v_mfma_f32_16x16x32_bf16 v[116:119], v[140:143], v[168:171], v[116:119]
	v_mfma_f32_16x16x32_bf16 v[112:115], v[152:155], v[168:171], v[112:115]
	v_mfma_f32_16x16x32_bf16 v[100:103], v[140:143], v[176:179], v[100:103]
	v_mfma_f32_16x16x32_bf16 v[96:99], v[152:155], v[176:179], v[96:99]
	v_mfma_f32_16x16x32_bf16 v[84:87], v[140:143], v[184:187], v[84:87]
	v_mfma_f32_16x16x32_bf16 v[80:83], v[152:155], v[184:187], v[80:83]
	v_mfma_f32_16x16x32_bf16 v[124:127], v[148:151], v[164:167], v[124:127]
	v_mfma_f32_16x16x32_bf16 v[120:123], v[156:159], v[164:167], v[120:123]
	v_mfma_f32_16x16x32_bf16 v[116:119], v[148:151], v[172:175], v[116:119]
	v_mfma_f32_16x16x32_bf16 v[112:115], v[156:159], v[172:175], v[112:115]
	v_mfma_f32_16x16x32_bf16 v[100:103], v[148:151], v[180:183], v[100:103]
	v_mfma_f32_16x16x32_bf16 v[96:99], v[156:159], v[180:183], v[96:99]
	v_mfma_f32_16x16x32_bf16 v[84:87], v[148:151], v[188:191], v[84:87]
	v_mfma_f32_16x16x32_bf16 v[80:83], v[156:159], v[188:191], v[80:83]
	s_barrier
	ds_read_b128 v[192:195], v146 offset:49152
	ds_read_b128 v[196:199], v146 offset:50176
	ds_read_b128 v[200:203], v146 offset:51200
	ds_read_b128 v[204:207], v146 offset:52224
	s_waitcnt vmcnt(0)
	s_barrier
	s_waitcnt lgkmcnt(0)
	s_waitcnt lgkmcnt(0)
	v_mfma_f32_16x16x32_bf16 v[108:111], v[192:195], v[160:163], v[108:111]
	v_mfma_f32_16x16x32_bf16 v[104:107], v[200:203], v[160:163], v[104:107]
	v_mfma_f32_16x16x32_bf16 v[92:95], v[192:195], v[168:171], v[92:95]
	v_mfma_f32_16x16x32_bf16 v[88:91], v[200:203], v[168:171], v[88:91]
	v_mfma_f32_16x16x32_bf16 v[76:79], v[192:195], v[176:179], v[76:79]
	v_mfma_f32_16x16x32_bf16 v[72:75], v[200:203], v[176:179], v[72:75]
	v_mfma_f32_16x16x32_bf16 v[68:71], v[192:195], v[184:187], v[68:71]
	v_mfma_f32_16x16x32_bf16 v[64:67], v[200:203], v[184:187], v[64:67]
	v_mfma_f32_16x16x32_bf16 v[108:111], v[196:199], v[164:167], v[108:111]
	v_mfma_f32_16x16x32_bf16 v[104:107], v[204:207], v[164:167], v[104:107]
	v_mfma_f32_16x16x32_bf16 v[92:95], v[196:199], v[172:175], v[92:95]
	v_mfma_f32_16x16x32_bf16 v[88:91], v[204:207], v[172:175], v[88:91]
	v_mfma_f32_16x16x32_bf16 v[76:79], v[196:199], v[180:183], v[76:79]
	v_mfma_f32_16x16x32_bf16 v[72:75], v[204:207], v[180:183], v[72:75]
	v_mfma_f32_16x16x32_bf16 v[68:71], v[196:199], v[188:191], v[68:71]
	v_mfma_f32_16x16x32_bf16 v[64:67], v[204:207], v[188:191], v[64:67]
	s_barrier
	ds_read_b128 v[160:163], v147 offset:49152
	ds_read_b128 v[164:167], v147 offset:50176
	ds_read_b128 v[168:171], v147 offset:51200
	ds_read_b128 v[172:175], v147 offset:52224
	ds_read_b128 v[176:179], v147 offset:53248
	ds_read_b128 v[180:183], v147 offset:54272
	ds_read_b128 v[184:187], v147 offset:55296
	ds_read_b128 v[188:191], v147 offset:56320
	s_barrier
	s_waitcnt lgkmcnt(0)
	s_waitcnt lgkmcnt(0)
	v_mfma_f32_16x16x32_bf16 v[60:63], v[140:143], v[160:163], v[60:63]
	v_mfma_f32_16x16x32_bf16 v[56:59], v[152:155], v[160:163], v[56:59]
	v_mfma_f32_16x16x32_bf16 v[52:55], v[140:143], v[168:171], v[52:55]
	v_mfma_f32_16x16x32_bf16 v[48:51], v[152:155], v[168:171], v[48:51]
	v_mfma_f32_16x16x32_bf16 v[36:39], v[140:143], v[176:179], v[36:39]
	v_mfma_f32_16x16x32_bf16 v[32:35], v[152:155], v[176:179], v[32:35]
	v_mfma_f32_16x16x32_bf16 v[20:23], v[140:143], v[184:187], v[20:23]
	v_mfma_f32_16x16x32_bf16 v[16:19], v[152:155], v[184:187], v[16:19]
	v_mfma_f32_16x16x32_bf16 v[60:63], v[148:151], v[164:167], v[60:63]
	v_mfma_f32_16x16x32_bf16 v[56:59], v[156:159], v[164:167], v[56:59]
	v_mfma_f32_16x16x32_bf16 v[52:55], v[148:151], v[172:175], v[52:55]
	v_mfma_f32_16x16x32_bf16 v[48:51], v[156:159], v[172:175], v[48:51]
	v_mfma_f32_16x16x32_bf16 v[36:39], v[148:151], v[180:183], v[36:39]
	v_mfma_f32_16x16x32_bf16 v[32:35], v[156:159], v[180:183], v[32:35]
	v_mfma_f32_16x16x32_bf16 v[20:23], v[148:151], v[188:191], v[20:23]
	v_mfma_f32_16x16x32_bf16 v[16:19], v[156:159], v[188:191], v[16:19]
	v_mfma_f32_16x16x32_bf16 v[44:47], v[192:195], v[160:163], v[44:47]
	v_mfma_f32_16x16x32_bf16 v[40:43], v[200:203], v[160:163], v[40:43]
	v_mfma_f32_16x16x32_bf16 v[28:31], v[192:195], v[168:171], v[28:31]
	v_mfma_f32_16x16x32_bf16 v[24:27], v[200:203], v[168:171], v[24:27]
	v_mfma_f32_16x16x32_bf16 v[12:15], v[192:195], v[176:179], v[12:15]
	v_mfma_f32_16x16x32_bf16 v[8:11], v[200:203], v[176:179], v[8:11]
	v_mfma_f32_16x16x32_bf16 v[4:7], v[192:195], v[184:187], v[4:7]
	v_mfma_f32_16x16x32_bf16 v[0:3], v[200:203], v[184:187], v[0:3]
	v_mfma_f32_16x16x32_bf16 v[44:47], v[196:199], v[164:167], v[44:47]
	v_mfma_f32_16x16x32_bf16 v[40:43], v[204:207], v[164:167], v[40:43]
	v_mfma_f32_16x16x32_bf16 v[28:31], v[196:199], v[172:175], v[28:31]
	v_mfma_f32_16x16x32_bf16 v[24:27], v[204:207], v[172:175], v[24:27]
	v_mfma_f32_16x16x32_bf16 v[12:15], v[196:199], v[180:183], v[12:15]
	v_mfma_f32_16x16x32_bf16 v[8:11], v[204:207], v[180:183], v[8:11]
	v_mfma_f32_16x16x32_bf16 v[4:7], v[196:199], v[188:191], v[4:7]
	v_mfma_f32_16x16x32_bf16 v[0:3], v[204:207], v[188:191], v[0:3]
	s_barrier
	s_branch .LBB0_696

.LBB0_738:
	ds_read_b128 v[148:151], v146
	ds_read_b128 v[152:155], v146 offset:1024
	ds_read_b128 v[156:159], v146 offset:2048
	ds_read_b128 v[160:163], v146 offset:3072
	s_add_i32 s11, s2, 2
	s_cmp_gt_u32 s2, 13
	s_cselect_b32 s22, s52, s16
	s_cselect_b32 s18, s51, s10
	s_mov_b32 m0, s46
	ds_read_b128 v[164:167], v147
	ds_read_b128 v[168:171], v147 offset:1024
	ds_read_b128 v[172:175], v147 offset:2048
	ds_read_b128 v[176:179], v147 offset:3072
	ds_read_b128 v[180:183], v147 offset:4096
	ds_read_b128 v[184:187], v147 offset:5120
	ds_read_b128 v[188:191], v147 offset:6144
	ds_read_b128 v[192:195], v147 offset:7168
	global_load_lds_dwordx4 v[140:141], off
	s_mov_b32 m0, s47
	s_nop 0
	global_load_lds_dwordx4 v[142:143], off
	s_waitcnt lgkmcnt(8)
	s_barrier
	s_waitcnt lgkmcnt(0)
	s_waitcnt lgkmcnt(0)
	v_mfma_f32_16x16x32_bf16 v[124:127], v[148:151], v[164:167], v[124:127]
	v_mfma_f32_16x16x32_bf16 v[120:123], v[156:159], v[164:167], v[120:123]
	v_mfma_f32_16x16x32_bf16 v[108:111], v[148:151], v[172:175], v[108:111]
	v_mfma_f32_16x16x32_bf16 v[104:107], v[156:159], v[172:175], v[104:107]
	v_mfma_f32_16x16x32_bf16 v[92:95], v[148:151], v[180:183], v[92:95]
	v_mfma_f32_16x16x32_bf16 v[88:91], v[156:159], v[180:183], v[88:91]
	v_mfma_f32_16x16x32_bf16 v[76:79], v[148:151], v[188:191], v[76:79]
	v_mfma_f32_16x16x32_bf16 v[72:75], v[156:159], v[188:191], v[72:75]
	v_mfma_f32_16x16x32_bf16 v[124:127], v[152:155], v[168:171], v[124:127]
	v_mfma_f32_16x16x32_bf16 v[120:123], v[160:163], v[168:171], v[120:123]
	v_mfma_f32_16x16x32_bf16 v[108:111], v[152:155], v[176:179], v[108:111]
	v_mfma_f32_16x16x32_bf16 v[104:107], v[160:163], v[176:179], v[104:107]
	v_mfma_f32_16x16x32_bf16 v[92:95], v[152:155], v[184:187], v[92:95]
	v_mfma_f32_16x16x32_bf16 v[88:91], v[160:163], v[184:187], v[88:91]
	v_mfma_f32_16x16x32_bf16 v[76:79], v[152:155], v[192:195], v[76:79]
	v_mfma_f32_16x16x32_bf16 v[72:75], v[160:163], v[192:195], v[72:75]
	s_barrier
	s_cselect_b32 s2, 0, s11
	s_ashr_i32 s23, s22, 31
	s_lshl_b64 s[20:21], s[22:23], 11
	s_add_u32 s58, s26, s20
	s_addc_u32 s59, s27, s21
	s_lshl_b64 s[20:21], s[2:3], 7
	s_add_u32 s56, s58, s20
	s_addc_u32 s57, s59, s21
	s_mov_b32 m0, s17
	v_lshl_add_u64 v[212:213], s[56:57], 0, v[132:133]
	ds_read_b128 v[196:199], v146 offset:16384
	ds_read_b128 v[200:203], v146 offset:17408
	ds_read_b128 v[204:207], v146 offset:18432
	ds_read_b128 v[208:211], v146 offset:19456
	global_load_lds_dwordx4 v[212:213], off
	v_lshl_add_u64 v[212:213], s[56:57], 0, v[128:129]
	s_mov_b32 m0, s29
	s_nop 0
	global_load_lds_dwordx4 v[212:213], off
	s_barrier
	s_waitcnt lgkmcnt(0)
	s_waitcnt lgkmcnt(0)
	v_mfma_f32_16x16x32_bf16 v[116:119], v[196:199], v[164:167], v[116:119]
	v_mfma_f32_16x16x32_bf16 v[112:115], v[204:207], v[164:167], v[112:115]
	v_mfma_f32_16x16x32_bf16 v[100:103], v[196:199], v[172:175], v[100:103]
	v_mfma_f32_16x16x32_bf16 v[96:99], v[204:207], v[172:175], v[96:99]
	v_mfma_f32_16x16x32_bf16 v[84:87], v[196:199], v[180:183], v[84:87]
	v_mfma_f32_16x16x32_bf16 v[80:83], v[204:207], v[180:183], v[80:83]
	v_mfma_f32_16x16x32_bf16 v[68:71], v[196:199], v[188:191], v[68:71]
	v_mfma_f32_16x16x32_bf16 v[64:67], v[204:207], v[188:191], v[64:67]
	v_mfma_f32_16x16x32_bf16 v[116:119], v[200:203], v[168:171], v[116:119]
	v_mfma_f32_16x16x32_bf16 v[112:115], v[208:211], v[168:171], v[112:115]
	v_mfma_f32_16x16x32_bf16 v[100:103], v[200:203], v[176:179], v[100:103]
	v_mfma_f32_16x16x32_bf16 v[96:99], v[208:211], v[176:179], v[96:99]
	v_mfma_f32_16x16x32_bf16 v[84:87], v[200:203], v[184:187], v[84:87]
	v_mfma_f32_16x16x32_bf16 v[80:83], v[208:211], v[184:187], v[80:83]
	v_mfma_f32_16x16x32_bf16 v[68:71], v[200:203], v[192:195], v[68:71]
	v_mfma_f32_16x16x32_bf16 v[64:67], v[208:211], v[192:195], v[64:67]
	s_ashr_i32 s19, s18, 31
	s_lshl_b64 s[56:57], s[18:19], 11
	s_add_u32 s60, s24, s56
	s_addc_u32 s61, s25, s57
	s_add_u32 s56, s60, s20
	s_addc_u32 s57, s61, s21
	s_mov_b32 m0, s28
	v_lshl_add_u64 v[212:213], s[56:57], 0, v[134:135]
	s_barrier
	ds_read_b128 v[164:167], v147 offset:16384
	ds_read_b128 v[168:171], v147 offset:17408
	ds_read_b128 v[172:175], v147 offset:18432
	ds_read_b128 v[176:179], v147 offset:19456
	ds_read_b128 v[180:183], v147 offset:20480
	ds_read_b128 v[184:187], v147 offset:21504
	ds_read_b128 v[188:191], v147 offset:22528
	ds_read_b128 v[192:195], v147 offset:23552
	global_load_lds_dwordx4 v[212:213], off
	v_lshl_add_u64 v[212:213], s[56:57], 0, v[130:131]
	s_mov_b32 m0, s30
	s_nop 0
	global_load_lds_dwordx4 v[212:213], off
	s_barrier
	s_waitcnt lgkmcnt(0)
	s_waitcnt lgkmcnt(0)
	v_mfma_f32_16x16x32_bf16 v[60:63], v[148:151], v[164:167], v[60:63]
	v_mfma_f32_16x16x32_bf16 v[56:59], v[156:159], v[164:167], v[56:59]
	v_mfma_f32_16x16x32_bf16 v[44:47], v[148:151], v[172:175], v[44:47]
	v_mfma_f32_16x16x32_bf16 v[40:43], v[156:159], v[172:175], v[40:43]
	v_mfma_f32_16x16x32_bf16 v[28:31], v[148:151], v[180:183], v[28:31]
	v_mfma_f32_16x16x32_bf16 v[24:27], v[156:159], v[180:183], v[24:27]
	v_mfma_f32_16x16x32_bf16 v[12:15], v[148:151], v[188:191], v[12:15]
	v_mfma_f32_16x16x32_bf16 v[8:11], v[156:159], v[188:191], v[8:11]
	v_mfma_f32_16x16x32_bf16 v[60:63], v[152:155], v[168:171], v[60:63]
	v_mfma_f32_16x16x32_bf16 v[56:59], v[160:163], v[168:171], v[56:59]
	v_mfma_f32_16x16x32_bf16 v[44:47], v[152:155], v[176:179], v[44:47]
	v_mfma_f32_16x16x32_bf16 v[40:43], v[160:163], v[176:179], v[40:43]
	v_mfma_f32_16x16x32_bf16 v[28:31], v[152:155], v[184:187], v[28:31]
	v_mfma_f32_16x16x32_bf16 v[24:27], v[160:163], v[184:187], v[24:27]
	v_mfma_f32_16x16x32_bf16 v[12:15], v[152:155], v[192:195], v[12:15]
	v_mfma_f32_16x16x32_bf16 v[8:11], v[160:163], v[192:195], v[8:11]
	s_barrier
	s_bitset1_b32 s22, 7
	s_ashr_i32 s23, s22, 31
	s_lshl_b64 s[22:23], s[22:23], 11
	s_add_u32 s56, s26, s22
	s_addc_u32 s57, s27, s23
	s_add_u32 s22, s56, s20
	s_addc_u32 s23, s57, s21
	s_mov_b32 m0, s31
	v_lshl_add_u64 v[148:149], s[22:23], 0, v[132:133]
	global_load_lds_dwordx4 v[148:149], off
	v_lshl_add_u64 v[148:149], s[22:23], 0, v[128:129]
	s_mov_b32 m0, s33
	s_nop 0
	global_load_lds_dwordx4 v[148:149], off
	s_waitcnt vmcnt(6)
	s_barrier
	v_mfma_f32_16x16x32_bf16 v[52:55], v[196:199], v[164:167], v[52:55]
	v_mfma_f32_16x16x32_bf16 v[48:51], v[204:207], v[164:167], v[48:51]
	v_mfma_f32_16x16x32_bf16 v[36:39], v[196:199], v[172:175], v[36:39]
	v_mfma_f32_16x16x32_bf16 v[32:35], v[204:207], v[172:175], v[32:35]
	v_mfma_f32_16x16x32_bf16 v[20:23], v[196:199], v[180:183], v[20:23]
	v_mfma_f32_16x16x32_bf16 v[16:19], v[204:207], v[180:183], v[16:19]
	v_mfma_f32_16x16x32_bf16 v[4:7], v[196:199], v[188:191], v[4:7]
	v_mfma_f32_16x16x32_bf16 v[0:3], v[204:207], v[188:191], v[0:3]
	v_mfma_f32_16x16x32_bf16 v[52:55], v[200:203], v[168:171], v[52:55]
	v_mfma_f32_16x16x32_bf16 v[48:51], v[208:211], v[168:171], v[48:51]
	v_mfma_f32_16x16x32_bf16 v[36:39], v[200:203], v[176:179], v[36:39]
	v_mfma_f32_16x16x32_bf16 v[32:35], v[208:211], v[176:179], v[32:35]
	v_mfma_f32_16x16x32_bf16 v[20:23], v[200:203], v[184:187], v[20:23]
	v_mfma_f32_16x16x32_bf16 v[16:19], v[208:211], v[184:187], v[16:19]
	v_mfma_f32_16x16x32_bf16 v[4:7], v[200:203], v[192:195], v[4:7]
	v_mfma_f32_16x16x32_bf16 v[0:3], v[208:211], v[192:195], v[0:3]
	s_barrier
	ds_read_b128 v[148:151], v146 offset:32768
	ds_read_b128 v[152:155], v146 offset:33792
	ds_read_b128 v[156:159], v146 offset:34816
	ds_read_b128 v[160:163], v146 offset:35840
	s_bitset1_b32 s18, 7
	s_ashr_i32 s19, s18, 31
	s_lshl_b64 s[18:19], s[18:19], 11
	s_add_u32 s18, s24, s18
	s_addc_u32 s19, s25, s19
	s_add_u32 s18, s18, s20
	s_addc_u32 s19, s19, s21
	s_mov_b32 m0, s36
	v_lshl_add_u64 v[196:197], s[18:19], 0, v[134:135]
	ds_read_b128 v[164:167], v147 offset:32768
	ds_read_b128 v[168:171], v147 offset:33792
	ds_read_b128 v[172:175], v147 offset:34816
	ds_read_b128 v[176:179], v147 offset:35840
	ds_read_b128 v[180:183], v147 offset:36864
	ds_read_b128 v[184:187], v147 offset:37888
	ds_read_b128 v[188:191], v147 offset:38912
	ds_read_b128 v[192:195], v147 offset:39936
	global_load_lds_dwordx4 v[196:197], off
	v_lshl_add_u64 v[196:197], s[18:19], 0, v[130:131]
	s_mov_b32 m0, s37
	s_nop 0
	global_load_lds_dwordx4 v[196:197], off
	s_waitcnt lgkmcnt(8)
	s_barrier
	s_waitcnt lgkmcnt(0)
	s_waitcnt lgkmcnt(0)
	v_mfma_f32_16x16x32_bf16 v[124:127], v[148:151], v[164:167], v[124:127]
	v_mfma_f32_16x16x32_bf16 v[120:123], v[156:159], v[164:167], v[120:123]
	v_mfma_f32_16x16x32_bf16 v[108:111], v[148:151], v[172:175], v[108:111]
	v_mfma_f32_16x16x32_bf16 v[104:107], v[156:159], v[172:175], v[104:107]
	v_mfma_f32_16x16x32_bf16 v[92:95], v[148:151], v[180:183], v[92:95]
	v_mfma_f32_16x16x32_bf16 v[88:91], v[156:159], v[180:183], v[88:91]
	v_mfma_f32_16x16x32_bf16 v[76:79], v[148:151], v[188:191], v[76:79]
	v_mfma_f32_16x16x32_bf16 v[72:75], v[156:159], v[188:191], v[72:75]
	v_mfma_f32_16x16x32_bf16 v[124:127], v[152:155], v[168:171], v[124:127]
	v_mfma_f32_16x16x32_bf16 v[120:123], v[160:163], v[168:171], v[120:123]
	v_mfma_f32_16x16x32_bf16 v[108:111], v[152:155], v[176:179], v[108:111]
	v_mfma_f32_16x16x32_bf16 v[104:107], v[160:163], v[176:179], v[104:107]
	v_mfma_f32_16x16x32_bf16 v[92:95], v[152:155], v[184:187], v[92:95]
	v_mfma_f32_16x16x32_bf16 v[88:91], v[160:163], v[184:187], v[88:91]
	v_mfma_f32_16x16x32_bf16 v[76:79], v[152:155], v[192:195], v[76:79]
	v_mfma_f32_16x16x32_bf16 v[72:75], v[160:163], v[192:195], v[72:75]
	s_barrier
	s_or_b32 s2, s2, 1
	s_lshl_b64 s[18:19], s[2:3], 7
	s_add_u32 s20, s58, s18
	s_addc_u32 s21, s59, s19
	s_mov_b32 m0, s38
	v_lshl_add_u64 v[212:213], s[20:21], 0, v[132:133]
	ds_read_b128 v[196:199], v146 offset:49152
	ds_read_b128 v[200:203], v146 offset:50176
	ds_read_b128 v[204:207], v146 offset:51200
	ds_read_b128 v[208:211], v146 offset:52224
	global_load_lds_dwordx4 v[212:213], off
	v_lshl_add_u64 v[212:213], s[20:21], 0, v[128:129]
	s_mov_b32 m0, s39
	s_nop 0
	global_load_lds_dwordx4 v[212:213], off
	s_barrier
	s_waitcnt lgkmcnt(0)
	s_waitcnt lgkmcnt(0)
	v_mfma_f32_16x16x32_bf16 v[116:119], v[196:199], v[164:167], v[116:119]
	v_mfma_f32_16x16x32_bf16 v[112:115], v[204:207], v[164:167], v[112:115]
	v_mfma_f32_16x16x32_bf16 v[100:103], v[196:199], v[172:175], v[100:103]
	v_mfma_f32_16x16x32_bf16 v[96:99], v[204:207], v[172:175], v[96:99]
	v_mfma_f32_16x16x32_bf16 v[84:87], v[196:199], v[180:183], v[84:87]
	v_mfma_f32_16x16x32_bf16 v[80:83], v[204:207], v[180:183], v[80:83]
	v_mfma_f32_16x16x32_bf16 v[68:71], v[196:199], v[188:191], v[68:71]
	v_mfma_f32_16x16x32_bf16 v[64:67], v[204:207], v[188:191], v[64:67]
	v_mfma_f32_16x16x32_bf16 v[116:119], v[200:203], v[168:171], v[116:119]
	v_mfma_f32_16x16x32_bf16 v[112:115], v[208:211], v[168:171], v[112:115]
	v_mfma_f32_16x16x32_bf16 v[100:103], v[200:203], v[176:179], v[100:103]
	v_mfma_f32_16x16x32_bf16 v[96:99], v[208:211], v[176:179], v[96:99]
	v_mfma_f32_16x16x32_bf16 v[84:87], v[200:203], v[184:187], v[84:87]
	v_mfma_f32_16x16x32_bf16 v[80:83], v[208:211], v[184:187], v[80:83]
	v_mfma_f32_16x16x32_bf16 v[68:71], v[200:203], v[192:195], v[68:71]
	v_mfma_f32_16x16x32_bf16 v[64:67], v[208:211], v[192:195], v[64:67]
	s_add_u32 s20, s60, s18
	s_addc_u32 s21, s61, s19
	s_mov_b32 m0, s40
	v_lshl_add_u64 v[212:213], s[20:21], 0, v[134:135]
	s_barrier
	ds_read_b128 v[164:167], v147 offset:49152
	ds_read_b128 v[168:171], v147 offset:50176
	ds_read_b128 v[172:175], v147 offset:51200
	ds_read_b128 v[176:179], v147 offset:52224
	ds_read_b128 v[180:183], v147 offset:53248
	ds_read_b128 v[184:187], v147 offset:54272
	ds_read_b128 v[188:191], v147 offset:55296
	ds_read_b128 v[192:195], v147 offset:56320
	global_load_lds_dwordx4 v[212:213], off
	v_lshl_add_u64 v[212:213], s[20:21], 0, v[130:131]
	s_mov_b32 m0, s41
	s_nop 0
	global_load_lds_dwordx4 v[212:213], off
	s_barrier
	s_waitcnt lgkmcnt(0)
	s_waitcnt lgkmcnt(0)
	v_mfma_f32_16x16x32_bf16 v[60:63], v[148:151], v[164:167], v[60:63]
	v_mfma_f32_16x16x32_bf16 v[56:59], v[156:159], v[164:167], v[56:59]
	v_mfma_f32_16x16x32_bf16 v[44:47], v[148:151], v[172:175], v[44:47]
	v_mfma_f32_16x16x32_bf16 v[40:43], v[156:159], v[172:175], v[40:43]
	v_mfma_f32_16x16x32_bf16 v[28:31], v[148:151], v[180:183], v[28:31]
	v_mfma_f32_16x16x32_bf16 v[24:27], v[156:159], v[180:183], v[24:27]
	v_mfma_f32_16x16x32_bf16 v[12:15], v[148:151], v[188:191], v[12:15]
	v_mfma_f32_16x16x32_bf16 v[8:11], v[156:159], v[188:191], v[8:11]
	v_mfma_f32_16x16x32_bf16 v[60:63], v[152:155], v[168:171], v[60:63]
	v_mfma_f32_16x16x32_bf16 v[56:59], v[160:163], v[168:171], v[56:59]
	v_mfma_f32_16x16x32_bf16 v[44:47], v[152:155], v[176:179], v[44:47]
	v_mfma_f32_16x16x32_bf16 v[40:43], v[160:163], v[176:179], v[40:43]
	v_mfma_f32_16x16x32_bf16 v[28:31], v[152:155], v[184:187], v[28:31]
	v_mfma_f32_16x16x32_bf16 v[24:27], v[160:163], v[184:187], v[24:27]
	v_mfma_f32_16x16x32_bf16 v[12:15], v[152:155], v[192:195], v[12:15]
	v_mfma_f32_16x16x32_bf16 v[8:11], v[160:163], v[192:195], v[8:11]
	s_barrier
	s_add_u32 s18, s56, s18
	s_addc_u32 s19, s57, s19
	s_mov_b32 m0, s42
	v_lshl_add_u64 v[148:149], s[18:19], 0, v[132:133]
	global_load_lds_dwordx4 v[148:149], off
	v_lshl_add_u64 v[148:149], s[18:19], 0, v[128:129]
	s_mov_b32 m0, s43
	s_nop 0
	global_load_lds_dwordx4 v[148:149], off
	s_waitcnt vmcnt(6)
	s_barrier
	v_mfma_f32_16x16x32_bf16 v[52:55], v[196:199], v[164:167], v[52:55]
	v_mfma_f32_16x16x32_bf16 v[48:51], v[204:207], v[164:167], v[48:51]
	v_mfma_f32_16x16x32_bf16 v[36:39], v[196:199], v[172:175], v[36:39]
	v_mfma_f32_16x16x32_bf16 v[32:35], v[204:207], v[172:175], v[32:35]
	v_mfma_f32_16x16x32_bf16 v[20:23], v[196:199], v[180:183], v[20:23]
	v_mfma_f32_16x16x32_bf16 v[16:19], v[204:207], v[180:183], v[16:19]
	v_mfma_f32_16x16x32_bf16 v[4:7], v[196:199], v[188:191], v[4:7]
	v_mfma_f32_16x16x32_bf16 v[0:3], v[204:207], v[188:191], v[0:3]
	v_mfma_f32_16x16x32_bf16 v[52:55], v[200:203], v[168:171], v[52:55]
	v_mfma_f32_16x16x32_bf16 v[48:51], v[208:211], v[168:171], v[48:51]
	v_mfma_f32_16x16x32_bf16 v[36:39], v[200:203], v[176:179], v[36:39]
	v_mfma_f32_16x16x32_bf16 v[32:35], v[208:211], v[176:179], v[32:35]
	v_mfma_f32_16x16x32_bf16 v[20:23], v[200:203], v[184:187], v[20:23]
	v_mfma_f32_16x16x32_bf16 v[16:19], v[208:211], v[184:187], v[16:19]
	v_mfma_f32_16x16x32_bf16 v[4:7], v[200:203], v[192:195], v[4:7]
	v_mfma_f32_16x16x32_bf16 v[0:3], v[208:211], v[192:195], v[0:3]
	v_lshl_add_u64 v[140:141], v[140:141], 0, s[4:5]
	v_lshl_add_u64 v[142:143], v[142:143], 0, s[4:5]
	s_cmp_ge_u32 s11, s55
	s_mov_b32 s2, s11
	s_barrier
	s_cbranch_scc0 .LBB0_738
	s_andn2_b64 vcc, exec, s[8:9]
	s_cbranch_vccnz .LBB0_734
	s_bitset1_b32 s10, 7
	s_ashr_i32 s11, s10, 31
	s_lshl_b64 s[10:11], s[10:11], 11
	s_add_u32 s10, s24, s10
	s_addc_u32 s11, s25, s11
	v_lshl_add_u64 v[192:193], s[10:11], 0, v[134:135]
	s_mov_b32 m0, s46
	v_lshl_add_u64 v[192:193], v[192:193], 0, s[6:7]
	ds_read_b128 v[140:143], v146
	ds_read_b128 v[148:151], v146 offset:1024
	ds_read_b128 v[152:155], v146 offset:2048
	ds_read_b128 v[156:159], v146 offset:3072
	ds_read_b128 v[160:163], v147
	ds_read_b128 v[164:167], v147 offset:1024
	ds_read_b128 v[168:171], v147 offset:2048
	ds_read_b128 v[172:175], v147 offset:3072
	ds_read_b128 v[176:179], v147 offset:4096
	ds_read_b128 v[180:183], v147 offset:5120
	ds_read_b128 v[184:187], v147 offset:6144
	ds_read_b128 v[188:191], v147 offset:7168
	global_load_lds_dwordx4 v[192:193], off
	v_lshl_add_u64 v[192:193], s[10:11], 0, v[130:131]
	v_lshl_add_u64 v[192:193], v[192:193], 0, s[6:7]
	s_mov_b32 m0, s47
	s_nop 0
	global_load_lds_dwordx4 v[192:193], off
	s_barrier
	s_waitcnt lgkmcnt(0)
	s_waitcnt lgkmcnt(0)
	v_mfma_f32_16x16x32_bf16 v[124:127], v[140:143], v[160:163], v[124:127]
	v_mfma_f32_16x16x32_bf16 v[120:123], v[152:155], v[160:163], v[120:123]
	v_mfma_f32_16x16x32_bf16 v[108:111], v[140:143], v[168:171], v[108:111]
	v_mfma_f32_16x16x32_bf16 v[104:107], v[152:155], v[168:171], v[104:107]
	v_mfma_f32_16x16x32_bf16 v[92:95], v[140:143], v[176:179], v[92:95]
	v_mfma_f32_16x16x32_bf16 v[88:91], v[152:155], v[176:179], v[88:91]
	v_mfma_f32_16x16x32_bf16 v[76:79], v[140:143], v[184:187], v[76:79]
	v_mfma_f32_16x16x32_bf16 v[72:75], v[152:155], v[184:187], v[72:75]
	v_mfma_f32_16x16x32_bf16 v[124:127], v[148:151], v[164:167], v[124:127]
	v_mfma_f32_16x16x32_bf16 v[120:123], v[156:159], v[164:167], v[120:123]
	v_mfma_f32_16x16x32_bf16 v[108:111], v[148:151], v[172:175], v[108:111]
	v_mfma_f32_16x16x32_bf16 v[104:107], v[156:159], v[172:175], v[104:107]
	v_mfma_f32_16x16x32_bf16 v[92:95], v[148:151], v[180:183], v[92:95]
	v_mfma_f32_16x16x32_bf16 v[88:91], v[156:159], v[180:183], v[88:91]
	v_mfma_f32_16x16x32_bf16 v[76:79], v[148:151], v[188:191], v[76:79]
	v_mfma_f32_16x16x32_bf16 v[72:75], v[156:159], v[188:191], v[72:75]
	s_barrier
	ds_read_b128 v[192:195], v146 offset:16384
	ds_read_b128 v[196:199], v146 offset:17408
	ds_read_b128 v[200:203], v146 offset:18432
	ds_read_b128 v[204:207], v146 offset:19456
	s_barrier
	s_waitcnt lgkmcnt(0)
	s_waitcnt lgkmcnt(0)
	v_mfma_f32_16x16x32_bf16 v[116:119], v[192:195], v[160:163], v[116:119]
	v_mfma_f32_16x16x32_bf16 v[112:115], v[200:203], v[160:163], v[112:115]
	v_mfma_f32_16x16x32_bf16 v[100:103], v[192:195], v[168:171], v[100:103]
	v_mfma_f32_16x16x32_bf16 v[96:99], v[200:203], v[168:171], v[96:99]
	v_mfma_f32_16x16x32_bf16 v[84:87], v[192:195], v[176:179], v[84:87]
	v_mfma_f32_16x16x32_bf16 v[80:83], v[200:203], v[176:179], v[80:83]
	v_mfma_f32_16x16x32_bf16 v[68:71], v[192:195], v[184:187], v[68:71]
	v_mfma_f32_16x16x32_bf16 v[64:67], v[200:203], v[184:187], v[64:67]
	v_mfma_f32_16x16x32_bf16 v[116:119], v[196:199], v[164:167], v[116:119]
	v_mfma_f32_16x16x32_bf16 v[112:115], v[204:207], v[164:167], v[112:115]
	v_mfma_f32_16x16x32_bf16 v[100:103], v[196:199], v[172:175], v[100:103]
	v_mfma_f32_16x16x32_bf16 v[96:99], v[204:207], v[172:175], v[96:99]
	v_mfma_f32_16x16x32_bf16 v[84:87], v[196:199], v[180:183], v[84:87]
	v_mfma_f32_16x16x32_bf16 v[80:83], v[204:207], v[180:183], v[80:83]
	v_mfma_f32_16x16x32_bf16 v[68:71], v[196:199], v[188:191], v[68:71]
	v_mfma_f32_16x16x32_bf16 v[64:67], v[204:207], v[188:191], v[64:67]
	s_barrier
	ds_read_b128 v[160:163], v147 offset:16384
	ds_read_b128 v[164:167], v147 offset:17408
	ds_read_b128 v[168:171], v147 offset:18432
	ds_read_b128 v[172:175], v147 offset:19456
	ds_read_b128 v[176:179], v147 offset:20480
	ds_read_b128 v[180:183], v147 offset:21504
	ds_read_b128 v[184:187], v147 offset:22528
	ds_read_b128 v[188:191], v147 offset:23552
	s_waitcnt vmcnt(4)
	s_barrier
	s_waitcnt lgkmcnt(0)
	s_waitcnt lgkmcnt(0)
	v_mfma_f32_16x16x32_bf16 v[60:63], v[140:143], v[160:163], v[60:63]
	v_mfma_f32_16x16x32_bf16 v[56:59], v[152:155], v[160:163], v[56:59]
	v_mfma_f32_16x16x32_bf16 v[44:47], v[140:143], v[168:171], v[44:47]
	v_mfma_f32_16x16x32_bf16 v[40:43], v[152:155], v[168:171], v[40:43]
	v_mfma_f32_16x16x32_bf16 v[28:31], v[140:143], v[176:179], v[28:31]
	v_mfma_f32_16x16x32_bf16 v[24:27], v[152:155], v[176:179], v[24:27]
	v_mfma_f32_16x16x32_bf16 v[12:15], v[140:143], v[184:187], v[12:15]
	v_mfma_f32_16x16x32_bf16 v[8:11], v[152:155], v[184:187], v[8:11]
	v_mfma_f32_16x16x32_bf16 v[60:63], v[148:151], v[164:167], v[60:63]
	v_mfma_f32_16x16x32_bf16 v[56:59], v[156:159], v[164:167], v[56:59]
	v_mfma_f32_16x16x32_bf16 v[44:47], v[148:151], v[172:175], v[44:47]
	v_mfma_f32_16x16x32_bf16 v[40:43], v[156:159], v[172:175], v[40:43]
	v_mfma_f32_16x16x32_bf16 v[28:31], v[148:151], v[180:183], v[28:31]
	v_mfma_f32_16x16x32_bf16 v[24:27], v[156:159], v[180:183], v[24:27]
	v_mfma_f32_16x16x32_bf16 v[12:15], v[148:151], v[188:191], v[12:15]
	v_mfma_f32_16x16x32_bf16 v[8:11], v[156:159], v[188:191], v[8:11]
	v_mfma_f32_16x16x32_bf16 v[52:55], v[192:195], v[160:163], v[52:55]
	v_mfma_f32_16x16x32_bf16 v[48:51], v[200:203], v[160:163], v[48:51]
	v_mfma_f32_16x16x32_bf16 v[36:39], v[192:195], v[168:171], v[36:39]
	v_mfma_f32_16x16x32_bf16 v[32:35], v[200:203], v[168:171], v[32:35]
	v_mfma_f32_16x16x32_bf16 v[20:23], v[192:195], v[176:179], v[20:23]
	v_mfma_f32_16x16x32_bf16 v[16:19], v[200:203], v[176:179], v[16:19]
	v_mfma_f32_16x16x32_bf16 v[4:7], v[192:195], v[184:187], v[4:7]
	v_mfma_f32_16x16x32_bf16 v[0:3], v[200:203], v[184:187], v[0:3]
	v_mfma_f32_16x16x32_bf16 v[52:55], v[196:199], v[164:167], v[52:55]
	v_mfma_f32_16x16x32_bf16 v[48:51], v[204:207], v[164:167], v[48:51]
	v_mfma_f32_16x16x32_bf16 v[36:39], v[196:199], v[172:175], v[36:39]
	v_mfma_f32_16x16x32_bf16 v[32:35], v[204:207], v[172:175], v[32:35]
	v_mfma_f32_16x16x32_bf16 v[20:23], v[196:199], v[180:183], v[20:23]
	v_mfma_f32_16x16x32_bf16 v[16:19], v[204:207], v[180:183], v[16:19]
	v_mfma_f32_16x16x32_bf16 v[4:7], v[196:199], v[188:191], v[4:7]
	v_mfma_f32_16x16x32_bf16 v[0:3], v[204:207], v[188:191], v[0:3]
	s_barrier
	ds_read_b128 v[140:143], v146 offset:32768
	ds_read_b128 v[148:151], v146 offset:33792
	ds_read_b128 v[152:155], v146 offset:34816
	ds_read_b128 v[156:159], v146 offset:35840
	ds_read_b128 v[160:163], v147 offset:32768
	ds_read_b128 v[164:167], v147 offset:33792
	ds_read_b128 v[168:171], v147 offset:34816
	ds_read_b128 v[172:175], v147 offset:35840
	ds_read_b128 v[176:179], v147 offset:36864
	ds_read_b128 v[180:183], v147 offset:37888
	ds_read_b128 v[184:187], v147 offset:38912
	ds_read_b128 v[188:191], v147 offset:39936
	s_waitcnt vmcnt(2)
	s_barrier
	s_waitcnt lgkmcnt(0)
	s_waitcnt lgkmcnt(0)
	v_mfma_f32_16x16x32_bf16 v[124:127], v[140:143], v[160:163], v[124:127]
	v_mfma_f32_16x16x32_bf16 v[120:123], v[152:155], v[160:163], v[120:123]
	v_mfma_f32_16x16x32_bf16 v[108:111], v[140:143], v[168:171], v[108:111]
	v_mfma_f32_16x16x32_bf16 v[104:107], v[152:155], v[168:171], v[104:107]
	v_mfma_f32_16x16x32_bf16 v[92:95], v[140:143], v[176:179], v[92:95]
	v_mfma_f32_16x16x32_bf16 v[88:91], v[152:155], v[176:179], v[88:91]
	v_mfma_f32_16x16x32_bf16 v[76:79], v[140:143], v[184:187], v[76:79]
	v_mfma_f32_16x16x32_bf16 v[72:75], v[152:155], v[184:187], v[72:75]
	v_mfma_f32_16x16x32_bf16 v[124:127], v[148:151], v[164:167], v[124:127]
	v_mfma_f32_16x16x32_bf16 v[120:123], v[156:159], v[164:167], v[120:123]
	v_mfma_f32_16x16x32_bf16 v[108:111], v[148:151], v[172:175], v[108:111]
	v_mfma_f32_16x16x32_bf16 v[104:107], v[156:159], v[172:175], v[104:107]
	v_mfma_f32_16x16x32_bf16 v[92:95], v[148:151], v[180:183], v[92:95]
	v_mfma_f32_16x16x32_bf16 v[88:91], v[156:159], v[180:183], v[88:91]
	v_mfma_f32_16x16x32_bf16 v[76:79], v[148:151], v[188:191], v[76:79]
	v_mfma_f32_16x16x32_bf16 v[72:75], v[156:159], v[188:191], v[72:75]
	s_barrier
	ds_read_b128 v[192:195], v146 offset:49152
	ds_read_b128 v[196:199], v146 offset:50176
	ds_read_b128 v[200:203], v146 offset:51200
	ds_read_b128 v[204:207], v146 offset:52224
	s_waitcnt vmcnt(0)
	s_barrier
	s_waitcnt lgkmcnt(0)
	s_waitcnt lgkmcnt(0)
	v_mfma_f32_16x16x32_bf16 v[116:119], v[192:195], v[160:163], v[116:119]
	v_mfma_f32_16x16x32_bf16 v[112:115], v[200:203], v[160:163], v[112:115]
	v_mfma_f32_16x16x32_bf16 v[100:103], v[192:195], v[168:171], v[100:103]
	v_mfma_f32_16x16x32_bf16 v[96:99], v[200:203], v[168:171], v[96:99]
	v_mfma_f32_16x16x32_bf16 v[84:87], v[192:195], v[176:179], v[84:87]
	v_mfma_f32_16x16x32_bf16 v[80:83], v[200:203], v[176:179], v[80:83]
	v_mfma_f32_16x16x32_bf16 v[68:71], v[192:195], v[184:187], v[68:71]
	v_mfma_f32_16x16x32_bf16 v[64:67], v[200:203], v[184:187], v[64:67]
	v_mfma_f32_16x16x32_bf16 v[116:119], v[196:199], v[164:167], v[116:119]
	v_mfma_f32_16x16x32_bf16 v[112:115], v[204:207], v[164:167], v[112:115]
	v_mfma_f32_16x16x32_bf16 v[100:103], v[196:199], v[172:175], v[100:103]
	v_mfma_f32_16x16x32_bf16 v[96:99], v[204:207], v[172:175], v[96:99]
	v_mfma_f32_16x16x32_bf16 v[84:87], v[196:199], v[180:183], v[84:87]
	v_mfma_f32_16x16x32_bf16 v[80:83], v[204:207], v[180:183], v[80:83]
	v_mfma_f32_16x16x32_bf16 v[68:71], v[196:199], v[188:191], v[68:71]
	v_mfma_f32_16x16x32_bf16 v[64:67], v[204:207], v[188:191], v[64:67]
	s_barrier
	ds_read_b128 v[160:163], v147 offset:49152
	ds_read_b128 v[164:167], v147 offset:50176
	ds_read_b128 v[168:171], v147 offset:51200
	ds_read_b128 v[172:175], v147 offset:52224
	ds_read_b128 v[176:179], v147 offset:53248
	ds_read_b128 v[180:183], v147 offset:54272
	ds_read_b128 v[184:187], v147 offset:55296
	ds_read_b128 v[188:191], v147 offset:56320
	s_barrier
	s_waitcnt lgkmcnt(0)
	s_waitcnt lgkmcnt(0)
	v_mfma_f32_16x16x32_bf16 v[60:63], v[140:143], v[160:163], v[60:63]
	v_mfma_f32_16x16x32_bf16 v[56:59], v[152:155], v[160:163], v[56:59]
	v_mfma_f32_16x16x32_bf16 v[44:47], v[140:143], v[168:171], v[44:47]
	v_mfma_f32_16x16x32_bf16 v[40:43], v[152:155], v[168:171], v[40:43]
	v_mfma_f32_16x16x32_bf16 v[28:31], v[140:143], v[176:179], v[28:31]
	v_mfma_f32_16x16x32_bf16 v[24:27], v[152:155], v[176:179], v[24:27]
	v_mfma_f32_16x16x32_bf16 v[12:15], v[140:143], v[184:187], v[12:15]
	v_mfma_f32_16x16x32_bf16 v[8:11], v[152:155], v[184:187], v[8:11]
	v_mfma_f32_16x16x32_bf16 v[60:63], v[148:151], v[164:167], v[60:63]
	v_mfma_f32_16x16x32_bf16 v[56:59], v[156:159], v[164:167], v[56:59]
	v_mfma_f32_16x16x32_bf16 v[44:47], v[148:151], v[172:175], v[44:47]
	v_mfma_f32_16x16x32_bf16 v[40:43], v[156:159], v[172:175], v[40:43]
	v_mfma_f32_16x16x32_bf16 v[28:31], v[148:151], v[180:183], v[28:31]
	v_mfma_f32_16x16x32_bf16 v[24:27], v[156:159], v[180:183], v[24:27]
	v_mfma_f32_16x16x32_bf16 v[12:15], v[148:151], v[188:191], v[12:15]
	v_mfma_f32_16x16x32_bf16 v[8:11], v[156:159], v[188:191], v[8:11]
	v_mfma_f32_16x16x32_bf16 v[52:55], v[192:195], v[160:163], v[52:55]
	v_mfma_f32_16x16x32_bf16 v[48:51], v[200:203], v[160:163], v[48:51]
	v_mfma_f32_16x16x32_bf16 v[36:39], v[192:195], v[168:171], v[36:39]
	v_mfma_f32_16x16x32_bf16 v[32:35], v[200:203], v[168:171], v[32:35]
	v_mfma_f32_16x16x32_bf16 v[20:23], v[192:195], v[176:179], v[20:23]
	v_mfma_f32_16x16x32_bf16 v[16:19], v[200:203], v[176:179], v[16:19]
	v_mfma_f32_16x16x32_bf16 v[4:7], v[192:195], v[184:187], v[4:7]
	v_mfma_f32_16x16x32_bf16 v[0:3], v[200:203], v[184:187], v[0:3]
	v_mfma_f32_16x16x32_bf16 v[52:55], v[196:199], v[164:167], v[52:55]
	v_mfma_f32_16x16x32_bf16 v[48:51], v[204:207], v[164:167], v[48:51]
	v_mfma_f32_16x16x32_bf16 v[36:39], v[196:199], v[172:175], v[36:39]
	v_mfma_f32_16x16x32_bf16 v[32:35], v[204:207], v[172:175], v[32:35]
	v_mfma_f32_16x16x32_bf16 v[20:23], v[196:199], v[180:183], v[20:23]
	v_mfma_f32_16x16x32_bf16 v[16:19], v[204:207], v[180:183], v[16:19]
	v_mfma_f32_16x16x32_bf16 v[4:7], v[196:199], v[188:191], v[4:7]
	v_mfma_f32_16x16x32_bf16 v[0:3], v[204:207], v[188:191], v[0:3]
	s_barrier
	s_branch .LBB0_734

.LBB0_763:
	ds_read_b128 v[148:151], v146
	ds_read_b128 v[152:155], v146 offset:1024
	ds_read_b128 v[156:159], v146 offset:2048
	ds_read_b128 v[160:163], v146 offset:3072
	s_add_i32 s9, s2, 2
	s_cmp_gt_u32 s2, 61
	s_cselect_b32 s20, s52, s10
	s_cselect_b32 s16, s51, s8
	s_mov_b32 m0, s44
	ds_read_b128 v[164:167], v147
	ds_read_b128 v[168:171], v147 offset:1024
	ds_read_b128 v[172:175], v147 offset:2048
	ds_read_b128 v[176:179], v147 offset:3072
	ds_read_b128 v[180:183], v147 offset:4096
	ds_read_b128 v[184:187], v147 offset:5120
	ds_read_b128 v[188:191], v147 offset:6144
	ds_read_b128 v[192:195], v147 offset:7168
	global_load_lds_dwordx4 v[140:141], off
	s_mov_b32 m0, s45
	s_nop 0
	global_load_lds_dwordx4 v[142:143], off
	s_waitcnt lgkmcnt(8)
	s_barrier
	s_waitcnt lgkmcnt(0)
	s_waitcnt lgkmcnt(0)
	v_mfma_f32_16x16x32_bf16 v[124:127], v[148:151], v[164:167], v[124:127]
	v_mfma_f32_16x16x32_bf16 v[120:123], v[156:159], v[164:167], v[120:123]
	v_mfma_f32_16x16x32_bf16 v[116:119], v[148:151], v[172:175], v[116:119]
	v_mfma_f32_16x16x32_bf16 v[112:115], v[156:159], v[172:175], v[112:115]
	v_mfma_f32_16x16x32_bf16 v[100:103], v[148:151], v[180:183], v[100:103]
	v_mfma_f32_16x16x32_bf16 v[96:99], v[156:159], v[180:183], v[96:99]
	v_mfma_f32_16x16x32_bf16 v[84:87], v[148:151], v[188:191], v[84:87]
	v_mfma_f32_16x16x32_bf16 v[80:83], v[156:159], v[188:191], v[80:83]
	v_mfma_f32_16x16x32_bf16 v[124:127], v[152:155], v[168:171], v[124:127]
	v_mfma_f32_16x16x32_bf16 v[120:123], v[160:163], v[168:171], v[120:123]
	v_mfma_f32_16x16x32_bf16 v[116:119], v[152:155], v[176:179], v[116:119]
	v_mfma_f32_16x16x32_bf16 v[112:115], v[160:163], v[176:179], v[112:115]
	v_mfma_f32_16x16x32_bf16 v[100:103], v[152:155], v[184:187], v[100:103]
	v_mfma_f32_16x16x32_bf16 v[96:99], v[160:163], v[184:187], v[96:99]
	v_mfma_f32_16x16x32_bf16 v[84:87], v[152:155], v[192:195], v[84:87]
	v_mfma_f32_16x16x32_bf16 v[80:83], v[160:163], v[192:195], v[80:83]
	s_barrier
	s_cselect_b32 s2, 0, s9
	s_ashr_i32 s21, s20, 31
	s_lshl_b64 s[18:19], s[20:21], 13
	s_add_u32 s56, s24, s18
	s_addc_u32 s57, s25, s19
	s_lshl_b64 s[18:19], s[2:3], 7
	s_add_u32 s54, s56, s18
	s_addc_u32 s55, s57, s19
	s_mov_b32 m0, s11
	v_lshl_add_u64 v[212:213], s[54:55], 0, v[132:133]
	ds_read_b128 v[196:199], v146 offset:16384
	ds_read_b128 v[200:203], v146 offset:17408
	ds_read_b128 v[204:207], v146 offset:18432
	ds_read_b128 v[208:211], v146 offset:19456
	global_load_lds_dwordx4 v[212:213], off
	v_lshl_add_u64 v[212:213], s[54:55], 0, v[128:129]
	s_mov_b32 m0, s27
	s_nop 0
	global_load_lds_dwordx4 v[212:213], off
	s_barrier
	s_waitcnt lgkmcnt(0)
	s_waitcnt lgkmcnt(0)
	v_mfma_f32_16x16x32_bf16 v[108:111], v[196:199], v[164:167], v[108:111]
	v_mfma_f32_16x16x32_bf16 v[104:107], v[204:207], v[164:167], v[104:107]
	v_mfma_f32_16x16x32_bf16 v[92:95], v[196:199], v[172:175], v[92:95]
	v_mfma_f32_16x16x32_bf16 v[88:91], v[204:207], v[172:175], v[88:91]
	v_mfma_f32_16x16x32_bf16 v[76:79], v[196:199], v[180:183], v[76:79]
	v_mfma_f32_16x16x32_bf16 v[72:75], v[204:207], v[180:183], v[72:75]
	v_mfma_f32_16x16x32_bf16 v[68:71], v[196:199], v[188:191], v[68:71]
	v_mfma_f32_16x16x32_bf16 v[64:67], v[204:207], v[188:191], v[64:67]
	v_mfma_f32_16x16x32_bf16 v[108:111], v[200:203], v[168:171], v[108:111]
	v_mfma_f32_16x16x32_bf16 v[104:107], v[208:211], v[168:171], v[104:107]
	v_mfma_f32_16x16x32_bf16 v[92:95], v[200:203], v[176:179], v[92:95]
	v_mfma_f32_16x16x32_bf16 v[88:91], v[208:211], v[176:179], v[88:91]
	v_mfma_f32_16x16x32_bf16 v[76:79], v[200:203], v[184:187], v[76:79]
	v_mfma_f32_16x16x32_bf16 v[72:75], v[208:211], v[184:187], v[72:75]
	v_mfma_f32_16x16x32_bf16 v[68:71], v[200:203], v[192:195], v[68:71]
	v_mfma_f32_16x16x32_bf16 v[64:67], v[208:211], v[192:195], v[64:67]
	s_ashr_i32 s17, s16, 31
	s_lshl_b64 s[54:55], s[16:17], 13
	s_add_u32 s58, s22, s54
	s_addc_u32 s59, s23, s55
	s_add_u32 s54, s58, s18
	s_addc_u32 s55, s59, s19
	s_mov_b32 m0, s26
	v_lshl_add_u64 v[212:213], s[54:55], 0, v[134:135]
	s_barrier
	ds_read_b128 v[164:167], v147 offset:16384
	ds_read_b128 v[168:171], v147 offset:17408
	ds_read_b128 v[172:175], v147 offset:18432
	ds_read_b128 v[176:179], v147 offset:19456
	ds_read_b128 v[180:183], v147 offset:20480
	ds_read_b128 v[184:187], v147 offset:21504
	ds_read_b128 v[188:191], v147 offset:22528
	ds_read_b128 v[192:195], v147 offset:23552
	global_load_lds_dwordx4 v[212:213], off
	v_lshl_add_u64 v[212:213], s[54:55], 0, v[130:131]
	s_mov_b32 m0, s28
	s_nop 0
	global_load_lds_dwordx4 v[212:213], off
	s_barrier
	s_waitcnt lgkmcnt(0)
	s_waitcnt lgkmcnt(0)
	v_mfma_f32_16x16x32_bf16 v[60:63], v[148:151], v[164:167], v[60:63]
	v_mfma_f32_16x16x32_bf16 v[56:59], v[156:159], v[164:167], v[56:59]
	v_mfma_f32_16x16x32_bf16 v[52:55], v[148:151], v[172:175], v[52:55]
	v_mfma_f32_16x16x32_bf16 v[48:51], v[156:159], v[172:175], v[48:51]
	v_mfma_f32_16x16x32_bf16 v[36:39], v[148:151], v[180:183], v[36:39]
	v_mfma_f32_16x16x32_bf16 v[32:35], v[156:159], v[180:183], v[32:35]
	v_mfma_f32_16x16x32_bf16 v[20:23], v[148:151], v[188:191], v[20:23]
	v_mfma_f32_16x16x32_bf16 v[16:19], v[156:159], v[188:191], v[16:19]
	v_mfma_f32_16x16x32_bf16 v[60:63], v[152:155], v[168:171], v[60:63]
	v_mfma_f32_16x16x32_bf16 v[56:59], v[160:163], v[168:171], v[56:59]
	v_mfma_f32_16x16x32_bf16 v[52:55], v[152:155], v[176:179], v[52:55]
	v_mfma_f32_16x16x32_bf16 v[48:51], v[160:163], v[176:179], v[48:51]
	v_mfma_f32_16x16x32_bf16 v[36:39], v[152:155], v[184:187], v[36:39]
	v_mfma_f32_16x16x32_bf16 v[32:35], v[160:163], v[184:187], v[32:35]
	v_mfma_f32_16x16x32_bf16 v[20:23], v[152:155], v[192:195], v[20:23]
	v_mfma_f32_16x16x32_bf16 v[16:19], v[160:163], v[192:195], v[16:19]
	s_barrier
	s_bitset1_b32 s20, 7
	s_ashr_i32 s21, s20, 31
	s_lshl_b64 s[20:21], s[20:21], 13
	s_add_u32 s54, s24, s20
	s_addc_u32 s55, s25, s21
	s_add_u32 s20, s54, s18
	s_addc_u32 s21, s55, s19
	s_mov_b32 m0, s29
	v_lshl_add_u64 v[148:149], s[20:21], 0, v[132:133]
	global_load_lds_dwordx4 v[148:149], off
	v_lshl_add_u64 v[148:149], s[20:21], 0, v[128:129]
	s_mov_b32 m0, s30
	s_nop 0
	global_load_lds_dwordx4 v[148:149], off
	s_waitcnt vmcnt(6)
	s_barrier
	v_mfma_f32_16x16x32_bf16 v[44:47], v[196:199], v[164:167], v[44:47]
	v_mfma_f32_16x16x32_bf16 v[40:43], v[204:207], v[164:167], v[40:43]
	v_mfma_f32_16x16x32_bf16 v[28:31], v[196:199], v[172:175], v[28:31]
	v_mfma_f32_16x16x32_bf16 v[24:27], v[204:207], v[172:175], v[24:27]
	v_mfma_f32_16x16x32_bf16 v[12:15], v[196:199], v[180:183], v[12:15]
	v_mfma_f32_16x16x32_bf16 v[8:11], v[204:207], v[180:183], v[8:11]
	v_mfma_f32_16x16x32_bf16 v[4:7], v[196:199], v[188:191], v[4:7]
	v_mfma_f32_16x16x32_bf16 v[0:3], v[204:207], v[188:191], v[0:3]
	v_mfma_f32_16x16x32_bf16 v[44:47], v[200:203], v[168:171], v[44:47]
	v_mfma_f32_16x16x32_bf16 v[40:43], v[208:211], v[168:171], v[40:43]
	v_mfma_f32_16x16x32_bf16 v[28:31], v[200:203], v[176:179], v[28:31]
	v_mfma_f32_16x16x32_bf16 v[24:27], v[208:211], v[176:179], v[24:27]
	v_mfma_f32_16x16x32_bf16 v[12:15], v[200:203], v[184:187], v[12:15]
	v_mfma_f32_16x16x32_bf16 v[8:11], v[208:211], v[184:187], v[8:11]
	v_mfma_f32_16x16x32_bf16 v[4:7], v[200:203], v[192:195], v[4:7]
	v_mfma_f32_16x16x32_bf16 v[0:3], v[208:211], v[192:195], v[0:3]
	s_barrier
	ds_read_b128 v[148:151], v146 offset:32768
	ds_read_b128 v[152:155], v146 offset:33792
	ds_read_b128 v[156:159], v146 offset:34816
	ds_read_b128 v[160:163], v146 offset:35840
	s_bitset1_b32 s16, 7
	s_ashr_i32 s17, s16, 31
	s_lshl_b64 s[16:17], s[16:17], 13
	s_add_u32 s16, s22, s16
	s_addc_u32 s17, s23, s17
	s_add_u32 s16, s16, s18
	s_addc_u32 s17, s17, s19
	s_mov_b32 m0, s31
	v_lshl_add_u64 v[196:197], s[16:17], 0, v[134:135]
	ds_read_b128 v[164:167], v147 offset:32768
	ds_read_b128 v[168:171], v147 offset:33792
	ds_read_b128 v[172:175], v147 offset:34816
	ds_read_b128 v[176:179], v147 offset:35840
	ds_read_b128 v[180:183], v147 offset:36864
	ds_read_b128 v[184:187], v147 offset:37888
	ds_read_b128 v[188:191], v147 offset:38912
	ds_read_b128 v[192:195], v147 offset:39936
	global_load_lds_dwordx4 v[196:197], off
	v_lshl_add_u64 v[196:197], s[16:17], 0, v[130:131]
	s_mov_b32 m0, s33
	s_nop 0
	global_load_lds_dwordx4 v[196:197], off
	s_waitcnt lgkmcnt(8)
	s_barrier
	s_waitcnt lgkmcnt(0)
	s_waitcnt lgkmcnt(0)
	v_mfma_f32_16x16x32_bf16 v[124:127], v[148:151], v[164:167], v[124:127]
	v_mfma_f32_16x16x32_bf16 v[120:123], v[156:159], v[164:167], v[120:123]
	v_mfma_f32_16x16x32_bf16 v[116:119], v[148:151], v[172:175], v[116:119]
	v_mfma_f32_16x16x32_bf16 v[112:115], v[156:159], v[172:175], v[112:115]
	v_mfma_f32_16x16x32_bf16 v[100:103], v[148:151], v[180:183], v[100:103]
	v_mfma_f32_16x16x32_bf16 v[96:99], v[156:159], v[180:183], v[96:99]
	v_mfma_f32_16x16x32_bf16 v[84:87], v[148:151], v[188:191], v[84:87]
	v_mfma_f32_16x16x32_bf16 v[80:83], v[156:159], v[188:191], v[80:83]
	v_mfma_f32_16x16x32_bf16 v[124:127], v[152:155], v[168:171], v[124:127]
	v_mfma_f32_16x16x32_bf16 v[120:123], v[160:163], v[168:171], v[120:123]
	v_mfma_f32_16x16x32_bf16 v[116:119], v[152:155], v[176:179], v[116:119]
	v_mfma_f32_16x16x32_bf16 v[112:115], v[160:163], v[176:179], v[112:115]
	v_mfma_f32_16x16x32_bf16 v[100:103], v[152:155], v[184:187], v[100:103]
	v_mfma_f32_16x16x32_bf16 v[96:99], v[160:163], v[184:187], v[96:99]
	v_mfma_f32_16x16x32_bf16 v[84:87], v[152:155], v[192:195], v[84:87]
	v_mfma_f32_16x16x32_bf16 v[80:83], v[160:163], v[192:195], v[80:83]
	s_barrier
	s_or_b32 s2, s2, 1
	s_lshl_b64 s[16:17], s[2:3], 7
	s_add_u32 s18, s56, s16
	s_addc_u32 s19, s57, s17
	s_mov_b32 m0, s36
	v_lshl_add_u64 v[212:213], s[18:19], 0, v[132:133]
	ds_read_b128 v[196:199], v146 offset:49152
	ds_read_b128 v[200:203], v146 offset:50176
	ds_read_b128 v[204:207], v146 offset:51200
	ds_read_b128 v[208:211], v146 offset:52224
	global_load_lds_dwordx4 v[212:213], off
	v_lshl_add_u64 v[212:213], s[18:19], 0, v[128:129]
	s_mov_b32 m0, s37
	s_nop 0
	global_load_lds_dwordx4 v[212:213], off
	s_barrier
	s_waitcnt lgkmcnt(0)
	s_waitcnt lgkmcnt(0)
	v_mfma_f32_16x16x32_bf16 v[108:111], v[196:199], v[164:167], v[108:111]
	v_mfma_f32_16x16x32_bf16 v[104:107], v[204:207], v[164:167], v[104:107]
	v_mfma_f32_16x16x32_bf16 v[92:95], v[196:199], v[172:175], v[92:95]
	v_mfma_f32_16x16x32_bf16 v[88:91], v[204:207], v[172:175], v[88:91]
	v_mfma_f32_16x16x32_bf16 v[76:79], v[196:199], v[180:183], v[76:79]
	v_mfma_f32_16x16x32_bf16 v[72:75], v[204:207], v[180:183], v[72:75]
	v_mfma_f32_16x16x32_bf16 v[68:71], v[196:199], v[188:191], v[68:71]
	v_mfma_f32_16x16x32_bf16 v[64:67], v[204:207], v[188:191], v[64:67]
	v_mfma_f32_16x16x32_bf16 v[108:111], v[200:203], v[168:171], v[108:111]
	v_mfma_f32_16x16x32_bf16 v[104:107], v[208:211], v[168:171], v[104:107]
	v_mfma_f32_16x16x32_bf16 v[92:95], v[200:203], v[176:179], v[92:95]
	v_mfma_f32_16x16x32_bf16 v[88:91], v[208:211], v[176:179], v[88:91]
	v_mfma_f32_16x16x32_bf16 v[76:79], v[200:203], v[184:187], v[76:79]
	v_mfma_f32_16x16x32_bf16 v[72:75], v[208:211], v[184:187], v[72:75]
	v_mfma_f32_16x16x32_bf16 v[68:71], v[200:203], v[192:195], v[68:71]
	v_mfma_f32_16x16x32_bf16 v[64:67], v[208:211], v[192:195], v[64:67]
	s_add_u32 s18, s58, s16
	s_addc_u32 s19, s59, s17
	s_mov_b32 m0, s38
	v_lshl_add_u64 v[212:213], s[18:19], 0, v[134:135]
	s_barrier
	ds_read_b128 v[164:167], v147 offset:49152
	ds_read_b128 v[168:171], v147 offset:50176
	ds_read_b128 v[172:175], v147 offset:51200
	ds_read_b128 v[176:179], v147 offset:52224
	ds_read_b128 v[180:183], v147 offset:53248
	ds_read_b128 v[184:187], v147 offset:54272
	ds_read_b128 v[188:191], v147 offset:55296
	ds_read_b128 v[192:195], v147 offset:56320
	global_load_lds_dwordx4 v[212:213], off
	v_lshl_add_u64 v[212:213], s[18:19], 0, v[130:131]
	s_mov_b32 m0, s39
	s_nop 0
	global_load_lds_dwordx4 v[212:213], off
	s_barrier
	s_waitcnt lgkmcnt(0)
	s_waitcnt lgkmcnt(0)
	v_mfma_f32_16x16x32_bf16 v[60:63], v[148:151], v[164:167], v[60:63]
	v_mfma_f32_16x16x32_bf16 v[56:59], v[156:159], v[164:167], v[56:59]
	v_mfma_f32_16x16x32_bf16 v[52:55], v[148:151], v[172:175], v[52:55]
	v_mfma_f32_16x16x32_bf16 v[48:51], v[156:159], v[172:175], v[48:51]
	v_mfma_f32_16x16x32_bf16 v[36:39], v[148:151], v[180:183], v[36:39]
	v_mfma_f32_16x16x32_bf16 v[32:35], v[156:159], v[180:183], v[32:35]
	v_mfma_f32_16x16x32_bf16 v[20:23], v[148:151], v[188:191], v[20:23]
	v_mfma_f32_16x16x32_bf16 v[16:19], v[156:159], v[188:191], v[16:19]
	v_mfma_f32_16x16x32_bf16 v[60:63], v[152:155], v[168:171], v[60:63]
	v_mfma_f32_16x16x32_bf16 v[56:59], v[160:163], v[168:171], v[56:59]
	v_mfma_f32_16x16x32_bf16 v[52:55], v[152:155], v[176:179], v[52:55]
	v_mfma_f32_16x16x32_bf16 v[48:51], v[160:163], v[176:179], v[48:51]
	v_mfma_f32_16x16x32_bf16 v[36:39], v[152:155], v[184:187], v[36:39]
	v_mfma_f32_16x16x32_bf16 v[32:35], v[160:163], v[184:187], v[32:35]
	v_mfma_f32_16x16x32_bf16 v[20:23], v[152:155], v[192:195], v[20:23]
	v_mfma_f32_16x16x32_bf16 v[16:19], v[160:163], v[192:195], v[16:19]
	s_barrier
	s_add_u32 s16, s54, s16
	s_addc_u32 s17, s55, s17
	s_mov_b32 m0, s40
	v_lshl_add_u64 v[148:149], s[16:17], 0, v[132:133]
	global_load_lds_dwordx4 v[148:149], off
	v_lshl_add_u64 v[148:149], s[16:17], 0, v[128:129]
	s_mov_b32 m0, s41
	s_nop 0
	global_load_lds_dwordx4 v[148:149], off
	s_waitcnt vmcnt(6)
	s_barrier
	v_mfma_f32_16x16x32_bf16 v[44:47], v[196:199], v[164:167], v[44:47]
	v_mfma_f32_16x16x32_bf16 v[40:43], v[204:207], v[164:167], v[40:43]
	v_mfma_f32_16x16x32_bf16 v[28:31], v[196:199], v[172:175], v[28:31]
	v_mfma_f32_16x16x32_bf16 v[24:27], v[204:207], v[172:175], v[24:27]
	v_mfma_f32_16x16x32_bf16 v[12:15], v[196:199], v[180:183], v[12:15]
	v_mfma_f32_16x16x32_bf16 v[8:11], v[204:207], v[180:183], v[8:11]
	v_mfma_f32_16x16x32_bf16 v[4:7], v[196:199], v[188:191], v[4:7]
	v_mfma_f32_16x16x32_bf16 v[0:3], v[204:207], v[188:191], v[0:3]
	v_mfma_f32_16x16x32_bf16 v[44:47], v[200:203], v[168:171], v[44:47]
	v_mfma_f32_16x16x32_bf16 v[40:43], v[208:211], v[168:171], v[40:43]
	v_mfma_f32_16x16x32_bf16 v[28:31], v[200:203], v[176:179], v[28:31]
	v_mfma_f32_16x16x32_bf16 v[24:27], v[208:211], v[176:179], v[24:27]
	v_mfma_f32_16x16x32_bf16 v[12:15], v[200:203], v[184:187], v[12:15]
	v_mfma_f32_16x16x32_bf16 v[8:11], v[208:211], v[184:187], v[8:11]
	v_mfma_f32_16x16x32_bf16 v[4:7], v[200:203], v[192:195], v[4:7]
	v_mfma_f32_16x16x32_bf16 v[0:3], v[208:211], v[192:195], v[0:3]
	v_lshl_add_u64 v[140:141], v[140:141], 0, s[4:5]
	v_lshl_add_u64 v[142:143], v[142:143], 0, s[4:5]
	s_cmp_ge_u32 s9, s53
	s_mov_b32 s2, s9
	s_barrier
	s_cbranch_scc0 .LBB0_763
	s_andn2_b64 vcc, exec, s[6:7]
	s_cbranch_vccnz .LBB0_759
	s_bitset1_b32 s8, 7
	s_ashr_i32 s9, s8, 31
	s_lshl_b64 s[8:9], s[8:9], 13
	s_add_u32 s2, s22, s8
	s_addc_u32 s9, s23, s9
	s_add_u32 s8, s2, 0x1f80
	s_addc_u32 s9, s9, 0
	s_mov_b32 m0, s44
	v_lshl_add_u64 v[192:193], s[8:9], 0, v[134:135]
	ds_read_b128 v[140:143], v146
	ds_read_b128 v[148:151], v146 offset:1024
	ds_read_b128 v[152:155], v146 offset:2048
	ds_read_b128 v[156:159], v146 offset:3072
	ds_read_b128 v[160:163], v147
	ds_read_b128 v[164:167], v147 offset:1024
	ds_read_b128 v[168:171], v147 offset:2048
	ds_read_b128 v[172:175], v147 offset:3072
	ds_read_b128 v[176:179], v147 offset:4096
	ds_read_b128 v[180:183], v147 offset:5120
	ds_read_b128 v[184:187], v147 offset:6144
	ds_read_b128 v[188:191], v147 offset:7168
	global_load_lds_dwordx4 v[192:193], off
	v_lshl_add_u64 v[192:193], s[8:9], 0, v[130:131]
	s_mov_b32 m0, s45
	s_nop 0
	global_load_lds_dwordx4 v[192:193], off
	s_barrier
	s_waitcnt lgkmcnt(0)
	s_waitcnt lgkmcnt(0)
	v_mfma_f32_16x16x32_bf16 v[124:127], v[140:143], v[160:163], v[124:127]
	v_mfma_f32_16x16x32_bf16 v[120:123], v[152:155], v[160:163], v[120:123]
	v_mfma_f32_16x16x32_bf16 v[116:119], v[140:143], v[168:171], v[116:119]
	v_mfma_f32_16x16x32_bf16 v[112:115], v[152:155], v[168:171], v[112:115]
	v_mfma_f32_16x16x32_bf16 v[100:103], v[140:143], v[176:179], v[100:103]
	v_mfma_f32_16x16x32_bf16 v[96:99], v[152:155], v[176:179], v[96:99]
	v_mfma_f32_16x16x32_bf16 v[84:87], v[140:143], v[184:187], v[84:87]
	v_mfma_f32_16x16x32_bf16 v[80:83], v[152:155], v[184:187], v[80:83]
	v_mfma_f32_16x16x32_bf16 v[124:127], v[148:151], v[164:167], v[124:127]
	v_mfma_f32_16x16x32_bf16 v[120:123], v[156:159], v[164:167], v[120:123]
	v_mfma_f32_16x16x32_bf16 v[116:119], v[148:151], v[172:175], v[116:119]
	v_mfma_f32_16x16x32_bf16 v[112:115], v[156:159], v[172:175], v[112:115]
	v_mfma_f32_16x16x32_bf16 v[100:103], v[148:151], v[180:183], v[100:103]
	v_mfma_f32_16x16x32_bf16 v[96:99], v[156:159], v[180:183], v[96:99]
	v_mfma_f32_16x16x32_bf16 v[84:87], v[148:151], v[188:191], v[84:87]
	v_mfma_f32_16x16x32_bf16 v[80:83], v[156:159], v[188:191], v[80:83]
	s_barrier
	ds_read_b128 v[192:195], v146 offset:16384
	ds_read_b128 v[196:199], v146 offset:17408
	ds_read_b128 v[200:203], v146 offset:18432
	ds_read_b128 v[204:207], v146 offset:19456
	s_barrier
	s_waitcnt lgkmcnt(0)
	s_waitcnt lgkmcnt(0)
	v_mfma_f32_16x16x32_bf16 v[108:111], v[192:195], v[160:163], v[108:111]
	v_mfma_f32_16x16x32_bf16 v[104:107], v[200:203], v[160:163], v[104:107]
	v_mfma_f32_16x16x32_bf16 v[92:95], v[192:195], v[168:171], v[92:95]
	v_mfma_f32_16x16x32_bf16 v[88:91], v[200:203], v[168:171], v[88:91]
	v_mfma_f32_16x16x32_bf16 v[76:79], v[192:195], v[176:179], v[76:79]
	v_mfma_f32_16x16x32_bf16 v[72:75], v[200:203], v[176:179], v[72:75]
	v_mfma_f32_16x16x32_bf16 v[68:71], v[192:195], v[184:187], v[68:71]
	v_mfma_f32_16x16x32_bf16 v[64:67], v[200:203], v[184:187], v[64:67]
	v_mfma_f32_16x16x32_bf16 v[108:111], v[196:199], v[164:167], v[108:111]
	v_mfma_f32_16x16x32_bf16 v[104:107], v[204:207], v[164:167], v[104:107]
	v_mfma_f32_16x16x32_bf16 v[92:95], v[196:199], v[172:175], v[92:95]
	v_mfma_f32_16x16x32_bf16 v[88:91], v[204:207], v[172:175], v[88:91]
	v_mfma_f32_16x16x32_bf16 v[76:79], v[196:199], v[180:183], v[76:79]
	v_mfma_f32_16x16x32_bf16 v[72:75], v[204:207], v[180:183], v[72:75]
	v_mfma_f32_16x16x32_bf16 v[68:71], v[196:199], v[188:191], v[68:71]
	v_mfma_f32_16x16x32_bf16 v[64:67], v[204:207], v[188:191], v[64:67]
	s_barrier
	ds_read_b128 v[160:163], v147 offset:16384
	ds_read_b128 v[164:167], v147 offset:17408
	ds_read_b128 v[168:171], v147 offset:18432
	ds_read_b128 v[172:175], v147 offset:19456
	ds_read_b128 v[176:179], v147 offset:20480
	ds_read_b128 v[180:183], v147 offset:21504
	ds_read_b128 v[184:187], v147 offset:22528
	ds_read_b128 v[188:191], v147 offset:23552
	s_waitcnt vmcnt(4)
	s_barrier
	s_waitcnt lgkmcnt(0)
	s_waitcnt lgkmcnt(0)
	v_mfma_f32_16x16x32_bf16 v[60:63], v[140:143], v[160:163], v[60:63]
	v_mfma_f32_16x16x32_bf16 v[56:59], v[152:155], v[160:163], v[56:59]
	v_mfma_f32_16x16x32_bf16 v[52:55], v[140:143], v[168:171], v[52:55]
	v_mfma_f32_16x16x32_bf16 v[48:51], v[152:155], v[168:171], v[48:51]
	v_mfma_f32_16x16x32_bf16 v[36:39], v[140:143], v[176:179], v[36:39]
	v_mfma_f32_16x16x32_bf16 v[32:35], v[152:155], v[176:179], v[32:35]
	v_mfma_f32_16x16x32_bf16 v[20:23], v[140:143], v[184:187], v[20:23]
	v_mfma_f32_16x16x32_bf16 v[16:19], v[152:155], v[184:187], v[16:19]
	v_mfma_f32_16x16x32_bf16 v[60:63], v[148:151], v[164:167], v[60:63]
	v_mfma_f32_16x16x32_bf16 v[56:59], v[156:159], v[164:167], v[56:59]
	v_mfma_f32_16x16x32_bf16 v[52:55], v[148:151], v[172:175], v[52:55]
	v_mfma_f32_16x16x32_bf16 v[48:51], v[156:159], v[172:175], v[48:51]
	v_mfma_f32_16x16x32_bf16 v[36:39], v[148:151], v[180:183], v[36:39]
	v_mfma_f32_16x16x32_bf16 v[32:35], v[156:159], v[180:183], v[32:35]
	v_mfma_f32_16x16x32_bf16 v[20:23], v[148:151], v[188:191], v[20:23]
	v_mfma_f32_16x16x32_bf16 v[16:19], v[156:159], v[188:191], v[16:19]
	v_mfma_f32_16x16x32_bf16 v[44:47], v[192:195], v[160:163], v[44:47]
	v_mfma_f32_16x16x32_bf16 v[40:43], v[200:203], v[160:163], v[40:43]
	v_mfma_f32_16x16x32_bf16 v[28:31], v[192:195], v[168:171], v[28:31]
	v_mfma_f32_16x16x32_bf16 v[24:27], v[200:203], v[168:171], v[24:27]
	v_mfma_f32_16x16x32_bf16 v[12:15], v[192:195], v[176:179], v[12:15]
	v_mfma_f32_16x16x32_bf16 v[8:11], v[200:203], v[176:179], v[8:11]
	v_mfma_f32_16x16x32_bf16 v[4:7], v[192:195], v[184:187], v[4:7]
	v_mfma_f32_16x16x32_bf16 v[0:3], v[200:203], v[184:187], v[0:3]
	v_mfma_f32_16x16x32_bf16 v[44:47], v[196:199], v[164:167], v[44:47]
	v_mfma_f32_16x16x32_bf16 v[40:43], v[204:207], v[164:167], v[40:43]
	v_mfma_f32_16x16x32_bf16 v[28:31], v[196:199], v[172:175], v[28:31]
	v_mfma_f32_16x16x32_bf16 v[24:27], v[204:207], v[172:175], v[24:27]
	v_mfma_f32_16x16x32_bf16 v[12:15], v[196:199], v[180:183], v[12:15]
	v_mfma_f32_16x16x32_bf16 v[8:11], v[204:207], v[180:183], v[8:11]
	v_mfma_f32_16x16x32_bf16 v[4:7], v[196:199], v[188:191], v[4:7]
	v_mfma_f32_16x16x32_bf16 v[0:3], v[204:207], v[188:191], v[0:3]
	s_barrier
	ds_read_b128 v[140:143], v146 offset:32768
	ds_read_b128 v[148:151], v146 offset:33792
	ds_read_b128 v[152:155], v146 offset:34816
	ds_read_b128 v[156:159], v146 offset:35840
	ds_read_b128 v[160:163], v147 offset:32768
	ds_read_b128 v[164:167], v147 offset:33792
	ds_read_b128 v[168:171], v147 offset:34816
	ds_read_b128 v[172:175], v147 offset:35840
	ds_read_b128 v[176:179], v147 offset:36864
	ds_read_b128 v[180:183], v147 offset:37888
	ds_read_b128 v[184:187], v147 offset:38912
	ds_read_b128 v[188:191], v147 offset:39936
	s_waitcnt vmcnt(2)
	s_barrier
	s_waitcnt lgkmcnt(0)
	s_waitcnt lgkmcnt(0)
	v_mfma_f32_16x16x32_bf16 v[124:127], v[140:143], v[160:163], v[124:127]
	v_mfma_f32_16x16x32_bf16 v[120:123], v[152:155], v[160:163], v[120:123]
	v_mfma_f32_16x16x32_bf16 v[116:119], v[140:143], v[168:171], v[116:119]
	v_mfma_f32_16x16x32_bf16 v[112:115], v[152:155], v[168:171], v[112:115]
	v_mfma_f32_16x16x32_bf16 v[100:103], v[140:143], v[176:179], v[100:103]
	v_mfma_f32_16x16x32_bf16 v[96:99], v[152:155], v[176:179], v[96:99]
	v_mfma_f32_16x16x32_bf16 v[84:87], v[140:143], v[184:187], v[84:87]
	v_mfma_f32_16x16x32_bf16 v[80:83], v[152:155], v[184:187], v[80:83]
	v_mfma_f32_16x16x32_bf16 v[124:127], v[148:151], v[164:167], v[124:127]
	v_mfma_f32_16x16x32_bf16 v[120:123], v[156:159], v[164:167], v[120:123]
	v_mfma_f32_16x16x32_bf16 v[116:119], v[148:151], v[172:175], v[116:119]
	v_mfma_f32_16x16x32_bf16 v[112:115], v[156:159], v[172:175], v[112:115]
	v_mfma_f32_16x16x32_bf16 v[100:103], v[148:151], v[180:183], v[100:103]
	v_mfma_f32_16x16x32_bf16 v[96:99], v[156:159], v[180:183], v[96:99]
	v_mfma_f32_16x16x32_bf16 v[84:87], v[148:151], v[188:191], v[84:87]
	v_mfma_f32_16x16x32_bf16 v[80:83], v[156:159], v[188:191], v[80:83]
	s_barrier
	ds_read_b128 v[192:195], v146 offset:49152
	ds_read_b128 v[196:199], v146 offset:50176
	ds_read_b128 v[200:203], v146 offset:51200
	ds_read_b128 v[204:207], v146 offset:52224
	s_waitcnt vmcnt(0)
	s_barrier
	s_waitcnt lgkmcnt(0)
	s_waitcnt lgkmcnt(0)
	v_mfma_f32_16x16x32_bf16 v[108:111], v[192:195], v[160:163], v[108:111]
	v_mfma_f32_16x16x32_bf16 v[104:107], v[200:203], v[160:163], v[104:107]
	v_mfma_f32_16x16x32_bf16 v[92:95], v[192:195], v[168:171], v[92:95]
	v_mfma_f32_16x16x32_bf16 v[88:91], v[200:203], v[168:171], v[88:91]
	v_mfma_f32_16x16x32_bf16 v[76:79], v[192:195], v[176:179], v[76:79]
	v_mfma_f32_16x16x32_bf16 v[72:75], v[200:203], v[176:179], v[72:75]
	v_mfma_f32_16x16x32_bf16 v[68:71], v[192:195], v[184:187], v[68:71]
	v_mfma_f32_16x16x32_bf16 v[64:67], v[200:203], v[184:187], v[64:67]
	v_mfma_f32_16x16x32_bf16 v[108:111], v[196:199], v[164:167], v[108:111]
	v_mfma_f32_16x16x32_bf16 v[104:107], v[204:207], v[164:167], v[104:107]
	v_mfma_f32_16x16x32_bf16 v[92:95], v[196:199], v[172:175], v[92:95]
	v_mfma_f32_16x16x32_bf16 v[88:91], v[204:207], v[172:175], v[88:91]
	v_mfma_f32_16x16x32_bf16 v[76:79], v[196:199], v[180:183], v[76:79]
	v_mfma_f32_16x16x32_bf16 v[72:75], v[204:207], v[180:183], v[72:75]
	v_mfma_f32_16x16x32_bf16 v[68:71], v[196:199], v[188:191], v[68:71]
	v_mfma_f32_16x16x32_bf16 v[64:67], v[204:207], v[188:191], v[64:67]
	s_barrier
	ds_read_b128 v[160:163], v147 offset:49152
	ds_read_b128 v[164:167], v147 offset:50176
	ds_read_b128 v[168:171], v147 offset:51200
	ds_read_b128 v[172:175], v147 offset:52224
	ds_read_b128 v[176:179], v147 offset:53248
	ds_read_b128 v[180:183], v147 offset:54272
	ds_read_b128 v[184:187], v147 offset:55296
	ds_read_b128 v[188:191], v147 offset:56320
	s_barrier
	s_waitcnt lgkmcnt(0)
	s_waitcnt lgkmcnt(0)
	v_mfma_f32_16x16x32_bf16 v[60:63], v[140:143], v[160:163], v[60:63]
	v_mfma_f32_16x16x32_bf16 v[56:59], v[152:155], v[160:163], v[56:59]
	v_mfma_f32_16x16x32_bf16 v[52:55], v[140:143], v[168:171], v[52:55]
	v_mfma_f32_16x16x32_bf16 v[48:51], v[152:155], v[168:171], v[48:51]
	v_mfma_f32_16x16x32_bf16 v[36:39], v[140:143], v[176:179], v[36:39]
	v_mfma_f32_16x16x32_bf16 v[32:35], v[152:155], v[176:179], v[32:35]
	v_mfma_f32_16x16x32_bf16 v[20:23], v[140:143], v[184:187], v[20:23]
	v_mfma_f32_16x16x32_bf16 v[16:19], v[152:155], v[184:187], v[16:19]
	v_mfma_f32_16x16x32_bf16 v[60:63], v[148:151], v[164:167], v[60:63]
	v_mfma_f32_16x16x32_bf16 v[56:59], v[156:159], v[164:167], v[56:59]
	v_mfma_f32_16x16x32_bf16 v[52:55], v[148:151], v[172:175], v[52:55]
	v_mfma_f32_16x16x32_bf16 v[48:51], v[156:159], v[172:175], v[48:51]
	v_mfma_f32_16x16x32_bf16 v[36:39], v[148:151], v[180:183], v[36:39]
	v_mfma_f32_16x16x32_bf16 v[32:35], v[156:159], v[180:183], v[32:35]
	v_mfma_f32_16x16x32_bf16 v[20:23], v[148:151], v[188:191], v[20:23]
	v_mfma_f32_16x16x32_bf16 v[16:19], v[156:159], v[188:191], v[16:19]
	v_mfma_f32_16x16x32_bf16 v[44:47], v[192:195], v[160:163], v[44:47]
	v_mfma_f32_16x16x32_bf16 v[40:43], v[200:203], v[160:163], v[40:43]
	v_mfma_f32_16x16x32_bf16 v[28:31], v[192:195], v[168:171], v[28:31]
	v_mfma_f32_16x16x32_bf16 v[24:27], v[200:203], v[168:171], v[24:27]
	v_mfma_f32_16x16x32_bf16 v[12:15], v[192:195], v[176:179], v[12:15]
	v_mfma_f32_16x16x32_bf16 v[8:11], v[200:203], v[176:179], v[8:11]
	v_mfma_f32_16x16x32_bf16 v[4:7], v[192:195], v[184:187], v[4:7]
	v_mfma_f32_16x16x32_bf16 v[0:3], v[200:203], v[184:187], v[0:3]
	v_mfma_f32_16x16x32_bf16 v[44:47], v[196:199], v[164:167], v[44:47]
	v_mfma_f32_16x16x32_bf16 v[40:43], v[204:207], v[164:167], v[40:43]
	v_mfma_f32_16x16x32_bf16 v[28:31], v[196:199], v[172:175], v[28:31]
	v_mfma_f32_16x16x32_bf16 v[24:27], v[204:207], v[172:175], v[24:27]
	v_mfma_f32_16x16x32_bf16 v[12:15], v[196:199], v[180:183], v[12:15]
	v_mfma_f32_16x16x32_bf16 v[8:11], v[204:207], v[180:183], v[8:11]
	v_mfma_f32_16x16x32_bf16 v[4:7], v[196:199], v[188:191], v[4:7]
	v_mfma_f32_16x16x32_bf16 v[0:3], v[204:207], v[188:191], v[0:3]
	s_barrier
	s_branch .LBB0_759
